# speedup vs baseline: 1.0030x; 1.0019x over previous
; #define STAGE(P, GP, ktrel) do { const GAS char* _g = (GP) + (ktrel) * (BK * 2); \
;     __builtin_amdgcn_global_load_lds((const GAS unsigned*)(_g + so0), (unsigned*)((char*)(P) + tid_ * 16), 16, 0, 0); \
;     __builtin_amdgcn_global_load_lds((const GAS unsigned*)(_g + so1), (unsigned*)((char*)(P) + tid_ * 16 + 8192), 16, 0, 0); } while (0)
; #define WAIT_V(n) asm volatile("s_waitcnt vmcnt(" #n ")" ::: "memory")
; #define WAIT_L(n) asm volatile("s_waitcnt lgkmcnt(" #n ")" ::: "memory")
; #define BAR __builtin_amdgcn_s_barrier()
; #define SCHED __builtin_amdgcn_sched_barrier(0)
; #define LDA(dst, b, h) for (int m = 0; m < 4; ++m) for (int k = 0; k < 2; ++k) \
;     dst[m][k] = *reinterpret_cast<const bf16x8*>((char*)SA(b, h) + lds_byte(wr * 64 + m * 16 + fr, k * 32 + fq * 8))
; #define LDB(dst, b, h) for (int n = 0; n < 2; ++n) for (int k = 0; k < 2; ++k) \
;     dst[n][k] = *reinterpret_cast<const bf16x8*>((char*)SB(b, h) + lds_byte(wc * 32 + n * 16 + fr, k * 32 + fq * 8))
; template <int K, int LD = K>
; __device__ __forceinline__ void gemm_main(const GAS bf16* A, const GAS bf16* Bt, int brow, int bcol, f32x4 (&acc)[2][2][4][2]) {
;     ...
;   for (int t = 0; t < nt - 2; t += 2) {
;     LDB(B0, 0, 0); SCHED; LDA(At, 0, 0); STAGE(SA(1, 1), pA1, 1);
;     WAIT_L(8); BAR; WAIT_L(0); MMA(0, 0, At, B0); BAR; SCHED;
;     LDB(B1, 0, 1); STAGE(SB(0, 0), pB0, 2);
;     BAR; WAIT_L(0); MMA(0, 1, At, B1); BAR;
;     LDA(At, 0, 1); STAGE(SA(0, 0), pA0, 2);
;     BAR; WAIT_L(0); MMA(1, 0, At, B0); BAR; SCHED;
;     STAGE(SB(0, 1), pB1, 2);
;     WAIT_V(6); BAR; MMA(1, 1, At, B1); BAR;
;     LDB(B0, 1, 0); SCHED; LDA(At, 1, 0); STAGE(SA(0, 1), pA1, 2);
;     WAIT_L(8); BAR; WAIT_L(0); MMA(0, 0, At, B0); BAR; SCHED;
;     LDB(B1, 1, 1); STAGE(SB(1, 0), pB0, 3);
;     BAR; WAIT_L(0); MMA(0, 1, At, B1); BAR;
;     LDA(At, 1, 1); STAGE(SA(1, 0), pA0, 3);
;     BAR; WAIT_L(0); MMA(1, 0, At, B0); BAR; SCHED;
;     STAGE(SB(1, 1), pB1, 3);
;     WAIT_V(6); BAR; MMA(1, 1, At, B1); BAR;
;     pA0 += 4 * BK; pA1 += 4 * BK; pB0 += 4 * BK; pB1 += 4 * BK;
;     asm volatile("" : "+s"(pA0), "+s"(pA1), "+s"(pB0), "+s"(pB1));
;   }
.LBB0_89:
	ds_read_b128 v[162:165], v144
	ds_read_b128 v[166:169], v144 offset:1024
	ds_read_b128 v[174:177], v144 offset:2048
	ds_read_b128 v[178:181], v144 offset:3072
	v_lshl_add_u64 v[230:231], s[14:15], 0, v[130:131]
	v_readfirstlane_b32 s24, v151
	v_lshl_add_u64 v[214:215], v[230:231], 0, s[8:9]
	s_mov_b32 m0, s24
	v_lshl_add_u64 v[232:233], s[14:15], 0, v[132:133]
	v_readfirstlane_b32 s24, v150
	ds_read_b128 v[182:185], v140
	ds_read_b128 v[186:189], v140 offset:1024
	ds_read_b128 v[190:193], v139
	ds_read_b128 v[194:197], v139 offset:1024
	ds_read_b128 v[198:201], v138
	ds_read_b128 v[202:205], v138 offset:1024
	ds_read_b128 v[206:209], v137
	ds_read_b128 v[210:213], v137 offset:1024
	global_load_lds_dwordx4 v[214:215], off
	v_lshl_add_u64 v[214:215], v[232:233], 0, s[8:9]
	s_mov_b32 m0, s24
	s_nop 0
	global_load_lds_dwordx4 v[214:215], off
	s_waitcnt lgkmcnt(8)
	s_waitcnt vmcnt(10)
	s_barrier
	s_waitcnt lgkmcnt(0)
	s_setprio 1
	s_waitcnt lgkmcnt(0)
	v_mfma_f32_16x16x32_bf16 v[126:129], v[182:185], v[162:165], v[126:129]
	v_mfma_f32_16x16x32_bf16 v[122:125], v[182:185], v[174:177], v[122:125]
	v_mfma_f32_16x16x32_bf16 v[118:121], v[190:193], v[162:165], v[118:121]
	v_mfma_f32_16x16x32_bf16 v[114:117], v[190:193], v[174:177], v[114:117]
	v_mfma_f32_16x16x32_bf16 v[110:113], v[198:201], v[162:165], v[110:113]
	v_mfma_f32_16x16x32_bf16 v[106:109], v[198:201], v[174:177], v[106:109]
	v_mfma_f32_16x16x32_bf16 v[102:105], v[206:209], v[162:165], v[102:105]
	v_mfma_f32_16x16x32_bf16 v[98:101], v[206:209], v[174:177], v[98:101]
	v_mfma_f32_16x16x32_bf16 v[126:129], v[186:189], v[166:169], v[126:129]
	v_mfma_f32_16x16x32_bf16 v[122:125], v[186:189], v[178:181], v[122:125]
	v_mfma_f32_16x16x32_bf16 v[118:121], v[194:197], v[166:169], v[118:121]
	v_mfma_f32_16x16x32_bf16 v[114:117], v[194:197], v[178:181], v[114:117]
	v_mfma_f32_16x16x32_bf16 v[110:113], v[202:205], v[166:169], v[110:113]
	v_mfma_f32_16x16x32_bf16 v[106:109], v[202:205], v[178:181], v[106:109]
	v_mfma_f32_16x16x32_bf16 v[102:105], v[210:213], v[166:169], v[102:105]
	v_mfma_f32_16x16x32_bf16 v[98:101], v[210:213], v[178:181], v[98:101]
	s_setprio 0
	s_barrier
	v_lshl_add_u64 v[234:235], s[22:23], 0, v[130:131]
	v_readfirstlane_b32 s24, v146
	v_lshl_add_u64 v[236:237], v[234:235], 0, s[10:11]
	s_mov_b32 m0, s24
	ds_read_b128 v[214:217], v143
	ds_read_b128 v[218:221], v143 offset:1024
	ds_read_b128 v[222:225], v143 offset:2048
	ds_read_b128 v[226:229], v143 offset:3072
	global_load_lds_dwordx4 v[236:237], off
	v_lshl_add_u64 v[236:237], s[22:23], 0, v[132:133]
	v_readfirstlane_b32 s24, v157
	v_lshl_add_u64 v[238:239], v[236:237], 0, s[10:11]
	s_mov_b32 m0, s24
	s_add_u32 s22, s22, 0x100
	global_load_lds_dwordx4 v[238:239], off
	s_waitcnt vmcnt(10)
	s_barrier
	s_waitcnt lgkmcnt(0)
	s_addc_u32 s23, s23, 0
	s_setprio 1
	s_waitcnt lgkmcnt(0)
	v_mfma_f32_16x16x32_bf16 v[94:97], v[182:185], v[214:217], v[94:97]
	v_mfma_f32_16x16x32_bf16 v[90:93], v[182:185], v[222:225], v[90:93]
	v_mfma_f32_16x16x32_bf16 v[86:89], v[190:193], v[214:217], v[86:89]
	v_mfma_f32_16x16x32_bf16 v[82:85], v[190:193], v[222:225], v[82:85]
	v_mfma_f32_16x16x32_bf16 v[78:81], v[198:201], v[214:217], v[78:81]
	v_mfma_f32_16x16x32_bf16 v[74:77], v[198:201], v[222:225], v[74:77]
	v_mfma_f32_16x16x32_bf16 v[70:73], v[206:209], v[214:217], v[70:73]
	v_mfma_f32_16x16x32_bf16 v[66:69], v[206:209], v[222:225], v[66:69]
	v_mfma_f32_16x16x32_bf16 v[94:97], v[186:189], v[218:221], v[94:97]
	v_mfma_f32_16x16x32_bf16 v[90:93], v[186:189], v[226:229], v[90:93]
	v_mfma_f32_16x16x32_bf16 v[86:89], v[194:197], v[218:221], v[86:89]
	v_mfma_f32_16x16x32_bf16 v[82:85], v[194:197], v[226:229], v[82:85]
	v_mfma_f32_16x16x32_bf16 v[78:81], v[202:205], v[218:221], v[78:81]
	v_mfma_f32_16x16x32_bf16 v[74:77], v[202:205], v[226:229], v[74:77]
	v_mfma_f32_16x16x32_bf16 v[70:73], v[210:213], v[218:221], v[70:73]
	v_mfma_f32_16x16x32_bf16 v[66:69], v[210:213], v[226:229], v[66:69]
	s_setprio 0
	v_lshl_add_u64 v[238:239], s[20:21], 0, v[130:131]
	v_readfirstlane_b32 s24, v145
	v_lshl_add_u64 v[240:241], v[238:239], 0, s[10:11]
	s_mov_b32 m0, s24
	s_barrier
	ds_read_b128 v[182:185], v140 offset:16384
	ds_read_b128 v[186:189], v140 offset:17408
	ds_read_b128 v[190:193], v139 offset:16384
	ds_read_b128 v[194:197], v139 offset:17408
	ds_read_b128 v[198:201], v138 offset:16384
	ds_read_b128 v[202:205], v138 offset:17408
	ds_read_b128 v[206:209], v137 offset:16384
	ds_read_b128 v[210:213], v137 offset:17408
	global_load_lds_dwordx4 v[240:241], off
	v_lshl_add_u64 v[240:241], s[20:21], 0, v[132:133]
	v_readfirstlane_b32 s24, v152
	v_lshl_add_u64 v[242:243], v[240:241], 0, s[10:11]
	s_mov_b32 m0, s24
	s_add_u32 s20, s20, 0x100
	global_load_lds_dwordx4 v[242:243], off
	s_barrier
	s_waitcnt lgkmcnt(0)
	s_addc_u32 s21, s21, 0
	s_setprio 1
	s_waitcnt lgkmcnt(0)
	v_mfma_f32_16x16x32_bf16 v[62:65], v[182:185], v[162:165], v[62:65]
	v_mfma_f32_16x16x32_bf16 v[58:61], v[182:185], v[174:177], v[58:61]
	v_mfma_f32_16x16x32_bf16 v[54:57], v[190:193], v[162:165], v[54:57]
	v_mfma_f32_16x16x32_bf16 v[50:53], v[190:193], v[174:177], v[50:53]
	v_mfma_f32_16x16x32_bf16 v[46:49], v[198:201], v[162:165], v[46:49]
	v_mfma_f32_16x16x32_bf16 v[42:45], v[198:201], v[174:177], v[42:45]
	v_mfma_f32_16x16x32_bf16 v[38:41], v[206:209], v[162:165], v[38:41]
	v_mfma_f32_16x16x32_bf16 v[34:37], v[206:209], v[174:177], v[34:37]
	v_mfma_f32_16x16x32_bf16 v[62:65], v[186:189], v[166:169], v[62:65]
	v_mfma_f32_16x16x32_bf16 v[58:61], v[186:189], v[178:181], v[58:61]
	v_mfma_f32_16x16x32_bf16 v[54:57], v[194:197], v[166:169], v[54:57]
	v_mfma_f32_16x16x32_bf16 v[50:53], v[194:197], v[178:181], v[50:53]
	v_mfma_f32_16x16x32_bf16 v[46:49], v[202:205], v[166:169], v[46:49]
	v_mfma_f32_16x16x32_bf16 v[42:45], v[202:205], v[178:181], v[42:45]
	v_mfma_f32_16x16x32_bf16 v[38:41], v[210:213], v[166:169], v[38:41]
	v_mfma_f32_16x16x32_bf16 v[34:37], v[210:213], v[178:181], v[34:37]
	s_setprio 0
	s_barrier
; #define STAGE(P, GP, ktrel) do { const GAS char* _g = (GP) + (ktrel) * (BK * 2); \
;     __builtin_amdgcn_global_load_lds((const GAS unsigned*)(_g + so0), (unsigned*)((char*)(P) + tid_ * 16), 16, 0, 0); \
;     __builtin_amdgcn_global_load_lds((const GAS unsigned*)(_g + so1), (unsigned*)((char*)(P) + tid_ * 16 + 8192), 16, 0, 0); } while (0)
; #define WAIT_V(n) asm volatile("s_waitcnt vmcnt(" #n ")" ::: "memory")
; #define WAIT_L(n) asm volatile("s_waitcnt lgkmcnt(" #n ")" ::: "memory")
; #define BAR __builtin_amdgcn_s_barrier()
; #define SCHED __builtin_amdgcn_sched_barrier(0)
; #define LDA(dst, b, h) for (int m = 0; m < 4; ++m) for (int k = 0; k < 2; ++k) \
;     dst[m][k] = *reinterpret_cast<const bf16x8*>((char*)SA(b, h) + lds_byte(wr * 64 + m * 16 + fr, k * 32 + fq * 8))
; #define LDB(dst, b, h) for (int n = 0; n < 2; ++n) for (int k = 0; k < 2; ++k) \
;     dst[n][k] = *reinterpret_cast<const bf16x8*>((char*)SB(b, h) + lds_byte(wc * 32 + n * 16 + fr, k * 32 + fq * 8))
; template <int K, int LD = K>
; __device__ __forceinline__ void gemm_main(const GAS bf16* A, const GAS bf16* Bt, int brow, int bcol, f32x4 (&acc)[2][2][4][2]) {
;     ...
;   for (int t = 0; t < nt - 2; t += 2) {
;     LDB(B0, 0, 0); SCHED; LDA(At, 0, 0); STAGE(SA(1, 1), pA1, 1);
;     WAIT_L(8); BAR; WAIT_L(0); MMA(0, 0, At, B0); BAR; SCHED;
;     LDB(B1, 0, 1); STAGE(SB(0, 0), pB0, 2);
;     BAR; WAIT_L(0); MMA(0, 1, At, B1); BAR;
;     LDA(At, 0, 1); STAGE(SA(0, 0), pA0, 2);
;     BAR; WAIT_L(0); MMA(1, 0, At, B0); BAR; SCHED;
;     STAGE(SB(0, 1), pB1, 2);
;     WAIT_V(6); BAR; MMA(1, 1, At, B1); BAR;
;     LDB(B0, 1, 0); SCHED; LDA(At, 1, 0); STAGE(SA(0, 1), pA1, 2);
;     WAIT_L(8); BAR; WAIT_L(0); MMA(0, 0, At, B0); BAR; SCHED;
;     LDB(B1, 1, 1); STAGE(SB(1, 0), pB0, 3);
;     BAR; WAIT_L(0); MMA(0, 1, At, B1); BAR;
;     LDA(At, 1, 1); STAGE(SA(1, 0), pA0, 3);
;     BAR; WAIT_L(0); MMA(1, 0, At, B0); BAR; SCHED;
;     STAGE(SB(1, 1), pB1, 3);
;     WAIT_V(6); BAR; MMA(1, 1, At, B1); BAR;
;     pA0 += 4 * BK; pA1 += 4 * BK; pB0 += 4 * BK; pB1 += 4 * BK;
;     asm volatile("" : "+s"(pA0), "+s"(pA1), "+s"(pB0), "+s"(pB1));
;   }
	v_lshl_add_u64 v[242:243], s[18:19], 0, v[130:131]
	v_readfirstlane_b32 s24, v147
	v_lshl_add_u64 v[162:163], v[242:243], 0, s[10:11]
	s_mov_b32 m0, s24
	v_lshl_add_u64 v[244:245], s[18:19], 0, v[132:133]
	v_readfirstlane_b32 s24, v158
	global_load_lds_dwordx4 v[162:163], off
	v_lshl_add_u64 v[162:163], v[244:245], 0, s[10:11]
	s_mov_b32 m0, s24
	s_add_u32 s18, s18, 0x100
	global_load_lds_dwordx4 v[162:163], off
	s_waitcnt vmcnt(10)
	s_addc_u32 s19, s19, 0
	s_barrier
	s_setprio 1
	v_mfma_f32_16x16x32_bf16 v[30:33], v[182:185], v[214:217], v[30:33]
	v_mfma_f32_16x16x32_bf16 v[26:29], v[182:185], v[222:225], v[26:29]
	v_mfma_f32_16x16x32_bf16 v[22:25], v[190:193], v[214:217], v[22:25]
	v_mfma_f32_16x16x32_bf16 v[18:21], v[190:193], v[222:225], v[18:21]
	v_mfma_f32_16x16x32_bf16 v[14:17], v[198:201], v[214:217], v[14:17]
	v_mfma_f32_16x16x32_bf16 v[10:13], v[198:201], v[222:225], v[10:13]
	v_mfma_f32_16x16x32_bf16 v[6:9], v[206:209], v[214:217], v[6:9]
	v_mfma_f32_16x16x32_bf16 v[2:5], v[206:209], v[222:225], v[2:5]
	v_mfma_f32_16x16x32_bf16 v[30:33], v[186:189], v[218:221], v[30:33]
	v_mfma_f32_16x16x32_bf16 v[26:29], v[186:189], v[226:229], v[26:29]
	v_mfma_f32_16x16x32_bf16 v[22:25], v[194:197], v[218:221], v[22:25]
	v_mfma_f32_16x16x32_bf16 v[18:21], v[194:197], v[226:229], v[18:21]
	v_mfma_f32_16x16x32_bf16 v[14:17], v[202:205], v[218:221], v[14:17]
	v_mfma_f32_16x16x32_bf16 v[10:13], v[202:205], v[226:229], v[10:13]
	v_mfma_f32_16x16x32_bf16 v[6:9], v[210:213], v[218:221], v[6:9]
	v_mfma_f32_16x16x32_bf16 v[2:5], v[210:213], v[226:229], v[2:5]
	s_setprio 0
	s_barrier
	ds_read_b128 v[162:165], v142
	ds_read_b128 v[166:169], v142 offset:1024
	ds_read_b128 v[174:177], v142 offset:2048
	ds_read_b128 v[178:181], v142 offset:3072
	v_readfirstlane_b32 s24, v153
	v_lshl_add_u64 v[214:215], v[230:231], 0, s[10:11]
	s_mov_b32 m0, s24
	v_readfirstlane_b32 s24, v154
	ds_read_b128 v[182:185], v140 offset:32768
	ds_read_b128 v[186:189], v140 offset:33792
	ds_read_b128 v[190:193], v139 offset:32768
	ds_read_b128 v[194:197], v139 offset:33792
	ds_read_b128 v[198:201], v138 offset:32768
	ds_read_b128 v[202:205], v138 offset:33792
	ds_read_b128 v[206:209], v137 offset:32768
	ds_read_b128 v[210:213], v137 offset:33792
	global_load_lds_dwordx4 v[214:215], off
	v_lshl_add_u64 v[214:215], v[232:233], 0, s[10:11]
	s_mov_b32 m0, s24
	s_add_u32 s14, s14, 0x100
	global_load_lds_dwordx4 v[214:215], off
	s_waitcnt lgkmcnt(8)
	s_waitcnt vmcnt(10)
	s_barrier
	s_waitcnt lgkmcnt(0)
	s_addc_u32 s15, s15, 0
	s_setprio 1
	s_waitcnt lgkmcnt(0)
	v_mfma_f32_16x16x32_bf16 v[126:129], v[182:185], v[162:165], v[126:129]
	v_mfma_f32_16x16x32_bf16 v[122:125], v[182:185], v[174:177], v[122:125]
	v_mfma_f32_16x16x32_bf16 v[118:121], v[190:193], v[162:165], v[118:121]
	v_mfma_f32_16x16x32_bf16 v[114:117], v[190:193], v[174:177], v[114:117]
	v_mfma_f32_16x16x32_bf16 v[110:113], v[198:201], v[162:165], v[110:113]
	v_mfma_f32_16x16x32_bf16 v[106:109], v[198:201], v[174:177], v[106:109]
	v_mfma_f32_16x16x32_bf16 v[102:105], v[206:209], v[162:165], v[102:105]
	v_mfma_f32_16x16x32_bf16 v[98:101], v[206:209], v[174:177], v[98:101]
	v_mfma_f32_16x16x32_bf16 v[126:129], v[186:189], v[166:169], v[126:129]
	v_mfma_f32_16x16x32_bf16 v[122:125], v[186:189], v[178:181], v[122:125]
	v_mfma_f32_16x16x32_bf16 v[118:121], v[194:197], v[166:169], v[118:121]
	v_mfma_f32_16x16x32_bf16 v[114:117], v[194:197], v[178:181], v[114:117]
	v_mfma_f32_16x16x32_bf16 v[110:113], v[202:205], v[166:169], v[110:113]
	v_mfma_f32_16x16x32_bf16 v[106:109], v[202:205], v[178:181], v[106:109]
	v_mfma_f32_16x16x32_bf16 v[102:105], v[210:213], v[166:169], v[102:105]
	v_mfma_f32_16x16x32_bf16 v[98:101], v[210:213], v[178:181], v[98:101]
	s_setprio 0
	s_barrier
	v_readfirstlane_b32 s24, v148
	v_lshl_add_u64 v[230:231], v[234:235], 0, s[12:13]
	s_mov_b32 m0, s24
	v_readfirstlane_b32 s24, v159
	ds_read_b128 v[214:217], v141
	ds_read_b128 v[218:221], v141 offset:1024
	ds_read_b128 v[222:225], v141 offset:2048
	ds_read_b128 v[226:229], v141 offset:3072
	global_load_lds_dwordx4 v[230:231], off
	v_lshl_add_u64 v[230:231], v[236:237], 0, s[12:13]
	s_mov_b32 m0, s24
	s_nop 0
	global_load_lds_dwordx4 v[230:231], off
	s_waitcnt vmcnt(10)
	s_barrier
	s_waitcnt lgkmcnt(0)
	s_setprio 1
	s_waitcnt lgkmcnt(0)
	v_mfma_f32_16x16x32_bf16 v[94:97], v[182:185], v[214:217], v[94:97]
	v_mfma_f32_16x16x32_bf16 v[90:93], v[182:185], v[222:225], v[90:93]
	v_mfma_f32_16x16x32_bf16 v[86:89], v[190:193], v[214:217], v[86:89]
	v_mfma_f32_16x16x32_bf16 v[82:85], v[190:193], v[222:225], v[82:85]
	v_mfma_f32_16x16x32_bf16 v[78:81], v[198:201], v[214:217], v[78:81]
	v_mfma_f32_16x16x32_bf16 v[74:77], v[198:201], v[222:225], v[74:77]
	v_mfma_f32_16x16x32_bf16 v[70:73], v[206:209], v[214:217], v[70:73]
	v_mfma_f32_16x16x32_bf16 v[66:69], v[206:209], v[222:225], v[66:69]
	v_mfma_f32_16x16x32_bf16 v[94:97], v[186:189], v[218:221], v[94:97]
	v_mfma_f32_16x16x32_bf16 v[90:93], v[186:189], v[226:229], v[90:93]
	v_mfma_f32_16x16x32_bf16 v[86:89], v[194:197], v[218:221], v[86:89]
	v_mfma_f32_16x16x32_bf16 v[82:85], v[194:197], v[226:229], v[82:85]
	v_mfma_f32_16x16x32_bf16 v[78:81], v[202:205], v[218:221], v[78:81]
	v_mfma_f32_16x16x32_bf16 v[74:77], v[202:205], v[226:229], v[74:77]
	v_mfma_f32_16x16x32_bf16 v[70:73], v[210:213], v[218:221], v[70:73]
	v_mfma_f32_16x16x32_bf16 v[66:69], v[210:213], v[226:229], v[66:69]
	s_setprio 0
	v_readfirstlane_b32 s24, v155
	v_lshl_add_u64 v[230:231], v[238:239], 0, s[12:13]
	s_mov_b32 m0, s24
	v_readfirstlane_b32 s24, v156
	s_barrier
; #define STAGE(P, GP, ktrel) do { const GAS char* _g = (GP) + (ktrel) * (BK * 2); \
;     __builtin_amdgcn_global_load_lds((const GAS unsigned*)(_g + so0), (unsigned*)((char*)(P) + tid_ * 16), 16, 0, 0); \
;     __builtin_amdgcn_global_load_lds((const GAS unsigned*)(_g + so1), (unsigned*)((char*)(P) + tid_ * 16 + 8192), 16, 0, 0); } while (0)
; #define WAIT_V(n) asm volatile("s_waitcnt vmcnt(" #n ")" ::: "memory")
; #define WAIT_L(n) asm volatile("s_waitcnt lgkmcnt(" #n ")" ::: "memory")
; #define BAR __builtin_amdgcn_s_barrier()
; #define SCHED __builtin_amdgcn_sched_barrier(0)
; #define LDA(dst, b, h) for (int m = 0; m < 4; ++m) for (int k = 0; k < 2; ++k) \
;     dst[m][k] = *reinterpret_cast<const bf16x8*>((char*)SA(b, h) + lds_byte(wr * 64 + m * 16 + fr, k * 32 + fq * 8))
; #define LDB(dst, b, h) for (int n = 0; n < 2; ++n) for (int k = 0; k < 2; ++k) \
;     dst[n][k] = *reinterpret_cast<const bf16x8*>((char*)SB(b, h) + lds_byte(wc * 32 + n * 16 + fr, k * 32 + fq * 8))
; template <int K, int LD = K>
; __device__ __forceinline__ void gemm_main(const GAS bf16* A, const GAS bf16* Bt, int brow, int bcol, f32x4 (&acc)[2][2][4][2]) {
;     ...
;   for (int t = 0; t < nt - 2; t += 2) {
;     LDB(B0, 0, 0); SCHED; LDA(At, 0, 0); STAGE(SA(1, 1), pA1, 1);
;     WAIT_L(8); BAR; WAIT_L(0); MMA(0, 0, At, B0); BAR; SCHED;
;     LDB(B1, 0, 1); STAGE(SB(0, 0), pB0, 2);
;     BAR; WAIT_L(0); MMA(0, 1, At, B1); BAR;
;     LDA(At, 0, 1); STAGE(SA(0, 0), pA0, 2);
;     BAR; WAIT_L(0); MMA(1, 0, At, B0); BAR; SCHED;
;     STAGE(SB(0, 1), pB1, 2);
;     WAIT_V(6); BAR; MMA(1, 1, At, B1); BAR;
;     LDB(B0, 1, 0); SCHED; LDA(At, 1, 0); STAGE(SA(0, 1), pA1, 2);
;     WAIT_L(8); BAR; WAIT_L(0); MMA(0, 0, At, B0); BAR; SCHED;
;     LDB(B1, 1, 1); STAGE(SB(1, 0), pB0, 3);
;     BAR; WAIT_L(0); MMA(0, 1, At, B1); BAR;
;     LDA(At, 1, 1); STAGE(SA(1, 0), pA0, 3);
;     BAR; WAIT_L(0); MMA(1, 0, At, B0); BAR; SCHED;
;     STAGE(SB(1, 1), pB1, 3);
;     WAIT_V(6); BAR; MMA(1, 1, At, B1); BAR;
;     pA0 += 4 * BK; pA1 += 4 * BK; pB0 += 4 * BK; pB1 += 4 * BK;
;     asm volatile("" : "+s"(pA0), "+s"(pA1), "+s"(pB0), "+s"(pB1));
;   }
;   { LDB(B0, 0, 0); LDA(At, 0, 0); STAGE(SA(1, 1), pA1, 1);
;     BAR; WAIT_L(0); MMA(0, 0, At, B0); BAR;
;     LDB(B1, 0, 1); BAR; WAIT_L(0); MMA(0, 1, At, B1); BAR;
;     LDA(At, 0, 1); WAIT_V(4); BAR; WAIT_L(0); MMA(1, 0, At, B0); MMA(1, 1, At, B1); BAR; }
	ds_read_b128 v[182:185], v140 offset:49152
	ds_read_b128 v[186:189], v140 offset:50176
	ds_read_b128 v[190:193], v139 offset:49152
	ds_read_b128 v[194:197], v139 offset:50176
	ds_read_b128 v[198:201], v138 offset:49152
	ds_read_b128 v[202:205], v138 offset:50176
	ds_read_b128 v[206:209], v137 offset:49152
	ds_read_b128 v[210:213], v137 offset:50176
	global_load_lds_dwordx4 v[230:231], off
	v_lshl_add_u64 v[230:231], v[240:241], 0, s[12:13]
	s_mov_b32 m0, s24
	s_nop 0
	global_load_lds_dwordx4 v[230:231], off
	s_barrier
	s_waitcnt lgkmcnt(0)
	s_setprio 1
	s_waitcnt lgkmcnt(0)
	v_mfma_f32_16x16x32_bf16 v[62:65], v[182:185], v[162:165], v[62:65]
	v_mfma_f32_16x16x32_bf16 v[58:61], v[182:185], v[174:177], v[58:61]
	v_mfma_f32_16x16x32_bf16 v[54:57], v[190:193], v[162:165], v[54:57]
	v_mfma_f32_16x16x32_bf16 v[50:53], v[190:193], v[174:177], v[50:53]
	v_mfma_f32_16x16x32_bf16 v[46:49], v[198:201], v[162:165], v[46:49]
	v_mfma_f32_16x16x32_bf16 v[42:45], v[198:201], v[174:177], v[42:45]
	v_mfma_f32_16x16x32_bf16 v[38:41], v[206:209], v[162:165], v[38:41]
	v_mfma_f32_16x16x32_bf16 v[34:37], v[206:209], v[174:177], v[34:37]
	v_mfma_f32_16x16x32_bf16 v[62:65], v[186:189], v[166:169], v[62:65]
	v_mfma_f32_16x16x32_bf16 v[58:61], v[186:189], v[178:181], v[58:61]
	v_mfma_f32_16x16x32_bf16 v[54:57], v[194:197], v[166:169], v[54:57]
	v_mfma_f32_16x16x32_bf16 v[50:53], v[194:197], v[178:181], v[50:53]
	v_mfma_f32_16x16x32_bf16 v[46:49], v[202:205], v[166:169], v[46:49]
	v_mfma_f32_16x16x32_bf16 v[42:45], v[202:205], v[178:181], v[42:45]
	v_mfma_f32_16x16x32_bf16 v[38:41], v[210:213], v[166:169], v[38:41]
	v_mfma_f32_16x16x32_bf16 v[34:37], v[210:213], v[178:181], v[34:37]
	s_setprio 0
	s_barrier
	v_readfirstlane_b32 s24, v149
	v_lshl_add_u64 v[162:163], v[242:243], 0, s[12:13]
	s_mov_b32 m0, s24
	v_readfirstlane_b32 s24, v160
	global_load_lds_dwordx4 v[162:163], off
	v_lshl_add_u64 v[162:163], v[244:245], 0, s[12:13]
	s_mov_b32 m0, s24
	s_nop 0
	global_load_lds_dwordx4 v[162:163], off
	s_waitcnt vmcnt(10)
	s_barrier
	s_setprio 1
	v_mfma_f32_16x16x32_bf16 v[30:33], v[182:185], v[214:217], v[30:33]
	v_mfma_f32_16x16x32_bf16 v[26:29], v[182:185], v[222:225], v[26:29]
	v_mfma_f32_16x16x32_bf16 v[22:25], v[190:193], v[214:217], v[22:25]
	v_mfma_f32_16x16x32_bf16 v[18:21], v[190:193], v[222:225], v[18:21]
	v_mfma_f32_16x16x32_bf16 v[14:17], v[198:201], v[214:217], v[14:17]
	v_mfma_f32_16x16x32_bf16 v[10:13], v[198:201], v[222:225], v[10:13]
	v_mfma_f32_16x16x32_bf16 v[6:9], v[206:209], v[214:217], v[6:9]
	v_mfma_f32_16x16x32_bf16 v[2:5], v[206:209], v[222:225], v[2:5]
	v_mfma_f32_16x16x32_bf16 v[30:33], v[186:189], v[218:221], v[30:33]
	v_mfma_f32_16x16x32_bf16 v[26:29], v[186:189], v[226:229], v[26:29]
	v_mfma_f32_16x16x32_bf16 v[22:25], v[194:197], v[218:221], v[22:25]
	v_mfma_f32_16x16x32_bf16 v[18:21], v[194:197], v[226:229], v[18:21]
	v_mfma_f32_16x16x32_bf16 v[14:17], v[202:205], v[218:221], v[14:17]
	v_mfma_f32_16x16x32_bf16 v[10:13], v[202:205], v[226:229], v[10:13]
	v_mfma_f32_16x16x32_bf16 v[6:9], v[210:213], v[218:221], v[6:9]
	v_mfma_f32_16x16x32_bf16 v[2:5], v[210:213], v[226:229], v[2:5]
	s_setprio 0
	s_add_i32 s17, s17, 2
	s_cmp_lt_u32 s17, 12
	s_barrier
	s_cbranch_scc1 .LBB0_89
	ds_read_b128 v[146:149], v144
	ds_read_b128 v[152:155], v144 offset:1024
	ds_read_b128 v[156:159], v144 offset:2048
	ds_read_b128 v[160:163], v144 offset:3072
	ds_read_b128 v[164:167], v140
	ds_read_b128 v[174:177], v140 offset:1024
	ds_read_b128 v[178:181], v139
	ds_read_b128 v[182:185], v139 offset:1024
	ds_read_b128 v[186:189], v138
	ds_read_b128 v[190:193], v138 offset:1024
	ds_read_b128 v[194:197], v137
	ds_read_b128 v[198:201], v137 offset:1024
	v_lshl_add_u64 v[144:145], s[14:15], 0, v[130:131]
	v_readfirstlane_b32 s17, v151
	v_lshl_add_u64 v[144:145], v[144:145], 0, s[8:9]
	s_mov_b32 m0, s17
	v_lshl_add_u64 v[132:133], s[14:15], 0, v[132:133]
	v_readfirstlane_b32 s14, v150
	global_load_lds_dwordx4 v[144:145], off
	v_lshl_add_u64 v[132:133], v[132:133], 0, s[8:9]
	s_mov_b32 m0, s14
	s_nop 0
	global_load_lds_dwordx4 v[132:133], off
	s_waitcnt vmcnt(10)
	s_barrier
	s_waitcnt lgkmcnt(0)
	s_setprio 1
	s_waitcnt lgkmcnt(0)
	v_mfma_f32_16x16x32_bf16 v[126:129], v[164:167], v[146:149], v[126:129]
	v_mfma_f32_16x16x32_bf16 v[122:125], v[164:167], v[156:159], v[122:125]
	v_mfma_f32_16x16x32_bf16 v[110:113], v[186:189], v[146:149], v[110:113]
	v_mfma_f32_16x16x32_bf16 v[106:109], v[186:189], v[156:159], v[106:109]
	v_mfma_f32_16x16x32_bf16 v[126:129], v[174:177], v[152:155], v[126:129]
	v_mfma_f32_16x16x32_bf16 v[122:125], v[174:177], v[160:163], v[122:125]
	v_mfma_f32_16x16x32_bf16 v[118:121], v[178:181], v[146:149], v[118:121]
	v_mfma_f32_16x16x32_bf16 v[114:117], v[178:181], v[156:159], v[114:117]
	v_mfma_f32_16x16x32_bf16 v[110:113], v[190:193], v[152:155], v[110:113]
	v_mfma_f32_16x16x32_bf16 v[106:109], v[190:193], v[160:163], v[106:109]
	v_mfma_f32_16x16x32_bf16 v[102:105], v[194:197], v[146:149], v[102:105]
	v_mfma_f32_16x16x32_bf16 v[98:101], v[194:197], v[156:159], v[98:101]
	v_mfma_f32_16x16x32_bf16 v[202:205], v[182:185], v[152:155], v[118:121]
	v_mfma_f32_16x16x32_bf16 v[206:209], v[182:185], v[160:163], v[114:117]
	v_mfma_f32_16x16x32_bf16 v[210:213], v[198:201], v[152:155], v[102:105]
	v_mfma_f32_16x16x32_bf16 v[214:217], v[198:201], v[160:163], v[98:101]
	s_setprio 0
	s_barrier
	s_nop 1
	ds_read_b128 v[98:101], v143
	ds_read_b128 v[102:105], v143 offset:1024
	ds_read_b128 v[114:117], v143 offset:2048
	ds_read_b128 v[118:121], v143 offset:3072
	s_waitcnt vmcnt(8)
	s_barrier
; #define STAGE(P, GP, ktrel) do { const GAS char* _g = (GP) + (ktrel) * (BK * 2); \
;     __builtin_amdgcn_global_load_lds((const GAS unsigned*)(_g + so0), (unsigned*)((char*)(P) + tid_ * 16), 16, 0, 0); \
;     __builtin_amdgcn_global_load_lds((const GAS unsigned*)(_g + so1), (unsigned*)((char*)(P) + tid_ * 16 + 8192), 16, 0, 0); } while (0)
; #define WAIT_V(n) asm volatile("s_waitcnt vmcnt(" #n ")" ::: "memory")
; #define WAIT_L(n) asm volatile("s_waitcnt lgkmcnt(" #n ")" ::: "memory")
; #define BAR __builtin_amdgcn_s_barrier()
; #define LDA(dst, b, h) for (int m = 0; m < 4; ++m) for (int k = 0; k < 2; ++k) \
;     dst[m][k] = *reinterpret_cast<const bf16x8*>((char*)SA(b, h) + lds_byte(wr * 64 + m * 16 + fr, k * 32 + fq * 8))
; #define LDB(dst, b, h) for (int n = 0; n < 2; ++n) for (int k = 0; k < 2; ++k) \
;     dst[n][k] = *reinterpret_cast<const bf16x8*>((char*)SB(b, h) + lds_byte(wc * 32 + n * 16 + fr, k * 32 + fq * 8))
; #define MMA(ai, bj, At_, Bt_) do { __builtin_amdgcn_s_setprio(1); \
;     for (int m = 0; m < 4; ++m) for (int n = 0; n < 2; ++n) for (int k = 0; k < 2; ++k) \
;       acc[ai][bj][m][n] = __builtin_amdgcn_mfma_f32_16x16x32_bf16(At_[m][k], Bt_[n][k], acc[ai][bj][m][n], 0, 0, 0); \
;     __builtin_amdgcn_s_setprio(0); } while (0)
; template <int K, int LD = K>
; __device__ __forceinline__ void gemm_main(const GAS bf16* A, const GAS bf16* Bt, int brow, int bcol, f32x4 (&acc)[2][2][4][2]) {
;     ...
;   { LDB(B0, 0, 0); LDA(At, 0, 0); STAGE(SA(1, 1), pA1, 1);
;     BAR; WAIT_L(0); MMA(0, 0, At, B0); BAR;
;     LDB(B1, 0, 1); BAR; WAIT_L(0); MMA(0, 1, At, B1); BAR;
;     LDA(At, 0, 1); WAIT_V(4); BAR; WAIT_L(0); MMA(1, 0, At, B0); MMA(1, 1, At, B1); BAR; }
;   { LDB(B0, 1, 0); LDA(At, 1, 0); WAIT_V(2); BAR; WAIT_L(0); MMA(0, 0, At, B0); BAR;
;     LDB(B1, 1, 1); WAIT_V(0); BAR; WAIT_L(0); MMA(0, 1, At, B1); BAR;
;     LDA(At, 1, 1); BAR; WAIT_L(0); MMA(1, 0, At, B0); MMA(1, 1, At, B1); BAR; }
	s_waitcnt lgkmcnt(0)
	s_setprio 1
	s_waitcnt lgkmcnt(0)
	v_mfma_f32_16x16x32_bf16 v[94:97], v[164:167], v[98:101], v[94:97]
	v_mfma_f32_16x16x32_bf16 v[90:93], v[164:167], v[114:117], v[90:93]
	v_mfma_f32_16x16x32_bf16 v[78:81], v[186:189], v[98:101], v[78:81]
	v_mfma_f32_16x16x32_bf16 v[74:77], v[186:189], v[114:117], v[74:77]
	v_mfma_f32_16x16x32_bf16 v[94:97], v[174:177], v[102:105], v[94:97]
	v_mfma_f32_16x16x32_bf16 v[90:93], v[174:177], v[118:121], v[90:93]
	v_mfma_f32_16x16x32_bf16 v[86:89], v[178:181], v[98:101], v[86:89]
	v_mfma_f32_16x16x32_bf16 v[82:85], v[178:181], v[114:117], v[82:85]
	v_mfma_f32_16x16x32_bf16 v[78:81], v[190:193], v[102:105], v[78:81]
	v_mfma_f32_16x16x32_bf16 v[74:77], v[190:193], v[118:121], v[74:77]
	v_mfma_f32_16x16x32_bf16 v[70:73], v[194:197], v[98:101], v[70:73]
	v_mfma_f32_16x16x32_bf16 v[66:69], v[194:197], v[114:117], v[66:69]
	v_mfma_f32_16x16x32_bf16 v[164:167], v[182:185], v[102:105], v[86:89]
	v_mfma_f32_16x16x32_bf16 v[174:177], v[182:185], v[118:121], v[82:85]
	v_mfma_f32_16x16x32_bf16 v[178:181], v[198:201], v[102:105], v[70:73]
	v_mfma_f32_16x16x32_bf16 v[182:185], v[198:201], v[118:121], v[66:69]
	s_setprio 0
	s_barrier
	s_nop 1
	ds_read_b128 v[66:69], v140 offset:16384
	ds_read_b128 v[70:73], v140 offset:17408
	ds_read_b128 v[82:85], v139 offset:16384
	ds_read_b128 v[86:89], v139 offset:17408
	ds_read_b128 v[186:189], v138 offset:16384
	ds_read_b128 v[190:193], v138 offset:17408
	ds_read_b128 v[194:197], v137 offset:16384
	ds_read_b128 v[198:201], v137 offset:17408
	s_waitcnt vmcnt(4)
	s_barrier
	s_waitcnt lgkmcnt(0)
	s_setprio 1
	s_waitcnt lgkmcnt(0)
	v_mfma_f32_16x16x32_bf16 v[62:65], v[66:69], v[146:149], v[62:65]
	v_mfma_f32_16x16x32_bf16 v[58:61], v[66:69], v[156:159], v[58:61]
	v_mfma_f32_16x16x32_bf16 v[46:49], v[186:189], v[146:149], v[46:49]
	v_mfma_f32_16x16x32_bf16 v[38:41], v[194:197], v[146:149], v[38:41]
	v_mfma_f32_16x16x32_bf16 v[62:65], v[70:73], v[152:155], v[62:65]
	v_mfma_f32_16x16x32_bf16 v[58:61], v[70:73], v[160:163], v[58:61]
	v_mfma_f32_16x16x32_bf16 v[54:57], v[82:85], v[146:149], v[54:57]
	v_mfma_f32_16x16x32_bf16 v[50:53], v[82:85], v[156:159], v[50:53]
	v_mfma_f32_16x16x32_bf16 v[46:49], v[190:193], v[152:155], v[46:49]
	v_mfma_f32_16x16x32_bf16 v[42:45], v[186:189], v[156:159], v[42:45]
	v_mfma_f32_16x16x32_bf16 v[38:41], v[198:201], v[152:155], v[38:41]
	v_mfma_f32_16x16x32_bf16 v[34:37], v[194:197], v[156:159], v[34:37]
	v_mfma_f32_16x16x32_bf16 v[218:221], v[86:89], v[152:155], v[54:57]
	v_mfma_f32_16x16x32_bf16 v[222:225], v[86:89], v[160:163], v[50:53]
	v_mfma_f32_16x16x32_bf16 v[226:229], v[190:193], v[160:163], v[42:45]
	v_mfma_f32_16x16x32_bf16 v[144:147], v[198:201], v[160:163], v[34:37]
	s_setprio 0
	s_setprio 1
	v_mfma_f32_16x16x32_bf16 v[30:33], v[66:69], v[98:101], v[30:33]
	v_mfma_f32_16x16x32_bf16 v[26:29], v[66:69], v[114:117], v[26:29]
	v_mfma_f32_16x16x32_bf16 v[14:17], v[186:189], v[98:101], v[14:17]
	v_mfma_f32_16x16x32_bf16 v[6:9], v[194:197], v[98:101], v[6:9]
	v_mfma_f32_16x16x32_bf16 v[30:33], v[70:73], v[102:105], v[30:33]
	v_mfma_f32_16x16x32_bf16 v[26:29], v[70:73], v[118:121], v[26:29]
	v_mfma_f32_16x16x32_bf16 v[22:25], v[82:85], v[98:101], v[22:25]
	v_mfma_f32_16x16x32_bf16 v[18:21], v[82:85], v[114:117], v[18:21]
	v_mfma_f32_16x16x32_bf16 v[14:17], v[190:193], v[102:105], v[14:17]
	v_mfma_f32_16x16x32_bf16 v[10:13], v[186:189], v[114:117], v[10:13]
	v_mfma_f32_16x16x32_bf16 v[6:9], v[198:201], v[102:105], v[6:9]
	v_mfma_f32_16x16x32_bf16 v[2:5], v[194:197], v[114:117], v[2:5]
	v_mfma_f32_16x16x32_bf16 v[148:151], v[86:89], v[102:105], v[22:25]
	v_mfma_f32_16x16x32_bf16 v[152:155], v[86:89], v[118:121], v[18:21]
	v_mfma_f32_16x16x32_bf16 v[156:159], v[190:193], v[118:121], v[10:13]
	v_mfma_f32_16x16x32_bf16 v[160:163], v[198:201], v[118:121], v[2:5]
	s_setprio 0
	s_barrier
	s_nop 1
	ds_read_b128 v[2:5], v142
	ds_read_b128 v[10:13], v142 offset:1024
	ds_read_b128 v[186:189], v142 offset:2048
	ds_read_b128 v[190:193], v142 offset:3072
	ds_read_b128 v[18:21], v140 offset:32768
	ds_read_b128 v[22:25], v140 offset:33792
	ds_read_b128 v[34:37], v139 offset:32768
	ds_read_b128 v[42:45], v139 offset:33792
	ds_read_b128 v[50:53], v138 offset:32768
	ds_read_b128 v[54:57], v138 offset:33792
	ds_read_b128 v[194:197], v137 offset:32768
	ds_read_b128 v[198:201], v137 offset:33792
	s_waitcnt vmcnt(2)
	s_barrier
; #define STAGE(P, GP, ktrel) do { const GAS char* _g = (GP) + (ktrel) * (BK * 2); \
;     __builtin_amdgcn_global_load_lds((const GAS unsigned*)(_g + so0), (unsigned*)((char*)(P) + tid_ * 16), 16, 0, 0); \
;     __builtin_amdgcn_global_load_lds((const GAS unsigned*)(_g + so1), (unsigned*)((char*)(P) + tid_ * 16 + 8192), 16, 0, 0); } while (0)
; #define WAIT_V(n) asm volatile("s_waitcnt vmcnt(" #n ")" ::: "memory")
; #define WAIT_L(n) asm volatile("s_waitcnt lgkmcnt(" #n ")" ::: "memory")
; #define BAR __builtin_amdgcn_s_barrier()
; #define LDA(dst, b, h) for (int m = 0; m < 4; ++m) for (int k = 0; k < 2; ++k) \
;     dst[m][k] = *reinterpret_cast<const bf16x8*>((char*)SA(b, h) + lds_byte(wr * 64 + m * 16 + fr, k * 32 + fq * 8))
; #define LDB(dst, b, h) for (int n = 0; n < 2; ++n) for (int k = 0; k < 2; ++k) \
;     dst[n][k] = *reinterpret_cast<const bf16x8*>((char*)SB(b, h) + lds_byte(wc * 32 + n * 16 + fr, k * 32 + fq * 8))
; #define MMA(ai, bj, At_, Bt_) do { __builtin_amdgcn_s_setprio(1); \
;     for (int m = 0; m < 4; ++m) for (int n = 0; n < 2; ++n) for (int k = 0; k < 2; ++k) \
;       acc[ai][bj][m][n] = __builtin_amdgcn_mfma_f32_16x16x32_bf16(At_[m][k], Bt_[n][k], acc[ai][bj][m][n], 0, 0, 0); \
;     __builtin_amdgcn_s_setprio(0); } while (0)
; template <int K, int LD = K>
; __device__ __forceinline__ void gemm_main(const GAS bf16* A, const GAS bf16* Bt, int brow, int bcol, f32x4 (&acc)[2][2][4][2]) {
;     ...
;   { LDB(B0, 0, 0); LDA(At, 0, 0); STAGE(SA(1, 1), pA1, 1);
;     BAR; WAIT_L(0); MMA(0, 0, At, B0); BAR;
;     LDB(B1, 0, 1); BAR; WAIT_L(0); MMA(0, 1, At, B1); BAR;
;     LDA(At, 0, 1); WAIT_V(4); BAR; WAIT_L(0); MMA(1, 0, At, B0); MMA(1, 1, At, B1); BAR; }
;   { LDB(B0, 1, 0); LDA(At, 1, 0); WAIT_V(2); BAR; WAIT_L(0); MMA(0, 0, At, B0); BAR;
;     LDB(B1, 1, 1); WAIT_V(0); BAR; WAIT_L(0); MMA(0, 1, At, B1); BAR;
;     LDA(At, 1, 1); BAR; WAIT_L(0); MMA(1, 0, At, B0); MMA(1, 1, At, B1); BAR; }
;   if (wr == 0) BAR;
	s_waitcnt lgkmcnt(0)
	s_setprio 1
	s_waitcnt lgkmcnt(0)
	v_mfma_f32_16x16x32_bf16 v[66:69], v[18:21], v[2:5], v[126:129]
	v_mfma_f32_16x16x32_bf16 v[118:121], v[22:25], v[10:13], v[66:69]
	v_mfma_f32_16x16x32_bf16 v[66:69], v[18:21], v[186:189], v[122:125]
	v_mfma_f32_16x16x32_bf16 v[114:117], v[22:25], v[190:193], v[66:69]
	v_mfma_f32_16x16x32_bf16 v[66:69], v[34:37], v[2:5], v[202:205]
	v_mfma_f32_16x16x32_bf16 v[102:105], v[42:45], v[10:13], v[66:69]
	v_mfma_f32_16x16x32_bf16 v[66:69], v[34:37], v[186:189], v[206:209]
	v_mfma_f32_16x16x32_bf16 v[98:101], v[42:45], v[190:193], v[66:69]
	v_mfma_f32_16x16x32_bf16 v[66:69], v[50:53], v[2:5], v[110:113]
	v_mfma_f32_16x16x32_bf16 v[86:89], v[54:57], v[10:13], v[66:69]
	v_mfma_f32_16x16x32_bf16 v[66:69], v[50:53], v[186:189], v[106:109]
	v_mfma_f32_16x16x32_bf16 v[82:85], v[54:57], v[190:193], v[66:69]
	v_mfma_f32_16x16x32_bf16 v[66:69], v[194:197], v[2:5], v[210:213]
	v_mfma_f32_16x16x32_bf16 v[70:73], v[198:201], v[10:13], v[66:69]
	v_mfma_f32_16x16x32_bf16 v[66:69], v[194:197], v[186:189], v[214:217]
	v_mfma_f32_16x16x32_bf16 v[66:69], v[198:201], v[190:193], v[66:69]
	s_setprio 0
	s_barrier
	ds_read_b128 v[202:205], v141
	ds_read_b128 v[206:209], v141 offset:1024
	ds_read_b128 v[210:213], v141 offset:2048
	ds_read_b128 v[214:217], v141 offset:3072
	s_waitcnt vmcnt(0)
	s_barrier
	s_waitcnt lgkmcnt(0)
	s_setprio 1
	s_waitcnt lgkmcnt(0)
	v_mfma_f32_16x16x32_bf16 v[94:97], v[18:21], v[202:205], v[94:97]
	v_mfma_f32_16x16x32_bf16 v[18:21], v[18:21], v[210:213], v[90:93]
	v_mfma_f32_16x16x32_bf16 v[122:125], v[22:25], v[214:217], v[18:21]
	v_mfma_f32_16x16x32_bf16 v[18:21], v[34:37], v[202:205], v[164:167]
	v_mfma_f32_16x16x32_bf16 v[110:113], v[42:45], v[206:209], v[18:21]
	v_mfma_f32_16x16x32_bf16 v[18:21], v[34:37], v[210:213], v[174:177]
	v_mfma_f32_16x16x32_bf16 v[106:109], v[42:45], v[214:217], v[18:21]
	v_mfma_f32_16x16x32_bf16 v[18:21], v[50:53], v[202:205], v[78:81]
	v_mfma_f32_16x16x32_bf16 v[126:129], v[22:25], v[206:209], v[94:97]
	v_mfma_f32_16x16x32_bf16 v[94:97], v[54:57], v[206:209], v[18:21]
	v_mfma_f32_16x16x32_bf16 v[18:21], v[50:53], v[210:213], v[74:77]
	v_mfma_f32_16x16x32_bf16 v[90:93], v[54:57], v[214:217], v[18:21]
	v_mfma_f32_16x16x32_bf16 v[18:21], v[194:197], v[202:205], v[178:181]
	v_mfma_f32_16x16x32_bf16 v[78:81], v[198:201], v[206:209], v[18:21]
	v_mfma_f32_16x16x32_bf16 v[18:21], v[194:197], v[210:213], v[182:185]
	v_mfma_f32_16x16x32_bf16 v[74:77], v[198:201], v[214:217], v[18:21]
	s_setprio 0
	s_barrier
	ds_read_b128 v[164:167], v140 offset:49152
	ds_read_b128 v[140:143], v140 offset:50176
	ds_read_b128 v[174:177], v139 offset:49152
	ds_read_b128 v[178:181], v139 offset:50176
	ds_read_b128 v[182:185], v138 offset:49152
	ds_read_b128 v[194:197], v138 offset:50176
	ds_read_b128 v[198:201], v137 offset:49152
	ds_read_b128 v[230:233], v137 offset:50176
	s_barrier
	s_waitcnt lgkmcnt(0)
	s_setprio 1
	s_waitcnt lgkmcnt(0)
	v_mfma_f32_16x16x32_bf16 v[18:21], v[164:167], v[2:5], v[62:65]
	v_mfma_f32_16x16x32_bf16 v[54:57], v[140:143], v[10:13], v[18:21]
	v_mfma_f32_16x16x32_bf16 v[18:21], v[164:167], v[186:189], v[58:61]
	v_mfma_f32_16x16x32_bf16 v[50:53], v[140:143], v[190:193], v[18:21]
	v_mfma_f32_16x16x32_bf16 v[18:21], v[174:177], v[2:5], v[218:221]
	v_mfma_f32_16x16x32_bf16 v[42:45], v[178:181], v[10:13], v[18:21]
	v_mfma_f32_16x16x32_bf16 v[18:21], v[174:177], v[186:189], v[222:225]
	v_mfma_f32_16x16x32_bf16 v[34:37], v[178:181], v[190:193], v[18:21]
	v_mfma_f32_16x16x32_bf16 v[18:21], v[182:185], v[2:5], v[46:49]
	v_mfma_f32_16x16x32_bf16 v[2:5], v[198:201], v[2:5], v[38:41]
	v_mfma_f32_16x16x32_bf16 v[22:25], v[194:197], v[10:13], v[18:21]
	v_mfma_f32_16x16x32_bf16 v[18:21], v[182:185], v[186:189], v[226:229]
	v_mfma_f32_16x16x32_bf16 v[10:13], v[230:233], v[10:13], v[2:5]
	v_mfma_f32_16x16x32_bf16 v[2:5], v[198:201], v[186:189], v[144:147]
	v_mfma_f32_16x16x32_bf16 v[18:21], v[194:197], v[190:193], v[18:21]
	v_mfma_f32_16x16x32_bf16 v[2:5], v[230:233], v[190:193], v[2:5]
	s_setprio 0
	s_setprio 1
	v_mfma_f32_16x16x32_bf16 v[26:29], v[164:167], v[210:213], v[26:29]
	v_mfma_f32_16x16x32_bf16 v[30:33], v[164:167], v[202:205], v[30:33]
	v_mfma_f32_16x16x32_bf16 v[58:61], v[140:143], v[214:217], v[26:29]
	v_mfma_f32_16x16x32_bf16 v[26:29], v[174:177], v[202:205], v[148:151]
	v_mfma_f32_16x16x32_bf16 v[14:17], v[182:185], v[202:205], v[14:17]
	v_mfma_f32_16x16x32_bf16 v[62:65], v[140:143], v[206:209], v[30:33]
	v_mfma_f32_16x16x32_bf16 v[46:49], v[178:181], v[206:209], v[26:29]
	v_mfma_f32_16x16x32_bf16 v[26:29], v[174:177], v[210:213], v[152:155]
	v_mfma_f32_16x16x32_bf16 v[30:33], v[194:197], v[206:209], v[14:17]
	v_mfma_f32_16x16x32_bf16 v[14:17], v[182:185], v[210:213], v[156:159]
	v_mfma_f32_16x16x32_bf16 v[6:9], v[198:201], v[202:205], v[6:9]
	v_mfma_f32_16x16x32_bf16 v[38:41], v[178:181], v[214:217], v[26:29]
	v_mfma_f32_16x16x32_bf16 v[26:29], v[194:197], v[214:217], v[14:17]
	v_mfma_f32_16x16x32_bf16 v[14:17], v[230:233], v[206:209], v[6:9]
	v_mfma_f32_16x16x32_bf16 v[6:9], v[198:201], v[210:213], v[160:163]
	v_mfma_f32_16x16x32_bf16 v[6:9], v[230:233], v[214:217], v[6:9]
	s_setprio 0
	v_cmp_gt_u32_e32 vcc, s34, v136
	s_barrier
	s_and_saveexec_b64 s[14:15], vcc
	s_cbranch_execz .LBB0_92
	s_barrier

; #define STAGE(P, GP, ktrel) do { const GAS char* _g = (GP) + (ktrel) * (BK * 2); \
;     __builtin_amdgcn_global_load_lds((const GAS unsigned*)(_g + so0), (unsigned*)((char*)(P) + tid_ * 16), 16, 0, 0); \
;     __builtin_amdgcn_global_load_lds((const GAS unsigned*)(_g + so1), (unsigned*)((char*)(P) + tid_ * 16 + 8192), 16, 0, 0); } while (0)
; #define WAIT_V(n) asm volatile("s_waitcnt vmcnt(" #n ")" ::: "memory")
; #define WAIT_L(n) asm volatile("s_waitcnt lgkmcnt(" #n ")" ::: "memory")
; #define BAR __builtin_amdgcn_s_barrier()
; #define SCHED __builtin_amdgcn_sched_barrier(0)
; #define LDA(dst, b, h) for (int m = 0; m < 4; ++m) for (int k = 0; k < 2; ++k) \
;     dst[m][k] = *reinterpret_cast<const bf16x8*>((char*)SA(b, h) + lds_byte(wr * 64 + m * 16 + fr, k * 32 + fq * 8))
; #define LDB(dst, b, h) for (int n = 0; n < 2; ++n) for (int k = 0; k < 2; ++k) \
;     dst[n][k] = *reinterpret_cast<const bf16x8*>((char*)SB(b, h) + lds_byte(wc * 32 + n * 16 + fr, k * 32 + fq * 8))
; template <int K, int LD = K>
; __device__ __forceinline__ void gemm_main(const GAS bf16* A, const GAS bf16* Bt, int brow, int bcol, f32x4 (&acc)[2][2][4][2]) {
;     ...
;   for (int t = 0; t < nt - 2; t += 2) {
;     LDB(B0, 0, 0); SCHED; LDA(At, 0, 0); STAGE(SA(1, 1), pA1, 1);
;     WAIT_L(8); BAR; WAIT_L(0); MMA(0, 0, At, B0); BAR; SCHED;
;     LDB(B1, 0, 1); STAGE(SB(0, 0), pB0, 2);
;     BAR; WAIT_L(0); MMA(0, 1, At, B1); BAR;
;     LDA(At, 0, 1); STAGE(SA(0, 0), pA0, 2);
;     BAR; WAIT_L(0); MMA(1, 0, At, B0); BAR; SCHED;
;     STAGE(SB(0, 1), pB1, 2);
;     WAIT_V(6); BAR; MMA(1, 1, At, B1); BAR;
;     LDB(B0, 1, 0); SCHED; LDA(At, 1, 0); STAGE(SA(0, 1), pA1, 2);
;     WAIT_L(8); BAR; WAIT_L(0); MMA(0, 0, At, B0); BAR; SCHED;
;     LDB(B1, 1, 1); STAGE(SB(1, 0), pB0, 3);
;     BAR; WAIT_L(0); MMA(0, 1, At, B1); BAR;
;     LDA(At, 1, 1); STAGE(SA(1, 0), pA0, 3);
;     BAR; WAIT_L(0); MMA(1, 0, At, B0); BAR; SCHED;
;     STAGE(SB(1, 1), pB1, 3);
;     WAIT_V(6); BAR; MMA(1, 1, At, B1); BAR;
;     pA0 += 4 * BK; pA1 += 4 * BK; pB0 += 4 * BK; pB1 += 4 * BK;
;     asm volatile("" : "+s"(pA0), "+s"(pA1), "+s"(pB0), "+s"(pB1));
;   }
.LBB0_230:
	ds_read_b128 v[160:163], v144
	ds_read_b128 v[164:167], v144 offset:1024
	ds_read_b128 v[174:177], v144 offset:2048
	ds_read_b128 v[178:181], v144 offset:3072
	v_lshl_add_u64 v[168:169], s[12:13], 0, v[130:131]
	v_readfirstlane_b32 s23, v143
	v_lshl_add_u64 v[214:215], v[168:169], 0, s[6:7]
	s_mov_b32 m0, s23
	v_lshl_add_u64 v[230:231], s[12:13], 0, v[132:133]
	v_readfirstlane_b32 s23, v142
	ds_read_b128 v[182:185], v138
	ds_read_b128 v[186:189], v138 offset:1024
	ds_read_b128 v[190:193], v137
	ds_read_b128 v[194:197], v137 offset:1024
	ds_read_b128 v[198:201], v136
	ds_read_b128 v[202:205], v136 offset:1024
	ds_read_b128 v[206:209], v135
	ds_read_b128 v[210:213], v135 offset:1024
	global_load_lds_dwordx4 v[214:215], off
	v_lshl_add_u64 v[214:215], v[230:231], 0, s[6:7]
	s_mov_b32 m0, s23
	s_nop 0
	global_load_lds_dwordx4 v[214:215], off
	s_waitcnt lgkmcnt(8)
	s_waitcnt vmcnt(10)
	s_barrier
	s_waitcnt lgkmcnt(0)
	s_setprio 1
	s_waitcnt lgkmcnt(0)
	v_mfma_f32_16x16x32_bf16 v[126:129], v[182:185], v[160:163], v[126:129]
	v_mfma_f32_16x16x32_bf16 v[122:125], v[182:185], v[174:177], v[122:125]
	v_mfma_f32_16x16x32_bf16 v[118:121], v[190:193], v[160:163], v[118:121]
	v_mfma_f32_16x16x32_bf16 v[114:117], v[190:193], v[174:177], v[114:117]
	v_mfma_f32_16x16x32_bf16 v[110:113], v[198:201], v[160:163], v[110:113]
	v_mfma_f32_16x16x32_bf16 v[106:109], v[198:201], v[174:177], v[106:109]
	v_mfma_f32_16x16x32_bf16 v[102:105], v[206:209], v[160:163], v[102:105]
	v_mfma_f32_16x16x32_bf16 v[98:101], v[206:209], v[174:177], v[98:101]
	v_mfma_f32_16x16x32_bf16 v[126:129], v[186:189], v[164:167], v[126:129]
	v_mfma_f32_16x16x32_bf16 v[122:125], v[186:189], v[178:181], v[122:125]
	v_mfma_f32_16x16x32_bf16 v[118:121], v[194:197], v[164:167], v[118:121]
	v_mfma_f32_16x16x32_bf16 v[114:117], v[194:197], v[178:181], v[114:117]
	v_mfma_f32_16x16x32_bf16 v[110:113], v[202:205], v[164:167], v[110:113]
	v_mfma_f32_16x16x32_bf16 v[106:109], v[202:205], v[178:181], v[106:109]
	v_mfma_f32_16x16x32_bf16 v[102:105], v[210:213], v[164:167], v[102:105]
	v_mfma_f32_16x16x32_bf16 v[98:101], v[210:213], v[178:181], v[98:101]
	s_setprio 0
	s_barrier
	v_lshl_add_u64 v[232:233], s[20:21], 0, v[130:131]
	v_readfirstlane_b32 s23, v151
	v_lshl_add_u64 v[234:235], v[232:233], 0, s[8:9]
	s_mov_b32 m0, s23
	ds_read_b128 v[214:217], v141
	ds_read_b128 v[218:221], v141 offset:1024
	ds_read_b128 v[222:225], v141 offset:2048
	ds_read_b128 v[226:229], v141 offset:3072
	global_load_lds_dwordx4 v[234:235], off
	v_lshl_add_u64 v[234:235], s[20:21], 0, v[132:133]
	v_readfirstlane_b32 s23, v152
	v_lshl_add_u64 v[236:237], v[234:235], 0, s[8:9]
	s_mov_b32 m0, s23
	s_add_u32 s20, s20, 0x100
	global_load_lds_dwordx4 v[236:237], off
	s_waitcnt vmcnt(10)
	s_barrier
	s_waitcnt lgkmcnt(0)
	s_addc_u32 s21, s21, 0
	s_setprio 1
	s_waitcnt lgkmcnt(0)
	v_mfma_f32_16x16x32_bf16 v[94:97], v[182:185], v[214:217], v[94:97]
	v_mfma_f32_16x16x32_bf16 v[90:93], v[182:185], v[222:225], v[90:93]
	v_mfma_f32_16x16x32_bf16 v[86:89], v[190:193], v[214:217], v[86:89]
	v_mfma_f32_16x16x32_bf16 v[82:85], v[190:193], v[222:225], v[82:85]
	v_mfma_f32_16x16x32_bf16 v[78:81], v[198:201], v[214:217], v[78:81]
	v_mfma_f32_16x16x32_bf16 v[74:77], v[198:201], v[222:225], v[74:77]
	v_mfma_f32_16x16x32_bf16 v[70:73], v[206:209], v[214:217], v[70:73]
	v_mfma_f32_16x16x32_bf16 v[66:69], v[206:209], v[222:225], v[66:69]
	v_mfma_f32_16x16x32_bf16 v[94:97], v[186:189], v[218:221], v[94:97]
	v_mfma_f32_16x16x32_bf16 v[90:93], v[186:189], v[226:229], v[90:93]
	v_mfma_f32_16x16x32_bf16 v[86:89], v[194:197], v[218:221], v[86:89]
	v_mfma_f32_16x16x32_bf16 v[82:85], v[194:197], v[226:229], v[82:85]
	v_mfma_f32_16x16x32_bf16 v[78:81], v[202:205], v[218:221], v[78:81]
	v_mfma_f32_16x16x32_bf16 v[74:77], v[202:205], v[226:229], v[74:77]
	v_mfma_f32_16x16x32_bf16 v[70:73], v[210:213], v[218:221], v[70:73]
	v_mfma_f32_16x16x32_bf16 v[66:69], v[210:213], v[226:229], v[66:69]
	s_setprio 0
	v_lshl_add_u64 v[236:237], s[18:19], 0, v[130:131]
	v_readfirstlane_b32 s23, v145
	v_lshl_add_u64 v[238:239], v[236:237], 0, s[8:9]
	s_mov_b32 m0, s23
	s_barrier
	ds_read_b128 v[182:185], v138 offset:16384
	ds_read_b128 v[186:189], v138 offset:17408
	ds_read_b128 v[190:193], v137 offset:16384
	ds_read_b128 v[194:197], v137 offset:17408
	ds_read_b128 v[198:201], v136 offset:16384
	ds_read_b128 v[202:205], v136 offset:17408
	ds_read_b128 v[206:209], v135 offset:16384
	ds_read_b128 v[210:213], v135 offset:17408
	global_load_lds_dwordx4 v[238:239], off
	v_lshl_add_u64 v[238:239], s[18:19], 0, v[132:133]
	v_readfirstlane_b32 s23, v146
	v_lshl_add_u64 v[240:241], v[238:239], 0, s[8:9]
	s_mov_b32 m0, s23
	s_add_u32 s18, s18, 0x100
	global_load_lds_dwordx4 v[240:241], off
	s_barrier
	s_waitcnt lgkmcnt(0)
	s_addc_u32 s19, s19, 0
	s_setprio 1
	s_waitcnt lgkmcnt(0)
	v_mfma_f32_16x16x32_bf16 v[62:65], v[182:185], v[160:163], v[62:65]
	v_mfma_f32_16x16x32_bf16 v[58:61], v[182:185], v[174:177], v[58:61]
	v_mfma_f32_16x16x32_bf16 v[54:57], v[190:193], v[160:163], v[54:57]
	v_mfma_f32_16x16x32_bf16 v[50:53], v[190:193], v[174:177], v[50:53]
	v_mfma_f32_16x16x32_bf16 v[46:49], v[198:201], v[160:163], v[46:49]
	v_mfma_f32_16x16x32_bf16 v[42:45], v[198:201], v[174:177], v[42:45]
	v_mfma_f32_16x16x32_bf16 v[38:41], v[206:209], v[160:163], v[38:41]
	v_mfma_f32_16x16x32_bf16 v[34:37], v[206:209], v[174:177], v[34:37]
	v_mfma_f32_16x16x32_bf16 v[62:65], v[186:189], v[164:167], v[62:65]
	v_mfma_f32_16x16x32_bf16 v[58:61], v[186:189], v[178:181], v[58:61]
	v_mfma_f32_16x16x32_bf16 v[54:57], v[194:197], v[164:167], v[54:57]
	v_mfma_f32_16x16x32_bf16 v[50:53], v[194:197], v[178:181], v[50:53]
	v_mfma_f32_16x16x32_bf16 v[46:49], v[202:205], v[164:167], v[46:49]
	v_mfma_f32_16x16x32_bf16 v[42:45], v[202:205], v[178:181], v[42:45]
	v_mfma_f32_16x16x32_bf16 v[38:41], v[210:213], v[164:167], v[38:41]
	v_mfma_f32_16x16x32_bf16 v[34:37], v[210:213], v[178:181], v[34:37]
	s_setprio 0
	s_barrier
; #define STAGE(P, GP, ktrel) do { const GAS char* _g = (GP) + (ktrel) * (BK * 2); \
;     __builtin_amdgcn_global_load_lds((const GAS unsigned*)(_g + so0), (unsigned*)((char*)(P) + tid_ * 16), 16, 0, 0); \
;     __builtin_amdgcn_global_load_lds((const GAS unsigned*)(_g + so1), (unsigned*)((char*)(P) + tid_ * 16 + 8192), 16, 0, 0); } while (0)
; #define WAIT_V(n) asm volatile("s_waitcnt vmcnt(" #n ")" ::: "memory")
; #define WAIT_L(n) asm volatile("s_waitcnt lgkmcnt(" #n ")" ::: "memory")
; #define BAR __builtin_amdgcn_s_barrier()
; #define SCHED __builtin_amdgcn_sched_barrier(0)
; #define LDA(dst, b, h) for (int m = 0; m < 4; ++m) for (int k = 0; k < 2; ++k) \
;     dst[m][k] = *reinterpret_cast<const bf16x8*>((char*)SA(b, h) + lds_byte(wr * 64 + m * 16 + fr, k * 32 + fq * 8))
; #define LDB(dst, b, h) for (int n = 0; n < 2; ++n) for (int k = 0; k < 2; ++k) \
;     dst[n][k] = *reinterpret_cast<const bf16x8*>((char*)SB(b, h) + lds_byte(wc * 32 + n * 16 + fr, k * 32 + fq * 8))
; template <int K, int LD = K>
; __device__ __forceinline__ void gemm_main(const GAS bf16* A, const GAS bf16* Bt, int brow, int bcol, f32x4 (&acc)[2][2][4][2]) {
;     ...
;   for (int t = 0; t < nt - 2; t += 2) {
;     LDB(B0, 0, 0); SCHED; LDA(At, 0, 0); STAGE(SA(1, 1), pA1, 1);
;     WAIT_L(8); BAR; WAIT_L(0); MMA(0, 0, At, B0); BAR; SCHED;
;     LDB(B1, 0, 1); STAGE(SB(0, 0), pB0, 2);
;     BAR; WAIT_L(0); MMA(0, 1, At, B1); BAR;
;     LDA(At, 0, 1); STAGE(SA(0, 0), pA0, 2);
;     BAR; WAIT_L(0); MMA(1, 0, At, B0); BAR; SCHED;
;     STAGE(SB(0, 1), pB1, 2);
;     WAIT_V(6); BAR; MMA(1, 1, At, B1); BAR;
;     LDB(B0, 1, 0); SCHED; LDA(At, 1, 0); STAGE(SA(0, 1), pA1, 2);
;     WAIT_L(8); BAR; WAIT_L(0); MMA(0, 0, At, B0); BAR; SCHED;
;     LDB(B1, 1, 1); STAGE(SB(1, 0), pB0, 3);
;     BAR; WAIT_L(0); MMA(0, 1, At, B1); BAR;
;     LDA(At, 1, 1); STAGE(SA(1, 0), pA0, 3);
;     BAR; WAIT_L(0); MMA(1, 0, At, B0); BAR; SCHED;
;     STAGE(SB(1, 1), pB1, 3);
;     WAIT_V(6); BAR; MMA(1, 1, At, B1); BAR;
;     pA0 += 4 * BK; pA1 += 4 * BK; pB0 += 4 * BK; pB1 += 4 * BK;
;     asm volatile("" : "+s"(pA0), "+s"(pA1), "+s"(pB0), "+s"(pB1));
;   }
	v_lshl_add_u64 v[240:241], s[16:17], 0, v[130:131]
	v_readfirstlane_b32 s23, v153
	v_lshl_add_u64 v[160:161], v[240:241], 0, s[8:9]
	s_mov_b32 m0, s23
	v_lshl_add_u64 v[242:243], s[16:17], 0, v[132:133]
	v_readfirstlane_b32 s23, v155
	global_load_lds_dwordx4 v[160:161], off
	v_lshl_add_u64 v[160:161], v[242:243], 0, s[8:9]
	s_mov_b32 m0, s23
	s_add_u32 s16, s16, 0x100
	global_load_lds_dwordx4 v[160:161], off
	s_waitcnt vmcnt(10)
	s_addc_u32 s17, s17, 0
	s_barrier
	s_setprio 1
	v_mfma_f32_16x16x32_bf16 v[30:33], v[182:185], v[214:217], v[30:33]
	v_mfma_f32_16x16x32_bf16 v[26:29], v[182:185], v[222:225], v[26:29]
	v_mfma_f32_16x16x32_bf16 v[22:25], v[190:193], v[214:217], v[22:25]
	v_mfma_f32_16x16x32_bf16 v[18:21], v[190:193], v[222:225], v[18:21]
	v_mfma_f32_16x16x32_bf16 v[14:17], v[198:201], v[214:217], v[14:17]
	v_mfma_f32_16x16x32_bf16 v[10:13], v[198:201], v[222:225], v[10:13]
	v_mfma_f32_16x16x32_bf16 v[6:9], v[206:209], v[214:217], v[6:9]
	v_mfma_f32_16x16x32_bf16 v[2:5], v[206:209], v[222:225], v[2:5]
	v_mfma_f32_16x16x32_bf16 v[30:33], v[186:189], v[218:221], v[30:33]
	v_mfma_f32_16x16x32_bf16 v[26:29], v[186:189], v[226:229], v[26:29]
	v_mfma_f32_16x16x32_bf16 v[22:25], v[194:197], v[218:221], v[22:25]
	v_mfma_f32_16x16x32_bf16 v[18:21], v[194:197], v[226:229], v[18:21]
	v_mfma_f32_16x16x32_bf16 v[14:17], v[202:205], v[218:221], v[14:17]
	v_mfma_f32_16x16x32_bf16 v[10:13], v[202:205], v[226:229], v[10:13]
	v_mfma_f32_16x16x32_bf16 v[6:9], v[210:213], v[218:221], v[6:9]
	v_mfma_f32_16x16x32_bf16 v[2:5], v[210:213], v[226:229], v[2:5]
	s_setprio 0
	s_barrier
	ds_read_b128 v[160:163], v140
	ds_read_b128 v[164:167], v140 offset:1024
	ds_read_b128 v[174:177], v140 offset:2048
	ds_read_b128 v[178:181], v140 offset:3072
	v_readfirstlane_b32 s23, v147
	v_lshl_add_u64 v[168:169], v[168:169], 0, s[8:9]
	s_mov_b32 m0, s23
	v_readfirstlane_b32 s23, v148
	ds_read_b128 v[182:185], v138 offset:32768
	ds_read_b128 v[186:189], v138 offset:33792
	ds_read_b128 v[190:193], v137 offset:32768
	ds_read_b128 v[194:197], v137 offset:33792
	ds_read_b128 v[198:201], v136 offset:32768
	ds_read_b128 v[202:205], v136 offset:33792
	ds_read_b128 v[206:209], v135 offset:32768
	ds_read_b128 v[210:213], v135 offset:33792
	global_load_lds_dwordx4 v[168:169], off
	v_lshl_add_u64 v[168:169], v[230:231], 0, s[8:9]
	s_mov_b32 m0, s23
	s_add_u32 s12, s12, 0x100
	global_load_lds_dwordx4 v[168:169], off
	s_waitcnt lgkmcnt(8)
	s_waitcnt vmcnt(10)
	s_barrier
	s_waitcnt lgkmcnt(0)
	s_addc_u32 s13, s13, 0
	s_setprio 1
	s_waitcnt lgkmcnt(0)
	v_mfma_f32_16x16x32_bf16 v[126:129], v[182:185], v[160:163], v[126:129]
	v_mfma_f32_16x16x32_bf16 v[122:125], v[182:185], v[174:177], v[122:125]
	v_mfma_f32_16x16x32_bf16 v[118:121], v[190:193], v[160:163], v[118:121]
	v_mfma_f32_16x16x32_bf16 v[114:117], v[190:193], v[174:177], v[114:117]
	v_mfma_f32_16x16x32_bf16 v[110:113], v[198:201], v[160:163], v[110:113]
	v_mfma_f32_16x16x32_bf16 v[106:109], v[198:201], v[174:177], v[106:109]
	v_mfma_f32_16x16x32_bf16 v[102:105], v[206:209], v[160:163], v[102:105]
	v_mfma_f32_16x16x32_bf16 v[98:101], v[206:209], v[174:177], v[98:101]
	v_mfma_f32_16x16x32_bf16 v[126:129], v[186:189], v[164:167], v[126:129]
	v_mfma_f32_16x16x32_bf16 v[122:125], v[186:189], v[178:181], v[122:125]
	v_mfma_f32_16x16x32_bf16 v[118:121], v[194:197], v[164:167], v[118:121]
	v_mfma_f32_16x16x32_bf16 v[114:117], v[194:197], v[178:181], v[114:117]
	v_mfma_f32_16x16x32_bf16 v[110:113], v[202:205], v[164:167], v[110:113]
	v_mfma_f32_16x16x32_bf16 v[106:109], v[202:205], v[178:181], v[106:109]
	v_mfma_f32_16x16x32_bf16 v[102:105], v[210:213], v[164:167], v[102:105]
	v_mfma_f32_16x16x32_bf16 v[98:101], v[210:213], v[178:181], v[98:101]
	s_setprio 0
	s_barrier
	v_readfirstlane_b32 s23, v156
	v_lshl_add_u64 v[168:169], v[232:233], 0, s[10:11]
	s_mov_b32 m0, s23
	v_readfirstlane_b32 s23, v157
	ds_read_b128 v[214:217], v139
	ds_read_b128 v[218:221], v139 offset:1024
	ds_read_b128 v[222:225], v139 offset:2048
	ds_read_b128 v[226:229], v139 offset:3072
	global_load_lds_dwordx4 v[168:169], off
	v_lshl_add_u64 v[168:169], v[234:235], 0, s[10:11]
	s_mov_b32 m0, s23
	s_nop 0
	global_load_lds_dwordx4 v[168:169], off
	s_waitcnt vmcnt(10)
	s_barrier
	s_waitcnt lgkmcnt(0)
	s_setprio 1
	s_waitcnt lgkmcnt(0)
	v_mfma_f32_16x16x32_bf16 v[94:97], v[182:185], v[214:217], v[94:97]
	v_mfma_f32_16x16x32_bf16 v[90:93], v[182:185], v[222:225], v[90:93]
	v_mfma_f32_16x16x32_bf16 v[86:89], v[190:193], v[214:217], v[86:89]
	v_mfma_f32_16x16x32_bf16 v[82:85], v[190:193], v[222:225], v[82:85]
	v_mfma_f32_16x16x32_bf16 v[78:81], v[198:201], v[214:217], v[78:81]
	v_mfma_f32_16x16x32_bf16 v[74:77], v[198:201], v[222:225], v[74:77]
	v_mfma_f32_16x16x32_bf16 v[70:73], v[206:209], v[214:217], v[70:73]
	v_mfma_f32_16x16x32_bf16 v[66:69], v[206:209], v[222:225], v[66:69]
	v_mfma_f32_16x16x32_bf16 v[94:97], v[186:189], v[218:221], v[94:97]
	v_mfma_f32_16x16x32_bf16 v[90:93], v[186:189], v[226:229], v[90:93]
	v_mfma_f32_16x16x32_bf16 v[86:89], v[194:197], v[218:221], v[86:89]
	v_mfma_f32_16x16x32_bf16 v[82:85], v[194:197], v[226:229], v[82:85]
	v_mfma_f32_16x16x32_bf16 v[78:81], v[202:205], v[218:221], v[78:81]
	v_mfma_f32_16x16x32_bf16 v[74:77], v[202:205], v[226:229], v[74:77]
	v_mfma_f32_16x16x32_bf16 v[70:73], v[210:213], v[218:221], v[70:73]
	v_mfma_f32_16x16x32_bf16 v[66:69], v[210:213], v[226:229], v[66:69]
	s_setprio 0
	v_readfirstlane_b32 s23, v149
	v_lshl_add_u64 v[168:169], v[236:237], 0, s[10:11]
	s_mov_b32 m0, s23
	v_readfirstlane_b32 s23, v150
	s_barrier
; #define STAGE(P, GP, ktrel) do { const GAS char* _g = (GP) + (ktrel) * (BK * 2); \
;     __builtin_amdgcn_global_load_lds((const GAS unsigned*)(_g + so0), (unsigned*)((char*)(P) + tid_ * 16), 16, 0, 0); \
;     __builtin_amdgcn_global_load_lds((const GAS unsigned*)(_g + so1), (unsigned*)((char*)(P) + tid_ * 16 + 8192), 16, 0, 0); } while (0)
; #define WAIT_V(n) asm volatile("s_waitcnt vmcnt(" #n ")" ::: "memory")
; #define WAIT_L(n) asm volatile("s_waitcnt lgkmcnt(" #n ")" ::: "memory")
; #define BAR __builtin_amdgcn_s_barrier()
; #define SCHED __builtin_amdgcn_sched_barrier(0)
; #define LDA(dst, b, h) for (int m = 0; m < 4; ++m) for (int k = 0; k < 2; ++k) \
;     dst[m][k] = *reinterpret_cast<const bf16x8*>((char*)SA(b, h) + lds_byte(wr * 64 + m * 16 + fr, k * 32 + fq * 8))
; #define LDB(dst, b, h) for (int n = 0; n < 2; ++n) for (int k = 0; k < 2; ++k) \
;     dst[n][k] = *reinterpret_cast<const bf16x8*>((char*)SB(b, h) + lds_byte(wc * 32 + n * 16 + fr, k * 32 + fq * 8))
; template <int K, int LD = K>
; __device__ __forceinline__ void gemm_main(const GAS bf16* A, const GAS bf16* Bt, int brow, int bcol, f32x4 (&acc)[2][2][4][2]) {
;     ...
;   for (int t = 0; t < nt - 2; t += 2) {
;     LDB(B0, 0, 0); SCHED; LDA(At, 0, 0); STAGE(SA(1, 1), pA1, 1);
;     WAIT_L(8); BAR; WAIT_L(0); MMA(0, 0, At, B0); BAR; SCHED;
;     LDB(B1, 0, 1); STAGE(SB(0, 0), pB0, 2);
;     BAR; WAIT_L(0); MMA(0, 1, At, B1); BAR;
;     LDA(At, 0, 1); STAGE(SA(0, 0), pA0, 2);
;     BAR; WAIT_L(0); MMA(1, 0, At, B0); BAR; SCHED;
;     STAGE(SB(0, 1), pB1, 2);
;     WAIT_V(6); BAR; MMA(1, 1, At, B1); BAR;
;     LDB(B0, 1, 0); SCHED; LDA(At, 1, 0); STAGE(SA(0, 1), pA1, 2);
;     WAIT_L(8); BAR; WAIT_L(0); MMA(0, 0, At, B0); BAR; SCHED;
;     LDB(B1, 1, 1); STAGE(SB(1, 0), pB0, 3);
;     BAR; WAIT_L(0); MMA(0, 1, At, B1); BAR;
;     LDA(At, 1, 1); STAGE(SA(1, 0), pA0, 3);
;     BAR; WAIT_L(0); MMA(1, 0, At, B0); BAR; SCHED;
;     STAGE(SB(1, 1), pB1, 3);
;     WAIT_V(6); BAR; MMA(1, 1, At, B1); BAR;
;     pA0 += 4 * BK; pA1 += 4 * BK; pB0 += 4 * BK; pB1 += 4 * BK;
;     asm volatile("" : "+s"(pA0), "+s"(pA1), "+s"(pB0), "+s"(pB1));
;   }
;   { LDB(B0, 0, 0); LDA(At, 0, 0); STAGE(SA(1, 1), pA1, 1);
;     BAR; WAIT_L(0); MMA(0, 0, At, B0); BAR;
;     LDB(B1, 0, 1); BAR; WAIT_L(0); MMA(0, 1, At, B1); BAR;
;     LDA(At, 0, 1); WAIT_V(4); BAR; WAIT_L(0); MMA(1, 0, At, B0); MMA(1, 1, At, B1); BAR; }
	ds_read_b128 v[182:185], v138 offset:49152
	ds_read_b128 v[186:189], v138 offset:50176
	ds_read_b128 v[190:193], v137 offset:49152
	ds_read_b128 v[194:197], v137 offset:50176
	ds_read_b128 v[198:201], v136 offset:49152
	ds_read_b128 v[202:205], v136 offset:50176
	ds_read_b128 v[206:209], v135 offset:49152
	ds_read_b128 v[210:213], v135 offset:50176
	global_load_lds_dwordx4 v[168:169], off
	v_lshl_add_u64 v[168:169], v[238:239], 0, s[10:11]
	s_mov_b32 m0, s23
	s_nop 0
	global_load_lds_dwordx4 v[168:169], off
	s_barrier
	s_waitcnt lgkmcnt(0)
	s_setprio 1
	s_waitcnt lgkmcnt(0)
	v_mfma_f32_16x16x32_bf16 v[62:65], v[182:185], v[160:163], v[62:65]
	v_mfma_f32_16x16x32_bf16 v[58:61], v[182:185], v[174:177], v[58:61]
	v_mfma_f32_16x16x32_bf16 v[54:57], v[190:193], v[160:163], v[54:57]
	v_mfma_f32_16x16x32_bf16 v[50:53], v[190:193], v[174:177], v[50:53]
	v_mfma_f32_16x16x32_bf16 v[46:49], v[198:201], v[160:163], v[46:49]
	v_mfma_f32_16x16x32_bf16 v[42:45], v[198:201], v[174:177], v[42:45]
	v_mfma_f32_16x16x32_bf16 v[38:41], v[206:209], v[160:163], v[38:41]
	v_mfma_f32_16x16x32_bf16 v[34:37], v[206:209], v[174:177], v[34:37]
	v_mfma_f32_16x16x32_bf16 v[62:65], v[186:189], v[164:167], v[62:65]
	v_mfma_f32_16x16x32_bf16 v[58:61], v[186:189], v[178:181], v[58:61]
	v_mfma_f32_16x16x32_bf16 v[54:57], v[194:197], v[164:167], v[54:57]
	v_mfma_f32_16x16x32_bf16 v[50:53], v[194:197], v[178:181], v[50:53]
	v_mfma_f32_16x16x32_bf16 v[46:49], v[202:205], v[164:167], v[46:49]
	v_mfma_f32_16x16x32_bf16 v[42:45], v[202:205], v[178:181], v[42:45]
	v_mfma_f32_16x16x32_bf16 v[38:41], v[210:213], v[164:167], v[38:41]
	v_mfma_f32_16x16x32_bf16 v[34:37], v[210:213], v[178:181], v[34:37]
	s_setprio 0
	s_barrier
	v_readfirstlane_b32 s23, v158
	v_lshl_add_u64 v[160:161], v[240:241], 0, s[10:11]
	s_mov_b32 m0, s23
	v_readfirstlane_b32 s23, v159
	global_load_lds_dwordx4 v[160:161], off
	v_lshl_add_u64 v[160:161], v[242:243], 0, s[10:11]
	s_mov_b32 m0, s23
	s_nop 0
	global_load_lds_dwordx4 v[160:161], off
	s_waitcnt vmcnt(10)
	s_barrier
	s_setprio 1
	v_mfma_f32_16x16x32_bf16 v[30:33], v[182:185], v[214:217], v[30:33]
	v_mfma_f32_16x16x32_bf16 v[26:29], v[182:185], v[222:225], v[26:29]
	v_mfma_f32_16x16x32_bf16 v[22:25], v[190:193], v[214:217], v[22:25]
	v_mfma_f32_16x16x32_bf16 v[18:21], v[190:193], v[222:225], v[18:21]
	v_mfma_f32_16x16x32_bf16 v[14:17], v[198:201], v[214:217], v[14:17]
	v_mfma_f32_16x16x32_bf16 v[10:13], v[198:201], v[222:225], v[10:13]
	v_mfma_f32_16x16x32_bf16 v[6:9], v[206:209], v[214:217], v[6:9]
	v_mfma_f32_16x16x32_bf16 v[2:5], v[206:209], v[222:225], v[2:5]
	v_mfma_f32_16x16x32_bf16 v[30:33], v[186:189], v[218:221], v[30:33]
	v_mfma_f32_16x16x32_bf16 v[26:29], v[186:189], v[226:229], v[26:29]
	v_mfma_f32_16x16x32_bf16 v[22:25], v[194:197], v[218:221], v[22:25]
	v_mfma_f32_16x16x32_bf16 v[18:21], v[194:197], v[226:229], v[18:21]
	v_mfma_f32_16x16x32_bf16 v[14:17], v[202:205], v[218:221], v[14:17]
	v_mfma_f32_16x16x32_bf16 v[10:13], v[202:205], v[226:229], v[10:13]
	v_mfma_f32_16x16x32_bf16 v[6:9], v[210:213], v[218:221], v[6:9]
	v_mfma_f32_16x16x32_bf16 v[2:5], v[210:213], v[226:229], v[2:5]
	s_setprio 0
	s_add_i32 s22, s22, 2
	s_cmp_lt_u32 s22, 40
	s_barrier
	s_cbranch_scc1 .LBB0_230
	ds_read_b128 v[146:149], v144
	ds_read_b128 v[150:153], v144 offset:1024
	ds_read_b128 v[156:159], v144 offset:2048
	ds_read_b128 v[160:163], v144 offset:3072
	ds_read_b128 v[164:167], v138
	ds_read_b128 v[174:177], v138 offset:1024
	ds_read_b128 v[178:181], v137
	ds_read_b128 v[182:185], v137 offset:1024
	ds_read_b128 v[186:189], v136
	ds_read_b128 v[190:193], v136 offset:1024
	ds_read_b128 v[194:197], v135
	ds_read_b128 v[198:201], v135 offset:1024
	v_lshl_add_u64 v[144:145], s[12:13], 0, v[130:131]
	v_readfirstlane_b32 s16, v143
	v_lshl_add_u64 v[144:145], v[144:145], 0, s[6:7]
	s_mov_b32 m0, s16
	v_lshl_add_u64 v[132:133], s[12:13], 0, v[132:133]
	v_readfirstlane_b32 s12, v142
	global_load_lds_dwordx4 v[144:145], off
	v_lshl_add_u64 v[132:133], v[132:133], 0, s[6:7]
	s_mov_b32 m0, s12
	s_nop 0
	global_load_lds_dwordx4 v[132:133], off
	s_waitcnt vmcnt(10)
	s_barrier
	s_waitcnt lgkmcnt(0)
	s_setprio 1
	s_waitcnt lgkmcnt(0)
	v_mfma_f32_16x16x32_bf16 v[126:129], v[164:167], v[146:149], v[126:129]
	v_mfma_f32_16x16x32_bf16 v[122:125], v[164:167], v[156:159], v[122:125]
	v_mfma_f32_16x16x32_bf16 v[110:113], v[186:189], v[146:149], v[110:113]
	v_mfma_f32_16x16x32_bf16 v[106:109], v[186:189], v[156:159], v[106:109]
	v_mfma_f32_16x16x32_bf16 v[126:129], v[174:177], v[150:153], v[126:129]
	v_mfma_f32_16x16x32_bf16 v[122:125], v[174:177], v[160:163], v[122:125]
	v_mfma_f32_16x16x32_bf16 v[118:121], v[178:181], v[146:149], v[118:121]
	v_mfma_f32_16x16x32_bf16 v[114:117], v[178:181], v[156:159], v[114:117]
	v_mfma_f32_16x16x32_bf16 v[110:113], v[190:193], v[150:153], v[110:113]
	v_mfma_f32_16x16x32_bf16 v[106:109], v[190:193], v[160:163], v[106:109]
	v_mfma_f32_16x16x32_bf16 v[102:105], v[194:197], v[146:149], v[102:105]
	v_mfma_f32_16x16x32_bf16 v[98:101], v[194:197], v[156:159], v[98:101]
	v_mfma_f32_16x16x32_bf16 v[142:145], v[182:185], v[150:153], v[118:121]
	v_mfma_f32_16x16x32_bf16 v[202:205], v[182:185], v[160:163], v[114:117]
	v_mfma_f32_16x16x32_bf16 v[206:209], v[198:201], v[150:153], v[102:105]
	v_mfma_f32_16x16x32_bf16 v[210:213], v[198:201], v[160:163], v[98:101]
	s_setprio 0
	s_barrier
	s_nop 1
	ds_read_b128 v[98:101], v141
	ds_read_b128 v[102:105], v141 offset:1024
	ds_read_b128 v[114:117], v141 offset:2048
	ds_read_b128 v[118:121], v141 offset:3072
	s_waitcnt vmcnt(8)
	s_barrier
; #define STAGE(P, GP, ktrel) do { const GAS char* _g = (GP) + (ktrel) * (BK * 2); \
;     __builtin_amdgcn_global_load_lds((const GAS unsigned*)(_g + so0), (unsigned*)((char*)(P) + tid_ * 16), 16, 0, 0); \
;     __builtin_amdgcn_global_load_lds((const GAS unsigned*)(_g + so1), (unsigned*)((char*)(P) + tid_ * 16 + 8192), 16, 0, 0); } while (0)
; #define WAIT_V(n) asm volatile("s_waitcnt vmcnt(" #n ")" ::: "memory")
; #define WAIT_L(n) asm volatile("s_waitcnt lgkmcnt(" #n ")" ::: "memory")
; #define BAR __builtin_amdgcn_s_barrier()
; #define LDA(dst, b, h) for (int m = 0; m < 4; ++m) for (int k = 0; k < 2; ++k) \
;     dst[m][k] = *reinterpret_cast<const bf16x8*>((char*)SA(b, h) + lds_byte(wr * 64 + m * 16 + fr, k * 32 + fq * 8))
; #define LDB(dst, b, h) for (int n = 0; n < 2; ++n) for (int k = 0; k < 2; ++k) \
;     dst[n][k] = *reinterpret_cast<const bf16x8*>((char*)SB(b, h) + lds_byte(wc * 32 + n * 16 + fr, k * 32 + fq * 8))
; #define MMA(ai, bj, At_, Bt_) do { __builtin_amdgcn_s_setprio(1); \
;     for (int m = 0; m < 4; ++m) for (int n = 0; n < 2; ++n) for (int k = 0; k < 2; ++k) \
;       acc[ai][bj][m][n] = __builtin_amdgcn_mfma_f32_16x16x32_bf16(At_[m][k], Bt_[n][k], acc[ai][bj][m][n], 0, 0, 0); \
;     __builtin_amdgcn_s_setprio(0); } while (0)
; template <int K, int LD = K>
; __device__ __forceinline__ void gemm_main(const GAS bf16* A, const GAS bf16* Bt, int brow, int bcol, f32x4 (&acc)[2][2][4][2]) {
;     ...
;   { LDB(B0, 0, 0); LDA(At, 0, 0); STAGE(SA(1, 1), pA1, 1);
;     BAR; WAIT_L(0); MMA(0, 0, At, B0); BAR;
;     LDB(B1, 0, 1); BAR; WAIT_L(0); MMA(0, 1, At, B1); BAR;
;     LDA(At, 0, 1); WAIT_V(4); BAR; WAIT_L(0); MMA(1, 0, At, B0); MMA(1, 1, At, B1); BAR; }
;   { LDB(B0, 1, 0); LDA(At, 1, 0); WAIT_V(2); BAR; WAIT_L(0); MMA(0, 0, At, B0); BAR;
;     LDB(B1, 1, 1); WAIT_V(0); BAR; WAIT_L(0); MMA(0, 1, At, B1); BAR;
;     LDA(At, 1, 1); BAR; WAIT_L(0); MMA(1, 0, At, B0); MMA(1, 1, At, B1); BAR; }
	s_waitcnt lgkmcnt(0)
	s_setprio 1
	s_waitcnt lgkmcnt(0)
	v_mfma_f32_16x16x32_bf16 v[94:97], v[164:167], v[98:101], v[94:97]
	v_mfma_f32_16x16x32_bf16 v[90:93], v[164:167], v[114:117], v[90:93]
	v_mfma_f32_16x16x32_bf16 v[78:81], v[186:189], v[98:101], v[78:81]
	v_mfma_f32_16x16x32_bf16 v[74:77], v[186:189], v[114:117], v[74:77]
	v_mfma_f32_16x16x32_bf16 v[94:97], v[174:177], v[102:105], v[94:97]
	v_mfma_f32_16x16x32_bf16 v[90:93], v[174:177], v[118:121], v[90:93]
	v_mfma_f32_16x16x32_bf16 v[86:89], v[178:181], v[98:101], v[86:89]
	v_mfma_f32_16x16x32_bf16 v[82:85], v[178:181], v[114:117], v[82:85]
	v_mfma_f32_16x16x32_bf16 v[78:81], v[190:193], v[102:105], v[78:81]
	v_mfma_f32_16x16x32_bf16 v[74:77], v[190:193], v[118:121], v[74:77]
	v_mfma_f32_16x16x32_bf16 v[70:73], v[194:197], v[98:101], v[70:73]
	v_mfma_f32_16x16x32_bf16 v[66:69], v[194:197], v[114:117], v[66:69]
	v_mfma_f32_16x16x32_bf16 v[164:167], v[182:185], v[102:105], v[86:89]
	v_mfma_f32_16x16x32_bf16 v[174:177], v[182:185], v[118:121], v[82:85]
	v_mfma_f32_16x16x32_bf16 v[178:181], v[198:201], v[102:105], v[70:73]
	v_mfma_f32_16x16x32_bf16 v[182:185], v[198:201], v[118:121], v[66:69]
	s_setprio 0
	s_barrier
	s_nop 1
	ds_read_b128 v[66:69], v138 offset:16384
	ds_read_b128 v[70:73], v138 offset:17408
	ds_read_b128 v[82:85], v137 offset:16384
	ds_read_b128 v[86:89], v137 offset:17408
	ds_read_b128 v[186:189], v136 offset:16384
	ds_read_b128 v[190:193], v136 offset:17408
	ds_read_b128 v[194:197], v135 offset:16384
	ds_read_b128 v[198:201], v135 offset:17408
	s_waitcnt vmcnt(4)
	s_barrier
	s_waitcnt lgkmcnt(0)
	s_setprio 1
	s_waitcnt lgkmcnt(0)
	v_mfma_f32_16x16x32_bf16 v[62:65], v[66:69], v[146:149], v[62:65]
	v_mfma_f32_16x16x32_bf16 v[58:61], v[66:69], v[156:159], v[58:61]
	v_mfma_f32_16x16x32_bf16 v[46:49], v[186:189], v[146:149], v[46:49]
	v_mfma_f32_16x16x32_bf16 v[42:45], v[186:189], v[156:159], v[42:45]
	v_mfma_f32_16x16x32_bf16 v[62:65], v[70:73], v[150:153], v[62:65]
	v_mfma_f32_16x16x32_bf16 v[58:61], v[70:73], v[160:163], v[58:61]
	v_mfma_f32_16x16x32_bf16 v[54:57], v[82:85], v[146:149], v[54:57]
	v_mfma_f32_16x16x32_bf16 v[50:53], v[82:85], v[156:159], v[50:53]
	v_mfma_f32_16x16x32_bf16 v[46:49], v[190:193], v[150:153], v[46:49]
	v_mfma_f32_16x16x32_bf16 v[42:45], v[190:193], v[160:163], v[42:45]
	v_mfma_f32_16x16x32_bf16 v[38:41], v[194:197], v[146:149], v[38:41]
	v_mfma_f32_16x16x32_bf16 v[34:37], v[194:197], v[156:159], v[34:37]
	v_mfma_f32_16x16x32_bf16 v[214:217], v[86:89], v[150:153], v[54:57]
	v_mfma_f32_16x16x32_bf16 v[218:221], v[86:89], v[160:163], v[50:53]
	v_mfma_f32_16x16x32_bf16 v[146:149], v[198:201], v[150:153], v[38:41]
	v_mfma_f32_16x16x32_bf16 v[150:153], v[198:201], v[160:163], v[34:37]
	s_setprio 0
	s_setprio 1
	v_mfma_f32_16x16x32_bf16 v[30:33], v[66:69], v[98:101], v[30:33]
	v_mfma_f32_16x16x32_bf16 v[26:29], v[66:69], v[114:117], v[26:29]
	v_mfma_f32_16x16x32_bf16 v[14:17], v[186:189], v[98:101], v[14:17]
	v_mfma_f32_16x16x32_bf16 v[10:13], v[186:189], v[114:117], v[10:13]
	v_mfma_f32_16x16x32_bf16 v[30:33], v[70:73], v[102:105], v[30:33]
	v_mfma_f32_16x16x32_bf16 v[26:29], v[70:73], v[118:121], v[26:29]
	v_mfma_f32_16x16x32_bf16 v[22:25], v[82:85], v[98:101], v[22:25]
	v_mfma_f32_16x16x32_bf16 v[18:21], v[82:85], v[114:117], v[18:21]
	v_mfma_f32_16x16x32_bf16 v[14:17], v[190:193], v[102:105], v[14:17]
	v_mfma_f32_16x16x32_bf16 v[10:13], v[190:193], v[118:121], v[10:13]
	v_mfma_f32_16x16x32_bf16 v[6:9], v[194:197], v[98:101], v[6:9]
	v_mfma_f32_16x16x32_bf16 v[2:5], v[194:197], v[114:117], v[2:5]
	v_mfma_f32_16x16x32_bf16 v[156:159], v[86:89], v[102:105], v[22:25]
	v_mfma_f32_16x16x32_bf16 v[160:163], v[86:89], v[118:121], v[18:21]
	v_mfma_f32_16x16x32_bf16 v[186:189], v[198:201], v[102:105], v[6:9]
	v_mfma_f32_16x16x32_bf16 v[190:193], v[198:201], v[118:121], v[2:5]
	s_setprio 0
	s_barrier
	s_nop 1
	ds_read_b128 v[2:5], v140
	ds_read_b128 v[6:9], v140 offset:1024
	ds_read_b128 v[194:197], v140 offset:2048
	ds_read_b128 v[198:201], v140 offset:3072
	ds_read_b128 v[18:21], v138 offset:32768
	ds_read_b128 v[22:25], v138 offset:33792
	ds_read_b128 v[34:37], v137 offset:32768
	ds_read_b128 v[38:41], v137 offset:33792
	ds_read_b128 v[50:53], v136 offset:32768
	ds_read_b128 v[54:57], v136 offset:33792
	ds_read_b128 v[222:225], v135 offset:32768
	ds_read_b128 v[226:229], v135 offset:33792
	s_waitcnt vmcnt(2)
	s_barrier
; #define STAGE(P, GP, ktrel) do { const GAS char* _g = (GP) + (ktrel) * (BK * 2); \
;     __builtin_amdgcn_global_load_lds((const GAS unsigned*)(_g + so0), (unsigned*)((char*)(P) + tid_ * 16), 16, 0, 0); \
;     __builtin_amdgcn_global_load_lds((const GAS unsigned*)(_g + so1), (unsigned*)((char*)(P) + tid_ * 16 + 8192), 16, 0, 0); } while (0)
; #define WAIT_V(n) asm volatile("s_waitcnt vmcnt(" #n ")" ::: "memory")
; #define WAIT_L(n) asm volatile("s_waitcnt lgkmcnt(" #n ")" ::: "memory")
; #define BAR __builtin_amdgcn_s_barrier()
; #define LDA(dst, b, h) for (int m = 0; m < 4; ++m) for (int k = 0; k < 2; ++k) \
;     dst[m][k] = *reinterpret_cast<const bf16x8*>((char*)SA(b, h) + lds_byte(wr * 64 + m * 16 + fr, k * 32 + fq * 8))
; #define LDB(dst, b, h) for (int n = 0; n < 2; ++n) for (int k = 0; k < 2; ++k) \
;     dst[n][k] = *reinterpret_cast<const bf16x8*>((char*)SB(b, h) + lds_byte(wc * 32 + n * 16 + fr, k * 32 + fq * 8))
; #define MMA(ai, bj, At_, Bt_) do { __builtin_amdgcn_s_setprio(1); \
;     for (int m = 0; m < 4; ++m) for (int n = 0; n < 2; ++n) for (int k = 0; k < 2; ++k) \
;       acc[ai][bj][m][n] = __builtin_amdgcn_mfma_f32_16x16x32_bf16(At_[m][k], Bt_[n][k], acc[ai][bj][m][n], 0, 0, 0); \
;     __builtin_amdgcn_s_setprio(0); } while (0)
; template <int K, int LD = K>
; __device__ __forceinline__ void gemm_main(const GAS bf16* A, const GAS bf16* Bt, int brow, int bcol, f32x4 (&acc)[2][2][4][2]) {
;     ...
;   { LDB(B0, 0, 0); LDA(At, 0, 0); STAGE(SA(1, 1), pA1, 1);
;     BAR; WAIT_L(0); MMA(0, 0, At, B0); BAR;
;     LDB(B1, 0, 1); BAR; WAIT_L(0); MMA(0, 1, At, B1); BAR;
;     LDA(At, 0, 1); WAIT_V(4); BAR; WAIT_L(0); MMA(1, 0, At, B0); MMA(1, 1, At, B1); BAR; }
;   { LDB(B0, 1, 0); LDA(At, 1, 0); WAIT_V(2); BAR; WAIT_L(0); MMA(0, 0, At, B0); BAR;
;     LDB(B1, 1, 1); WAIT_V(0); BAR; WAIT_L(0); MMA(0, 1, At, B1); BAR;
;     LDA(At, 1, 1); BAR; WAIT_L(0); MMA(1, 0, At, B0); MMA(1, 1, At, B1); BAR; }
;   if (wr == 0) BAR;
	s_waitcnt lgkmcnt(0)
	s_setprio 1
	s_waitcnt lgkmcnt(0)
	v_mfma_f32_16x16x32_bf16 v[66:69], v[18:21], v[2:5], v[126:129]
	v_mfma_f32_16x16x32_bf16 v[118:121], v[22:25], v[6:9], v[66:69]
	v_mfma_f32_16x16x32_bf16 v[66:69], v[18:21], v[194:197], v[122:125]
	v_mfma_f32_16x16x32_bf16 v[114:117], v[22:25], v[198:201], v[66:69]
	v_mfma_f32_16x16x32_bf16 v[66:69], v[34:37], v[2:5], v[142:145]
	v_mfma_f32_16x16x32_bf16 v[102:105], v[38:41], v[6:9], v[66:69]
	v_mfma_f32_16x16x32_bf16 v[66:69], v[34:37], v[194:197], v[202:205]
	v_mfma_f32_16x16x32_bf16 v[98:101], v[38:41], v[198:201], v[66:69]
	v_mfma_f32_16x16x32_bf16 v[66:69], v[50:53], v[2:5], v[110:113]
	v_mfma_f32_16x16x32_bf16 v[86:89], v[54:57], v[6:9], v[66:69]
	v_mfma_f32_16x16x32_bf16 v[66:69], v[50:53], v[194:197], v[106:109]
	v_mfma_f32_16x16x32_bf16 v[82:85], v[54:57], v[198:201], v[66:69]
	v_mfma_f32_16x16x32_bf16 v[66:69], v[222:225], v[2:5], v[206:209]
	v_mfma_f32_16x16x32_bf16 v[70:73], v[226:229], v[6:9], v[66:69]
	v_mfma_f32_16x16x32_bf16 v[66:69], v[222:225], v[194:197], v[210:213]
	v_mfma_f32_16x16x32_bf16 v[66:69], v[226:229], v[198:201], v[66:69]
	s_setprio 0
	s_barrier
	ds_read_b128 v[140:143], v139
	ds_read_b128 v[202:205], v139 offset:1024
	ds_read_b128 v[206:209], v139 offset:2048
	ds_read_b128 v[210:213], v139 offset:3072
	s_waitcnt vmcnt(0)
	s_barrier
	s_waitcnt lgkmcnt(0)
	s_setprio 1
	s_waitcnt lgkmcnt(0)
	v_mfma_f32_16x16x32_bf16 v[94:97], v[18:21], v[140:143], v[94:97]
	v_mfma_f32_16x16x32_bf16 v[18:21], v[18:21], v[206:209], v[90:93]
	v_mfma_f32_16x16x32_bf16 v[122:125], v[22:25], v[210:213], v[18:21]
	v_mfma_f32_16x16x32_bf16 v[18:21], v[34:37], v[140:143], v[164:167]
	v_mfma_f32_16x16x32_bf16 v[110:113], v[38:41], v[202:205], v[18:21]
	v_mfma_f32_16x16x32_bf16 v[18:21], v[34:37], v[206:209], v[174:177]
	v_mfma_f32_16x16x32_bf16 v[106:109], v[38:41], v[210:213], v[18:21]
	v_mfma_f32_16x16x32_bf16 v[18:21], v[50:53], v[140:143], v[78:81]
	v_mfma_f32_16x16x32_bf16 v[126:129], v[22:25], v[202:205], v[94:97]
	v_mfma_f32_16x16x32_bf16 v[94:97], v[54:57], v[202:205], v[18:21]
	v_mfma_f32_16x16x32_bf16 v[18:21], v[50:53], v[206:209], v[74:77]
	v_mfma_f32_16x16x32_bf16 v[90:93], v[54:57], v[210:213], v[18:21]
	v_mfma_f32_16x16x32_bf16 v[18:21], v[222:225], v[140:143], v[178:181]
	v_mfma_f32_16x16x32_bf16 v[78:81], v[226:229], v[202:205], v[18:21]
	v_mfma_f32_16x16x32_bf16 v[18:21], v[222:225], v[206:209], v[182:185]
	v_mfma_f32_16x16x32_bf16 v[74:77], v[226:229], v[210:213], v[18:21]
	s_setprio 0
	s_barrier
	ds_read_b128 v[164:167], v138 offset:49152
	ds_read_b128 v[174:177], v138 offset:50176
	ds_read_b128 v[178:181], v137 offset:49152
	ds_read_b128 v[182:185], v137 offset:50176
	ds_read_b128 v[222:225], v136 offset:49152
	ds_read_b128 v[136:139], v136 offset:50176
	ds_read_b128 v[226:229], v135 offset:49152
	ds_read_b128 v[230:233], v135 offset:50176
	s_barrier
	s_waitcnt lgkmcnt(0)
	s_setprio 1
	s_waitcnt lgkmcnt(0)
	v_mfma_f32_16x16x32_bf16 v[18:21], v[164:167], v[2:5], v[62:65]
	v_mfma_f32_16x16x32_bf16 v[54:57], v[174:177], v[6:9], v[18:21]
	v_mfma_f32_16x16x32_bf16 v[18:21], v[164:167], v[194:197], v[58:61]
	v_mfma_f32_16x16x32_bf16 v[50:53], v[174:177], v[198:201], v[18:21]
	v_mfma_f32_16x16x32_bf16 v[18:21], v[178:181], v[2:5], v[214:217]
	v_mfma_f32_16x16x32_bf16 v[38:41], v[182:185], v[6:9], v[18:21]
	v_mfma_f32_16x16x32_bf16 v[18:21], v[178:181], v[194:197], v[218:221]
	v_mfma_f32_16x16x32_bf16 v[34:37], v[182:185], v[198:201], v[18:21]
	v_mfma_f32_16x16x32_bf16 v[18:21], v[222:225], v[2:5], v[46:49]
	v_mfma_f32_16x16x32_bf16 v[2:5], v[226:229], v[2:5], v[146:149]
	v_mfma_f32_16x16x32_bf16 v[22:25], v[136:139], v[6:9], v[18:21]
	v_mfma_f32_16x16x32_bf16 v[18:21], v[222:225], v[194:197], v[42:45]
	v_mfma_f32_16x16x32_bf16 v[6:9], v[230:233], v[6:9], v[2:5]
	v_mfma_f32_16x16x32_bf16 v[2:5], v[226:229], v[194:197], v[150:153]
	v_mfma_f32_16x16x32_bf16 v[18:21], v[136:139], v[198:201], v[18:21]
	v_mfma_f32_16x16x32_bf16 v[2:5], v[230:233], v[198:201], v[2:5]
	s_setprio 0
	s_setprio 1
	v_mfma_f32_16x16x32_bf16 v[26:29], v[164:167], v[206:209], v[26:29]
	v_mfma_f32_16x16x32_bf16 v[58:61], v[174:177], v[210:213], v[26:29]
	v_mfma_f32_16x16x32_bf16 v[26:29], v[178:181], v[140:143], v[156:159]
	v_mfma_f32_16x16x32_bf16 v[46:49], v[182:185], v[202:205], v[26:29]
	v_mfma_f32_16x16x32_bf16 v[26:29], v[178:181], v[206:209], v[160:163]
	v_mfma_f32_16x16x32_bf16 v[10:13], v[222:225], v[206:209], v[10:13]
	v_mfma_f32_16x16x32_bf16 v[30:33], v[164:167], v[140:143], v[30:33]
	v_mfma_f32_16x16x32_bf16 v[42:45], v[182:185], v[210:213], v[26:29]
	v_mfma_f32_16x16x32_bf16 v[14:17], v[222:225], v[140:143], v[14:17]
	v_mfma_f32_16x16x32_bf16 v[26:29], v[136:139], v[210:213], v[10:13]
	v_mfma_f32_16x16x32_bf16 v[10:13], v[226:229], v[140:143], v[186:189]
	v_mfma_f32_16x16x32_bf16 v[62:65], v[174:177], v[202:205], v[30:33]
	v_mfma_f32_16x16x32_bf16 v[30:33], v[136:139], v[202:205], v[14:17]
	v_mfma_f32_16x16x32_bf16 v[14:17], v[230:233], v[202:205], v[10:13]
	v_mfma_f32_16x16x32_bf16 v[10:13], v[226:229], v[206:209], v[190:193]
	v_mfma_f32_16x16x32_bf16 v[10:13], v[230:233], v[210:213], v[10:13]
	s_setprio 0
	v_cmp_gt_u32_e32 vcc, s35, v134
	s_barrier
	s_and_saveexec_b64 s[12:13], vcc
	s_cbranch_execz .LBB0_233
	s_barrier

; #define STAGE(P, GP, ktrel) do { const GAS char* _g = (GP) + (ktrel) * (BK * 2); \
;     __builtin_amdgcn_global_load_lds((const GAS unsigned*)(_g + so0), (unsigned*)((char*)(P) + tid_ * 16), 16, 0, 0); \
;     __builtin_amdgcn_global_load_lds((const GAS unsigned*)(_g + so1), (unsigned*)((char*)(P) + tid_ * 16 + 8192), 16, 0, 0); } while (0)
; #define WAIT_V(n) asm volatile("s_waitcnt vmcnt(" #n ")" ::: "memory")
; #define WAIT_L(n) asm volatile("s_waitcnt lgkmcnt(" #n ")" ::: "memory")
; #define BAR __builtin_amdgcn_s_barrier()
; #define SCHED __builtin_amdgcn_sched_barrier(0)
; #define LDA(dst, b, h) for (int m = 0; m < 4; ++m) for (int k = 0; k < 2; ++k) \
;     dst[m][k] = *reinterpret_cast<const bf16x8*>((char*)SA(b, h) + lds_byte(wr * 64 + m * 16 + fr, k * 32 + fq * 8))
; #define LDB(dst, b, h) for (int n = 0; n < 2; ++n) for (int k = 0; k < 2; ++k) \
;     dst[n][k] = *reinterpret_cast<const bf16x8*>((char*)SB(b, h) + lds_byte(wc * 32 + n * 16 + fr, k * 32 + fq * 8))
; template <int K, int LD = K>
; __device__ __forceinline__ void gemm_main(const GAS bf16* A, const GAS bf16* Bt, int brow, int bcol, f32x4 (&acc)[2][2][4][2]) {
;     ...
;   for (int t = 0; t < nt - 2; t += 2) {
;     LDB(B0, 0, 0); SCHED; LDA(At, 0, 0); STAGE(SA(1, 1), pA1, 1);
;     WAIT_L(8); BAR; WAIT_L(0); MMA(0, 0, At, B0); BAR; SCHED;
;     LDB(B1, 0, 1); STAGE(SB(0, 0), pB0, 2);
;     BAR; WAIT_L(0); MMA(0, 1, At, B1); BAR;
;     LDA(At, 0, 1); STAGE(SA(0, 0), pA0, 2);
;     BAR; WAIT_L(0); MMA(1, 0, At, B0); BAR; SCHED;
;     STAGE(SB(0, 1), pB1, 2);
;     WAIT_V(6); BAR; MMA(1, 1, At, B1); BAR;
;     LDB(B0, 1, 0); SCHED; LDA(At, 1, 0); STAGE(SA(0, 1), pA1, 2);
;     WAIT_L(8); BAR; WAIT_L(0); MMA(0, 0, At, B0); BAR; SCHED;
;     LDB(B1, 1, 1); STAGE(SB(1, 0), pB0, 3);
;     BAR; WAIT_L(0); MMA(0, 1, At, B1); BAR;
;     LDA(At, 1, 1); STAGE(SA(1, 0), pA0, 3);
;     BAR; WAIT_L(0); MMA(1, 0, At, B0); BAR; SCHED;
;     STAGE(SB(1, 1), pB1, 3);
;     WAIT_V(6); BAR; MMA(1, 1, At, B1); BAR;
;     pA0 += 4 * BK; pA1 += 4 * BK; pB0 += 4 * BK; pB1 += 4 * BK;
;     asm volatile("" : "+s"(pA0), "+s"(pA1), "+s"(pB0), "+s"(pB1));
;   }
.LBB0_346:
	ds_read_b128 v[162:165], v146
	ds_read_b128 v[166:169], v146 offset:1024
	ds_read_b128 v[174:177], v146 offset:2048
	ds_read_b128 v[178:181], v146 offset:3072
	v_lshl_add_u64 v[230:231], s[26:27], 0, v[130:131]
	v_readfirstlane_b32 s20, v143
	v_lshl_add_u64 v[214:215], v[230:231], 0, s[14:15]
	s_mov_b32 m0, s20
	v_lshl_add_u64 v[232:233], s[26:27], 0, v[132:133]
	v_readfirstlane_b32 s20, v142
	ds_read_b128 v[182:185], v138
	ds_read_b128 v[186:189], v138 offset:1024
	ds_read_b128 v[190:193], v137
	ds_read_b128 v[194:197], v137 offset:1024
	ds_read_b128 v[198:201], v136
	ds_read_b128 v[202:205], v136 offset:1024
	ds_read_b128 v[206:209], v135
	ds_read_b128 v[210:213], v135 offset:1024
	global_load_lds_dwordx4 v[214:215], off
	v_lshl_add_u64 v[214:215], v[232:233], 0, s[14:15]
	s_mov_b32 m0, s20
	s_nop 0
	global_load_lds_dwordx4 v[214:215], off
	s_waitcnt lgkmcnt(8)
	s_waitcnt vmcnt(10)
	s_barrier
	s_waitcnt lgkmcnt(0)
	s_setprio 1
	s_waitcnt lgkmcnt(0)
	v_mfma_f32_16x16x32_bf16 v[126:129], v[182:185], v[162:165], v[126:129]
	v_mfma_f32_16x16x32_bf16 v[122:125], v[182:185], v[174:177], v[122:125]
	v_mfma_f32_16x16x32_bf16 v[118:121], v[190:193], v[162:165], v[118:121]
	v_mfma_f32_16x16x32_bf16 v[114:117], v[190:193], v[174:177], v[114:117]
	v_mfma_f32_16x16x32_bf16 v[110:113], v[198:201], v[162:165], v[110:113]
	v_mfma_f32_16x16x32_bf16 v[106:109], v[198:201], v[174:177], v[106:109]
	v_mfma_f32_16x16x32_bf16 v[102:105], v[206:209], v[162:165], v[102:105]
	v_mfma_f32_16x16x32_bf16 v[98:101], v[206:209], v[174:177], v[98:101]
	v_mfma_f32_16x16x32_bf16 v[126:129], v[186:189], v[166:169], v[126:129]
	v_mfma_f32_16x16x32_bf16 v[122:125], v[186:189], v[178:181], v[122:125]
	v_mfma_f32_16x16x32_bf16 v[118:121], v[194:197], v[166:169], v[118:121]
	v_mfma_f32_16x16x32_bf16 v[114:117], v[194:197], v[178:181], v[114:117]
	v_mfma_f32_16x16x32_bf16 v[110:113], v[202:205], v[166:169], v[110:113]
	v_mfma_f32_16x16x32_bf16 v[106:109], v[202:205], v[178:181], v[106:109]
	v_mfma_f32_16x16x32_bf16 v[102:105], v[210:213], v[166:169], v[102:105]
	v_mfma_f32_16x16x32_bf16 v[98:101], v[210:213], v[178:181], v[98:101]
	s_setprio 0
	s_barrier
	v_lshl_add_u64 v[234:235], s[36:37], 0, v[130:131]
	v_readfirstlane_b32 s20, v153
	v_lshl_add_u64 v[236:237], v[234:235], 0, s[22:23]
	s_mov_b32 m0, s20
	ds_read_b128 v[214:217], v141
	ds_read_b128 v[218:221], v141 offset:1024
	ds_read_b128 v[222:225], v141 offset:2048
	ds_read_b128 v[226:229], v141 offset:3072
	global_load_lds_dwordx4 v[236:237], off
	v_lshl_add_u64 v[236:237], s[36:37], 0, v[132:133]
	v_readfirstlane_b32 s20, v154
	v_lshl_add_u64 v[238:239], v[236:237], 0, s[22:23]
	s_mov_b32 m0, s20
	s_add_u32 s36, s36, 0x100
	global_load_lds_dwordx4 v[238:239], off
	s_waitcnt vmcnt(10)
	s_barrier
	s_waitcnt lgkmcnt(0)
	s_addc_u32 s37, s37, 0
	s_setprio 1
	s_waitcnt lgkmcnt(0)
	v_mfma_f32_16x16x32_bf16 v[94:97], v[182:185], v[214:217], v[94:97]
	v_mfma_f32_16x16x32_bf16 v[90:93], v[182:185], v[222:225], v[90:93]
	v_mfma_f32_16x16x32_bf16 v[86:89], v[190:193], v[214:217], v[86:89]
	v_mfma_f32_16x16x32_bf16 v[82:85], v[190:193], v[222:225], v[82:85]
	v_mfma_f32_16x16x32_bf16 v[78:81], v[198:201], v[214:217], v[78:81]
	v_mfma_f32_16x16x32_bf16 v[74:77], v[198:201], v[222:225], v[74:77]
	v_mfma_f32_16x16x32_bf16 v[70:73], v[206:209], v[214:217], v[70:73]
	v_mfma_f32_16x16x32_bf16 v[66:69], v[206:209], v[222:225], v[66:69]
	v_mfma_f32_16x16x32_bf16 v[94:97], v[186:189], v[218:221], v[94:97]
	v_mfma_f32_16x16x32_bf16 v[90:93], v[186:189], v[226:229], v[90:93]
	v_mfma_f32_16x16x32_bf16 v[86:89], v[194:197], v[218:221], v[86:89]
	v_mfma_f32_16x16x32_bf16 v[82:85], v[194:197], v[226:229], v[82:85]
	v_mfma_f32_16x16x32_bf16 v[78:81], v[202:205], v[218:221], v[78:81]
	v_mfma_f32_16x16x32_bf16 v[74:77], v[202:205], v[226:229], v[74:77]
	v_mfma_f32_16x16x32_bf16 v[70:73], v[210:213], v[218:221], v[70:73]
	v_mfma_f32_16x16x32_bf16 v[66:69], v[210:213], v[226:229], v[66:69]
	s_setprio 0
	v_lshl_add_u64 v[238:239], s[34:35], 0, v[130:131]
	v_readfirstlane_b32 s20, v147
	v_lshl_add_u64 v[240:241], v[238:239], 0, s[22:23]
	s_mov_b32 m0, s20
	s_barrier
	ds_read_b128 v[182:185], v138 offset:16384
	ds_read_b128 v[186:189], v138 offset:17408
	ds_read_b128 v[190:193], v137 offset:16384
	ds_read_b128 v[194:197], v137 offset:17408
	ds_read_b128 v[198:201], v136 offset:16384
	ds_read_b128 v[202:205], v136 offset:17408
	ds_read_b128 v[206:209], v135 offset:16384
	ds_read_b128 v[210:213], v135 offset:17408
	global_load_lds_dwordx4 v[240:241], off
	v_lshl_add_u64 v[240:241], s[34:35], 0, v[132:133]
	v_readfirstlane_b32 s20, v148
	v_lshl_add_u64 v[242:243], v[240:241], 0, s[22:23]
	s_mov_b32 m0, s20
	s_add_u32 s34, s34, 0x100
	global_load_lds_dwordx4 v[242:243], off
	s_barrier
	s_waitcnt lgkmcnt(0)
	s_addc_u32 s35, s35, 0
	s_setprio 1
	s_waitcnt lgkmcnt(0)
	v_mfma_f32_16x16x32_bf16 v[62:65], v[182:185], v[162:165], v[62:65]
	v_mfma_f32_16x16x32_bf16 v[58:61], v[182:185], v[174:177], v[58:61]
	v_mfma_f32_16x16x32_bf16 v[54:57], v[190:193], v[162:165], v[54:57]
	v_mfma_f32_16x16x32_bf16 v[50:53], v[190:193], v[174:177], v[50:53]
	v_mfma_f32_16x16x32_bf16 v[46:49], v[198:201], v[162:165], v[46:49]
	v_mfma_f32_16x16x32_bf16 v[42:45], v[198:201], v[174:177], v[42:45]
	v_mfma_f32_16x16x32_bf16 v[38:41], v[206:209], v[162:165], v[38:41]
	v_mfma_f32_16x16x32_bf16 v[34:37], v[206:209], v[174:177], v[34:37]
	v_mfma_f32_16x16x32_bf16 v[62:65], v[186:189], v[166:169], v[62:65]
	v_mfma_f32_16x16x32_bf16 v[58:61], v[186:189], v[178:181], v[58:61]
	v_mfma_f32_16x16x32_bf16 v[54:57], v[194:197], v[166:169], v[54:57]
	v_mfma_f32_16x16x32_bf16 v[50:53], v[194:197], v[178:181], v[50:53]
	v_mfma_f32_16x16x32_bf16 v[46:49], v[202:205], v[166:169], v[46:49]
	v_mfma_f32_16x16x32_bf16 v[42:45], v[202:205], v[178:181], v[42:45]
	v_mfma_f32_16x16x32_bf16 v[38:41], v[210:213], v[166:169], v[38:41]
	v_mfma_f32_16x16x32_bf16 v[34:37], v[210:213], v[178:181], v[34:37]
	s_setprio 0
	s_barrier
; #define STAGE(P, GP, ktrel) do { const GAS char* _g = (GP) + (ktrel) * (BK * 2); \
;     __builtin_amdgcn_global_load_lds((const GAS unsigned*)(_g + so0), (unsigned*)((char*)(P) + tid_ * 16), 16, 0, 0); \
;     __builtin_amdgcn_global_load_lds((const GAS unsigned*)(_g + so1), (unsigned*)((char*)(P) + tid_ * 16 + 8192), 16, 0, 0); } while (0)
; #define WAIT_V(n) asm volatile("s_waitcnt vmcnt(" #n ")" ::: "memory")
; #define WAIT_L(n) asm volatile("s_waitcnt lgkmcnt(" #n ")" ::: "memory")
; #define BAR __builtin_amdgcn_s_barrier()
; #define SCHED __builtin_amdgcn_sched_barrier(0)
; #define LDA(dst, b, h) for (int m = 0; m < 4; ++m) for (int k = 0; k < 2; ++k) \
;     dst[m][k] = *reinterpret_cast<const bf16x8*>((char*)SA(b, h) + lds_byte(wr * 64 + m * 16 + fr, k * 32 + fq * 8))
; #define LDB(dst, b, h) for (int n = 0; n < 2; ++n) for (int k = 0; k < 2; ++k) \
;     dst[n][k] = *reinterpret_cast<const bf16x8*>((char*)SB(b, h) + lds_byte(wc * 32 + n * 16 + fr, k * 32 + fq * 8))
; template <int K, int LD = K>
; __device__ __forceinline__ void gemm_main(const GAS bf16* A, const GAS bf16* Bt, int brow, int bcol, f32x4 (&acc)[2][2][4][2]) {
;     ...
;   for (int t = 0; t < nt - 2; t += 2) {
;     LDB(B0, 0, 0); SCHED; LDA(At, 0, 0); STAGE(SA(1, 1), pA1, 1);
;     WAIT_L(8); BAR; WAIT_L(0); MMA(0, 0, At, B0); BAR; SCHED;
;     LDB(B1, 0, 1); STAGE(SB(0, 0), pB0, 2);
;     BAR; WAIT_L(0); MMA(0, 1, At, B1); BAR;
;     LDA(At, 0, 1); STAGE(SA(0, 0), pA0, 2);
;     BAR; WAIT_L(0); MMA(1, 0, At, B0); BAR; SCHED;
;     STAGE(SB(0, 1), pB1, 2);
;     WAIT_V(6); BAR; MMA(1, 1, At, B1); BAR;
;     LDB(B0, 1, 0); SCHED; LDA(At, 1, 0); STAGE(SA(0, 1), pA1, 2);
;     WAIT_L(8); BAR; WAIT_L(0); MMA(0, 0, At, B0); BAR; SCHED;
;     LDB(B1, 1, 1); STAGE(SB(1, 0), pB0, 3);
;     BAR; WAIT_L(0); MMA(0, 1, At, B1); BAR;
;     LDA(At, 1, 1); STAGE(SA(1, 0), pA0, 3);
;     BAR; WAIT_L(0); MMA(1, 0, At, B0); BAR; SCHED;
;     STAGE(SB(1, 1), pB1, 3);
;     WAIT_V(6); BAR; MMA(1, 1, At, B1); BAR;
;     pA0 += 4 * BK; pA1 += 4 * BK; pB0 += 4 * BK; pB1 += 4 * BK;
;     asm volatile("" : "+s"(pA0), "+s"(pA1), "+s"(pB0), "+s"(pB1));
;   }
	v_lshl_add_u64 v[242:243], s[28:29], 0, v[130:131]
	v_readfirstlane_b32 s20, v155
	v_lshl_add_u64 v[162:163], v[242:243], 0, s[22:23]
	s_mov_b32 m0, s20
	v_lshl_add_u64 v[244:245], s[28:29], 0, v[132:133]
	v_readfirstlane_b32 s20, v156
	global_load_lds_dwordx4 v[162:163], off
	v_lshl_add_u64 v[162:163], v[244:245], 0, s[22:23]
	s_mov_b32 m0, s20
	s_add_u32 s28, s28, 0x100
	global_load_lds_dwordx4 v[162:163], off
	s_waitcnt vmcnt(10)
	s_addc_u32 s29, s29, 0
	s_barrier
	s_setprio 1
	v_mfma_f32_16x16x32_bf16 v[30:33], v[182:185], v[214:217], v[30:33]
	v_mfma_f32_16x16x32_bf16 v[26:29], v[182:185], v[222:225], v[26:29]
	v_mfma_f32_16x16x32_bf16 v[22:25], v[190:193], v[214:217], v[22:25]
	v_mfma_f32_16x16x32_bf16 v[18:21], v[190:193], v[222:225], v[18:21]
	v_mfma_f32_16x16x32_bf16 v[14:17], v[198:201], v[214:217], v[14:17]
	v_mfma_f32_16x16x32_bf16 v[10:13], v[198:201], v[222:225], v[10:13]
	v_mfma_f32_16x16x32_bf16 v[6:9], v[206:209], v[214:217], v[6:9]
	v_mfma_f32_16x16x32_bf16 v[2:5], v[206:209], v[222:225], v[2:5]
	v_mfma_f32_16x16x32_bf16 v[30:33], v[186:189], v[218:221], v[30:33]
	v_mfma_f32_16x16x32_bf16 v[26:29], v[186:189], v[226:229], v[26:29]
	v_mfma_f32_16x16x32_bf16 v[22:25], v[194:197], v[218:221], v[22:25]
	v_mfma_f32_16x16x32_bf16 v[18:21], v[194:197], v[226:229], v[18:21]
	v_mfma_f32_16x16x32_bf16 v[14:17], v[202:205], v[218:221], v[14:17]
	v_mfma_f32_16x16x32_bf16 v[10:13], v[202:205], v[226:229], v[10:13]
	v_mfma_f32_16x16x32_bf16 v[6:9], v[210:213], v[218:221], v[6:9]
	v_mfma_f32_16x16x32_bf16 v[2:5], v[210:213], v[226:229], v[2:5]
	s_setprio 0
	s_barrier
	ds_read_b128 v[162:165], v140
	ds_read_b128 v[166:169], v140 offset:1024
	ds_read_b128 v[174:177], v140 offset:2048
	ds_read_b128 v[178:181], v140 offset:3072
	v_readfirstlane_b32 s20, v149
	v_lshl_add_u64 v[214:215], v[230:231], 0, s[22:23]
	s_mov_b32 m0, s20
	v_readfirstlane_b32 s20, v150
	ds_read_b128 v[182:185], v138 offset:32768
	ds_read_b128 v[186:189], v138 offset:33792
	ds_read_b128 v[190:193], v137 offset:32768
	ds_read_b128 v[194:197], v137 offset:33792
	ds_read_b128 v[198:201], v136 offset:32768
	ds_read_b128 v[202:205], v136 offset:33792
	ds_read_b128 v[206:209], v135 offset:32768
	ds_read_b128 v[210:213], v135 offset:33792
	global_load_lds_dwordx4 v[214:215], off
	v_lshl_add_u64 v[214:215], v[232:233], 0, s[22:23]
	s_mov_b32 m0, s20
	s_add_u32 s26, s26, 0x100
	global_load_lds_dwordx4 v[214:215], off
	s_waitcnt lgkmcnt(8)
	s_waitcnt vmcnt(10)
	s_barrier
	s_waitcnt lgkmcnt(0)
	s_addc_u32 s27, s27, 0
	s_setprio 1
	s_waitcnt lgkmcnt(0)
	v_mfma_f32_16x16x32_bf16 v[126:129], v[182:185], v[162:165], v[126:129]
	v_mfma_f32_16x16x32_bf16 v[122:125], v[182:185], v[174:177], v[122:125]
	v_mfma_f32_16x16x32_bf16 v[118:121], v[190:193], v[162:165], v[118:121]
	v_mfma_f32_16x16x32_bf16 v[114:117], v[190:193], v[174:177], v[114:117]
	v_mfma_f32_16x16x32_bf16 v[110:113], v[198:201], v[162:165], v[110:113]
	v_mfma_f32_16x16x32_bf16 v[106:109], v[198:201], v[174:177], v[106:109]
	v_mfma_f32_16x16x32_bf16 v[102:105], v[206:209], v[162:165], v[102:105]
	v_mfma_f32_16x16x32_bf16 v[98:101], v[206:209], v[174:177], v[98:101]
	v_mfma_f32_16x16x32_bf16 v[126:129], v[186:189], v[166:169], v[126:129]
	v_mfma_f32_16x16x32_bf16 v[122:125], v[186:189], v[178:181], v[122:125]
	v_mfma_f32_16x16x32_bf16 v[118:121], v[194:197], v[166:169], v[118:121]
	v_mfma_f32_16x16x32_bf16 v[114:117], v[194:197], v[178:181], v[114:117]
	v_mfma_f32_16x16x32_bf16 v[110:113], v[202:205], v[166:169], v[110:113]
	v_mfma_f32_16x16x32_bf16 v[106:109], v[202:205], v[178:181], v[106:109]
	v_mfma_f32_16x16x32_bf16 v[102:105], v[210:213], v[166:169], v[102:105]
	v_mfma_f32_16x16x32_bf16 v[98:101], v[210:213], v[178:181], v[98:101]
	s_setprio 0
	s_barrier
	v_readfirstlane_b32 s20, v157
	v_lshl_add_u64 v[230:231], v[234:235], 0, s[24:25]
	s_mov_b32 m0, s20
	v_readfirstlane_b32 s20, v158
	ds_read_b128 v[214:217], v139
	ds_read_b128 v[218:221], v139 offset:1024
	ds_read_b128 v[222:225], v139 offset:2048
	ds_read_b128 v[226:229], v139 offset:3072
	global_load_lds_dwordx4 v[230:231], off
	v_lshl_add_u64 v[230:231], v[236:237], 0, s[24:25]
	s_mov_b32 m0, s20
	s_nop 0
	global_load_lds_dwordx4 v[230:231], off
	s_waitcnt vmcnt(10)
	s_barrier
	s_waitcnt lgkmcnt(0)
	s_setprio 1
	s_waitcnt lgkmcnt(0)
	v_mfma_f32_16x16x32_bf16 v[94:97], v[182:185], v[214:217], v[94:97]
	v_mfma_f32_16x16x32_bf16 v[90:93], v[182:185], v[222:225], v[90:93]
	v_mfma_f32_16x16x32_bf16 v[86:89], v[190:193], v[214:217], v[86:89]
	v_mfma_f32_16x16x32_bf16 v[82:85], v[190:193], v[222:225], v[82:85]
	v_mfma_f32_16x16x32_bf16 v[78:81], v[198:201], v[214:217], v[78:81]
	v_mfma_f32_16x16x32_bf16 v[74:77], v[198:201], v[222:225], v[74:77]
	v_mfma_f32_16x16x32_bf16 v[70:73], v[206:209], v[214:217], v[70:73]
	v_mfma_f32_16x16x32_bf16 v[66:69], v[206:209], v[222:225], v[66:69]
	v_mfma_f32_16x16x32_bf16 v[94:97], v[186:189], v[218:221], v[94:97]
	v_mfma_f32_16x16x32_bf16 v[90:93], v[186:189], v[226:229], v[90:93]
	v_mfma_f32_16x16x32_bf16 v[86:89], v[194:197], v[218:221], v[86:89]
	v_mfma_f32_16x16x32_bf16 v[82:85], v[194:197], v[226:229], v[82:85]
	v_mfma_f32_16x16x32_bf16 v[78:81], v[202:205], v[218:221], v[78:81]
	v_mfma_f32_16x16x32_bf16 v[74:77], v[202:205], v[226:229], v[74:77]
	v_mfma_f32_16x16x32_bf16 v[70:73], v[210:213], v[218:221], v[70:73]
	v_mfma_f32_16x16x32_bf16 v[66:69], v[210:213], v[226:229], v[66:69]
	s_setprio 0
	v_readfirstlane_b32 s20, v151
	v_lshl_add_u64 v[230:231], v[238:239], 0, s[24:25]
	s_mov_b32 m0, s20
	v_readfirstlane_b32 s20, v152
	s_barrier
; #define STAGE(P, GP, ktrel) do { const GAS char* _g = (GP) + (ktrel) * (BK * 2); \
;     __builtin_amdgcn_global_load_lds((const GAS unsigned*)(_g + so0), (unsigned*)((char*)(P) + tid_ * 16), 16, 0, 0); \
;     __builtin_amdgcn_global_load_lds((const GAS unsigned*)(_g + so1), (unsigned*)((char*)(P) + tid_ * 16 + 8192), 16, 0, 0); } while (0)
; #define WAIT_V(n) asm volatile("s_waitcnt vmcnt(" #n ")" ::: "memory")
; #define WAIT_L(n) asm volatile("s_waitcnt lgkmcnt(" #n ")" ::: "memory")
; #define BAR __builtin_amdgcn_s_barrier()
; #define SCHED __builtin_amdgcn_sched_barrier(0)
; #define LDA(dst, b, h) for (int m = 0; m < 4; ++m) for (int k = 0; k < 2; ++k) \
;     dst[m][k] = *reinterpret_cast<const bf16x8*>((char*)SA(b, h) + lds_byte(wr * 64 + m * 16 + fr, k * 32 + fq * 8))
; #define LDB(dst, b, h) for (int n = 0; n < 2; ++n) for (int k = 0; k < 2; ++k) \
;     dst[n][k] = *reinterpret_cast<const bf16x8*>((char*)SB(b, h) + lds_byte(wc * 32 + n * 16 + fr, k * 32 + fq * 8))
; template <int K, int LD = K>
; __device__ __forceinline__ void gemm_main(const GAS bf16* A, const GAS bf16* Bt, int brow, int bcol, f32x4 (&acc)[2][2][4][2]) {
;     ...
;   for (int t = 0; t < nt - 2; t += 2) {
;     LDB(B0, 0, 0); SCHED; LDA(At, 0, 0); STAGE(SA(1, 1), pA1, 1);
;     WAIT_L(8); BAR; WAIT_L(0); MMA(0, 0, At, B0); BAR; SCHED;
;     LDB(B1, 0, 1); STAGE(SB(0, 0), pB0, 2);
;     BAR; WAIT_L(0); MMA(0, 1, At, B1); BAR;
;     LDA(At, 0, 1); STAGE(SA(0, 0), pA0, 2);
;     BAR; WAIT_L(0); MMA(1, 0, At, B0); BAR; SCHED;
;     STAGE(SB(0, 1), pB1, 2);
;     WAIT_V(6); BAR; MMA(1, 1, At, B1); BAR;
;     LDB(B0, 1, 0); SCHED; LDA(At, 1, 0); STAGE(SA(0, 1), pA1, 2);
;     WAIT_L(8); BAR; WAIT_L(0); MMA(0, 0, At, B0); BAR; SCHED;
;     LDB(B1, 1, 1); STAGE(SB(1, 0), pB0, 3);
;     BAR; WAIT_L(0); MMA(0, 1, At, B1); BAR;
;     LDA(At, 1, 1); STAGE(SA(1, 0), pA0, 3);
;     BAR; WAIT_L(0); MMA(1, 0, At, B0); BAR; SCHED;
;     STAGE(SB(1, 1), pB1, 3);
;     WAIT_V(6); BAR; MMA(1, 1, At, B1); BAR;
;     pA0 += 4 * BK; pA1 += 4 * BK; pB0 += 4 * BK; pB1 += 4 * BK;
;     asm volatile("" : "+s"(pA0), "+s"(pA1), "+s"(pB0), "+s"(pB1));
;   }
;   { LDB(B0, 0, 0); LDA(At, 0, 0); STAGE(SA(1, 1), pA1, 1);
;     BAR; WAIT_L(0); MMA(0, 0, At, B0); BAR;
;     LDB(B1, 0, 1); BAR; WAIT_L(0); MMA(0, 1, At, B1); BAR;
;     LDA(At, 0, 1); WAIT_V(4); BAR; WAIT_L(0); MMA(1, 0, At, B0); MMA(1, 1, At, B1); BAR; }
	ds_read_b128 v[182:185], v138 offset:49152
	ds_read_b128 v[186:189], v138 offset:50176
	ds_read_b128 v[190:193], v137 offset:49152
	ds_read_b128 v[194:197], v137 offset:50176
	ds_read_b128 v[198:201], v136 offset:49152
	ds_read_b128 v[202:205], v136 offset:50176
	ds_read_b128 v[206:209], v135 offset:49152
	ds_read_b128 v[210:213], v135 offset:50176
	global_load_lds_dwordx4 v[230:231], off
	v_lshl_add_u64 v[230:231], v[240:241], 0, s[24:25]
	s_mov_b32 m0, s20
	s_nop 0
	global_load_lds_dwordx4 v[230:231], off
	s_barrier
	s_waitcnt lgkmcnt(0)
	s_setprio 1
	s_waitcnt lgkmcnt(0)
	v_mfma_f32_16x16x32_bf16 v[62:65], v[182:185], v[162:165], v[62:65]
	v_mfma_f32_16x16x32_bf16 v[58:61], v[182:185], v[174:177], v[58:61]
	v_mfma_f32_16x16x32_bf16 v[54:57], v[190:193], v[162:165], v[54:57]
	v_mfma_f32_16x16x32_bf16 v[50:53], v[190:193], v[174:177], v[50:53]
	v_mfma_f32_16x16x32_bf16 v[46:49], v[198:201], v[162:165], v[46:49]
	v_mfma_f32_16x16x32_bf16 v[42:45], v[198:201], v[174:177], v[42:45]
	v_mfma_f32_16x16x32_bf16 v[38:41], v[206:209], v[162:165], v[38:41]
	v_mfma_f32_16x16x32_bf16 v[34:37], v[206:209], v[174:177], v[34:37]
	v_mfma_f32_16x16x32_bf16 v[62:65], v[186:189], v[166:169], v[62:65]
	v_mfma_f32_16x16x32_bf16 v[58:61], v[186:189], v[178:181], v[58:61]
	v_mfma_f32_16x16x32_bf16 v[54:57], v[194:197], v[166:169], v[54:57]
	v_mfma_f32_16x16x32_bf16 v[50:53], v[194:197], v[178:181], v[50:53]
	v_mfma_f32_16x16x32_bf16 v[46:49], v[202:205], v[166:169], v[46:49]
	v_mfma_f32_16x16x32_bf16 v[42:45], v[202:205], v[178:181], v[42:45]
	v_mfma_f32_16x16x32_bf16 v[38:41], v[210:213], v[166:169], v[38:41]
	v_mfma_f32_16x16x32_bf16 v[34:37], v[210:213], v[178:181], v[34:37]
	s_setprio 0
	s_barrier
	v_readfirstlane_b32 s20, v159
	v_lshl_add_u64 v[162:163], v[242:243], 0, s[24:25]
	s_mov_b32 m0, s20
	v_readfirstlane_b32 s20, v160
	global_load_lds_dwordx4 v[162:163], off
	v_lshl_add_u64 v[162:163], v[244:245], 0, s[24:25]
	s_mov_b32 m0, s20
	s_nop 0
	global_load_lds_dwordx4 v[162:163], off
	s_waitcnt vmcnt(10)
	s_barrier
	s_setprio 1
	v_mfma_f32_16x16x32_bf16 v[30:33], v[182:185], v[214:217], v[30:33]
	v_mfma_f32_16x16x32_bf16 v[26:29], v[182:185], v[222:225], v[26:29]
	v_mfma_f32_16x16x32_bf16 v[22:25], v[190:193], v[214:217], v[22:25]
	v_mfma_f32_16x16x32_bf16 v[18:21], v[190:193], v[222:225], v[18:21]
	v_mfma_f32_16x16x32_bf16 v[14:17], v[198:201], v[214:217], v[14:17]
	v_mfma_f32_16x16x32_bf16 v[10:13], v[198:201], v[222:225], v[10:13]
	v_mfma_f32_16x16x32_bf16 v[6:9], v[206:209], v[214:217], v[6:9]
	v_mfma_f32_16x16x32_bf16 v[2:5], v[206:209], v[222:225], v[2:5]
	v_mfma_f32_16x16x32_bf16 v[30:33], v[186:189], v[218:221], v[30:33]
	v_mfma_f32_16x16x32_bf16 v[26:29], v[186:189], v[226:229], v[26:29]
	v_mfma_f32_16x16x32_bf16 v[22:25], v[194:197], v[218:221], v[22:25]
	v_mfma_f32_16x16x32_bf16 v[18:21], v[194:197], v[226:229], v[18:21]
	v_mfma_f32_16x16x32_bf16 v[14:17], v[202:205], v[218:221], v[14:17]
	v_mfma_f32_16x16x32_bf16 v[10:13], v[202:205], v[226:229], v[10:13]
	v_mfma_f32_16x16x32_bf16 v[6:9], v[210:213], v[218:221], v[6:9]
	v_mfma_f32_16x16x32_bf16 v[2:5], v[210:213], v[226:229], v[2:5]
	s_setprio 0
	s_add_i32 s5, s5, 2
	s_cmp_lt_u32 s5, 12
	s_barrier
	s_cbranch_scc1 .LBB0_346
	ds_read_b128 v[148:151], v146
	ds_read_b128 v[152:155], v146 offset:1024
	ds_read_b128 v[156:159], v146 offset:2048
	ds_read_b128 v[160:163], v146 offset:3072
	ds_read_b128 v[164:167], v138
	ds_read_b128 v[174:177], v138 offset:1024
	ds_read_b128 v[178:181], v137
	ds_read_b128 v[182:185], v137 offset:1024
	ds_read_b128 v[186:189], v136
	ds_read_b128 v[190:193], v136 offset:1024
	ds_read_b128 v[194:197], v135
	ds_read_b128 v[198:201], v135 offset:1024
	v_lshl_add_u64 v[146:147], s[26:27], 0, v[130:131]
	v_readfirstlane_b32 s5, v143
	v_lshl_add_u64 v[146:147], v[146:147], 0, s[14:15]
	s_mov_b32 m0, s5
	v_lshl_add_u64 v[132:133], s[26:27], 0, v[132:133]
	v_readfirstlane_b32 s5, v142
	global_load_lds_dwordx4 v[146:147], off
	v_lshl_add_u64 v[132:133], v[132:133], 0, s[14:15]
	s_mov_b32 m0, s5
	s_nop 0
	global_load_lds_dwordx4 v[132:133], off
	s_waitcnt vmcnt(10)
	s_barrier
	s_waitcnt lgkmcnt(0)
	s_setprio 1
	s_waitcnt lgkmcnt(0)
	v_mfma_f32_16x16x32_bf16 v[126:129], v[164:167], v[148:151], v[126:129]
	v_mfma_f32_16x16x32_bf16 v[122:125], v[164:167], v[156:159], v[122:125]
	v_mfma_f32_16x16x32_bf16 v[110:113], v[186:189], v[148:151], v[110:113]
	v_mfma_f32_16x16x32_bf16 v[106:109], v[186:189], v[156:159], v[106:109]
	v_mfma_f32_16x16x32_bf16 v[126:129], v[174:177], v[152:155], v[126:129]
	v_mfma_f32_16x16x32_bf16 v[122:125], v[174:177], v[160:163], v[122:125]
	v_mfma_f32_16x16x32_bf16 v[118:121], v[178:181], v[148:151], v[118:121]
	v_mfma_f32_16x16x32_bf16 v[114:117], v[178:181], v[156:159], v[114:117]
	v_mfma_f32_16x16x32_bf16 v[110:113], v[190:193], v[152:155], v[110:113]
	v_mfma_f32_16x16x32_bf16 v[106:109], v[190:193], v[160:163], v[106:109]
	v_mfma_f32_16x16x32_bf16 v[102:105], v[194:197], v[148:151], v[102:105]
	v_mfma_f32_16x16x32_bf16 v[98:101], v[194:197], v[156:159], v[98:101]
	v_mfma_f32_16x16x32_bf16 v[202:205], v[182:185], v[152:155], v[118:121]
	v_mfma_f32_16x16x32_bf16 v[206:209], v[182:185], v[160:163], v[114:117]
	v_mfma_f32_16x16x32_bf16 v[210:213], v[198:201], v[152:155], v[102:105]
	v_mfma_f32_16x16x32_bf16 v[214:217], v[198:201], v[160:163], v[98:101]
	s_setprio 0
	s_barrier
	s_nop 1
	ds_read_b128 v[98:101], v141
	ds_read_b128 v[102:105], v141 offset:1024
	ds_read_b128 v[114:117], v141 offset:2048
	ds_read_b128 v[118:121], v141 offset:3072
	s_waitcnt vmcnt(8)
	s_barrier
; #define STAGE(P, GP, ktrel) do { const GAS char* _g = (GP) + (ktrel) * (BK * 2); \
;     __builtin_amdgcn_global_load_lds((const GAS unsigned*)(_g + so0), (unsigned*)((char*)(P) + tid_ * 16), 16, 0, 0); \
;     __builtin_amdgcn_global_load_lds((const GAS unsigned*)(_g + so1), (unsigned*)((char*)(P) + tid_ * 16 + 8192), 16, 0, 0); } while (0)
; #define WAIT_V(n) asm volatile("s_waitcnt vmcnt(" #n ")" ::: "memory")
; #define WAIT_L(n) asm volatile("s_waitcnt lgkmcnt(" #n ")" ::: "memory")
; #define BAR __builtin_amdgcn_s_barrier()
; #define LDA(dst, b, h) for (int m = 0; m < 4; ++m) for (int k = 0; k < 2; ++k) \
;     dst[m][k] = *reinterpret_cast<const bf16x8*>((char*)SA(b, h) + lds_byte(wr * 64 + m * 16 + fr, k * 32 + fq * 8))
; #define LDB(dst, b, h) for (int n = 0; n < 2; ++n) for (int k = 0; k < 2; ++k) \
;     dst[n][k] = *reinterpret_cast<const bf16x8*>((char*)SB(b, h) + lds_byte(wc * 32 + n * 16 + fr, k * 32 + fq * 8))
; #define MMA(ai, bj, At_, Bt_) do { __builtin_amdgcn_s_setprio(1); \
;     for (int m = 0; m < 4; ++m) for (int n = 0; n < 2; ++n) for (int k = 0; k < 2; ++k) \
;       acc[ai][bj][m][n] = __builtin_amdgcn_mfma_f32_16x16x32_bf16(At_[m][k], Bt_[n][k], acc[ai][bj][m][n], 0, 0, 0); \
;     __builtin_amdgcn_s_setprio(0); } while (0)
; template <int K, int LD = K>
; __device__ __forceinline__ void gemm_main(const GAS bf16* A, const GAS bf16* Bt, int brow, int bcol, f32x4 (&acc)[2][2][4][2]) {
;     ...
;   { LDB(B0, 0, 0); LDA(At, 0, 0); STAGE(SA(1, 1), pA1, 1);
;     BAR; WAIT_L(0); MMA(0, 0, At, B0); BAR;
;     LDB(B1, 0, 1); BAR; WAIT_L(0); MMA(0, 1, At, B1); BAR;
;     LDA(At, 0, 1); WAIT_V(4); BAR; WAIT_L(0); MMA(1, 0, At, B0); MMA(1, 1, At, B1); BAR; }
;   { LDB(B0, 1, 0); LDA(At, 1, 0); WAIT_V(2); BAR; WAIT_L(0); MMA(0, 0, At, B0); BAR;
;     LDB(B1, 1, 1); WAIT_V(0); BAR; WAIT_L(0); MMA(0, 1, At, B1); BAR;
;     LDA(At, 1, 1); BAR; WAIT_L(0); MMA(1, 0, At, B0); MMA(1, 1, At, B1); BAR; }
	s_waitcnt lgkmcnt(0)
	s_setprio 1
	s_waitcnt lgkmcnt(0)
	v_mfma_f32_16x16x32_bf16 v[94:97], v[164:167], v[98:101], v[94:97]
	v_mfma_f32_16x16x32_bf16 v[90:93], v[164:167], v[114:117], v[90:93]
	v_mfma_f32_16x16x32_bf16 v[78:81], v[186:189], v[98:101], v[78:81]
	v_mfma_f32_16x16x32_bf16 v[74:77], v[186:189], v[114:117], v[74:77]
	v_mfma_f32_16x16x32_bf16 v[94:97], v[174:177], v[102:105], v[94:97]
	v_mfma_f32_16x16x32_bf16 v[90:93], v[174:177], v[118:121], v[90:93]
	v_mfma_f32_16x16x32_bf16 v[86:89], v[178:181], v[98:101], v[86:89]
	v_mfma_f32_16x16x32_bf16 v[82:85], v[178:181], v[114:117], v[82:85]
	v_mfma_f32_16x16x32_bf16 v[78:81], v[190:193], v[102:105], v[78:81]
	v_mfma_f32_16x16x32_bf16 v[74:77], v[190:193], v[118:121], v[74:77]
	v_mfma_f32_16x16x32_bf16 v[70:73], v[194:197], v[98:101], v[70:73]
	v_mfma_f32_16x16x32_bf16 v[66:69], v[194:197], v[114:117], v[66:69]
	v_mfma_f32_16x16x32_bf16 v[164:167], v[182:185], v[102:105], v[86:89]
	v_mfma_f32_16x16x32_bf16 v[174:177], v[182:185], v[118:121], v[82:85]
	v_mfma_f32_16x16x32_bf16 v[178:181], v[198:201], v[102:105], v[70:73]
	v_mfma_f32_16x16x32_bf16 v[182:185], v[198:201], v[118:121], v[66:69]
	s_setprio 0
	s_barrier
	s_nop 1
	ds_read_b128 v[66:69], v138 offset:16384
	ds_read_b128 v[70:73], v138 offset:17408
	ds_read_b128 v[82:85], v137 offset:16384
	ds_read_b128 v[86:89], v137 offset:17408
	ds_read_b128 v[186:189], v136 offset:16384
	ds_read_b128 v[190:193], v136 offset:17408
	ds_read_b128 v[194:197], v135 offset:16384
	ds_read_b128 v[198:201], v135 offset:17408
	s_waitcnt vmcnt(4)
	s_barrier
	s_waitcnt lgkmcnt(0)
	s_setprio 1
	s_waitcnt lgkmcnt(0)
	v_mfma_f32_16x16x32_bf16 v[62:65], v[66:69], v[148:151], v[62:65]
	v_mfma_f32_16x16x32_bf16 v[58:61], v[66:69], v[156:159], v[58:61]
	v_mfma_f32_16x16x32_bf16 v[46:49], v[186:189], v[148:151], v[46:49]
	v_mfma_f32_16x16x32_bf16 v[42:45], v[186:189], v[156:159], v[42:45]
	v_mfma_f32_16x16x32_bf16 v[62:65], v[70:73], v[152:155], v[62:65]
	v_mfma_f32_16x16x32_bf16 v[58:61], v[70:73], v[160:163], v[58:61]
	v_mfma_f32_16x16x32_bf16 v[54:57], v[82:85], v[148:151], v[54:57]
	v_mfma_f32_16x16x32_bf16 v[50:53], v[82:85], v[156:159], v[50:53]
	v_mfma_f32_16x16x32_bf16 v[46:49], v[190:193], v[152:155], v[46:49]
	v_mfma_f32_16x16x32_bf16 v[42:45], v[190:193], v[160:163], v[42:45]
	v_mfma_f32_16x16x32_bf16 v[38:41], v[194:197], v[148:151], v[38:41]
	v_mfma_f32_16x16x32_bf16 v[34:37], v[194:197], v[156:159], v[34:37]
	v_mfma_f32_16x16x32_bf16 v[218:221], v[86:89], v[152:155], v[54:57]
	v_mfma_f32_16x16x32_bf16 v[222:225], v[86:89], v[160:163], v[50:53]
	v_mfma_f32_16x16x32_bf16 v[146:149], v[198:201], v[152:155], v[38:41]
	v_mfma_f32_16x16x32_bf16 v[150:153], v[198:201], v[160:163], v[34:37]
	s_setprio 0
	s_setprio 1
	v_mfma_f32_16x16x32_bf16 v[30:33], v[66:69], v[98:101], v[30:33]
	v_mfma_f32_16x16x32_bf16 v[26:29], v[66:69], v[114:117], v[26:29]
	v_mfma_f32_16x16x32_bf16 v[14:17], v[186:189], v[98:101], v[14:17]
	v_mfma_f32_16x16x32_bf16 v[10:13], v[186:189], v[114:117], v[10:13]
	v_mfma_f32_16x16x32_bf16 v[30:33], v[70:73], v[102:105], v[30:33]
	v_mfma_f32_16x16x32_bf16 v[26:29], v[70:73], v[118:121], v[26:29]
	v_mfma_f32_16x16x32_bf16 v[22:25], v[82:85], v[98:101], v[22:25]
	v_mfma_f32_16x16x32_bf16 v[18:21], v[82:85], v[114:117], v[18:21]
	v_mfma_f32_16x16x32_bf16 v[14:17], v[190:193], v[102:105], v[14:17]
	v_mfma_f32_16x16x32_bf16 v[10:13], v[190:193], v[118:121], v[10:13]
	v_mfma_f32_16x16x32_bf16 v[6:9], v[194:197], v[98:101], v[6:9]
	v_mfma_f32_16x16x32_bf16 v[2:5], v[194:197], v[114:117], v[2:5]
	v_mfma_f32_16x16x32_bf16 v[154:157], v[86:89], v[102:105], v[22:25]
	v_mfma_f32_16x16x32_bf16 v[158:161], v[86:89], v[118:121], v[18:21]
	v_mfma_f32_16x16x32_bf16 v[186:189], v[198:201], v[102:105], v[6:9]
	v_mfma_f32_16x16x32_bf16 v[190:193], v[198:201], v[118:121], v[2:5]
	s_setprio 0
	s_barrier
	s_nop 1
	ds_read_b128 v[2:5], v140
	ds_read_b128 v[6:9], v140 offset:1024
	ds_read_b128 v[194:197], v140 offset:2048
	ds_read_b128 v[140:143], v140 offset:3072
	ds_read_b128 v[18:21], v138 offset:32768
	ds_read_b128 v[22:25], v138 offset:33792
	ds_read_b128 v[34:37], v137 offset:32768
	ds_read_b128 v[38:41], v137 offset:33792
	ds_read_b128 v[50:53], v136 offset:32768
	ds_read_b128 v[54:57], v136 offset:33792
	ds_read_b128 v[198:201], v135 offset:32768
	ds_read_b128 v[226:229], v135 offset:33792
	s_waitcnt vmcnt(2)
	s_barrier
; #define STAGE(P, GP, ktrel) do { const GAS char* _g = (GP) + (ktrel) * (BK * 2); \
;     __builtin_amdgcn_global_load_lds((const GAS unsigned*)(_g + so0), (unsigned*)((char*)(P) + tid_ * 16), 16, 0, 0); \
;     __builtin_amdgcn_global_load_lds((const GAS unsigned*)(_g + so1), (unsigned*)((char*)(P) + tid_ * 16 + 8192), 16, 0, 0); } while (0)
; #define WAIT_V(n) asm volatile("s_waitcnt vmcnt(" #n ")" ::: "memory")
; #define WAIT_L(n) asm volatile("s_waitcnt lgkmcnt(" #n ")" ::: "memory")
; #define BAR __builtin_amdgcn_s_barrier()
; #define LDA(dst, b, h) for (int m = 0; m < 4; ++m) for (int k = 0; k < 2; ++k) \
;     dst[m][k] = *reinterpret_cast<const bf16x8*>((char*)SA(b, h) + lds_byte(wr * 64 + m * 16 + fr, k * 32 + fq * 8))
; #define LDB(dst, b, h) for (int n = 0; n < 2; ++n) for (int k = 0; k < 2; ++k) \
;     dst[n][k] = *reinterpret_cast<const bf16x8*>((char*)SB(b, h) + lds_byte(wc * 32 + n * 16 + fr, k * 32 + fq * 8))
; #define MMA(ai, bj, At_, Bt_) do { __builtin_amdgcn_s_setprio(1); \
;     for (int m = 0; m < 4; ++m) for (int n = 0; n < 2; ++n) for (int k = 0; k < 2; ++k) \
;       acc[ai][bj][m][n] = __builtin_amdgcn_mfma_f32_16x16x32_bf16(At_[m][k], Bt_[n][k], acc[ai][bj][m][n], 0, 0, 0); \
;     __builtin_amdgcn_s_setprio(0); } while (0)
; template <int K, int LD = K>
; __device__ __forceinline__ void gemm_main(const GAS bf16* A, const GAS bf16* Bt, int brow, int bcol, f32x4 (&acc)[2][2][4][2]) {
;     ...
;   { LDB(B0, 0, 0); LDA(At, 0, 0); STAGE(SA(1, 1), pA1, 1);
;     BAR; WAIT_L(0); MMA(0, 0, At, B0); BAR;
;     LDB(B1, 0, 1); BAR; WAIT_L(0); MMA(0, 1, At, B1); BAR;
;     LDA(At, 0, 1); WAIT_V(4); BAR; WAIT_L(0); MMA(1, 0, At, B0); MMA(1, 1, At, B1); BAR; }
;   { LDB(B0, 1, 0); LDA(At, 1, 0); WAIT_V(2); BAR; WAIT_L(0); MMA(0, 0, At, B0); BAR;
;     LDB(B1, 1, 1); WAIT_V(0); BAR; WAIT_L(0); MMA(0, 1, At, B1); BAR;
;     LDA(At, 1, 1); BAR; WAIT_L(0); MMA(1, 0, At, B0); MMA(1, 1, At, B1); BAR; }
;   if (wr == 0) BAR;
	s_waitcnt lgkmcnt(0)
	s_setprio 1
	s_waitcnt lgkmcnt(0)
	v_mfma_f32_16x16x32_bf16 v[66:69], v[18:21], v[2:5], v[126:129]
	v_mfma_f32_16x16x32_bf16 v[114:117], v[22:25], v[6:9], v[66:69]
	v_mfma_f32_16x16x32_bf16 v[66:69], v[18:21], v[194:197], v[122:125]
	v_mfma_f32_16x16x32_bf16 v[118:121], v[22:25], v[140:143], v[66:69]
	v_mfma_f32_16x16x32_bf16 v[66:69], v[34:37], v[2:5], v[202:205]
	v_mfma_f32_16x16x32_bf16 v[102:105], v[38:41], v[6:9], v[66:69]
	v_mfma_f32_16x16x32_bf16 v[66:69], v[34:37], v[194:197], v[206:209]
	v_mfma_f32_16x16x32_bf16 v[98:101], v[38:41], v[140:143], v[66:69]
	v_mfma_f32_16x16x32_bf16 v[66:69], v[50:53], v[2:5], v[110:113]
	v_mfma_f32_16x16x32_bf16 v[82:85], v[54:57], v[6:9], v[66:69]
	v_mfma_f32_16x16x32_bf16 v[66:69], v[50:53], v[194:197], v[106:109]
	v_mfma_f32_16x16x32_bf16 v[86:89], v[54:57], v[140:143], v[66:69]
	v_mfma_f32_16x16x32_bf16 v[66:69], v[198:201], v[2:5], v[210:213]
	v_mfma_f32_16x16x32_bf16 v[70:73], v[226:229], v[6:9], v[66:69]
	v_mfma_f32_16x16x32_bf16 v[66:69], v[198:201], v[194:197], v[214:217]
	v_mfma_f32_16x16x32_bf16 v[66:69], v[226:229], v[140:143], v[66:69]
	s_setprio 0
	s_barrier
	ds_read_b128 v[202:205], v139
	ds_read_b128 v[206:209], v139 offset:1024
	ds_read_b128 v[210:213], v139 offset:2048
	ds_read_b128 v[214:217], v139 offset:3072
	s_waitcnt vmcnt(0)
	s_barrier
	s_waitcnt lgkmcnt(0)
	s_setprio 1
	s_waitcnt lgkmcnt(0)
	v_mfma_f32_16x16x32_bf16 v[94:97], v[18:21], v[202:205], v[94:97]
	v_mfma_f32_16x16x32_bf16 v[18:21], v[18:21], v[210:213], v[90:93]
	v_mfma_f32_16x16x32_bf16 v[126:129], v[22:25], v[214:217], v[18:21]
	v_mfma_f32_16x16x32_bf16 v[18:21], v[34:37], v[202:205], v[164:167]
	v_mfma_f32_16x16x32_bf16 v[106:109], v[38:41], v[206:209], v[18:21]
	v_mfma_f32_16x16x32_bf16 v[18:21], v[34:37], v[210:213], v[174:177]
	v_mfma_f32_16x16x32_bf16 v[110:113], v[38:41], v[214:217], v[18:21]
	v_mfma_f32_16x16x32_bf16 v[18:21], v[50:53], v[202:205], v[78:81]
	v_mfma_f32_16x16x32_bf16 v[90:93], v[54:57], v[206:209], v[18:21]
	v_mfma_f32_16x16x32_bf16 v[18:21], v[50:53], v[210:213], v[74:77]
	v_mfma_f32_16x16x32_bf16 v[122:125], v[22:25], v[206:209], v[94:97]
	v_mfma_f32_16x16x32_bf16 v[94:97], v[54:57], v[214:217], v[18:21]
	v_mfma_f32_16x16x32_bf16 v[18:21], v[198:201], v[202:205], v[178:181]
	v_mfma_f32_16x16x32_bf16 v[74:77], v[226:229], v[206:209], v[18:21]
	v_mfma_f32_16x16x32_bf16 v[18:21], v[198:201], v[210:213], v[182:185]
	v_mfma_f32_16x16x32_bf16 v[78:81], v[226:229], v[214:217], v[18:21]
	s_setprio 0
	s_barrier
	ds_read_b128 v[162:165], v138 offset:49152
	ds_read_b128 v[166:169], v138 offset:50176
	ds_read_b128 v[174:177], v137 offset:49152
	ds_read_b128 v[178:181], v137 offset:50176
	ds_read_b128 v[182:185], v136 offset:49152
	ds_read_b128 v[136:139], v136 offset:50176
	ds_read_b128 v[198:201], v135 offset:49152
	ds_read_b128 v[226:229], v135 offset:50176
	s_barrier
	s_waitcnt lgkmcnt(0)
	s_setprio 1
	s_waitcnt lgkmcnt(0)
	v_mfma_f32_16x16x32_bf16 v[18:21], v[162:165], v[2:5], v[62:65]
	v_mfma_f32_16x16x32_bf16 v[50:53], v[166:169], v[6:9], v[18:21]
	v_mfma_f32_16x16x32_bf16 v[18:21], v[162:165], v[194:197], v[58:61]
	v_mfma_f32_16x16x32_bf16 v[54:57], v[166:169], v[140:143], v[18:21]
	v_mfma_f32_16x16x32_bf16 v[18:21], v[174:177], v[2:5], v[218:221]
	v_mfma_f32_16x16x32_bf16 v[38:41], v[178:181], v[6:9], v[18:21]
	v_mfma_f32_16x16x32_bf16 v[18:21], v[174:177], v[194:197], v[222:225]
	v_mfma_f32_16x16x32_bf16 v[34:37], v[178:181], v[140:143], v[18:21]
	v_mfma_f32_16x16x32_bf16 v[18:21], v[182:185], v[2:5], v[46:49]
	v_mfma_f32_16x16x32_bf16 v[2:5], v[198:201], v[2:5], v[146:149]
	v_mfma_f32_16x16x32_bf16 v[18:21], v[136:139], v[6:9], v[18:21]
	v_mfma_f32_16x16x32_bf16 v[22:25], v[182:185], v[194:197], v[42:45]
	v_mfma_f32_16x16x32_bf16 v[6:9], v[226:229], v[6:9], v[2:5]
	v_mfma_f32_16x16x32_bf16 v[2:5], v[198:201], v[194:197], v[150:153]
	v_mfma_f32_16x16x32_bf16 v[22:25], v[136:139], v[140:143], v[22:25]
	v_mfma_f32_16x16x32_bf16 v[2:5], v[226:229], v[140:143], v[2:5]
	s_setprio 0
	s_setprio 1
	v_mfma_f32_16x16x32_bf16 v[26:29], v[162:165], v[210:213], v[26:29]
	v_mfma_f32_16x16x32_bf16 v[62:65], v[166:169], v[214:217], v[26:29]
	v_mfma_f32_16x16x32_bf16 v[26:29], v[174:177], v[202:205], v[154:157]
	v_mfma_f32_16x16x32_bf16 v[30:33], v[162:165], v[202:205], v[30:33]
	v_mfma_f32_16x16x32_bf16 v[42:45], v[178:181], v[206:209], v[26:29]
	v_mfma_f32_16x16x32_bf16 v[26:29], v[174:177], v[210:213], v[158:161]
	v_mfma_f32_16x16x32_bf16 v[14:17], v[182:185], v[202:205], v[14:17]
	v_mfma_f32_16x16x32_bf16 v[10:13], v[182:185], v[210:213], v[10:13]
	v_mfma_f32_16x16x32_bf16 v[58:61], v[166:169], v[206:209], v[30:33]
	v_mfma_f32_16x16x32_bf16 v[46:49], v[178:181], v[214:217], v[26:29]
	v_mfma_f32_16x16x32_bf16 v[26:29], v[136:139], v[206:209], v[14:17]
	v_mfma_f32_16x16x32_bf16 v[30:33], v[136:139], v[214:217], v[10:13]
	v_mfma_f32_16x16x32_bf16 v[10:13], v[198:201], v[202:205], v[186:189]
	v_mfma_f32_16x16x32_bf16 v[14:17], v[198:201], v[210:213], v[190:193]
	v_mfma_f32_16x16x32_bf16 v[10:13], v[226:229], v[206:209], v[10:13]
	v_mfma_f32_16x16x32_bf16 v[14:17], v[226:229], v[214:217], v[14:17]
	s_setprio 0
	v_cmp_gt_u32_e32 vcc, s48, v134
	s_barrier
	s_and_saveexec_b64 s[26:27], vcc
	s_cbranch_execz .LBB0_349
	s_barrier

; #define STAGE(P, GP, ktrel) do { const GAS char* _g = (GP) + (ktrel) * (BK * 2); \
;     __builtin_amdgcn_global_load_lds((const GAS unsigned*)(_g + so0), (unsigned*)((char*)(P) + tid_ * 16), 16, 0, 0); \
;     __builtin_amdgcn_global_load_lds((const GAS unsigned*)(_g + so1), (unsigned*)((char*)(P) + tid_ * 16 + 8192), 16, 0, 0); } while (0)
; #define WAIT_V(n) asm volatile("s_waitcnt vmcnt(" #n ")" ::: "memory")
; #define WAIT_L(n) asm volatile("s_waitcnt lgkmcnt(" #n ")" ::: "memory")
; #define BAR __builtin_amdgcn_s_barrier()
; #define SCHED __builtin_amdgcn_sched_barrier(0)
; #define LDA(dst, b, h) for (int m = 0; m < 4; ++m) for (int k = 0; k < 2; ++k) \
;     dst[m][k] = *reinterpret_cast<const bf16x8*>((char*)SA(b, h) + lds_byte(wr * 64 + m * 16 + fr, k * 32 + fq * 8))
; #define LDB(dst, b, h) for (int n = 0; n < 2; ++n) for (int k = 0; k < 2; ++k) \
;     dst[n][k] = *reinterpret_cast<const bf16x8*>((char*)SB(b, h) + lds_byte(wc * 32 + n * 16 + fr, k * 32 + fq * 8))
; template <int K, int LD = K>
; __device__ __forceinline__ void gemm_main(const GAS bf16* A, const GAS bf16* Bt, int brow, int bcol, f32x4 (&acc)[2][2][4][2]) {
;     ...
;   for (int t = 0; t < nt - 2; t += 2) {
;     LDB(B0, 0, 0); SCHED; LDA(At, 0, 0); STAGE(SA(1, 1), pA1, 1);
;     WAIT_L(8); BAR; WAIT_L(0); MMA(0, 0, At, B0); BAR; SCHED;
;     LDB(B1, 0, 1); STAGE(SB(0, 0), pB0, 2);
;     BAR; WAIT_L(0); MMA(0, 1, At, B1); BAR;
;     LDA(At, 0, 1); STAGE(SA(0, 0), pA0, 2);
;     BAR; WAIT_L(0); MMA(1, 0, At, B0); BAR; SCHED;
;     STAGE(SB(0, 1), pB1, 2);
;     WAIT_V(6); BAR; MMA(1, 1, At, B1); BAR;
;     LDB(B0, 1, 0); SCHED; LDA(At, 1, 0); STAGE(SA(0, 1), pA1, 2);
;     WAIT_L(8); BAR; WAIT_L(0); MMA(0, 0, At, B0); BAR; SCHED;
;     LDB(B1, 1, 1); STAGE(SB(1, 0), pB0, 3);
;     BAR; WAIT_L(0); MMA(0, 1, At, B1); BAR;
;     LDA(At, 1, 1); STAGE(SA(1, 0), pA0, 3);
;     BAR; WAIT_L(0); MMA(1, 0, At, B0); BAR; SCHED;
;     STAGE(SB(1, 1), pB1, 3);
;     WAIT_V(6); BAR; MMA(1, 1, At, B1); BAR;
;     pA0 += 4 * BK; pA1 += 4 * BK; pB0 += 4 * BK; pB1 += 4 * BK;
;     asm volatile("" : "+s"(pA0), "+s"(pA1), "+s"(pB0), "+s"(pB1));
;   }
.LBB0_709:
	ds_read_b128 v[146:149], v143
	ds_read_b128 v[150:153], v143 offset:1024
	ds_read_b128 v[154:157], v143 offset:2048
	ds_read_b128 v[158:161], v143 offset:3072
	v_add_u32_e32 v230, 0x100, v141
	v_add_u32_e32 v144, 0xc000, v230
	v_lshl_add_u64 v[214:215], s[20:21], 0, v[130:131]
	v_readfirstlane_b32 s30, v144
	v_add_u32_e32 v145, 0xe000, v230
	v_lshl_add_u64 v[198:199], v[214:215], 0, s[6:7]
	s_mov_b32 m0, s30
	v_lshl_add_u64 v[216:217], s[20:21], 0, v[132:133]
	v_readfirstlane_b32 s30, v145
	ds_read_b128 v[162:165], v138
	ds_read_b128 v[166:169], v138 offset:1024
	ds_read_b128 v[174:177], v137
	ds_read_b128 v[178:181], v137 offset:1024
	ds_read_b128 v[182:185], v136
	ds_read_b128 v[186:189], v136 offset:1024
	ds_read_b128 v[190:193], v135
	ds_read_b128 v[194:197], v135 offset:1024
	global_load_lds_dwordx4 v[198:199], off
	v_lshl_add_u64 v[198:199], v[216:217], 0, s[6:7]
	s_mov_b32 m0, s30
	s_nop 0
	global_load_lds_dwordx4 v[198:199], off
	s_waitcnt lgkmcnt(8)
	s_waitcnt vmcnt(10)
	s_barrier
	s_waitcnt lgkmcnt(0)
	s_setprio 1
	s_waitcnt lgkmcnt(0)
	v_mfma_f32_16x16x32_bf16 v[126:129], v[162:165], v[146:149], v[126:129]
	v_mfma_f32_16x16x32_bf16 v[122:125], v[162:165], v[154:157], v[122:125]
	v_mfma_f32_16x16x32_bf16 v[118:121], v[174:177], v[146:149], v[118:121]
	v_mfma_f32_16x16x32_bf16 v[114:117], v[174:177], v[154:157], v[114:117]
	v_mfma_f32_16x16x32_bf16 v[110:113], v[182:185], v[146:149], v[110:113]
	v_mfma_f32_16x16x32_bf16 v[106:109], v[182:185], v[154:157], v[106:109]
	v_mfma_f32_16x16x32_bf16 v[102:105], v[190:193], v[146:149], v[102:105]
	v_mfma_f32_16x16x32_bf16 v[98:101], v[190:193], v[154:157], v[98:101]
	v_mfma_f32_16x16x32_bf16 v[126:129], v[166:169], v[150:153], v[126:129]
	v_mfma_f32_16x16x32_bf16 v[122:125], v[166:169], v[158:161], v[122:125]
	v_mfma_f32_16x16x32_bf16 v[118:121], v[178:181], v[150:153], v[118:121]
	v_mfma_f32_16x16x32_bf16 v[114:117], v[178:181], v[158:161], v[114:117]
	v_mfma_f32_16x16x32_bf16 v[110:113], v[186:189], v[150:153], v[110:113]
	v_mfma_f32_16x16x32_bf16 v[106:109], v[186:189], v[158:161], v[106:109]
	v_mfma_f32_16x16x32_bf16 v[102:105], v[194:197], v[150:153], v[102:105]
	v_mfma_f32_16x16x32_bf16 v[98:101], v[194:197], v[158:161], v[98:101]
	s_setprio 0
	s_barrier
	v_add_u32_e32 v224, s47, v141
	v_lshl_add_u64 v[218:219], s[28:29], 0, v[130:131]
	v_readfirstlane_b32 s30, v224
	v_lshl_add_u64 v[220:221], v[218:219], 0, s[10:11]
	s_mov_b32 m0, s30
	v_add_u32_e32 v224, 0x2000, v224
	ds_read_b128 v[198:201], v142
	ds_read_b128 v[202:205], v142 offset:1024
	ds_read_b128 v[206:209], v142 offset:2048
	ds_read_b128 v[210:213], v142 offset:3072
	global_load_lds_dwordx4 v[220:221], off
	v_lshl_add_u64 v[220:221], s[28:29], 0, v[132:133]
	v_readfirstlane_b32 s30, v224
	v_lshl_add_u64 v[222:223], v[220:221], 0, s[10:11]
	s_mov_b32 m0, s30
	s_add_u32 s28, s28, 0x100
	global_load_lds_dwordx4 v[222:223], off
	s_waitcnt vmcnt(10)
	s_barrier
	s_waitcnt lgkmcnt(0)
	s_addc_u32 s29, s29, 0
	s_setprio 1
	s_waitcnt lgkmcnt(0)
	v_mfma_f32_16x16x32_bf16 v[94:97], v[162:165], v[198:201], v[94:97]
	v_mfma_f32_16x16x32_bf16 v[90:93], v[162:165], v[206:209], v[90:93]
	v_mfma_f32_16x16x32_bf16 v[86:89], v[174:177], v[198:201], v[86:89]
	v_mfma_f32_16x16x32_bf16 v[82:85], v[174:177], v[206:209], v[82:85]
	v_mfma_f32_16x16x32_bf16 v[78:81], v[182:185], v[198:201], v[78:81]
	v_mfma_f32_16x16x32_bf16 v[74:77], v[182:185], v[206:209], v[74:77]
	v_mfma_f32_16x16x32_bf16 v[70:73], v[190:193], v[198:201], v[70:73]
	v_mfma_f32_16x16x32_bf16 v[66:69], v[190:193], v[206:209], v[66:69]
	v_mfma_f32_16x16x32_bf16 v[94:97], v[166:169], v[202:205], v[94:97]
	v_mfma_f32_16x16x32_bf16 v[90:93], v[166:169], v[210:213], v[90:93]
	v_mfma_f32_16x16x32_bf16 v[86:89], v[178:181], v[202:205], v[86:89]
	v_mfma_f32_16x16x32_bf16 v[82:85], v[178:181], v[210:213], v[82:85]
	v_mfma_f32_16x16x32_bf16 v[78:81], v[186:189], v[202:205], v[78:81]
	v_mfma_f32_16x16x32_bf16 v[74:77], v[186:189], v[210:213], v[74:77]
	v_mfma_f32_16x16x32_bf16 v[70:73], v[194:197], v[202:205], v[70:73]
	v_mfma_f32_16x16x32_bf16 v[66:69], v[194:197], v[210:213], v[66:69]
	s_setprio 0
	v_lshl_add_u64 v[222:223], s[26:27], 0, v[130:131]
	v_readfirstlane_b32 s30, v230
	v_lshl_add_u64 v[224:225], v[222:223], 0, s[10:11]
	s_mov_b32 m0, s30
	v_add_u32_e32 v228, 0x2000, v230
	s_barrier
	ds_read_b128 v[162:165], v138 offset:16384
	ds_read_b128 v[166:169], v138 offset:17408
	ds_read_b128 v[174:177], v137 offset:16384
	ds_read_b128 v[178:181], v137 offset:17408
	ds_read_b128 v[182:185], v136 offset:16384
	ds_read_b128 v[186:189], v136 offset:17408
	ds_read_b128 v[190:193], v135 offset:16384
	ds_read_b128 v[194:197], v135 offset:17408
	global_load_lds_dwordx4 v[224:225], off
	v_lshl_add_u64 v[224:225], s[26:27], 0, v[132:133]
	v_readfirstlane_b32 s30, v228
	v_lshl_add_u64 v[226:227], v[224:225], 0, s[10:11]
	s_mov_b32 m0, s30
	s_add_u32 s26, s26, 0x100
	global_load_lds_dwordx4 v[226:227], off
	s_barrier
	s_waitcnt lgkmcnt(0)
	s_addc_u32 s27, s27, 0
	s_setprio 1
	s_waitcnt lgkmcnt(0)
	v_mfma_f32_16x16x32_bf16 v[62:65], v[162:165], v[146:149], v[62:65]
	v_mfma_f32_16x16x32_bf16 v[58:61], v[162:165], v[154:157], v[58:61]
	v_mfma_f32_16x16x32_bf16 v[54:57], v[174:177], v[146:149], v[54:57]
	v_mfma_f32_16x16x32_bf16 v[50:53], v[174:177], v[154:157], v[50:53]
	v_mfma_f32_16x16x32_bf16 v[46:49], v[182:185], v[146:149], v[46:49]
	v_mfma_f32_16x16x32_bf16 v[42:45], v[182:185], v[154:157], v[42:45]
	v_mfma_f32_16x16x32_bf16 v[38:41], v[190:193], v[146:149], v[38:41]
	v_mfma_f32_16x16x32_bf16 v[34:37], v[190:193], v[154:157], v[34:37]
	v_mfma_f32_16x16x32_bf16 v[62:65], v[166:169], v[150:153], v[62:65]
	v_mfma_f32_16x16x32_bf16 v[58:61], v[166:169], v[158:161], v[58:61]
	v_mfma_f32_16x16x32_bf16 v[54:57], v[178:181], v[150:153], v[54:57]
	v_mfma_f32_16x16x32_bf16 v[50:53], v[178:181], v[158:161], v[50:53]
	v_mfma_f32_16x16x32_bf16 v[46:49], v[186:189], v[150:153], v[46:49]
	v_mfma_f32_16x16x32_bf16 v[42:45], v[186:189], v[158:161], v[42:45]
	v_mfma_f32_16x16x32_bf16 v[38:41], v[194:197], v[150:153], v[38:41]
	v_mfma_f32_16x16x32_bf16 v[34:37], v[194:197], v[158:161], v[34:37]
	s_setprio 0
	s_barrier
; #define STAGE(P, GP, ktrel) do { const GAS char* _g = (GP) + (ktrel) * (BK * 2); \
;     __builtin_amdgcn_global_load_lds((const GAS unsigned*)(_g + so0), (unsigned*)((char*)(P) + tid_ * 16), 16, 0, 0); \
;     __builtin_amdgcn_global_load_lds((const GAS unsigned*)(_g + so1), (unsigned*)((char*)(P) + tid_ * 16 + 8192), 16, 0, 0); } while (0)
; #define WAIT_V(n) asm volatile("s_waitcnt vmcnt(" #n ")" ::: "memory")
; #define WAIT_L(n) asm volatile("s_waitcnt lgkmcnt(" #n ")" ::: "memory")
; #define BAR __builtin_amdgcn_s_barrier()
; #define SCHED __builtin_amdgcn_sched_barrier(0)
; #define LDA(dst, b, h) for (int m = 0; m < 4; ++m) for (int k = 0; k < 2; ++k) \
;     dst[m][k] = *reinterpret_cast<const bf16x8*>((char*)SA(b, h) + lds_byte(wr * 64 + m * 16 + fr, k * 32 + fq * 8))
; #define LDB(dst, b, h) for (int n = 0; n < 2; ++n) for (int k = 0; k < 2; ++k) \
;     dst[n][k] = *reinterpret_cast<const bf16x8*>((char*)SB(b, h) + lds_byte(wc * 32 + n * 16 + fr, k * 32 + fq * 8))
; #define MMA(ai, bj, At_, Bt_) do { __builtin_amdgcn_s_setprio(1); \
;     for (int m = 0; m < 4; ++m) for (int n = 0; n < 2; ++n) for (int k = 0; k < 2; ++k) \
;       acc[ai][bj][m][n] = __builtin_amdgcn_mfma_f32_16x16x32_bf16(At_[m][k], Bt_[n][k], acc[ai][bj][m][n], 0, 0, 0); \
;     __builtin_amdgcn_s_setprio(0); } while (0)
; template <int K, int LD = K>
; __device__ __forceinline__ void gemm_main(const GAS bf16* A, const GAS bf16* Bt, int brow, int bcol, f32x4 (&acc)[2][2][4][2]) {
;     ...
;     STAGE(SB(0, 1), pB1, 2);
;     WAIT_V(6); BAR; MMA(1, 1, At, B1); BAR;
;     LDB(B0, 1, 0); SCHED; LDA(At, 1, 0); STAGE(SA(0, 1), pA1, 2);
;     WAIT_L(8); BAR; WAIT_L(0); MMA(0, 0, At, B0); BAR; SCHED;
;     LDB(B1, 1, 1); STAGE(SB(1, 0), pB0, 3);
;     BAR; WAIT_L(0); MMA(0, 1, At, B1); BAR;
	v_add_u32_e32 v148, s48, v141
	v_lshl_add_u64 v[226:227], s[24:25], 0, v[130:131]
	v_readfirstlane_b32 s30, v148
	v_add_u32_e32 v148, 0x2000, v148
	v_lshl_add_u64 v[146:147], v[226:227], 0, s[10:11]
	s_mov_b32 m0, s30
	v_lshl_add_u64 v[228:229], s[24:25], 0, v[132:133]
	v_readfirstlane_b32 s30, v148
	global_load_lds_dwordx4 v[146:147], off
	v_lshl_add_u64 v[146:147], v[228:229], 0, s[10:11]
	s_mov_b32 m0, s30
	s_add_u32 s24, s24, 0x100
	global_load_lds_dwordx4 v[146:147], off
	s_waitcnt vmcnt(10)
	s_addc_u32 s25, s25, 0
	s_barrier
	s_setprio 1
	v_mfma_f32_16x16x32_bf16 v[30:33], v[162:165], v[198:201], v[30:33]
	v_mfma_f32_16x16x32_bf16 v[26:29], v[162:165], v[206:209], v[26:29]
	v_mfma_f32_16x16x32_bf16 v[22:25], v[174:177], v[198:201], v[22:25]
	v_mfma_f32_16x16x32_bf16 v[18:21], v[174:177], v[206:209], v[18:21]
	v_mfma_f32_16x16x32_bf16 v[14:17], v[182:185], v[198:201], v[14:17]
	v_mfma_f32_16x16x32_bf16 v[10:13], v[182:185], v[206:209], v[10:13]
	v_mfma_f32_16x16x32_bf16 v[6:9], v[190:193], v[198:201], v[6:9]
	v_mfma_f32_16x16x32_bf16 v[2:5], v[190:193], v[206:209], v[2:5]
	v_mfma_f32_16x16x32_bf16 v[30:33], v[166:169], v[202:205], v[30:33]
	v_mfma_f32_16x16x32_bf16 v[26:29], v[166:169], v[210:213], v[26:29]
	v_mfma_f32_16x16x32_bf16 v[22:25], v[178:181], v[202:205], v[22:25]
	v_mfma_f32_16x16x32_bf16 v[18:21], v[178:181], v[210:213], v[18:21]
	v_mfma_f32_16x16x32_bf16 v[14:17], v[186:189], v[202:205], v[14:17]
	v_mfma_f32_16x16x32_bf16 v[10:13], v[186:189], v[210:213], v[10:13]
	v_mfma_f32_16x16x32_bf16 v[6:9], v[194:197], v[202:205], v[6:9]
	v_mfma_f32_16x16x32_bf16 v[2:5], v[194:197], v[210:213], v[2:5]
	s_setprio 0
	s_barrier
	ds_read_b128 v[146:149], v140
	ds_read_b128 v[150:153], v140 offset:1024
	ds_read_b128 v[154:157], v140 offset:2048
	ds_read_b128 v[158:161], v140 offset:3072
	v_add_u32_e32 v200, 0x4000, v230
	v_lshl_add_u64 v[198:199], v[214:215], 0, s[10:11]
	v_readfirstlane_b32 s30, v200
	v_add_u32_e32 v200, 0x6000, v230
	s_mov_b32 m0, s30
	v_readfirstlane_b32 s30, v200
	ds_read_b128 v[162:165], v138 offset:32768
	ds_read_b128 v[166:169], v138 offset:33792
	ds_read_b128 v[174:177], v137 offset:32768
	ds_read_b128 v[178:181], v137 offset:33792
	ds_read_b128 v[182:185], v136 offset:32768
	ds_read_b128 v[186:189], v136 offset:33792
	ds_read_b128 v[190:193], v135 offset:32768
	ds_read_b128 v[194:197], v135 offset:33792
	global_load_lds_dwordx4 v[198:199], off
	v_lshl_add_u64 v[198:199], v[216:217], 0, s[10:11]
	s_mov_b32 m0, s30
	s_add_u32 s20, s20, 0x100
	global_load_lds_dwordx4 v[198:199], off
	s_waitcnt lgkmcnt(8)
	s_waitcnt vmcnt(10)
	s_barrier
	s_waitcnt lgkmcnt(0)
	s_addc_u32 s21, s21, 0
	s_setprio 1
	s_waitcnt lgkmcnt(0)
	v_mfma_f32_16x16x32_bf16 v[126:129], v[162:165], v[146:149], v[126:129]
	v_mfma_f32_16x16x32_bf16 v[122:125], v[162:165], v[154:157], v[122:125]
	v_mfma_f32_16x16x32_bf16 v[118:121], v[174:177], v[146:149], v[118:121]
	v_mfma_f32_16x16x32_bf16 v[114:117], v[174:177], v[154:157], v[114:117]
	v_mfma_f32_16x16x32_bf16 v[110:113], v[182:185], v[146:149], v[110:113]
	v_mfma_f32_16x16x32_bf16 v[106:109], v[182:185], v[154:157], v[106:109]
	v_mfma_f32_16x16x32_bf16 v[102:105], v[190:193], v[146:149], v[102:105]
	v_mfma_f32_16x16x32_bf16 v[98:101], v[190:193], v[154:157], v[98:101]
	v_mfma_f32_16x16x32_bf16 v[126:129], v[166:169], v[150:153], v[126:129]
	v_mfma_f32_16x16x32_bf16 v[122:125], v[166:169], v[158:161], v[122:125]
	v_mfma_f32_16x16x32_bf16 v[118:121], v[178:181], v[150:153], v[118:121]
	v_mfma_f32_16x16x32_bf16 v[114:117], v[178:181], v[158:161], v[114:117]
	v_mfma_f32_16x16x32_bf16 v[110:113], v[186:189], v[150:153], v[110:113]
	v_mfma_f32_16x16x32_bf16 v[106:109], v[186:189], v[158:161], v[106:109]
	v_mfma_f32_16x16x32_bf16 v[102:105], v[194:197], v[150:153], v[102:105]
	v_mfma_f32_16x16x32_bf16 v[98:101], v[194:197], v[158:161], v[98:101]
	s_setprio 0
	s_barrier
	v_add_u32_e32 v216, s49, v141
	v_lshl_add_u64 v[214:215], v[218:219], 0, s[12:13]
	v_readfirstlane_b32 s30, v216
	v_add_u32_e32 v216, 0x2000, v216
	s_mov_b32 m0, s30
	v_readfirstlane_b32 s30, v216
	ds_read_b128 v[198:201], v139
	ds_read_b128 v[202:205], v139 offset:1024
	ds_read_b128 v[206:209], v139 offset:2048
	ds_read_b128 v[210:213], v139 offset:3072
	global_load_lds_dwordx4 v[214:215], off
	v_lshl_add_u64 v[214:215], v[220:221], 0, s[12:13]
	s_mov_b32 m0, s30
	s_nop 0
	global_load_lds_dwordx4 v[214:215], off
	s_waitcnt vmcnt(10)
	s_barrier
	s_waitcnt lgkmcnt(0)
	s_setprio 1
	s_waitcnt lgkmcnt(0)
	v_mfma_f32_16x16x32_bf16 v[94:97], v[162:165], v[198:201], v[94:97]
	v_mfma_f32_16x16x32_bf16 v[90:93], v[162:165], v[206:209], v[90:93]
	v_mfma_f32_16x16x32_bf16 v[86:89], v[174:177], v[198:201], v[86:89]
	v_mfma_f32_16x16x32_bf16 v[82:85], v[174:177], v[206:209], v[82:85]
	v_mfma_f32_16x16x32_bf16 v[78:81], v[182:185], v[198:201], v[78:81]
	v_mfma_f32_16x16x32_bf16 v[74:77], v[182:185], v[206:209], v[74:77]
	v_mfma_f32_16x16x32_bf16 v[70:73], v[190:193], v[198:201], v[70:73]
	v_mfma_f32_16x16x32_bf16 v[66:69], v[190:193], v[206:209], v[66:69]
	v_mfma_f32_16x16x32_bf16 v[94:97], v[166:169], v[202:205], v[94:97]
	v_mfma_f32_16x16x32_bf16 v[90:93], v[166:169], v[210:213], v[90:93]
	v_mfma_f32_16x16x32_bf16 v[86:89], v[178:181], v[202:205], v[86:89]
	v_mfma_f32_16x16x32_bf16 v[82:85], v[178:181], v[210:213], v[82:85]
	v_mfma_f32_16x16x32_bf16 v[78:81], v[186:189], v[202:205], v[78:81]
	v_mfma_f32_16x16x32_bf16 v[74:77], v[186:189], v[210:213], v[74:77]
	v_mfma_f32_16x16x32_bf16 v[70:73], v[194:197], v[202:205], v[70:73]
	v_mfma_f32_16x16x32_bf16 v[66:69], v[194:197], v[210:213], v[66:69]
	s_setprio 0
	v_add_u32_e32 v216, 0x8000, v230
	v_lshl_add_u64 v[214:215], v[222:223], 0, s[12:13]
	v_readfirstlane_b32 s30, v216
	v_add_u32_e32 v216, 0xa000, v230
	s_mov_b32 m0, s30
	v_readfirstlane_b32 s30, v216
	s_barrier
; #define STAGE(P, GP, ktrel) do { const GAS char* _g = (GP) + (ktrel) * (BK * 2); \
;     __builtin_amdgcn_global_load_lds((const GAS unsigned*)(_g + so0), (unsigned*)((char*)(P) + tid_ * 16), 16, 0, 0); \
;     __builtin_amdgcn_global_load_lds((const GAS unsigned*)(_g + so1), (unsigned*)((char*)(P) + tid_ * 16 + 8192), 16, 0, 0); } while (0)
; #define WAIT_V(n) asm volatile("s_waitcnt vmcnt(" #n ")" ::: "memory")
; #define WAIT_L(n) asm volatile("s_waitcnt lgkmcnt(" #n ")" ::: "memory")
; #define BAR __builtin_amdgcn_s_barrier()
; #define SCHED __builtin_amdgcn_sched_barrier(0)
; #define LDA(dst, b, h) for (int m = 0; m < 4; ++m) for (int k = 0; k < 2; ++k) \
;     dst[m][k] = *reinterpret_cast<const bf16x8*>((char*)SA(b, h) + lds_byte(wr * 64 + m * 16 + fr, k * 32 + fq * 8))
; #define LDB(dst, b, h) for (int n = 0; n < 2; ++n) for (int k = 0; k < 2; ++k) \
;     dst[n][k] = *reinterpret_cast<const bf16x8*>((char*)SB(b, h) + lds_byte(wc * 32 + n * 16 + fr, k * 32 + fq * 8))
; #define MMA(ai, bj, At_, Bt_) do { __builtin_amdgcn_s_setprio(1); \
;     for (int m = 0; m < 4; ++m) for (int n = 0; n < 2; ++n) for (int k = 0; k < 2; ++k) \
;       acc[ai][bj][m][n] = __builtin_amdgcn_mfma_f32_16x16x32_bf16(At_[m][k], Bt_[n][k], acc[ai][bj][m][n], 0, 0, 0); \
;     __builtin_amdgcn_s_setprio(0); } while (0)
; template <int K, int LD = K>
; __device__ __forceinline__ void gemm_main(const GAS bf16* A, const GAS bf16* Bt, int brow, int bcol, f32x4 (&acc)[2][2][4][2]) {
;     ...
;     LDA(At, 1, 1); STAGE(SA(1, 0), pA0, 3);
;     BAR; WAIT_L(0); MMA(1, 0, At, B0); BAR; SCHED;
;     STAGE(SB(1, 1), pB1, 3);
;     WAIT_V(6); BAR; MMA(1, 1, At, B1); BAR;
;     pA0 += 4 * BK; pA1 += 4 * BK; pB0 += 4 * BK; pB1 += 4 * BK;
;     asm volatile("" : "+s"(pA0), "+s"(pA1), "+s"(pB0), "+s"(pB1));
;   }
;   { LDB(B0, 0, 0); LDA(At, 0, 0); STAGE(SA(1, 1), pA1, 1);
;     BAR; WAIT_L(0); MMA(0, 0, At, B0); BAR;
;     LDB(B1, 0, 1); BAR; WAIT_L(0); MMA(0, 1, At, B1); BAR;
	ds_read_b128 v[162:165], v138 offset:49152
	ds_read_b128 v[166:169], v138 offset:50176
	ds_read_b128 v[174:177], v137 offset:49152
	ds_read_b128 v[178:181], v137 offset:50176
	ds_read_b128 v[182:185], v136 offset:49152
	ds_read_b128 v[186:189], v136 offset:50176
	ds_read_b128 v[190:193], v135 offset:49152
	ds_read_b128 v[194:197], v135 offset:50176
	global_load_lds_dwordx4 v[214:215], off
	v_lshl_add_u64 v[214:215], v[224:225], 0, s[12:13]
	s_mov_b32 m0, s30
	s_nop 0
	global_load_lds_dwordx4 v[214:215], off
	s_barrier
	s_waitcnt lgkmcnt(0)
	s_setprio 1
	s_waitcnt lgkmcnt(0)
	v_mfma_f32_16x16x32_bf16 v[62:65], v[162:165], v[146:149], v[62:65]
	v_mfma_f32_16x16x32_bf16 v[58:61], v[162:165], v[154:157], v[58:61]
	v_mfma_f32_16x16x32_bf16 v[54:57], v[174:177], v[146:149], v[54:57]
	v_mfma_f32_16x16x32_bf16 v[50:53], v[174:177], v[154:157], v[50:53]
	v_mfma_f32_16x16x32_bf16 v[46:49], v[182:185], v[146:149], v[46:49]
	v_mfma_f32_16x16x32_bf16 v[42:45], v[182:185], v[154:157], v[42:45]
	v_mfma_f32_16x16x32_bf16 v[38:41], v[190:193], v[146:149], v[38:41]
	v_mfma_f32_16x16x32_bf16 v[34:37], v[190:193], v[154:157], v[34:37]
	v_mfma_f32_16x16x32_bf16 v[62:65], v[166:169], v[150:153], v[62:65]
	v_mfma_f32_16x16x32_bf16 v[58:61], v[166:169], v[158:161], v[58:61]
	v_mfma_f32_16x16x32_bf16 v[54:57], v[178:181], v[150:153], v[54:57]
	v_mfma_f32_16x16x32_bf16 v[50:53], v[178:181], v[158:161], v[50:53]
	v_mfma_f32_16x16x32_bf16 v[46:49], v[186:189], v[150:153], v[46:49]
	v_mfma_f32_16x16x32_bf16 v[42:45], v[186:189], v[158:161], v[42:45]
	v_mfma_f32_16x16x32_bf16 v[38:41], v[194:197], v[150:153], v[38:41]
	v_mfma_f32_16x16x32_bf16 v[34:37], v[194:197], v[158:161], v[34:37]
	s_setprio 0
	s_barrier
	v_add_u32_e32 v148, s50, v141
	v_lshl_add_u64 v[146:147], v[226:227], 0, s[12:13]
	v_readfirstlane_b32 s30, v148
	v_add_u32_e32 v148, 0x2000, v148
	s_mov_b32 m0, s30
	v_readfirstlane_b32 s30, v148
	global_load_lds_dwordx4 v[146:147], off
	v_lshl_add_u64 v[146:147], v[228:229], 0, s[12:13]
	s_mov_b32 m0, s30
	s_nop 0
	global_load_lds_dwordx4 v[146:147], off
	s_waitcnt vmcnt(10)
	s_barrier
	s_setprio 1
	v_mfma_f32_16x16x32_bf16 v[30:33], v[162:165], v[198:201], v[30:33]
	v_mfma_f32_16x16x32_bf16 v[26:29], v[162:165], v[206:209], v[26:29]
	v_mfma_f32_16x16x32_bf16 v[22:25], v[174:177], v[198:201], v[22:25]
	v_mfma_f32_16x16x32_bf16 v[18:21], v[174:177], v[206:209], v[18:21]
	v_mfma_f32_16x16x32_bf16 v[14:17], v[182:185], v[198:201], v[14:17]
	v_mfma_f32_16x16x32_bf16 v[10:13], v[182:185], v[206:209], v[10:13]
	v_mfma_f32_16x16x32_bf16 v[6:9], v[190:193], v[198:201], v[6:9]
	v_mfma_f32_16x16x32_bf16 v[2:5], v[190:193], v[206:209], v[2:5]
	v_mfma_f32_16x16x32_bf16 v[30:33], v[166:169], v[202:205], v[30:33]
	v_mfma_f32_16x16x32_bf16 v[26:29], v[166:169], v[210:213], v[26:29]
	v_mfma_f32_16x16x32_bf16 v[22:25], v[178:181], v[202:205], v[22:25]
	v_mfma_f32_16x16x32_bf16 v[18:21], v[178:181], v[210:213], v[18:21]
	v_mfma_f32_16x16x32_bf16 v[14:17], v[186:189], v[202:205], v[14:17]
	v_mfma_f32_16x16x32_bf16 v[10:13], v[186:189], v[210:213], v[10:13]
	v_mfma_f32_16x16x32_bf16 v[6:9], v[194:197], v[202:205], v[6:9]
	v_mfma_f32_16x16x32_bf16 v[2:5], v[194:197], v[210:213], v[2:5]
	s_setprio 0
	s_add_i32 s17, s17, 2
	s_cmp_lt_u32 s17, 4
	s_barrier
	s_cbranch_scc1 .LBB0_709
	v_lshl_add_u64 v[198:199], s[20:21], 0, v[130:131]
	v_readfirstlane_b32 s17, v144
	v_lshl_add_u64 v[198:199], v[198:199], 0, s[6:7]
	s_mov_b32 m0, s17
	v_lshl_add_u64 v[132:133], s[20:21], 0, v[132:133]
	v_readfirstlane_b32 s17, v145
	ds_read_b128 v[146:149], v143
	ds_read_b128 v[150:153], v143 offset:1024
	ds_read_b128 v[154:157], v143 offset:2048
	ds_read_b128 v[158:161], v143 offset:3072
	ds_read_b128 v[162:165], v138
	ds_read_b128 v[166:169], v138 offset:1024
	ds_read_b128 v[174:177], v137
	ds_read_b128 v[178:181], v137 offset:1024
	ds_read_b128 v[182:185], v136
	ds_read_b128 v[186:189], v136 offset:1024
	ds_read_b128 v[190:193], v135
	ds_read_b128 v[194:197], v135 offset:1024
	global_load_lds_dwordx4 v[198:199], off
	v_lshl_add_u64 v[132:133], v[132:133], 0, s[6:7]
	s_mov_b32 m0, s17
	s_nop 0
	global_load_lds_dwordx4 v[132:133], off
	s_waitcnt vmcnt(10)
	s_barrier
	s_waitcnt lgkmcnt(0)
	s_setprio 1
	s_waitcnt lgkmcnt(0)
	v_mfma_f32_16x16x32_bf16 v[126:129], v[162:165], v[146:149], v[126:129]
	v_mfma_f32_16x16x32_bf16 v[122:125], v[162:165], v[154:157], v[122:125]
	v_mfma_f32_16x16x32_bf16 v[110:113], v[182:185], v[146:149], v[110:113]
	v_mfma_f32_16x16x32_bf16 v[106:109], v[182:185], v[154:157], v[106:109]
	v_mfma_f32_16x16x32_bf16 v[126:129], v[166:169], v[150:153], v[126:129]
	v_mfma_f32_16x16x32_bf16 v[122:125], v[166:169], v[158:161], v[122:125]
	v_mfma_f32_16x16x32_bf16 v[118:121], v[174:177], v[146:149], v[118:121]
	v_mfma_f32_16x16x32_bf16 v[114:117], v[174:177], v[154:157], v[114:117]
	v_mfma_f32_16x16x32_bf16 v[110:113], v[186:189], v[150:153], v[110:113]
	v_mfma_f32_16x16x32_bf16 v[106:109], v[186:189], v[158:161], v[106:109]
	v_mfma_f32_16x16x32_bf16 v[102:105], v[190:193], v[146:149], v[102:105]
	v_mfma_f32_16x16x32_bf16 v[98:101], v[190:193], v[154:157], v[98:101]
	v_mfma_f32_16x16x32_bf16 v[198:201], v[178:181], v[150:153], v[118:121]
	v_mfma_f32_16x16x32_bf16 v[202:205], v[178:181], v[158:161], v[114:117]
	v_mfma_f32_16x16x32_bf16 v[206:209], v[194:197], v[150:153], v[102:105]
	v_mfma_f32_16x16x32_bf16 v[210:213], v[194:197], v[158:161], v[98:101]
	s_setprio 0
	s_barrier
	s_nop 1
	ds_read_b128 v[98:101], v142
	ds_read_b128 v[102:105], v142 offset:1024
	ds_read_b128 v[114:117], v142 offset:2048
	ds_read_b128 v[118:121], v142 offset:3072
	s_waitcnt vmcnt(8)
	s_barrier
; #define WAIT_V(n) asm volatile("s_waitcnt vmcnt(" #n ")" ::: "memory")
; #define WAIT_L(n) asm volatile("s_waitcnt lgkmcnt(" #n ")" ::: "memory")
; #define BAR __builtin_amdgcn_s_barrier()
; #define LDA(dst, b, h) for (int m = 0; m < 4; ++m) for (int k = 0; k < 2; ++k) \
;     dst[m][k] = *reinterpret_cast<const bf16x8*>((char*)SA(b, h) + lds_byte(wr * 64 + m * 16 + fr, k * 32 + fq * 8))
; #define LDB(dst, b, h) for (int n = 0; n < 2; ++n) for (int k = 0; k < 2; ++k) \
;     dst[n][k] = *reinterpret_cast<const bf16x8*>((char*)SB(b, h) + lds_byte(wc * 32 + n * 16 + fr, k * 32 + fq * 8))
; #define MMA(ai, bj, At_, Bt_) do { __builtin_amdgcn_s_setprio(1); \
;     for (int m = 0; m < 4; ++m) for (int n = 0; n < 2; ++n) for (int k = 0; k < 2; ++k) \
;       acc[ai][bj][m][n] = __builtin_amdgcn_mfma_f32_16x16x32_bf16(At_[m][k], Bt_[n][k], acc[ai][bj][m][n], 0, 0, 0); \
;     __builtin_amdgcn_s_setprio(0); } while (0)
; template <int K, int LD = K>
; __device__ __forceinline__ void gemm_main(const GAS bf16* A, const GAS bf16* Bt, int brow, int bcol, f32x4 (&acc)[2][2][4][2]) {
;     ...
;     LDB(B1, 0, 1); BAR; WAIT_L(0); MMA(0, 1, At, B1); BAR;
;     LDA(At, 0, 1); WAIT_V(4); BAR; WAIT_L(0); MMA(1, 0, At, B0); MMA(1, 1, At, B1); BAR; }
;   { LDB(B0, 1, 0); LDA(At, 1, 0); WAIT_V(2); BAR; WAIT_L(0); MMA(0, 0, At, B0); BAR;
	s_waitcnt lgkmcnt(0)
	s_setprio 1
	s_waitcnt lgkmcnt(0)
	v_mfma_f32_16x16x32_bf16 v[94:97], v[162:165], v[98:101], v[94:97]
	v_mfma_f32_16x16x32_bf16 v[90:93], v[162:165], v[114:117], v[90:93]
	v_mfma_f32_16x16x32_bf16 v[70:73], v[190:193], v[98:101], v[70:73]
	v_mfma_f32_16x16x32_bf16 v[66:69], v[190:193], v[114:117], v[66:69]
	v_mfma_f32_16x16x32_bf16 v[94:97], v[166:169], v[102:105], v[94:97]
	v_mfma_f32_16x16x32_bf16 v[90:93], v[166:169], v[118:121], v[90:93]
	v_mfma_f32_16x16x32_bf16 v[86:89], v[174:177], v[98:101], v[86:89]
	v_mfma_f32_16x16x32_bf16 v[82:85], v[174:177], v[114:117], v[82:85]
	v_mfma_f32_16x16x32_bf16 v[78:81], v[182:185], v[98:101], v[78:81]
	v_mfma_f32_16x16x32_bf16 v[74:77], v[182:185], v[114:117], v[74:77]
	v_mfma_f32_16x16x32_bf16 v[70:73], v[194:197], v[102:105], v[70:73]
	v_mfma_f32_16x16x32_bf16 v[66:69], v[194:197], v[118:121], v[66:69]
	v_mfma_f32_16x16x32_bf16 v[142:145], v[178:181], v[102:105], v[86:89]
	v_mfma_f32_16x16x32_bf16 v[162:165], v[178:181], v[118:121], v[82:85]
	v_mfma_f32_16x16x32_bf16 v[166:169], v[186:189], v[102:105], v[78:81]
	v_mfma_f32_16x16x32_bf16 v[174:177], v[186:189], v[118:121], v[74:77]
	s_setprio 0
	s_barrier
	s_nop 0
	ds_read_b128 v[74:77], v138 offset:16384
	ds_read_b128 v[78:81], v138 offset:17408
	ds_read_b128 v[82:85], v137 offset:16384
	ds_read_b128 v[86:89], v137 offset:17408
	ds_read_b128 v[178:181], v136 offset:16384
	ds_read_b128 v[182:185], v136 offset:17408
	ds_read_b128 v[186:189], v135 offset:16384
	ds_read_b128 v[190:193], v135 offset:17408
	s_waitcnt vmcnt(4)
	s_barrier
	s_waitcnt lgkmcnt(0)
	s_setprio 1
	s_waitcnt lgkmcnt(0)
	v_mfma_f32_16x16x32_bf16 v[62:65], v[74:77], v[146:149], v[62:65]
	v_mfma_f32_16x16x32_bf16 v[58:61], v[74:77], v[154:157], v[58:61]
	v_mfma_f32_16x16x32_bf16 v[54:57], v[82:85], v[146:149], v[54:57]
	v_mfma_f32_16x16x32_bf16 v[50:53], v[82:85], v[154:157], v[50:53]
	v_mfma_f32_16x16x32_bf16 v[38:41], v[186:189], v[146:149], v[38:41]
	v_mfma_f32_16x16x32_bf16 v[34:37], v[186:189], v[154:157], v[34:37]
	v_mfma_f32_16x16x32_bf16 v[62:65], v[78:81], v[150:153], v[62:65]
	v_mfma_f32_16x16x32_bf16 v[58:61], v[78:81], v[158:161], v[58:61]
	v_mfma_f32_16x16x32_bf16 v[54:57], v[86:89], v[150:153], v[54:57]
	v_mfma_f32_16x16x32_bf16 v[50:53], v[86:89], v[158:161], v[50:53]
	v_mfma_f32_16x16x32_bf16 v[46:49], v[178:181], v[146:149], v[46:49]
	v_mfma_f32_16x16x32_bf16 v[42:45], v[178:181], v[154:157], v[42:45]
	v_mfma_f32_16x16x32_bf16 v[38:41], v[190:193], v[150:153], v[38:41]
	v_mfma_f32_16x16x32_bf16 v[34:37], v[190:193], v[158:161], v[34:37]
	v_mfma_f32_16x16x32_bf16 v[194:197], v[182:185], v[150:153], v[46:49]
	v_mfma_f32_16x16x32_bf16 v[214:217], v[182:185], v[158:161], v[42:45]
	s_setprio 0
	s_setprio 1
	v_mfma_f32_16x16x32_bf16 v[22:25], v[82:85], v[98:101], v[22:25]
	v_mfma_f32_16x16x32_bf16 v[18:21], v[82:85], v[114:117], v[18:21]
	v_mfma_f32_16x16x32_bf16 v[14:17], v[178:181], v[98:101], v[14:17]
	v_mfma_f32_16x16x32_bf16 v[10:13], v[178:181], v[114:117], v[10:13]
	v_mfma_f32_16x16x32_bf16 v[30:33], v[74:77], v[98:101], v[30:33]
	v_mfma_f32_16x16x32_bf16 v[26:29], v[74:77], v[114:117], v[26:29]
	v_mfma_f32_16x16x32_bf16 v[22:25], v[86:89], v[102:105], v[22:25]
	v_mfma_f32_16x16x32_bf16 v[18:21], v[86:89], v[118:121], v[18:21]
	v_mfma_f32_16x16x32_bf16 v[14:17], v[182:185], v[102:105], v[14:17]
	v_mfma_f32_16x16x32_bf16 v[10:13], v[182:185], v[118:121], v[10:13]
	v_mfma_f32_16x16x32_bf16 v[6:9], v[186:189], v[98:101], v[6:9]
	v_mfma_f32_16x16x32_bf16 v[2:5], v[186:189], v[114:117], v[2:5]
	v_mfma_f32_16x16x32_bf16 v[146:149], v[78:81], v[102:105], v[30:33]
	v_mfma_f32_16x16x32_bf16 v[150:153], v[78:81], v[118:121], v[26:29]
	v_mfma_f32_16x16x32_bf16 v[154:157], v[190:193], v[102:105], v[6:9]
	v_mfma_f32_16x16x32_bf16 v[158:161], v[190:193], v[118:121], v[2:5]
	s_setprio 0
	s_barrier
	s_nop 1
	ds_read_b128 v[2:5], v140
	ds_read_b128 v[6:9], v140 offset:1024
	ds_read_b128 v[178:181], v140 offset:2048
	ds_read_b128 v[182:185], v140 offset:3072
	ds_read_b128 v[26:29], v138 offset:32768
	ds_read_b128 v[30:33], v138 offset:33792
	ds_read_b128 v[42:45], v137 offset:32768
	ds_read_b128 v[46:49], v137 offset:33792
	ds_read_b128 v[186:189], v136 offset:32768
	ds_read_b128 v[190:193], v136 offset:33792
	ds_read_b128 v[218:221], v135 offset:32768
	ds_read_b128 v[222:225], v135 offset:33792
	s_waitcnt vmcnt(2)
	s_barrier
; #define WAIT_V(n) asm volatile("s_waitcnt vmcnt(" #n ")" ::: "memory")
; #define WAIT_L(n) asm volatile("s_waitcnt lgkmcnt(" #n ")" ::: "memory")
; #define BAR __builtin_amdgcn_s_barrier()
; #define LDA(dst, b, h) for (int m = 0; m < 4; ++m) for (int k = 0; k < 2; ++k) \
;     dst[m][k] = *reinterpret_cast<const bf16x8*>((char*)SA(b, h) + lds_byte(wr * 64 + m * 16 + fr, k * 32 + fq * 8))
; #define LDB(dst, b, h) for (int n = 0; n < 2; ++n) for (int k = 0; k < 2; ++k) \
;     dst[n][k] = *reinterpret_cast<const bf16x8*>((char*)SB(b, h) + lds_byte(wc * 32 + n * 16 + fr, k * 32 + fq * 8))
; #define MMA(ai, bj, At_, Bt_) do { __builtin_amdgcn_s_setprio(1); \
;     for (int m = 0; m < 4; ++m) for (int n = 0; n < 2; ++n) for (int k = 0; k < 2; ++k) \
;       acc[ai][bj][m][n] = __builtin_amdgcn_mfma_f32_16x16x32_bf16(At_[m][k], Bt_[n][k], acc[ai][bj][m][n], 0, 0, 0); \
;     __builtin_amdgcn_s_setprio(0); } while (0)
; template <int K, int LD = K>
; __device__ __forceinline__ void gemm_main(const GAS bf16* A, const GAS bf16* Bt, int brow, int bcol, f32x4 (&acc)[2][2][4][2]) {
;     ...
;   { LDB(B0, 1, 0); LDA(At, 1, 0); WAIT_V(2); BAR; WAIT_L(0); MMA(0, 0, At, B0); BAR;
;     LDB(B1, 1, 1); WAIT_V(0); BAR; WAIT_L(0); MMA(0, 1, At, B1); BAR;
;     LDA(At, 1, 1); BAR; WAIT_L(0); MMA(1, 0, At, B0); MMA(1, 1, At, B1); BAR; }
;   if (wr == 0) BAR;
	s_waitcnt lgkmcnt(0)
	s_setprio 1
	s_waitcnt lgkmcnt(0)
	v_mfma_f32_16x16x32_bf16 v[74:77], v[26:29], v[2:5], v[126:129]
	v_mfma_f32_16x16x32_bf16 v[118:121], v[30:33], v[6:9], v[74:77]
	v_mfma_f32_16x16x32_bf16 v[74:77], v[26:29], v[178:181], v[122:125]
	v_mfma_f32_16x16x32_bf16 v[114:117], v[30:33], v[182:185], v[74:77]
	v_mfma_f32_16x16x32_bf16 v[74:77], v[42:45], v[2:5], v[198:201]
	v_mfma_f32_16x16x32_bf16 v[102:105], v[46:49], v[6:9], v[74:77]
	v_mfma_f32_16x16x32_bf16 v[74:77], v[42:45], v[178:181], v[202:205]
	v_mfma_f32_16x16x32_bf16 v[98:101], v[46:49], v[182:185], v[74:77]
	v_mfma_f32_16x16x32_bf16 v[74:77], v[186:189], v[2:5], v[110:113]
	v_mfma_f32_16x16x32_bf16 v[86:89], v[190:193], v[6:9], v[74:77]
	v_mfma_f32_16x16x32_bf16 v[74:77], v[186:189], v[178:181], v[106:109]
	v_mfma_f32_16x16x32_bf16 v[82:85], v[190:193], v[182:185], v[74:77]
	v_mfma_f32_16x16x32_bf16 v[74:77], v[218:221], v[2:5], v[206:209]
	v_mfma_f32_16x16x32_bf16 v[78:81], v[222:225], v[6:9], v[74:77]
	v_mfma_f32_16x16x32_bf16 v[74:77], v[218:221], v[178:181], v[210:213]
	v_mfma_f32_16x16x32_bf16 v[74:77], v[222:225], v[182:185], v[74:77]
	s_setprio 0
	s_barrier
	ds_read_b128 v[198:201], v139
	ds_read_b128 v[202:205], v139 offset:1024
	ds_read_b128 v[206:209], v139 offset:2048
	ds_read_b128 v[210:213], v139 offset:3072
	s_waitcnt vmcnt(0)
	s_barrier
	s_waitcnt lgkmcnt(0)
	s_setprio 1
	s_waitcnt lgkmcnt(0)
	v_mfma_f32_16x16x32_bf16 v[94:97], v[26:29], v[198:201], v[94:97]
	v_mfma_f32_16x16x32_bf16 v[26:29], v[26:29], v[206:209], v[90:93]
	v_mfma_f32_16x16x32_bf16 v[122:125], v[30:33], v[210:213], v[26:29]
	v_mfma_f32_16x16x32_bf16 v[26:29], v[42:45], v[198:201], v[142:145]
	v_mfma_f32_16x16x32_bf16 v[110:113], v[46:49], v[202:205], v[26:29]
	v_mfma_f32_16x16x32_bf16 v[26:29], v[42:45], v[206:209], v[162:165]
	v_mfma_f32_16x16x32_bf16 v[106:109], v[46:49], v[210:213], v[26:29]
	v_mfma_f32_16x16x32_bf16 v[26:29], v[186:189], v[198:201], v[166:169]
	v_mfma_f32_16x16x32_bf16 v[126:129], v[30:33], v[202:205], v[94:97]
	v_mfma_f32_16x16x32_bf16 v[94:97], v[190:193], v[202:205], v[26:29]
	v_mfma_f32_16x16x32_bf16 v[26:29], v[186:189], v[206:209], v[174:177]
	v_mfma_f32_16x16x32_bf16 v[90:93], v[190:193], v[210:213], v[26:29]
	v_mfma_f32_16x16x32_bf16 v[26:29], v[218:221], v[198:201], v[70:73]
	v_mfma_f32_16x16x32_bf16 v[70:73], v[222:225], v[202:205], v[26:29]
	v_mfma_f32_16x16x32_bf16 v[26:29], v[218:221], v[206:209], v[66:69]
	v_mfma_f32_16x16x32_bf16 v[66:69], v[222:225], v[210:213], v[26:29]
	s_setprio 0
	s_barrier
	ds_read_b128 v[140:143], v138 offset:49152
	ds_read_b128 v[162:165], v138 offset:50176
	ds_read_b128 v[166:169], v137 offset:49152
	ds_read_b128 v[174:177], v137 offset:50176
	ds_read_b128 v[186:189], v136 offset:49152
	ds_read_b128 v[136:139], v136 offset:50176
	ds_read_b128 v[190:193], v135 offset:49152
	ds_read_b128 v[218:221], v135 offset:50176
	s_barrier
	s_waitcnt lgkmcnt(0)
	s_setprio 1
	s_waitcnt lgkmcnt(0)
	v_mfma_f32_16x16x32_bf16 v[26:29], v[140:143], v[2:5], v[62:65]
	v_mfma_f32_16x16x32_bf16 v[62:65], v[162:165], v[6:9], v[26:29]
	v_mfma_f32_16x16x32_bf16 v[26:29], v[140:143], v[178:181], v[58:61]
	v_mfma_f32_16x16x32_bf16 v[58:61], v[162:165], v[182:185], v[26:29]
	v_mfma_f32_16x16x32_bf16 v[26:29], v[166:169], v[2:5], v[54:57]
	v_mfma_f32_16x16x32_bf16 v[46:49], v[174:177], v[6:9], v[26:29]
	v_mfma_f32_16x16x32_bf16 v[26:29], v[166:169], v[178:181], v[50:53]
	v_mfma_f32_16x16x32_bf16 v[42:45], v[174:177], v[182:185], v[26:29]
	v_mfma_f32_16x16x32_bf16 v[26:29], v[186:189], v[2:5], v[194:197]
	v_mfma_f32_16x16x32_bf16 v[2:5], v[190:193], v[2:5], v[38:41]
	v_mfma_f32_16x16x32_bf16 v[30:33], v[136:139], v[6:9], v[26:29]
	v_mfma_f32_16x16x32_bf16 v[26:29], v[186:189], v[178:181], v[214:217]
	v_mfma_f32_16x16x32_bf16 v[6:9], v[218:221], v[6:9], v[2:5]
	v_mfma_f32_16x16x32_bf16 v[2:5], v[190:193], v[178:181], v[34:37]
	v_mfma_f32_16x16x32_bf16 v[26:29], v[136:139], v[182:185], v[26:29]
	v_mfma_f32_16x16x32_bf16 v[2:5], v[218:221], v[182:185], v[2:5]
	s_setprio 0
	s_setprio 1
	v_mfma_f32_16x16x32_bf16 v[34:37], v[140:143], v[198:201], v[146:149]
	v_mfma_f32_16x16x32_bf16 v[54:57], v[162:165], v[202:205], v[34:37]
	v_mfma_f32_16x16x32_bf16 v[34:37], v[140:143], v[206:209], v[150:153]
	v_mfma_f32_16x16x32_bf16 v[18:21], v[166:169], v[206:209], v[18:21]
	v_mfma_f32_16x16x32_bf16 v[10:13], v[186:189], v[206:209], v[10:13]
	v_mfma_f32_16x16x32_bf16 v[50:53], v[162:165], v[210:213], v[34:37]
	v_mfma_f32_16x16x32_bf16 v[22:25], v[166:169], v[198:201], v[22:25]
	v_mfma_f32_16x16x32_bf16 v[34:37], v[174:177], v[210:213], v[18:21]
	v_mfma_f32_16x16x32_bf16 v[14:17], v[186:189], v[198:201], v[14:17]
	v_mfma_f32_16x16x32_bf16 v[18:21], v[136:139], v[210:213], v[10:13]
	v_mfma_f32_16x16x32_bf16 v[10:13], v[190:193], v[198:201], v[154:157]
	v_mfma_f32_16x16x32_bf16 v[38:41], v[174:177], v[202:205], v[22:25]
	v_mfma_f32_16x16x32_bf16 v[22:25], v[136:139], v[202:205], v[14:17]
	v_mfma_f32_16x16x32_bf16 v[14:17], v[218:221], v[202:205], v[10:13]
	v_mfma_f32_16x16x32_bf16 v[10:13], v[190:193], v[206:209], v[158:161]
	v_mfma_f32_16x16x32_bf16 v[10:13], v[218:221], v[210:213], v[10:13]
	s_setprio 0
	v_cmp_gt_u32_e32 vcc, s51, v134
	s_barrier
	s_and_saveexec_b64 s[20:21], vcc
	s_cbranch_execz .LBB0_712
	s_barrier

; #define STAGE(P, GP, ktrel) do { const GAS char* _g = (GP) + (ktrel) * (BK * 2); \
;     __builtin_amdgcn_global_load_lds((const GAS unsigned*)(_g + so0), (unsigned*)((char*)(P) + tid_ * 16), 16, 0, 0); \
;     __builtin_amdgcn_global_load_lds((const GAS unsigned*)(_g + so1), (unsigned*)((char*)(P) + tid_ * 16 + 8192), 16, 0, 0); } while (0)
; #define WAIT_L(n) asm volatile("s_waitcnt lgkmcnt(" #n ")" ::: "memory")
; #define BAR __builtin_amdgcn_s_barrier()
; #define SCHED __builtin_amdgcn_sched_barrier(0)
; #define LDA(dst, b, h) for (int m = 0; m < 4; ++m) for (int k = 0; k < 2; ++k) \
;     dst[m][k] = *reinterpret_cast<const bf16x8*>((char*)SA(b, h) + lds_byte(wr * 64 + m * 16 + fr, k * 32 + fq * 8))
; #define LDB(dst, b, h) for (int n = 0; n < 2; ++n) for (int k = 0; k < 2; ++k) \
;     dst[n][k] = *reinterpret_cast<const bf16x8*>((char*)SB(b, h) + lds_byte(wc * 32 + n * 16 + fr, k * 32 + fq * 8))
; #define MMA(ai, bj, At_, Bt_) do { __builtin_amdgcn_s_setprio(1); \
;     for (int m = 0; m < 4; ++m) for (int n = 0; n < 2; ++n) for (int k = 0; k < 2; ++k) \
;       acc[ai][bj][m][n] = __builtin_amdgcn_mfma_f32_16x16x32_bf16(At_[m][k], Bt_[n][k], acc[ai][bj][m][n], 0, 0, 0); \
;     __builtin_amdgcn_s_setprio(0); } while (0)
; template <int K, int LD = K>
; __device__ __forceinline__ void gemm_main(const GAS bf16* A, const GAS bf16* Bt, int brow, int bcol, f32x4 (&acc)[2][2][4][2]) {
;     ...
;     LDB(B0, 0, 0); SCHED; LDA(At, 0, 0); STAGE(SA(1, 1), pA1, 1);
;     WAIT_L(8); BAR; WAIT_L(0); MMA(0, 0, At, B0); BAR; SCHED;
;     LDB(B1, 0, 1); STAGE(SB(0, 0), pB0, 2);
;     BAR; WAIT_L(0); MMA(0, 1, At, B1); BAR;
;     LDA(At, 0, 1); STAGE(SA(0, 0), pA0, 2);
;     BAR; WAIT_L(0); MMA(1, 0, At, B0); BAR; SCHED;
.LBB0_715:
	ds_read_b128 v[146:149], v143
	ds_read_b128 v[150:153], v143 offset:1024
	ds_read_b128 v[154:157], v143 offset:2048
	ds_read_b128 v[158:161], v143 offset:3072
	v_add_u32_e32 v230, 0x100, v141
	v_add_u32_e32 v144, 0xc000, v230
	v_lshl_add_u64 v[214:215], s[20:21], 0, v[130:131]
	v_readfirstlane_b32 s28, v144
	v_add_u32_e32 v145, 0xe000, v230
	v_lshl_add_u64 v[198:199], v[214:215], 0, s[6:7]
	s_mov_b32 m0, s28
	v_lshl_add_u64 v[216:217], s[20:21], 0, v[132:133]
	v_readfirstlane_b32 s28, v145
	ds_read_b128 v[162:165], v138
	ds_read_b128 v[166:169], v138 offset:1024
	ds_read_b128 v[174:177], v137
	ds_read_b128 v[178:181], v137 offset:1024
	ds_read_b128 v[182:185], v136
	ds_read_b128 v[186:189], v136 offset:1024
	ds_read_b128 v[190:193], v135
	ds_read_b128 v[194:197], v135 offset:1024
	global_load_lds_dwordx4 v[198:199], off
	v_lshl_add_u64 v[198:199], v[216:217], 0, s[6:7]
	s_mov_b32 m0, s28
	s_nop 0
	global_load_lds_dwordx4 v[198:199], off
	s_waitcnt lgkmcnt(8)
	s_waitcnt vmcnt(10)
	s_barrier
	s_waitcnt lgkmcnt(0)
	s_setprio 1
	s_waitcnt lgkmcnt(0)
	v_mfma_f32_16x16x32_bf16 v[126:129], v[162:165], v[146:149], v[126:129]
	v_mfma_f32_16x16x32_bf16 v[122:125], v[162:165], v[154:157], v[122:125]
	v_mfma_f32_16x16x32_bf16 v[118:121], v[174:177], v[146:149], v[118:121]
	v_mfma_f32_16x16x32_bf16 v[114:117], v[174:177], v[154:157], v[114:117]
	v_mfma_f32_16x16x32_bf16 v[110:113], v[182:185], v[146:149], v[110:113]
	v_mfma_f32_16x16x32_bf16 v[106:109], v[182:185], v[154:157], v[106:109]
	v_mfma_f32_16x16x32_bf16 v[102:105], v[190:193], v[146:149], v[102:105]
	v_mfma_f32_16x16x32_bf16 v[98:101], v[190:193], v[154:157], v[98:101]
	v_mfma_f32_16x16x32_bf16 v[126:129], v[166:169], v[150:153], v[126:129]
	v_mfma_f32_16x16x32_bf16 v[122:125], v[166:169], v[158:161], v[122:125]
	v_mfma_f32_16x16x32_bf16 v[118:121], v[178:181], v[150:153], v[118:121]
	v_mfma_f32_16x16x32_bf16 v[114:117], v[178:181], v[158:161], v[114:117]
	v_mfma_f32_16x16x32_bf16 v[110:113], v[186:189], v[150:153], v[110:113]
	v_mfma_f32_16x16x32_bf16 v[106:109], v[186:189], v[158:161], v[106:109]
	v_mfma_f32_16x16x32_bf16 v[102:105], v[194:197], v[150:153], v[102:105]
	v_mfma_f32_16x16x32_bf16 v[98:101], v[194:197], v[158:161], v[98:101]
	s_setprio 0
	s_barrier
	v_add_u32_e32 v224, s47, v141
	v_lshl_add_u64 v[218:219], s[26:27], 0, v[130:131]
	v_readfirstlane_b32 s28, v224
	v_lshl_add_u64 v[220:221], v[218:219], 0, s[10:11]
	s_mov_b32 m0, s28
	v_add_u32_e32 v224, 0x2000, v224
	ds_read_b128 v[198:201], v142
	ds_read_b128 v[202:205], v142 offset:1024
	ds_read_b128 v[206:209], v142 offset:2048
	ds_read_b128 v[210:213], v142 offset:3072
	global_load_lds_dwordx4 v[220:221], off
	v_lshl_add_u64 v[220:221], s[26:27], 0, v[132:133]
	v_readfirstlane_b32 s28, v224
	v_lshl_add_u64 v[222:223], v[220:221], 0, s[10:11]
	s_mov_b32 m0, s28
	s_add_u32 s26, s26, 0x100
	global_load_lds_dwordx4 v[222:223], off
	s_waitcnt vmcnt(10)
	s_barrier
	s_waitcnt lgkmcnt(0)
	s_addc_u32 s27, s27, 0
	s_setprio 1
	s_waitcnt lgkmcnt(0)
	v_mfma_f32_16x16x32_bf16 v[94:97], v[162:165], v[198:201], v[94:97]
	v_mfma_f32_16x16x32_bf16 v[90:93], v[162:165], v[206:209], v[90:93]
	v_mfma_f32_16x16x32_bf16 v[86:89], v[174:177], v[198:201], v[86:89]
	v_mfma_f32_16x16x32_bf16 v[82:85], v[174:177], v[206:209], v[82:85]
	v_mfma_f32_16x16x32_bf16 v[78:81], v[182:185], v[198:201], v[78:81]
	v_mfma_f32_16x16x32_bf16 v[74:77], v[182:185], v[206:209], v[74:77]
	v_mfma_f32_16x16x32_bf16 v[70:73], v[190:193], v[198:201], v[70:73]
	v_mfma_f32_16x16x32_bf16 v[66:69], v[190:193], v[206:209], v[66:69]
	v_mfma_f32_16x16x32_bf16 v[94:97], v[166:169], v[202:205], v[94:97]
	v_mfma_f32_16x16x32_bf16 v[90:93], v[166:169], v[210:213], v[90:93]
	v_mfma_f32_16x16x32_bf16 v[86:89], v[178:181], v[202:205], v[86:89]
	v_mfma_f32_16x16x32_bf16 v[82:85], v[178:181], v[210:213], v[82:85]
	v_mfma_f32_16x16x32_bf16 v[78:81], v[186:189], v[202:205], v[78:81]
	v_mfma_f32_16x16x32_bf16 v[74:77], v[186:189], v[210:213], v[74:77]
	v_mfma_f32_16x16x32_bf16 v[70:73], v[194:197], v[202:205], v[70:73]
	v_mfma_f32_16x16x32_bf16 v[66:69], v[194:197], v[210:213], v[66:69]
	s_setprio 0
	v_lshl_add_u64 v[222:223], s[24:25], 0, v[130:131]
	v_readfirstlane_b32 s28, v230
	v_lshl_add_u64 v[224:225], v[222:223], 0, s[10:11]
	s_mov_b32 m0, s28
	v_add_u32_e32 v228, 0x2000, v230
	s_barrier
	ds_read_b128 v[162:165], v138 offset:16384
	ds_read_b128 v[166:169], v138 offset:17408
	ds_read_b128 v[174:177], v137 offset:16384
	ds_read_b128 v[178:181], v137 offset:17408
	ds_read_b128 v[182:185], v136 offset:16384
	ds_read_b128 v[186:189], v136 offset:17408
	ds_read_b128 v[190:193], v135 offset:16384
	ds_read_b128 v[194:197], v135 offset:17408
	global_load_lds_dwordx4 v[224:225], off
	v_lshl_add_u64 v[224:225], s[24:25], 0, v[132:133]
	v_readfirstlane_b32 s28, v228
	v_lshl_add_u64 v[226:227], v[224:225], 0, s[10:11]
	s_mov_b32 m0, s28
	s_add_u32 s24, s24, 0x100
	global_load_lds_dwordx4 v[226:227], off
	s_barrier
	s_waitcnt lgkmcnt(0)
	s_addc_u32 s25, s25, 0
	s_setprio 1
	s_waitcnt lgkmcnt(0)
	v_mfma_f32_16x16x32_bf16 v[62:65], v[162:165], v[146:149], v[62:65]
	v_mfma_f32_16x16x32_bf16 v[58:61], v[162:165], v[154:157], v[58:61]
	v_mfma_f32_16x16x32_bf16 v[54:57], v[174:177], v[146:149], v[54:57]
	v_mfma_f32_16x16x32_bf16 v[50:53], v[174:177], v[154:157], v[50:53]
	v_mfma_f32_16x16x32_bf16 v[46:49], v[182:185], v[146:149], v[46:49]
	v_mfma_f32_16x16x32_bf16 v[42:45], v[182:185], v[154:157], v[42:45]
	v_mfma_f32_16x16x32_bf16 v[38:41], v[190:193], v[146:149], v[38:41]
	v_mfma_f32_16x16x32_bf16 v[34:37], v[190:193], v[154:157], v[34:37]
	v_mfma_f32_16x16x32_bf16 v[62:65], v[166:169], v[150:153], v[62:65]
	v_mfma_f32_16x16x32_bf16 v[58:61], v[166:169], v[158:161], v[58:61]
	v_mfma_f32_16x16x32_bf16 v[54:57], v[178:181], v[150:153], v[54:57]
	v_mfma_f32_16x16x32_bf16 v[50:53], v[178:181], v[158:161], v[50:53]
	v_mfma_f32_16x16x32_bf16 v[46:49], v[186:189], v[150:153], v[46:49]
	v_mfma_f32_16x16x32_bf16 v[42:45], v[186:189], v[158:161], v[42:45]
	v_mfma_f32_16x16x32_bf16 v[38:41], v[194:197], v[150:153], v[38:41]
	v_mfma_f32_16x16x32_bf16 v[34:37], v[194:197], v[158:161], v[34:37]
	s_setprio 0
	s_barrier
; #define STAGE(P, GP, ktrel) do { const GAS char* _g = (GP) + (ktrel) * (BK * 2); \
;     __builtin_amdgcn_global_load_lds((const GAS unsigned*)(_g + so0), (unsigned*)((char*)(P) + tid_ * 16), 16, 0, 0); \
;     __builtin_amdgcn_global_load_lds((const GAS unsigned*)(_g + so1), (unsigned*)((char*)(P) + tid_ * 16 + 8192), 16, 0, 0); } while (0)
; #define WAIT_V(n) asm volatile("s_waitcnt vmcnt(" #n ")" ::: "memory")
; #define WAIT_L(n) asm volatile("s_waitcnt lgkmcnt(" #n ")" ::: "memory")
; #define BAR __builtin_amdgcn_s_barrier()
; #define SCHED __builtin_amdgcn_sched_barrier(0)
; #define LDA(dst, b, h) for (int m = 0; m < 4; ++m) for (int k = 0; k < 2; ++k) \
;     dst[m][k] = *reinterpret_cast<const bf16x8*>((char*)SA(b, h) + lds_byte(wr * 64 + m * 16 + fr, k * 32 + fq * 8))
; #define LDB(dst, b, h) for (int n = 0; n < 2; ++n) for (int k = 0; k < 2; ++k) \
;     dst[n][k] = *reinterpret_cast<const bf16x8*>((char*)SB(b, h) + lds_byte(wc * 32 + n * 16 + fr, k * 32 + fq * 8))
; #define MMA(ai, bj, At_, Bt_) do { __builtin_amdgcn_s_setprio(1); \
;     for (int m = 0; m < 4; ++m) for (int n = 0; n < 2; ++n) for (int k = 0; k < 2; ++k) \
;       acc[ai][bj][m][n] = __builtin_amdgcn_mfma_f32_16x16x32_bf16(At_[m][k], Bt_[n][k], acc[ai][bj][m][n], 0, 0, 0); \
;     __builtin_amdgcn_s_setprio(0); } while (0)
; template <int K, int LD = K>
; __device__ __forceinline__ void gemm_main(const GAS bf16* A, const GAS bf16* Bt, int brow, int bcol, f32x4 (&acc)[2][2][4][2]) {
;     ...
;     STAGE(SB(0, 1), pB1, 2);
;     WAIT_V(6); BAR; MMA(1, 1, At, B1); BAR;
;     LDB(B0, 1, 0); SCHED; LDA(At, 1, 0); STAGE(SA(0, 1), pA1, 2);
;     WAIT_L(8); BAR; WAIT_L(0); MMA(0, 0, At, B0); BAR; SCHED;
;     LDB(B1, 1, 1); STAGE(SB(1, 0), pB0, 3);
;     BAR; WAIT_L(0); MMA(0, 1, At, B1); BAR;
	v_add_u32_e32 v148, s48, v141
	v_lshl_add_u64 v[226:227], s[22:23], 0, v[130:131]
	v_readfirstlane_b32 s28, v148
	v_add_u32_e32 v148, 0x2000, v148
	v_lshl_add_u64 v[146:147], v[226:227], 0, s[10:11]
	s_mov_b32 m0, s28
	v_lshl_add_u64 v[228:229], s[22:23], 0, v[132:133]
	v_readfirstlane_b32 s28, v148
	global_load_lds_dwordx4 v[146:147], off
	v_lshl_add_u64 v[146:147], v[228:229], 0, s[10:11]
	s_mov_b32 m0, s28
	s_add_u32 s22, s22, 0x100
	global_load_lds_dwordx4 v[146:147], off
	s_waitcnt vmcnt(10)
	s_addc_u32 s23, s23, 0
	s_barrier
	s_setprio 1
	v_mfma_f32_16x16x32_bf16 v[30:33], v[162:165], v[198:201], v[30:33]
	v_mfma_f32_16x16x32_bf16 v[26:29], v[162:165], v[206:209], v[26:29]
	v_mfma_f32_16x16x32_bf16 v[22:25], v[174:177], v[198:201], v[22:25]
	v_mfma_f32_16x16x32_bf16 v[18:21], v[174:177], v[206:209], v[18:21]
	v_mfma_f32_16x16x32_bf16 v[14:17], v[182:185], v[198:201], v[14:17]
	v_mfma_f32_16x16x32_bf16 v[10:13], v[182:185], v[206:209], v[10:13]
	v_mfma_f32_16x16x32_bf16 v[6:9], v[190:193], v[198:201], v[6:9]
	v_mfma_f32_16x16x32_bf16 v[2:5], v[190:193], v[206:209], v[2:5]
	v_mfma_f32_16x16x32_bf16 v[30:33], v[166:169], v[202:205], v[30:33]
	v_mfma_f32_16x16x32_bf16 v[26:29], v[166:169], v[210:213], v[26:29]
	v_mfma_f32_16x16x32_bf16 v[22:25], v[178:181], v[202:205], v[22:25]
	v_mfma_f32_16x16x32_bf16 v[18:21], v[178:181], v[210:213], v[18:21]
	v_mfma_f32_16x16x32_bf16 v[14:17], v[186:189], v[202:205], v[14:17]
	v_mfma_f32_16x16x32_bf16 v[10:13], v[186:189], v[210:213], v[10:13]
	v_mfma_f32_16x16x32_bf16 v[6:9], v[194:197], v[202:205], v[6:9]
	v_mfma_f32_16x16x32_bf16 v[2:5], v[194:197], v[210:213], v[2:5]
	s_setprio 0
	s_barrier
	ds_read_b128 v[146:149], v140
	ds_read_b128 v[150:153], v140 offset:1024
	ds_read_b128 v[154:157], v140 offset:2048
	ds_read_b128 v[158:161], v140 offset:3072
	v_add_u32_e32 v200, 0x4000, v230
	v_lshl_add_u64 v[198:199], v[214:215], 0, s[10:11]
	v_readfirstlane_b32 s28, v200
	v_add_u32_e32 v200, 0x6000, v230
	s_mov_b32 m0, s28
	v_readfirstlane_b32 s28, v200
	ds_read_b128 v[162:165], v138 offset:32768
	ds_read_b128 v[166:169], v138 offset:33792
	ds_read_b128 v[174:177], v137 offset:32768
	ds_read_b128 v[178:181], v137 offset:33792
	ds_read_b128 v[182:185], v136 offset:32768
	ds_read_b128 v[186:189], v136 offset:33792
	ds_read_b128 v[190:193], v135 offset:32768
	ds_read_b128 v[194:197], v135 offset:33792
	global_load_lds_dwordx4 v[198:199], off
	v_lshl_add_u64 v[198:199], v[216:217], 0, s[10:11]
	s_mov_b32 m0, s28
	s_add_u32 s20, s20, 0x100
	global_load_lds_dwordx4 v[198:199], off
	s_waitcnt lgkmcnt(8)
	s_waitcnt vmcnt(10)
	s_barrier
	s_waitcnt lgkmcnt(0)
	s_addc_u32 s21, s21, 0
	s_setprio 1
	s_waitcnt lgkmcnt(0)
	v_mfma_f32_16x16x32_bf16 v[126:129], v[162:165], v[146:149], v[126:129]
	v_mfma_f32_16x16x32_bf16 v[122:125], v[162:165], v[154:157], v[122:125]
	v_mfma_f32_16x16x32_bf16 v[118:121], v[174:177], v[146:149], v[118:121]
	v_mfma_f32_16x16x32_bf16 v[114:117], v[174:177], v[154:157], v[114:117]
	v_mfma_f32_16x16x32_bf16 v[110:113], v[182:185], v[146:149], v[110:113]
	v_mfma_f32_16x16x32_bf16 v[106:109], v[182:185], v[154:157], v[106:109]
	v_mfma_f32_16x16x32_bf16 v[102:105], v[190:193], v[146:149], v[102:105]
	v_mfma_f32_16x16x32_bf16 v[98:101], v[190:193], v[154:157], v[98:101]
	v_mfma_f32_16x16x32_bf16 v[126:129], v[166:169], v[150:153], v[126:129]
	v_mfma_f32_16x16x32_bf16 v[122:125], v[166:169], v[158:161], v[122:125]
	v_mfma_f32_16x16x32_bf16 v[118:121], v[178:181], v[150:153], v[118:121]
	v_mfma_f32_16x16x32_bf16 v[114:117], v[178:181], v[158:161], v[114:117]
	v_mfma_f32_16x16x32_bf16 v[110:113], v[186:189], v[150:153], v[110:113]
	v_mfma_f32_16x16x32_bf16 v[106:109], v[186:189], v[158:161], v[106:109]
	v_mfma_f32_16x16x32_bf16 v[102:105], v[194:197], v[150:153], v[102:105]
	v_mfma_f32_16x16x32_bf16 v[98:101], v[194:197], v[158:161], v[98:101]
	s_setprio 0
	s_barrier
	v_add_u32_e32 v216, s49, v141
	v_lshl_add_u64 v[214:215], v[218:219], 0, s[12:13]
	v_readfirstlane_b32 s28, v216
	v_add_u32_e32 v216, 0x2000, v216
	s_mov_b32 m0, s28
	v_readfirstlane_b32 s28, v216
	ds_read_b128 v[198:201], v139
	ds_read_b128 v[202:205], v139 offset:1024
	ds_read_b128 v[206:209], v139 offset:2048
	ds_read_b128 v[210:213], v139 offset:3072
	global_load_lds_dwordx4 v[214:215], off
	v_lshl_add_u64 v[214:215], v[220:221], 0, s[12:13]
	s_mov_b32 m0, s28
	s_nop 0
	global_load_lds_dwordx4 v[214:215], off
	s_waitcnt vmcnt(10)
	s_barrier
	s_waitcnt lgkmcnt(0)
	s_setprio 1
	s_waitcnt lgkmcnt(0)
	v_mfma_f32_16x16x32_bf16 v[94:97], v[162:165], v[198:201], v[94:97]
	v_mfma_f32_16x16x32_bf16 v[90:93], v[162:165], v[206:209], v[90:93]
	v_mfma_f32_16x16x32_bf16 v[86:89], v[174:177], v[198:201], v[86:89]
	v_mfma_f32_16x16x32_bf16 v[82:85], v[174:177], v[206:209], v[82:85]
	v_mfma_f32_16x16x32_bf16 v[78:81], v[182:185], v[198:201], v[78:81]
	v_mfma_f32_16x16x32_bf16 v[74:77], v[182:185], v[206:209], v[74:77]
	v_mfma_f32_16x16x32_bf16 v[70:73], v[190:193], v[198:201], v[70:73]
	v_mfma_f32_16x16x32_bf16 v[66:69], v[190:193], v[206:209], v[66:69]
	v_mfma_f32_16x16x32_bf16 v[94:97], v[166:169], v[202:205], v[94:97]
	v_mfma_f32_16x16x32_bf16 v[90:93], v[166:169], v[210:213], v[90:93]
	v_mfma_f32_16x16x32_bf16 v[86:89], v[178:181], v[202:205], v[86:89]
	v_mfma_f32_16x16x32_bf16 v[82:85], v[178:181], v[210:213], v[82:85]
	v_mfma_f32_16x16x32_bf16 v[78:81], v[186:189], v[202:205], v[78:81]
	v_mfma_f32_16x16x32_bf16 v[74:77], v[186:189], v[210:213], v[74:77]
	v_mfma_f32_16x16x32_bf16 v[70:73], v[194:197], v[202:205], v[70:73]
	v_mfma_f32_16x16x32_bf16 v[66:69], v[194:197], v[210:213], v[66:69]
	s_setprio 0
	v_add_u32_e32 v216, 0x8000, v230
	v_lshl_add_u64 v[214:215], v[222:223], 0, s[12:13]
	v_readfirstlane_b32 s28, v216
	v_add_u32_e32 v216, 0xa000, v230
	s_mov_b32 m0, s28
	v_readfirstlane_b32 s28, v216
	s_barrier
; #define STAGE(P, GP, ktrel) do { const GAS char* _g = (GP) + (ktrel) * (BK * 2); \
;     __builtin_amdgcn_global_load_lds((const GAS unsigned*)(_g + so0), (unsigned*)((char*)(P) + tid_ * 16), 16, 0, 0); \
;     __builtin_amdgcn_global_load_lds((const GAS unsigned*)(_g + so1), (unsigned*)((char*)(P) + tid_ * 16 + 8192), 16, 0, 0); } while (0)
; #define WAIT_V(n) asm volatile("s_waitcnt vmcnt(" #n ")" ::: "memory")
; #define WAIT_L(n) asm volatile("s_waitcnt lgkmcnt(" #n ")" ::: "memory")
; #define BAR __builtin_amdgcn_s_barrier()
; #define SCHED __builtin_amdgcn_sched_barrier(0)
; #define LDA(dst, b, h) for (int m = 0; m < 4; ++m) for (int k = 0; k < 2; ++k) \
;     dst[m][k] = *reinterpret_cast<const bf16x8*>((char*)SA(b, h) + lds_byte(wr * 64 + m * 16 + fr, k * 32 + fq * 8))
; #define LDB(dst, b, h) for (int n = 0; n < 2; ++n) for (int k = 0; k < 2; ++k) \
;     dst[n][k] = *reinterpret_cast<const bf16x8*>((char*)SB(b, h) + lds_byte(wc * 32 + n * 16 + fr, k * 32 + fq * 8))
; #define MMA(ai, bj, At_, Bt_) do { __builtin_amdgcn_s_setprio(1); \
;     for (int m = 0; m < 4; ++m) for (int n = 0; n < 2; ++n) for (int k = 0; k < 2; ++k) \
;       acc[ai][bj][m][n] = __builtin_amdgcn_mfma_f32_16x16x32_bf16(At_[m][k], Bt_[n][k], acc[ai][bj][m][n], 0, 0, 0); \
;     __builtin_amdgcn_s_setprio(0); } while (0)
; template <int K, int LD = K>
; __device__ __forceinline__ void gemm_main(const GAS bf16* A, const GAS bf16* Bt, int brow, int bcol, f32x4 (&acc)[2][2][4][2]) {
;     ...
;     LDA(At, 1, 1); STAGE(SA(1, 0), pA0, 3);
;     BAR; WAIT_L(0); MMA(1, 0, At, B0); BAR; SCHED;
;     STAGE(SB(1, 1), pB1, 3);
;     WAIT_V(6); BAR; MMA(1, 1, At, B1); BAR;
;     pA0 += 4 * BK; pA1 += 4 * BK; pB0 += 4 * BK; pB1 += 4 * BK;
;     asm volatile("" : "+s"(pA0), "+s"(pA1), "+s"(pB0), "+s"(pB1));
;   }
;   { LDB(B0, 0, 0); LDA(At, 0, 0); STAGE(SA(1, 1), pA1, 1);
;     BAR; WAIT_L(0); MMA(0, 0, At, B0); BAR;
;     LDB(B1, 0, 1); BAR; WAIT_L(0); MMA(0, 1, At, B1); BAR;
	ds_read_b128 v[162:165], v138 offset:49152
	ds_read_b128 v[166:169], v138 offset:50176
	ds_read_b128 v[174:177], v137 offset:49152
	ds_read_b128 v[178:181], v137 offset:50176
	ds_read_b128 v[182:185], v136 offset:49152
	ds_read_b128 v[186:189], v136 offset:50176
	ds_read_b128 v[190:193], v135 offset:49152
	ds_read_b128 v[194:197], v135 offset:50176
	global_load_lds_dwordx4 v[214:215], off
	v_lshl_add_u64 v[214:215], v[224:225], 0, s[12:13]
	s_mov_b32 m0, s28
	s_nop 0
	global_load_lds_dwordx4 v[214:215], off
	s_barrier
	s_waitcnt lgkmcnt(0)
	s_setprio 1
	s_waitcnt lgkmcnt(0)
	v_mfma_f32_16x16x32_bf16 v[62:65], v[162:165], v[146:149], v[62:65]
	v_mfma_f32_16x16x32_bf16 v[58:61], v[162:165], v[154:157], v[58:61]
	v_mfma_f32_16x16x32_bf16 v[54:57], v[174:177], v[146:149], v[54:57]
	v_mfma_f32_16x16x32_bf16 v[50:53], v[174:177], v[154:157], v[50:53]
	v_mfma_f32_16x16x32_bf16 v[46:49], v[182:185], v[146:149], v[46:49]
	v_mfma_f32_16x16x32_bf16 v[42:45], v[182:185], v[154:157], v[42:45]
	v_mfma_f32_16x16x32_bf16 v[38:41], v[190:193], v[146:149], v[38:41]
	v_mfma_f32_16x16x32_bf16 v[34:37], v[190:193], v[154:157], v[34:37]
	v_mfma_f32_16x16x32_bf16 v[62:65], v[166:169], v[150:153], v[62:65]
	v_mfma_f32_16x16x32_bf16 v[58:61], v[166:169], v[158:161], v[58:61]
	v_mfma_f32_16x16x32_bf16 v[54:57], v[178:181], v[150:153], v[54:57]
	v_mfma_f32_16x16x32_bf16 v[50:53], v[178:181], v[158:161], v[50:53]
	v_mfma_f32_16x16x32_bf16 v[46:49], v[186:189], v[150:153], v[46:49]
	v_mfma_f32_16x16x32_bf16 v[42:45], v[186:189], v[158:161], v[42:45]
	v_mfma_f32_16x16x32_bf16 v[38:41], v[194:197], v[150:153], v[38:41]
	v_mfma_f32_16x16x32_bf16 v[34:37], v[194:197], v[158:161], v[34:37]
	s_setprio 0
	s_barrier
	v_add_u32_e32 v148, s50, v141
	v_lshl_add_u64 v[146:147], v[226:227], 0, s[12:13]
	v_readfirstlane_b32 s28, v148
	v_add_u32_e32 v148, 0x2000, v148
	s_mov_b32 m0, s28
	v_readfirstlane_b32 s28, v148
	global_load_lds_dwordx4 v[146:147], off
	v_lshl_add_u64 v[146:147], v[228:229], 0, s[12:13]
	s_mov_b32 m0, s28
	s_nop 0
	global_load_lds_dwordx4 v[146:147], off
	s_waitcnt vmcnt(10)
	s_barrier
	s_setprio 1
	v_mfma_f32_16x16x32_bf16 v[30:33], v[162:165], v[198:201], v[30:33]
	v_mfma_f32_16x16x32_bf16 v[26:29], v[162:165], v[206:209], v[26:29]
	v_mfma_f32_16x16x32_bf16 v[22:25], v[174:177], v[198:201], v[22:25]
	v_mfma_f32_16x16x32_bf16 v[18:21], v[174:177], v[206:209], v[18:21]
	v_mfma_f32_16x16x32_bf16 v[14:17], v[182:185], v[198:201], v[14:17]
	v_mfma_f32_16x16x32_bf16 v[10:13], v[182:185], v[206:209], v[10:13]
	v_mfma_f32_16x16x32_bf16 v[6:9], v[190:193], v[198:201], v[6:9]
	v_mfma_f32_16x16x32_bf16 v[2:5], v[190:193], v[206:209], v[2:5]
	v_mfma_f32_16x16x32_bf16 v[30:33], v[166:169], v[202:205], v[30:33]
	v_mfma_f32_16x16x32_bf16 v[26:29], v[166:169], v[210:213], v[26:29]
	v_mfma_f32_16x16x32_bf16 v[22:25], v[178:181], v[202:205], v[22:25]
	v_mfma_f32_16x16x32_bf16 v[18:21], v[178:181], v[210:213], v[18:21]
	v_mfma_f32_16x16x32_bf16 v[14:17], v[186:189], v[202:205], v[14:17]
	v_mfma_f32_16x16x32_bf16 v[10:13], v[186:189], v[210:213], v[10:13]
	v_mfma_f32_16x16x32_bf16 v[6:9], v[194:197], v[202:205], v[6:9]
	v_mfma_f32_16x16x32_bf16 v[2:5], v[194:197], v[210:213], v[2:5]
	s_setprio 0
	s_add_i32 s17, s17, 2
	s_cmp_lt_u32 s17, 4
	s_barrier
	s_cbranch_scc1 .LBB0_715
	v_lshl_add_u64 v[198:199], s[20:21], 0, v[130:131]
	v_readfirstlane_b32 s17, v144
	v_lshl_add_u64 v[198:199], v[198:199], 0, s[6:7]
	s_mov_b32 m0, s17
	v_lshl_add_u64 v[132:133], s[20:21], 0, v[132:133]
	v_readfirstlane_b32 s17, v145
	ds_read_b128 v[146:149], v143
	ds_read_b128 v[150:153], v143 offset:1024
	ds_read_b128 v[154:157], v143 offset:2048
	ds_read_b128 v[158:161], v143 offset:3072
	ds_read_b128 v[162:165], v138
	ds_read_b128 v[166:169], v138 offset:1024
	ds_read_b128 v[174:177], v137
	ds_read_b128 v[178:181], v137 offset:1024
	ds_read_b128 v[182:185], v136
	ds_read_b128 v[186:189], v136 offset:1024
	ds_read_b128 v[190:193], v135
	ds_read_b128 v[194:197], v135 offset:1024
	global_load_lds_dwordx4 v[198:199], off
	v_lshl_add_u64 v[132:133], v[132:133], 0, s[6:7]
	s_mov_b32 m0, s17
	s_nop 0
	global_load_lds_dwordx4 v[132:133], off
	s_waitcnt vmcnt(10)
	s_barrier
	s_waitcnt lgkmcnt(0)
	s_setprio 1
	s_waitcnt lgkmcnt(0)
	v_mfma_f32_16x16x32_bf16 v[126:129], v[162:165], v[146:149], v[126:129]
	v_mfma_f32_16x16x32_bf16 v[122:125], v[162:165], v[154:157], v[122:125]
	v_mfma_f32_16x16x32_bf16 v[110:113], v[182:185], v[146:149], v[110:113]
	v_mfma_f32_16x16x32_bf16 v[106:109], v[182:185], v[154:157], v[106:109]
	v_mfma_f32_16x16x32_bf16 v[126:129], v[166:169], v[150:153], v[126:129]
	v_mfma_f32_16x16x32_bf16 v[122:125], v[166:169], v[158:161], v[122:125]
	v_mfma_f32_16x16x32_bf16 v[118:121], v[174:177], v[146:149], v[118:121]
	v_mfma_f32_16x16x32_bf16 v[114:117], v[174:177], v[154:157], v[114:117]
	v_mfma_f32_16x16x32_bf16 v[110:113], v[186:189], v[150:153], v[110:113]
	v_mfma_f32_16x16x32_bf16 v[106:109], v[186:189], v[158:161], v[106:109]
	v_mfma_f32_16x16x32_bf16 v[102:105], v[190:193], v[146:149], v[102:105]
	v_mfma_f32_16x16x32_bf16 v[98:101], v[190:193], v[154:157], v[98:101]
	v_mfma_f32_16x16x32_bf16 v[198:201], v[178:181], v[150:153], v[118:121]
	v_mfma_f32_16x16x32_bf16 v[202:205], v[178:181], v[158:161], v[114:117]
	v_mfma_f32_16x16x32_bf16 v[206:209], v[194:197], v[150:153], v[102:105]
	v_mfma_f32_16x16x32_bf16 v[210:213], v[194:197], v[158:161], v[98:101]
	s_setprio 0
	s_barrier
	s_nop 1
	ds_read_b128 v[98:101], v142
	ds_read_b128 v[102:105], v142 offset:1024
	ds_read_b128 v[114:117], v142 offset:2048
	ds_read_b128 v[118:121], v142 offset:3072
	s_waitcnt vmcnt(8)
	s_barrier
; #define WAIT_V(n) asm volatile("s_waitcnt vmcnt(" #n ")" ::: "memory")
; #define WAIT_L(n) asm volatile("s_waitcnt lgkmcnt(" #n ")" ::: "memory")
; #define BAR __builtin_amdgcn_s_barrier()
; #define LDA(dst, b, h) for (int m = 0; m < 4; ++m) for (int k = 0; k < 2; ++k) \
;     dst[m][k] = *reinterpret_cast<const bf16x8*>((char*)SA(b, h) + lds_byte(wr * 64 + m * 16 + fr, k * 32 + fq * 8))
; #define LDB(dst, b, h) for (int n = 0; n < 2; ++n) for (int k = 0; k < 2; ++k) \
;     dst[n][k] = *reinterpret_cast<const bf16x8*>((char*)SB(b, h) + lds_byte(wc * 32 + n * 16 + fr, k * 32 + fq * 8))
; #define MMA(ai, bj, At_, Bt_) do { __builtin_amdgcn_s_setprio(1); \
;     for (int m = 0; m < 4; ++m) for (int n = 0; n < 2; ++n) for (int k = 0; k < 2; ++k) \
;       acc[ai][bj][m][n] = __builtin_amdgcn_mfma_f32_16x16x32_bf16(At_[m][k], Bt_[n][k], acc[ai][bj][m][n], 0, 0, 0); \
;     __builtin_amdgcn_s_setprio(0); } while (0)
; template <int K, int LD = K>
; __device__ __forceinline__ void gemm_main(const GAS bf16* A, const GAS bf16* Bt, int brow, int bcol, f32x4 (&acc)[2][2][4][2]) {
;     ...
;     LDB(B1, 0, 1); BAR; WAIT_L(0); MMA(0, 1, At, B1); BAR;
;     LDA(At, 0, 1); WAIT_V(4); BAR; WAIT_L(0); MMA(1, 0, At, B0); MMA(1, 1, At, B1); BAR; }
;   { LDB(B0, 1, 0); LDA(At, 1, 0); WAIT_V(2); BAR; WAIT_L(0); MMA(0, 0, At, B0); BAR;
	s_waitcnt lgkmcnt(0)
	s_setprio 1
	s_waitcnt lgkmcnt(0)
	v_mfma_f32_16x16x32_bf16 v[94:97], v[162:165], v[98:101], v[94:97]
	v_mfma_f32_16x16x32_bf16 v[90:93], v[162:165], v[114:117], v[90:93]
	v_mfma_f32_16x16x32_bf16 v[78:81], v[182:185], v[98:101], v[78:81]
	v_mfma_f32_16x16x32_bf16 v[74:77], v[182:185], v[114:117], v[74:77]
	v_mfma_f32_16x16x32_bf16 v[94:97], v[166:169], v[102:105], v[94:97]
	v_mfma_f32_16x16x32_bf16 v[90:93], v[166:169], v[118:121], v[90:93]
	v_mfma_f32_16x16x32_bf16 v[86:89], v[174:177], v[98:101], v[86:89]
	v_mfma_f32_16x16x32_bf16 v[82:85], v[174:177], v[114:117], v[82:85]
	v_mfma_f32_16x16x32_bf16 v[78:81], v[186:189], v[102:105], v[78:81]
	v_mfma_f32_16x16x32_bf16 v[74:77], v[186:189], v[118:121], v[74:77]
	v_mfma_f32_16x16x32_bf16 v[70:73], v[190:193], v[98:101], v[70:73]
	v_mfma_f32_16x16x32_bf16 v[66:69], v[190:193], v[114:117], v[66:69]
	v_mfma_f32_16x16x32_bf16 v[142:145], v[178:181], v[102:105], v[86:89]
	v_mfma_f32_16x16x32_bf16 v[162:165], v[178:181], v[118:121], v[82:85]
	v_mfma_f32_16x16x32_bf16 v[166:169], v[194:197], v[102:105], v[70:73]
	v_mfma_f32_16x16x32_bf16 v[174:177], v[194:197], v[118:121], v[66:69]
	s_setprio 0
	s_barrier
	s_nop 1
	ds_read_b128 v[66:69], v138 offset:16384
	ds_read_b128 v[70:73], v138 offset:17408
	ds_read_b128 v[82:85], v137 offset:16384
	ds_read_b128 v[86:89], v137 offset:17408
	ds_read_b128 v[178:181], v136 offset:16384
	ds_read_b128 v[182:185], v136 offset:17408
	ds_read_b128 v[186:189], v135 offset:16384
	ds_read_b128 v[190:193], v135 offset:17408
	s_waitcnt vmcnt(4)
	s_barrier
	s_waitcnt lgkmcnt(0)
	s_setprio 1
	s_waitcnt lgkmcnt(0)
	v_mfma_f32_16x16x32_bf16 v[62:65], v[66:69], v[146:149], v[62:65]
	v_mfma_f32_16x16x32_bf16 v[54:57], v[82:85], v[146:149], v[54:57]
	v_mfma_f32_16x16x32_bf16 v[46:49], v[178:181], v[146:149], v[46:49]
	v_mfma_f32_16x16x32_bf16 v[38:41], v[186:189], v[146:149], v[38:41]
	v_mfma_f32_16x16x32_bf16 v[62:65], v[70:73], v[150:153], v[62:65]
	v_mfma_f32_16x16x32_bf16 v[58:61], v[66:69], v[154:157], v[58:61]
	v_mfma_f32_16x16x32_bf16 v[54:57], v[86:89], v[150:153], v[54:57]
	v_mfma_f32_16x16x32_bf16 v[50:53], v[82:85], v[154:157], v[50:53]
	v_mfma_f32_16x16x32_bf16 v[46:49], v[182:185], v[150:153], v[46:49]
	v_mfma_f32_16x16x32_bf16 v[42:45], v[178:181], v[154:157], v[42:45]
	v_mfma_f32_16x16x32_bf16 v[38:41], v[190:193], v[150:153], v[38:41]
	v_mfma_f32_16x16x32_bf16 v[34:37], v[186:189], v[154:157], v[34:37]
	v_mfma_f32_16x16x32_bf16 v[194:197], v[70:73], v[158:161], v[58:61]
	v_mfma_f32_16x16x32_bf16 v[214:217], v[86:89], v[158:161], v[50:53]
	v_mfma_f32_16x16x32_bf16 v[218:221], v[182:185], v[158:161], v[42:45]
	v_mfma_f32_16x16x32_bf16 v[146:149], v[190:193], v[158:161], v[34:37]
	s_setprio 0
	s_setprio 1
	v_mfma_f32_16x16x32_bf16 v[30:33], v[66:69], v[98:101], v[30:33]
	v_mfma_f32_16x16x32_bf16 v[22:25], v[82:85], v[98:101], v[22:25]
	v_mfma_f32_16x16x32_bf16 v[14:17], v[178:181], v[98:101], v[14:17]
	v_mfma_f32_16x16x32_bf16 v[6:9], v[186:189], v[98:101], v[6:9]
	v_mfma_f32_16x16x32_bf16 v[30:33], v[70:73], v[102:105], v[30:33]
	v_mfma_f32_16x16x32_bf16 v[26:29], v[66:69], v[114:117], v[26:29]
	v_mfma_f32_16x16x32_bf16 v[22:25], v[86:89], v[102:105], v[22:25]
	v_mfma_f32_16x16x32_bf16 v[18:21], v[82:85], v[114:117], v[18:21]
	v_mfma_f32_16x16x32_bf16 v[14:17], v[182:185], v[102:105], v[14:17]
	v_mfma_f32_16x16x32_bf16 v[10:13], v[178:181], v[114:117], v[10:13]
	v_mfma_f32_16x16x32_bf16 v[6:9], v[190:193], v[102:105], v[6:9]
	v_mfma_f32_16x16x32_bf16 v[2:5], v[186:189], v[114:117], v[2:5]
	v_mfma_f32_16x16x32_bf16 v[150:153], v[70:73], v[118:121], v[26:29]
	v_mfma_f32_16x16x32_bf16 v[154:157], v[86:89], v[118:121], v[18:21]
	v_mfma_f32_16x16x32_bf16 v[158:161], v[182:185], v[118:121], v[10:13]
	v_mfma_f32_16x16x32_bf16 v[178:181], v[190:193], v[118:121], v[2:5]
	s_setprio 0
	s_barrier
	s_nop 1
	ds_read_b128 v[2:5], v140
	ds_read_b128 v[10:13], v140 offset:1024
	ds_read_b128 v[182:185], v140 offset:2048
	ds_read_b128 v[186:189], v140 offset:3072
	ds_read_b128 v[18:21], v138 offset:32768
	ds_read_b128 v[26:29], v138 offset:33792
	ds_read_b128 v[34:37], v137 offset:32768
	ds_read_b128 v[42:45], v137 offset:33792
	ds_read_b128 v[50:53], v136 offset:32768
	ds_read_b128 v[58:61], v136 offset:33792
	ds_read_b128 v[190:193], v135 offset:32768
	ds_read_b128 v[222:225], v135 offset:33792
	s_waitcnt vmcnt(2)
	s_barrier
; #define WAIT_V(n) asm volatile("s_waitcnt vmcnt(" #n ")" ::: "memory")
; #define WAIT_L(n) asm volatile("s_waitcnt lgkmcnt(" #n ")" ::: "memory")
; #define BAR __builtin_amdgcn_s_barrier()
; #define LDA(dst, b, h) for (int m = 0; m < 4; ++m) for (int k = 0; k < 2; ++k) \
;     dst[m][k] = *reinterpret_cast<const bf16x8*>((char*)SA(b, h) + lds_byte(wr * 64 + m * 16 + fr, k * 32 + fq * 8))
; #define LDB(dst, b, h) for (int n = 0; n < 2; ++n) for (int k = 0; k < 2; ++k) \
;     dst[n][k] = *reinterpret_cast<const bf16x8*>((char*)SB(b, h) + lds_byte(wc * 32 + n * 16 + fr, k * 32 + fq * 8))
; #define MMA(ai, bj, At_, Bt_) do { __builtin_amdgcn_s_setprio(1); \
;     for (int m = 0; m < 4; ++m) for (int n = 0; n < 2; ++n) for (int k = 0; k < 2; ++k) \
;       acc[ai][bj][m][n] = __builtin_amdgcn_mfma_f32_16x16x32_bf16(At_[m][k], Bt_[n][k], acc[ai][bj][m][n], 0, 0, 0); \
;     __builtin_amdgcn_s_setprio(0); } while (0)
; template <int K, int LD = K>
; __device__ __forceinline__ void gemm_main(const GAS bf16* A, const GAS bf16* Bt, int brow, int bcol, f32x4 (&acc)[2][2][4][2]) {
;     ...
;   { LDB(B0, 1, 0); LDA(At, 1, 0); WAIT_V(2); BAR; WAIT_L(0); MMA(0, 0, At, B0); BAR;
;     LDB(B1, 1, 1); WAIT_V(0); BAR; WAIT_L(0); MMA(0, 1, At, B1); BAR;
;     LDA(At, 1, 1); BAR; WAIT_L(0); MMA(1, 0, At, B0); MMA(1, 1, At, B1); BAR; }
;   if (wr == 0) BAR;
	s_waitcnt lgkmcnt(0)
	s_setprio 1
	s_waitcnt lgkmcnt(0)
	v_mfma_f32_16x16x32_bf16 v[66:69], v[18:21], v[2:5], v[126:129]
	v_mfma_f32_16x16x32_bf16 v[118:121], v[26:29], v[10:13], v[66:69]
	v_mfma_f32_16x16x32_bf16 v[66:69], v[18:21], v[182:185], v[122:125]
	v_mfma_f32_16x16x32_bf16 v[114:117], v[26:29], v[186:189], v[66:69]
	v_mfma_f32_16x16x32_bf16 v[66:69], v[34:37], v[2:5], v[198:201]
	v_mfma_f32_16x16x32_bf16 v[102:105], v[42:45], v[10:13], v[66:69]
	v_mfma_f32_16x16x32_bf16 v[66:69], v[34:37], v[182:185], v[202:205]
	v_mfma_f32_16x16x32_bf16 v[98:101], v[42:45], v[186:189], v[66:69]
	v_mfma_f32_16x16x32_bf16 v[66:69], v[50:53], v[2:5], v[110:113]
	v_mfma_f32_16x16x32_bf16 v[86:89], v[58:61], v[10:13], v[66:69]
	v_mfma_f32_16x16x32_bf16 v[66:69], v[50:53], v[182:185], v[106:109]
	v_mfma_f32_16x16x32_bf16 v[82:85], v[58:61], v[186:189], v[66:69]
	v_mfma_f32_16x16x32_bf16 v[66:69], v[190:193], v[2:5], v[206:209]
	v_mfma_f32_16x16x32_bf16 v[70:73], v[222:225], v[10:13], v[66:69]
	v_mfma_f32_16x16x32_bf16 v[66:69], v[190:193], v[182:185], v[210:213]
	v_mfma_f32_16x16x32_bf16 v[66:69], v[222:225], v[186:189], v[66:69]
	s_setprio 0
	s_barrier
	ds_read_b128 v[198:201], v139
	ds_read_b128 v[202:205], v139 offset:1024
	ds_read_b128 v[206:209], v139 offset:2048
	ds_read_b128 v[210:213], v139 offset:3072
	s_waitcnt vmcnt(0)
	s_barrier
	s_waitcnt lgkmcnt(0)
	s_setprio 1
	s_waitcnt lgkmcnt(0)
	v_mfma_f32_16x16x32_bf16 v[94:97], v[18:21], v[198:201], v[94:97]
	v_mfma_f32_16x16x32_bf16 v[18:21], v[18:21], v[206:209], v[90:93]
	v_mfma_f32_16x16x32_bf16 v[122:125], v[26:29], v[210:213], v[18:21]
	v_mfma_f32_16x16x32_bf16 v[18:21], v[34:37], v[198:201], v[142:145]
	v_mfma_f32_16x16x32_bf16 v[110:113], v[42:45], v[202:205], v[18:21]
	v_mfma_f32_16x16x32_bf16 v[18:21], v[34:37], v[206:209], v[162:165]
	v_mfma_f32_16x16x32_bf16 v[106:109], v[42:45], v[210:213], v[18:21]
	v_mfma_f32_16x16x32_bf16 v[18:21], v[50:53], v[198:201], v[78:81]
	v_mfma_f32_16x16x32_bf16 v[126:129], v[26:29], v[202:205], v[94:97]
	v_mfma_f32_16x16x32_bf16 v[94:97], v[58:61], v[202:205], v[18:21]
	v_mfma_f32_16x16x32_bf16 v[18:21], v[50:53], v[206:209], v[74:77]
	v_mfma_f32_16x16x32_bf16 v[90:93], v[58:61], v[210:213], v[18:21]
	v_mfma_f32_16x16x32_bf16 v[18:21], v[190:193], v[198:201], v[166:169]
	v_mfma_f32_16x16x32_bf16 v[78:81], v[222:225], v[202:205], v[18:21]
	v_mfma_f32_16x16x32_bf16 v[18:21], v[190:193], v[206:209], v[174:177]
	v_mfma_f32_16x16x32_bf16 v[74:77], v[222:225], v[210:213], v[18:21]
	s_setprio 0
	s_barrier
	ds_read_b128 v[140:143], v138 offset:49152
	ds_read_b128 v[162:165], v138 offset:50176
	ds_read_b128 v[166:169], v137 offset:49152
	ds_read_b128 v[174:177], v137 offset:50176
	ds_read_b128 v[190:193], v136 offset:49152
	ds_read_b128 v[136:139], v136 offset:50176
	ds_read_b128 v[222:225], v135 offset:49152
	ds_read_b128 v[226:229], v135 offset:50176
	s_barrier
	s_waitcnt lgkmcnt(0)
	s_setprio 1
	s_waitcnt lgkmcnt(0)
	v_mfma_f32_16x16x32_bf16 v[18:21], v[140:143], v[2:5], v[62:65]
	v_mfma_f32_16x16x32_bf16 v[58:61], v[162:165], v[10:13], v[18:21]
	v_mfma_f32_16x16x32_bf16 v[18:21], v[140:143], v[182:185], v[194:197]
	v_mfma_f32_16x16x32_bf16 v[50:53], v[162:165], v[186:189], v[18:21]
	v_mfma_f32_16x16x32_bf16 v[18:21], v[166:169], v[2:5], v[54:57]
	v_mfma_f32_16x16x32_bf16 v[42:45], v[174:177], v[10:13], v[18:21]
	v_mfma_f32_16x16x32_bf16 v[18:21], v[166:169], v[182:185], v[214:217]
	v_mfma_f32_16x16x32_bf16 v[34:37], v[174:177], v[186:189], v[18:21]
	v_mfma_f32_16x16x32_bf16 v[18:21], v[190:193], v[2:5], v[46:49]
	v_mfma_f32_16x16x32_bf16 v[2:5], v[222:225], v[2:5], v[38:41]
	v_mfma_f32_16x16x32_bf16 v[26:29], v[136:139], v[10:13], v[18:21]
	v_mfma_f32_16x16x32_bf16 v[18:21], v[190:193], v[182:185], v[218:221]
	v_mfma_f32_16x16x32_bf16 v[10:13], v[226:229], v[10:13], v[2:5]
	v_mfma_f32_16x16x32_bf16 v[2:5], v[222:225], v[182:185], v[146:149]
	v_mfma_f32_16x16x32_bf16 v[18:21], v[136:139], v[186:189], v[18:21]
	v_mfma_f32_16x16x32_bf16 v[2:5], v[226:229], v[186:189], v[2:5]
	s_setprio 0
	s_setprio 1
	v_mfma_f32_16x16x32_bf16 v[30:33], v[140:143], v[198:201], v[30:33]
	v_mfma_f32_16x16x32_bf16 v[62:65], v[162:165], v[202:205], v[30:33]
	v_mfma_f32_16x16x32_bf16 v[30:33], v[140:143], v[206:209], v[150:153]
	v_mfma_f32_16x16x32_bf16 v[22:25], v[166:169], v[198:201], v[22:25]
	v_mfma_f32_16x16x32_bf16 v[14:17], v[190:193], v[198:201], v[14:17]
	v_mfma_f32_16x16x32_bf16 v[54:57], v[162:165], v[210:213], v[30:33]
	v_mfma_f32_16x16x32_bf16 v[46:49], v[174:177], v[202:205], v[22:25]
	v_mfma_f32_16x16x32_bf16 v[22:25], v[166:169], v[206:209], v[154:157]
	v_mfma_f32_16x16x32_bf16 v[30:33], v[136:139], v[202:205], v[14:17]
	v_mfma_f32_16x16x32_bf16 v[14:17], v[190:193], v[206:209], v[158:161]
	v_mfma_f32_16x16x32_bf16 v[6:9], v[222:225], v[198:201], v[6:9]
	v_mfma_f32_16x16x32_bf16 v[38:41], v[174:177], v[210:213], v[22:25]
	v_mfma_f32_16x16x32_bf16 v[22:25], v[136:139], v[210:213], v[14:17]
	v_mfma_f32_16x16x32_bf16 v[14:17], v[226:229], v[202:205], v[6:9]
	v_mfma_f32_16x16x32_bf16 v[6:9], v[222:225], v[206:209], v[178:181]
	v_mfma_f32_16x16x32_bf16 v[6:9], v[226:229], v[210:213], v[6:9]
	s_setprio 0
	v_cmp_gt_u32_e32 vcc, s51, v134
	s_barrier
	s_and_saveexec_b64 s[20:21], vcc
	s_cbranch_execz .LBB0_718
	s_barrier

; #define STAGE(P, GP, ktrel) do { const GAS char* _g = (GP) + (ktrel) * (BK * 2); \
;     __builtin_amdgcn_global_load_lds((const GAS unsigned*)(_g + so0), (unsigned*)((char*)(P) + tid_ * 16), 16, 0, 0); \
;     __builtin_amdgcn_global_load_lds((const GAS unsigned*)(_g + so1), (unsigned*)((char*)(P) + tid_ * 16 + 8192), 16, 0, 0); } while (0)
; #define WAIT_L(n) asm volatile("s_waitcnt lgkmcnt(" #n ")" ::: "memory")
; #define BAR __builtin_amdgcn_s_barrier()
; #define SCHED __builtin_amdgcn_sched_barrier(0)
; #define LDA(dst, b, h) for (int m = 0; m < 4; ++m) for (int k = 0; k < 2; ++k) \
;     dst[m][k] = *reinterpret_cast<const bf16x8*>((char*)SA(b, h) + lds_byte(wr * 64 + m * 16 + fr, k * 32 + fq * 8))
; #define LDB(dst, b, h) for (int n = 0; n < 2; ++n) for (int k = 0; k < 2; ++k) \
;     dst[n][k] = *reinterpret_cast<const bf16x8*>((char*)SB(b, h) + lds_byte(wc * 32 + n * 16 + fr, k * 32 + fq * 8))
; #define MMA(ai, bj, At_, Bt_) do { __builtin_amdgcn_s_setprio(1); \
;     for (int m = 0; m < 4; ++m) for (int n = 0; n < 2; ++n) for (int k = 0; k < 2; ++k) \
;       acc[ai][bj][m][n] = __builtin_amdgcn_mfma_f32_16x16x32_bf16(At_[m][k], Bt_[n][k], acc[ai][bj][m][n], 0, 0, 0); \
;     __builtin_amdgcn_s_setprio(0); } while (0)
; template <int K, int LD = K>
; __device__ __forceinline__ void gemm_main(const GAS bf16* A, const GAS bf16* Bt, int brow, int bcol, f32x4 (&acc)[2][2][4][2]) {
;     ...
;     LDB(B0, 0, 0); SCHED; LDA(At, 0, 0); STAGE(SA(1, 1), pA1, 1);
;     WAIT_L(8); BAR; WAIT_L(0); MMA(0, 0, At, B0); BAR; SCHED;
;     LDB(B1, 0, 1); STAGE(SB(0, 0), pB0, 2);
;     BAR; WAIT_L(0); MMA(0, 1, At, B1); BAR;
;     LDA(At, 0, 1); STAGE(SA(0, 0), pA0, 2);
;     BAR; WAIT_L(0); MMA(1, 0, At, B0); BAR; SCHED;
.LBB0_767:
	ds_read_b128 v[160:163], v144
	ds_read_b128 v[164:167], v144 offset:1024
	ds_read_b128 v[174:177], v144 offset:2048
	ds_read_b128 v[178:181], v144 offset:3072
	v_lshl_add_u64 v[168:169], s[10:11], 0, v[130:131]
	v_readfirstlane_b32 s22, v143
	v_lshl_add_u64 v[214:215], v[168:169], 0, s[4:5]
	s_mov_b32 m0, s22
	v_lshl_add_u64 v[230:231], s[10:11], 0, v[132:133]
	v_readfirstlane_b32 s22, v142
	ds_read_b128 v[182:185], v138
	ds_read_b128 v[186:189], v138 offset:1024
	ds_read_b128 v[190:193], v137
	ds_read_b128 v[194:197], v137 offset:1024
	ds_read_b128 v[198:201], v136
	ds_read_b128 v[202:205], v136 offset:1024
	ds_read_b128 v[206:209], v135
	ds_read_b128 v[210:213], v135 offset:1024
	global_load_lds_dwordx4 v[214:215], off
	v_lshl_add_u64 v[214:215], v[230:231], 0, s[4:5]
	s_mov_b32 m0, s22
	s_nop 0
	global_load_lds_dwordx4 v[214:215], off
	s_waitcnt lgkmcnt(8)
	s_waitcnt vmcnt(10)
	s_barrier
	s_waitcnt lgkmcnt(0)
	s_setprio 1
	s_waitcnt lgkmcnt(0)
	v_mfma_f32_16x16x32_bf16 v[126:129], v[182:185], v[160:163], v[126:129]
	v_mfma_f32_16x16x32_bf16 v[122:125], v[182:185], v[174:177], v[122:125]
	v_mfma_f32_16x16x32_bf16 v[118:121], v[190:193], v[160:163], v[118:121]
	v_mfma_f32_16x16x32_bf16 v[114:117], v[190:193], v[174:177], v[114:117]
	v_mfma_f32_16x16x32_bf16 v[110:113], v[198:201], v[160:163], v[110:113]
	v_mfma_f32_16x16x32_bf16 v[106:109], v[198:201], v[174:177], v[106:109]
	v_mfma_f32_16x16x32_bf16 v[102:105], v[206:209], v[160:163], v[102:105]
	v_mfma_f32_16x16x32_bf16 v[98:101], v[206:209], v[174:177], v[98:101]
	v_mfma_f32_16x16x32_bf16 v[126:129], v[186:189], v[164:167], v[126:129]
	v_mfma_f32_16x16x32_bf16 v[122:125], v[186:189], v[178:181], v[122:125]
	v_mfma_f32_16x16x32_bf16 v[118:121], v[194:197], v[164:167], v[118:121]
	v_mfma_f32_16x16x32_bf16 v[114:117], v[194:197], v[178:181], v[114:117]
	v_mfma_f32_16x16x32_bf16 v[110:113], v[202:205], v[164:167], v[110:113]
	v_mfma_f32_16x16x32_bf16 v[106:109], v[202:205], v[178:181], v[106:109]
	v_mfma_f32_16x16x32_bf16 v[102:105], v[210:213], v[164:167], v[102:105]
	v_mfma_f32_16x16x32_bf16 v[98:101], v[210:213], v[178:181], v[98:101]
	s_setprio 0
	s_barrier
	v_lshl_add_u64 v[232:233], s[20:21], 0, v[130:131]
	v_readfirstlane_b32 s22, v151
	v_lshl_add_u64 v[234:235], v[232:233], 0, s[6:7]
	s_mov_b32 m0, s22
	ds_read_b128 v[214:217], v141
	ds_read_b128 v[218:221], v141 offset:1024
	ds_read_b128 v[222:225], v141 offset:2048
	ds_read_b128 v[226:229], v141 offset:3072
	global_load_lds_dwordx4 v[234:235], off
	v_lshl_add_u64 v[234:235], s[20:21], 0, v[132:133]
	v_readfirstlane_b32 s22, v152
	v_lshl_add_u64 v[236:237], v[234:235], 0, s[6:7]
	s_mov_b32 m0, s22
	s_add_u32 s20, s20, 0x100
	global_load_lds_dwordx4 v[236:237], off
	s_waitcnt vmcnt(10)
	s_barrier
	s_waitcnt lgkmcnt(0)
	s_addc_u32 s21, s21, 0
	s_setprio 1
	s_waitcnt lgkmcnt(0)
	v_mfma_f32_16x16x32_bf16 v[94:97], v[182:185], v[214:217], v[94:97]
	v_mfma_f32_16x16x32_bf16 v[90:93], v[182:185], v[222:225], v[90:93]
	v_mfma_f32_16x16x32_bf16 v[86:89], v[190:193], v[214:217], v[86:89]
	v_mfma_f32_16x16x32_bf16 v[82:85], v[190:193], v[222:225], v[82:85]
	v_mfma_f32_16x16x32_bf16 v[78:81], v[198:201], v[214:217], v[78:81]
	v_mfma_f32_16x16x32_bf16 v[74:77], v[198:201], v[222:225], v[74:77]
	v_mfma_f32_16x16x32_bf16 v[70:73], v[206:209], v[214:217], v[70:73]
	v_mfma_f32_16x16x32_bf16 v[66:69], v[206:209], v[222:225], v[66:69]
	v_mfma_f32_16x16x32_bf16 v[94:97], v[186:189], v[218:221], v[94:97]
	v_mfma_f32_16x16x32_bf16 v[90:93], v[186:189], v[226:229], v[90:93]
	v_mfma_f32_16x16x32_bf16 v[86:89], v[194:197], v[218:221], v[86:89]
	v_mfma_f32_16x16x32_bf16 v[82:85], v[194:197], v[226:229], v[82:85]
	v_mfma_f32_16x16x32_bf16 v[78:81], v[202:205], v[218:221], v[78:81]
	v_mfma_f32_16x16x32_bf16 v[74:77], v[202:205], v[226:229], v[74:77]
	v_mfma_f32_16x16x32_bf16 v[70:73], v[210:213], v[218:221], v[70:73]
	v_mfma_f32_16x16x32_bf16 v[66:69], v[210:213], v[226:229], v[66:69]
	s_setprio 0
	v_lshl_add_u64 v[236:237], s[18:19], 0, v[130:131]
	v_readfirstlane_b32 s22, v145
	v_lshl_add_u64 v[238:239], v[236:237], 0, s[6:7]
	s_mov_b32 m0, s22
	s_barrier
	ds_read_b128 v[182:185], v138 offset:16384
	ds_read_b128 v[186:189], v138 offset:17408
	ds_read_b128 v[190:193], v137 offset:16384
	ds_read_b128 v[194:197], v137 offset:17408
	ds_read_b128 v[198:201], v136 offset:16384
	ds_read_b128 v[202:205], v136 offset:17408
	ds_read_b128 v[206:209], v135 offset:16384
	ds_read_b128 v[210:213], v135 offset:17408
	global_load_lds_dwordx4 v[238:239], off
	v_lshl_add_u64 v[238:239], s[18:19], 0, v[132:133]
	v_readfirstlane_b32 s22, v146
	v_lshl_add_u64 v[240:241], v[238:239], 0, s[6:7]
	s_mov_b32 m0, s22
	s_add_u32 s18, s18, 0x100
	global_load_lds_dwordx4 v[240:241], off
	s_barrier
	s_waitcnt lgkmcnt(0)
	s_addc_u32 s19, s19, 0
	s_setprio 1
	s_waitcnt lgkmcnt(0)
	v_mfma_f32_16x16x32_bf16 v[62:65], v[182:185], v[160:163], v[62:65]
	v_mfma_f32_16x16x32_bf16 v[58:61], v[182:185], v[174:177], v[58:61]
	v_mfma_f32_16x16x32_bf16 v[54:57], v[190:193], v[160:163], v[54:57]
	v_mfma_f32_16x16x32_bf16 v[50:53], v[190:193], v[174:177], v[50:53]
	v_mfma_f32_16x16x32_bf16 v[46:49], v[198:201], v[160:163], v[46:49]
	v_mfma_f32_16x16x32_bf16 v[42:45], v[198:201], v[174:177], v[42:45]
	v_mfma_f32_16x16x32_bf16 v[38:41], v[206:209], v[160:163], v[38:41]
	v_mfma_f32_16x16x32_bf16 v[34:37], v[206:209], v[174:177], v[34:37]
	v_mfma_f32_16x16x32_bf16 v[62:65], v[186:189], v[164:167], v[62:65]
	v_mfma_f32_16x16x32_bf16 v[58:61], v[186:189], v[178:181], v[58:61]
	v_mfma_f32_16x16x32_bf16 v[54:57], v[194:197], v[164:167], v[54:57]
	v_mfma_f32_16x16x32_bf16 v[50:53], v[194:197], v[178:181], v[50:53]
	v_mfma_f32_16x16x32_bf16 v[46:49], v[202:205], v[164:167], v[46:49]
	v_mfma_f32_16x16x32_bf16 v[42:45], v[202:205], v[178:181], v[42:45]
	v_mfma_f32_16x16x32_bf16 v[38:41], v[210:213], v[164:167], v[38:41]
	v_mfma_f32_16x16x32_bf16 v[34:37], v[210:213], v[178:181], v[34:37]
	s_setprio 0
	s_barrier
; #define STAGE(P, GP, ktrel) do { const GAS char* _g = (GP) + (ktrel) * (BK * 2); \
;     __builtin_amdgcn_global_load_lds((const GAS unsigned*)(_g + so0), (unsigned*)((char*)(P) + tid_ * 16), 16, 0, 0); \
;     __builtin_amdgcn_global_load_lds((const GAS unsigned*)(_g + so1), (unsigned*)((char*)(P) + tid_ * 16 + 8192), 16, 0, 0); } while (0)
; #define WAIT_V(n) asm volatile("s_waitcnt vmcnt(" #n ")" ::: "memory")
; #define WAIT_L(n) asm volatile("s_waitcnt lgkmcnt(" #n ")" ::: "memory")
; #define BAR __builtin_amdgcn_s_barrier()
; #define SCHED __builtin_amdgcn_sched_barrier(0)
; #define LDA(dst, b, h) for (int m = 0; m < 4; ++m) for (int k = 0; k < 2; ++k) \
;     dst[m][k] = *reinterpret_cast<const bf16x8*>((char*)SA(b, h) + lds_byte(wr * 64 + m * 16 + fr, k * 32 + fq * 8))
; #define LDB(dst, b, h) for (int n = 0; n < 2; ++n) for (int k = 0; k < 2; ++k) \
;     dst[n][k] = *reinterpret_cast<const bf16x8*>((char*)SB(b, h) + lds_byte(wc * 32 + n * 16 + fr, k * 32 + fq * 8))
; #define MMA(ai, bj, At_, Bt_) do { __builtin_amdgcn_s_setprio(1); \
;     for (int m = 0; m < 4; ++m) for (int n = 0; n < 2; ++n) for (int k = 0; k < 2; ++k) \
;       acc[ai][bj][m][n] = __builtin_amdgcn_mfma_f32_16x16x32_bf16(At_[m][k], Bt_[n][k], acc[ai][bj][m][n], 0, 0, 0); \
;     __builtin_amdgcn_s_setprio(0); } while (0)
; template <int K, int LD = K>
; __device__ __forceinline__ void gemm_main(const GAS bf16* A, const GAS bf16* Bt, int brow, int bcol, f32x4 (&acc)[2][2][4][2]) {
;     ...
;     STAGE(SB(0, 1), pB1, 2);
;     WAIT_V(6); BAR; MMA(1, 1, At, B1); BAR;
;     LDB(B0, 1, 0); SCHED; LDA(At, 1, 0); STAGE(SA(0, 1), pA1, 2);
;     WAIT_L(8); BAR; WAIT_L(0); MMA(0, 0, At, B0); BAR; SCHED;
;     LDB(B1, 1, 1); STAGE(SB(1, 0), pB0, 3);
;     BAR; WAIT_L(0); MMA(0, 1, At, B1); BAR;
	v_lshl_add_u64 v[240:241], s[16:17], 0, v[130:131]
	v_readfirstlane_b32 s22, v153
	v_lshl_add_u64 v[160:161], v[240:241], 0, s[6:7]
	s_mov_b32 m0, s22
	v_lshl_add_u64 v[242:243], s[16:17], 0, v[132:133]
	v_readfirstlane_b32 s22, v154
	global_load_lds_dwordx4 v[160:161], off
	v_lshl_add_u64 v[160:161], v[242:243], 0, s[6:7]
	s_mov_b32 m0, s22
	s_add_u32 s16, s16, 0x100
	global_load_lds_dwordx4 v[160:161], off
	s_waitcnt vmcnt(10)
	s_addc_u32 s17, s17, 0
	s_barrier
	s_setprio 1
	v_mfma_f32_16x16x32_bf16 v[30:33], v[182:185], v[214:217], v[30:33]
	v_mfma_f32_16x16x32_bf16 v[26:29], v[182:185], v[222:225], v[26:29]
	v_mfma_f32_16x16x32_bf16 v[22:25], v[190:193], v[214:217], v[22:25]
	v_mfma_f32_16x16x32_bf16 v[18:21], v[190:193], v[222:225], v[18:21]
	v_mfma_f32_16x16x32_bf16 v[14:17], v[198:201], v[214:217], v[14:17]
	v_mfma_f32_16x16x32_bf16 v[10:13], v[198:201], v[222:225], v[10:13]
	v_mfma_f32_16x16x32_bf16 v[6:9], v[206:209], v[214:217], v[6:9]
	v_mfma_f32_16x16x32_bf16 v[2:5], v[206:209], v[222:225], v[2:5]
	v_mfma_f32_16x16x32_bf16 v[30:33], v[186:189], v[218:221], v[30:33]
	v_mfma_f32_16x16x32_bf16 v[26:29], v[186:189], v[226:229], v[26:29]
	v_mfma_f32_16x16x32_bf16 v[22:25], v[194:197], v[218:221], v[22:25]
	v_mfma_f32_16x16x32_bf16 v[18:21], v[194:197], v[226:229], v[18:21]
	v_mfma_f32_16x16x32_bf16 v[14:17], v[202:205], v[218:221], v[14:17]
	v_mfma_f32_16x16x32_bf16 v[10:13], v[202:205], v[226:229], v[10:13]
	v_mfma_f32_16x16x32_bf16 v[6:9], v[210:213], v[218:221], v[6:9]
	v_mfma_f32_16x16x32_bf16 v[2:5], v[210:213], v[226:229], v[2:5]
	s_setprio 0
	s_barrier
	ds_read_b128 v[160:163], v140
	ds_read_b128 v[164:167], v140 offset:1024
	ds_read_b128 v[174:177], v140 offset:2048
	ds_read_b128 v[178:181], v140 offset:3072
	v_readfirstlane_b32 s22, v147
	v_lshl_add_u64 v[168:169], v[168:169], 0, s[6:7]
	s_mov_b32 m0, s22
	v_readfirstlane_b32 s22, v148
	ds_read_b128 v[182:185], v138 offset:32768
	ds_read_b128 v[186:189], v138 offset:33792
	ds_read_b128 v[190:193], v137 offset:32768
	ds_read_b128 v[194:197], v137 offset:33792
	ds_read_b128 v[198:201], v136 offset:32768
	ds_read_b128 v[202:205], v136 offset:33792
	ds_read_b128 v[206:209], v135 offset:32768
	ds_read_b128 v[210:213], v135 offset:33792
	global_load_lds_dwordx4 v[168:169], off
	v_lshl_add_u64 v[168:169], v[230:231], 0, s[6:7]
	s_mov_b32 m0, s22
	s_add_u32 s10, s10, 0x100
	global_load_lds_dwordx4 v[168:169], off
	s_waitcnt lgkmcnt(8)
	s_waitcnt vmcnt(10)
	s_barrier
	s_waitcnt lgkmcnt(0)
	s_addc_u32 s11, s11, 0
	s_setprio 1
	s_waitcnt lgkmcnt(0)
	v_mfma_f32_16x16x32_bf16 v[126:129], v[182:185], v[160:163], v[126:129]
	v_mfma_f32_16x16x32_bf16 v[122:125], v[182:185], v[174:177], v[122:125]
	v_mfma_f32_16x16x32_bf16 v[118:121], v[190:193], v[160:163], v[118:121]
	v_mfma_f32_16x16x32_bf16 v[114:117], v[190:193], v[174:177], v[114:117]
	v_mfma_f32_16x16x32_bf16 v[110:113], v[198:201], v[160:163], v[110:113]
	v_mfma_f32_16x16x32_bf16 v[106:109], v[198:201], v[174:177], v[106:109]
	v_mfma_f32_16x16x32_bf16 v[102:105], v[206:209], v[160:163], v[102:105]
	v_mfma_f32_16x16x32_bf16 v[98:101], v[206:209], v[174:177], v[98:101]
	v_mfma_f32_16x16x32_bf16 v[126:129], v[186:189], v[164:167], v[126:129]
	v_mfma_f32_16x16x32_bf16 v[122:125], v[186:189], v[178:181], v[122:125]
	v_mfma_f32_16x16x32_bf16 v[118:121], v[194:197], v[164:167], v[118:121]
	v_mfma_f32_16x16x32_bf16 v[114:117], v[194:197], v[178:181], v[114:117]
	v_mfma_f32_16x16x32_bf16 v[110:113], v[202:205], v[164:167], v[110:113]
	v_mfma_f32_16x16x32_bf16 v[106:109], v[202:205], v[178:181], v[106:109]
	v_mfma_f32_16x16x32_bf16 v[102:105], v[210:213], v[164:167], v[102:105]
	v_mfma_f32_16x16x32_bf16 v[98:101], v[210:213], v[178:181], v[98:101]
	s_setprio 0
	s_barrier
	v_readfirstlane_b32 s22, v155
	v_lshl_add_u64 v[168:169], v[232:233], 0, s[8:9]
	s_mov_b32 m0, s22
	v_readfirstlane_b32 s22, v156
	ds_read_b128 v[214:217], v139
	ds_read_b128 v[218:221], v139 offset:1024
	ds_read_b128 v[222:225], v139 offset:2048
	ds_read_b128 v[226:229], v139 offset:3072
	global_load_lds_dwordx4 v[168:169], off
	v_lshl_add_u64 v[168:169], v[234:235], 0, s[8:9]
	s_mov_b32 m0, s22
	s_nop 0
	global_load_lds_dwordx4 v[168:169], off
	s_waitcnt vmcnt(10)
	s_barrier
	s_waitcnt lgkmcnt(0)
	s_setprio 1
	s_waitcnt lgkmcnt(0)
	v_mfma_f32_16x16x32_bf16 v[94:97], v[182:185], v[214:217], v[94:97]
	v_mfma_f32_16x16x32_bf16 v[90:93], v[182:185], v[222:225], v[90:93]
	v_mfma_f32_16x16x32_bf16 v[86:89], v[190:193], v[214:217], v[86:89]
	v_mfma_f32_16x16x32_bf16 v[82:85], v[190:193], v[222:225], v[82:85]
	v_mfma_f32_16x16x32_bf16 v[78:81], v[198:201], v[214:217], v[78:81]
	v_mfma_f32_16x16x32_bf16 v[74:77], v[198:201], v[222:225], v[74:77]
	v_mfma_f32_16x16x32_bf16 v[70:73], v[206:209], v[214:217], v[70:73]
	v_mfma_f32_16x16x32_bf16 v[66:69], v[206:209], v[222:225], v[66:69]
	v_mfma_f32_16x16x32_bf16 v[94:97], v[186:189], v[218:221], v[94:97]
	v_mfma_f32_16x16x32_bf16 v[90:93], v[186:189], v[226:229], v[90:93]
	v_mfma_f32_16x16x32_bf16 v[86:89], v[194:197], v[218:221], v[86:89]
	v_mfma_f32_16x16x32_bf16 v[82:85], v[194:197], v[226:229], v[82:85]
	v_mfma_f32_16x16x32_bf16 v[78:81], v[202:205], v[218:221], v[78:81]
	v_mfma_f32_16x16x32_bf16 v[74:77], v[202:205], v[226:229], v[74:77]
	v_mfma_f32_16x16x32_bf16 v[70:73], v[210:213], v[218:221], v[70:73]
	v_mfma_f32_16x16x32_bf16 v[66:69], v[210:213], v[226:229], v[66:69]
	s_setprio 0
	v_readfirstlane_b32 s22, v149
	v_lshl_add_u64 v[168:169], v[236:237], 0, s[8:9]
	s_mov_b32 m0, s22
	v_readfirstlane_b32 s22, v150
	s_barrier
; #define STAGE(P, GP, ktrel) do { const GAS char* _g = (GP) + (ktrel) * (BK * 2); \
;     __builtin_amdgcn_global_load_lds((const GAS unsigned*)(_g + so0), (unsigned*)((char*)(P) + tid_ * 16), 16, 0, 0); \
;     __builtin_amdgcn_global_load_lds((const GAS unsigned*)(_g + so1), (unsigned*)((char*)(P) + tid_ * 16 + 8192), 16, 0, 0); } while (0)
; #define WAIT_V(n) asm volatile("s_waitcnt vmcnt(" #n ")" ::: "memory")
; #define WAIT_L(n) asm volatile("s_waitcnt lgkmcnt(" #n ")" ::: "memory")
; #define BAR __builtin_amdgcn_s_barrier()
; #define SCHED __builtin_amdgcn_sched_barrier(0)
; #define LDA(dst, b, h) for (int m = 0; m < 4; ++m) for (int k = 0; k < 2; ++k) \
;     dst[m][k] = *reinterpret_cast<const bf16x8*>((char*)SA(b, h) + lds_byte(wr * 64 + m * 16 + fr, k * 32 + fq * 8))
; #define LDB(dst, b, h) for (int n = 0; n < 2; ++n) for (int k = 0; k < 2; ++k) \
;     dst[n][k] = *reinterpret_cast<const bf16x8*>((char*)SB(b, h) + lds_byte(wc * 32 + n * 16 + fr, k * 32 + fq * 8))
; #define MMA(ai, bj, At_, Bt_) do { __builtin_amdgcn_s_setprio(1); \
;     for (int m = 0; m < 4; ++m) for (int n = 0; n < 2; ++n) for (int k = 0; k < 2; ++k) \
;       acc[ai][bj][m][n] = __builtin_amdgcn_mfma_f32_16x16x32_bf16(At_[m][k], Bt_[n][k], acc[ai][bj][m][n], 0, 0, 0); \
;     __builtin_amdgcn_s_setprio(0); } while (0)
; template <int K, int LD = K>
; __device__ __forceinline__ void gemm_main(const GAS bf16* A, const GAS bf16* Bt, int brow, int bcol, f32x4 (&acc)[2][2][4][2]) {
;     ...
;     LDA(At, 1, 1); STAGE(SA(1, 0), pA0, 3);
;     BAR; WAIT_L(0); MMA(1, 0, At, B0); BAR; SCHED;
;     STAGE(SB(1, 1), pB1, 3);
;     WAIT_V(6); BAR; MMA(1, 1, At, B1); BAR;
;     pA0 += 4 * BK; pA1 += 4 * BK; pB0 += 4 * BK; pB1 += 4 * BK;
;     asm volatile("" : "+s"(pA0), "+s"(pA1), "+s"(pB0), "+s"(pB1));
;   }
;   { LDB(B0, 0, 0); LDA(At, 0, 0); STAGE(SA(1, 1), pA1, 1);
;     BAR; WAIT_L(0); MMA(0, 0, At, B0); BAR;
;     LDB(B1, 0, 1); BAR; WAIT_L(0); MMA(0, 1, At, B1); BAR;
	ds_read_b128 v[182:185], v138 offset:49152
	ds_read_b128 v[186:189], v138 offset:50176
	ds_read_b128 v[190:193], v137 offset:49152
	ds_read_b128 v[194:197], v137 offset:50176
	ds_read_b128 v[198:201], v136 offset:49152
	ds_read_b128 v[202:205], v136 offset:50176
	ds_read_b128 v[206:209], v135 offset:49152
	ds_read_b128 v[210:213], v135 offset:50176
	global_load_lds_dwordx4 v[168:169], off
	v_lshl_add_u64 v[168:169], v[238:239], 0, s[8:9]
	s_mov_b32 m0, s22
	s_nop 0
	global_load_lds_dwordx4 v[168:169], off
	s_barrier
	s_waitcnt lgkmcnt(0)
	s_setprio 1
	s_waitcnt lgkmcnt(0)
	v_mfma_f32_16x16x32_bf16 v[62:65], v[182:185], v[160:163], v[62:65]
	v_mfma_f32_16x16x32_bf16 v[58:61], v[182:185], v[174:177], v[58:61]
	v_mfma_f32_16x16x32_bf16 v[54:57], v[190:193], v[160:163], v[54:57]
	v_mfma_f32_16x16x32_bf16 v[50:53], v[190:193], v[174:177], v[50:53]
	v_mfma_f32_16x16x32_bf16 v[46:49], v[198:201], v[160:163], v[46:49]
	v_mfma_f32_16x16x32_bf16 v[42:45], v[198:201], v[174:177], v[42:45]
	v_mfma_f32_16x16x32_bf16 v[38:41], v[206:209], v[160:163], v[38:41]
	v_mfma_f32_16x16x32_bf16 v[34:37], v[206:209], v[174:177], v[34:37]
	v_mfma_f32_16x16x32_bf16 v[62:65], v[186:189], v[164:167], v[62:65]
	v_mfma_f32_16x16x32_bf16 v[58:61], v[186:189], v[178:181], v[58:61]
	v_mfma_f32_16x16x32_bf16 v[54:57], v[194:197], v[164:167], v[54:57]
	v_mfma_f32_16x16x32_bf16 v[50:53], v[194:197], v[178:181], v[50:53]
	v_mfma_f32_16x16x32_bf16 v[46:49], v[202:205], v[164:167], v[46:49]
	v_mfma_f32_16x16x32_bf16 v[42:45], v[202:205], v[178:181], v[42:45]
	v_mfma_f32_16x16x32_bf16 v[38:41], v[210:213], v[164:167], v[38:41]
	v_mfma_f32_16x16x32_bf16 v[34:37], v[210:213], v[178:181], v[34:37]
	s_setprio 0
	s_barrier
	v_readfirstlane_b32 s22, v157
	v_lshl_add_u64 v[160:161], v[240:241], 0, s[8:9]
	s_mov_b32 m0, s22
	v_readfirstlane_b32 s22, v158
	global_load_lds_dwordx4 v[160:161], off
	v_lshl_add_u64 v[160:161], v[242:243], 0, s[8:9]
	s_mov_b32 m0, s22
	s_nop 0
	global_load_lds_dwordx4 v[160:161], off
	s_waitcnt vmcnt(10)
	s_barrier
	s_setprio 1
	v_mfma_f32_16x16x32_bf16 v[30:33], v[182:185], v[214:217], v[30:33]
	v_mfma_f32_16x16x32_bf16 v[26:29], v[182:185], v[222:225], v[26:29]
	v_mfma_f32_16x16x32_bf16 v[22:25], v[190:193], v[214:217], v[22:25]
	v_mfma_f32_16x16x32_bf16 v[18:21], v[190:193], v[222:225], v[18:21]
	v_mfma_f32_16x16x32_bf16 v[14:17], v[198:201], v[214:217], v[14:17]
	v_mfma_f32_16x16x32_bf16 v[10:13], v[198:201], v[222:225], v[10:13]
	v_mfma_f32_16x16x32_bf16 v[6:9], v[206:209], v[214:217], v[6:9]
	v_mfma_f32_16x16x32_bf16 v[2:5], v[206:209], v[222:225], v[2:5]
	v_mfma_f32_16x16x32_bf16 v[30:33], v[186:189], v[218:221], v[30:33]
	v_mfma_f32_16x16x32_bf16 v[26:29], v[186:189], v[226:229], v[26:29]
	v_mfma_f32_16x16x32_bf16 v[22:25], v[194:197], v[218:221], v[22:25]
	v_mfma_f32_16x16x32_bf16 v[18:21], v[194:197], v[226:229], v[18:21]
	v_mfma_f32_16x16x32_bf16 v[14:17], v[202:205], v[218:221], v[14:17]
	v_mfma_f32_16x16x32_bf16 v[10:13], v[202:205], v[226:229], v[10:13]
	v_mfma_f32_16x16x32_bf16 v[6:9], v[210:213], v[218:221], v[6:9]
	v_mfma_f32_16x16x32_bf16 v[2:5], v[210:213], v[226:229], v[2:5]
	s_setprio 0
	s_add_i32 s15, s15, 2
	s_cmp_lt_u32 s15, 12
	s_barrier
	s_cbranch_scc1 .LBB0_767
	ds_read_b128 v[146:149], v144
	ds_read_b128 v[150:153], v144 offset:1024
	ds_read_b128 v[154:157], v144 offset:2048
	ds_read_b128 v[158:161], v144 offset:3072
	ds_read_b128 v[162:165], v138
	ds_read_b128 v[166:169], v138 offset:1024
	ds_read_b128 v[174:177], v137
	ds_read_b128 v[178:181], v137 offset:1024
	ds_read_b128 v[182:185], v136
	ds_read_b128 v[186:189], v136 offset:1024
	ds_read_b128 v[190:193], v135
	ds_read_b128 v[194:197], v135 offset:1024
	v_lshl_add_u64 v[144:145], s[10:11], 0, v[130:131]
	v_readfirstlane_b32 s15, v143
	v_lshl_add_u64 v[144:145], v[144:145], 0, s[4:5]
	s_mov_b32 m0, s15
	v_lshl_add_u64 v[132:133], s[10:11], 0, v[132:133]
	v_readfirstlane_b32 s10, v142
	global_load_lds_dwordx4 v[144:145], off
	v_lshl_add_u64 v[132:133], v[132:133], 0, s[4:5]
	s_mov_b32 m0, s10
	s_nop 0
	global_load_lds_dwordx4 v[132:133], off
	s_waitcnt vmcnt(10)
	s_barrier
	s_waitcnt lgkmcnt(0)
	s_setprio 1
	s_waitcnt lgkmcnt(0)
	v_mfma_f32_16x16x32_bf16 v[126:129], v[162:165], v[146:149], v[126:129]
	v_mfma_f32_16x16x32_bf16 v[122:125], v[162:165], v[154:157], v[122:125]
	v_mfma_f32_16x16x32_bf16 v[110:113], v[182:185], v[146:149], v[110:113]
	v_mfma_f32_16x16x32_bf16 v[106:109], v[182:185], v[154:157], v[106:109]
	v_mfma_f32_16x16x32_bf16 v[126:129], v[166:169], v[150:153], v[126:129]
	v_mfma_f32_16x16x32_bf16 v[122:125], v[166:169], v[158:161], v[122:125]
	v_mfma_f32_16x16x32_bf16 v[118:121], v[174:177], v[146:149], v[118:121]
	v_mfma_f32_16x16x32_bf16 v[114:117], v[174:177], v[154:157], v[114:117]
	v_mfma_f32_16x16x32_bf16 v[110:113], v[186:189], v[150:153], v[110:113]
	v_mfma_f32_16x16x32_bf16 v[106:109], v[186:189], v[158:161], v[106:109]
	v_mfma_f32_16x16x32_bf16 v[102:105], v[190:193], v[146:149], v[102:105]
	v_mfma_f32_16x16x32_bf16 v[98:101], v[190:193], v[154:157], v[98:101]
	v_mfma_f32_16x16x32_bf16 v[142:145], v[178:181], v[150:153], v[118:121]
	v_mfma_f32_16x16x32_bf16 v[198:201], v[178:181], v[158:161], v[114:117]
	v_mfma_f32_16x16x32_bf16 v[202:205], v[194:197], v[150:153], v[102:105]
	v_mfma_f32_16x16x32_bf16 v[206:209], v[194:197], v[158:161], v[98:101]
	s_setprio 0
	s_barrier
	s_nop 1
	ds_read_b128 v[98:101], v141
	ds_read_b128 v[102:105], v141 offset:1024
	ds_read_b128 v[114:117], v141 offset:2048
	ds_read_b128 v[118:121], v141 offset:3072
	s_waitcnt vmcnt(8)
	s_barrier
; #define WAIT_V(n) asm volatile("s_waitcnt vmcnt(" #n ")" ::: "memory")
; #define WAIT_L(n) asm volatile("s_waitcnt lgkmcnt(" #n ")" ::: "memory")
; #define BAR __builtin_amdgcn_s_barrier()
; #define LDA(dst, b, h) for (int m = 0; m < 4; ++m) for (int k = 0; k < 2; ++k) \
;     dst[m][k] = *reinterpret_cast<const bf16x8*>((char*)SA(b, h) + lds_byte(wr * 64 + m * 16 + fr, k * 32 + fq * 8))
; #define LDB(dst, b, h) for (int n = 0; n < 2; ++n) for (int k = 0; k < 2; ++k) \
;     dst[n][k] = *reinterpret_cast<const bf16x8*>((char*)SB(b, h) + lds_byte(wc * 32 + n * 16 + fr, k * 32 + fq * 8))
; #define MMA(ai, bj, At_, Bt_) do { __builtin_amdgcn_s_setprio(1); \
;     for (int m = 0; m < 4; ++m) for (int n = 0; n < 2; ++n) for (int k = 0; k < 2; ++k) \
;       acc[ai][bj][m][n] = __builtin_amdgcn_mfma_f32_16x16x32_bf16(At_[m][k], Bt_[n][k], acc[ai][bj][m][n], 0, 0, 0); \
;     __builtin_amdgcn_s_setprio(0); } while (0)
; template <int K, int LD = K>
; __device__ __forceinline__ void gemm_main(const GAS bf16* A, const GAS bf16* Bt, int brow, int bcol, f32x4 (&acc)[2][2][4][2]) {
;     ...
;     LDB(B1, 0, 1); BAR; WAIT_L(0); MMA(0, 1, At, B1); BAR;
;     LDA(At, 0, 1); WAIT_V(4); BAR; WAIT_L(0); MMA(1, 0, At, B0); MMA(1, 1, At, B1); BAR; }
;   { LDB(B0, 1, 0); LDA(At, 1, 0); WAIT_V(2); BAR; WAIT_L(0); MMA(0, 0, At, B0); BAR;
	s_waitcnt lgkmcnt(0)
	s_setprio 1
	s_waitcnt lgkmcnt(0)
	v_mfma_f32_16x16x32_bf16 v[94:97], v[162:165], v[98:101], v[94:97]
	v_mfma_f32_16x16x32_bf16 v[90:93], v[162:165], v[114:117], v[90:93]
	v_mfma_f32_16x16x32_bf16 v[78:81], v[182:185], v[98:101], v[78:81]
	v_mfma_f32_16x16x32_bf16 v[74:77], v[182:185], v[114:117], v[74:77]
	v_mfma_f32_16x16x32_bf16 v[94:97], v[166:169], v[102:105], v[94:97]
	v_mfma_f32_16x16x32_bf16 v[90:93], v[166:169], v[118:121], v[90:93]
	v_mfma_f32_16x16x32_bf16 v[86:89], v[174:177], v[98:101], v[86:89]
	v_mfma_f32_16x16x32_bf16 v[82:85], v[174:177], v[114:117], v[82:85]
	v_mfma_f32_16x16x32_bf16 v[78:81], v[186:189], v[102:105], v[78:81]
	v_mfma_f32_16x16x32_bf16 v[74:77], v[186:189], v[118:121], v[74:77]
	v_mfma_f32_16x16x32_bf16 v[70:73], v[190:193], v[98:101], v[70:73]
	v_mfma_f32_16x16x32_bf16 v[66:69], v[190:193], v[114:117], v[66:69]
	v_mfma_f32_16x16x32_bf16 v[162:165], v[178:181], v[102:105], v[86:89]
	v_mfma_f32_16x16x32_bf16 v[166:169], v[178:181], v[118:121], v[82:85]
	v_mfma_f32_16x16x32_bf16 v[174:177], v[194:197], v[102:105], v[70:73]
	v_mfma_f32_16x16x32_bf16 v[178:181], v[194:197], v[118:121], v[66:69]
	s_setprio 0
	s_barrier
	s_nop 1
	ds_read_b128 v[66:69], v138 offset:16384
	ds_read_b128 v[70:73], v138 offset:17408
	ds_read_b128 v[82:85], v137 offset:16384
	ds_read_b128 v[86:89], v137 offset:17408
	ds_read_b128 v[182:185], v136 offset:16384
	ds_read_b128 v[186:189], v136 offset:17408
	ds_read_b128 v[190:193], v135 offset:16384
	ds_read_b128 v[194:197], v135 offset:17408
	s_waitcnt vmcnt(4)
	s_barrier
	s_waitcnt lgkmcnt(0)
	s_setprio 1
	s_waitcnt lgkmcnt(0)
	v_mfma_f32_16x16x32_bf16 v[62:65], v[66:69], v[146:149], v[62:65]
	v_mfma_f32_16x16x32_bf16 v[58:61], v[66:69], v[154:157], v[58:61]
	v_mfma_f32_16x16x32_bf16 v[46:49], v[182:185], v[146:149], v[46:49]
	v_mfma_f32_16x16x32_bf16 v[42:45], v[182:185], v[154:157], v[42:45]
	v_mfma_f32_16x16x32_bf16 v[62:65], v[70:73], v[150:153], v[62:65]
	v_mfma_f32_16x16x32_bf16 v[58:61], v[70:73], v[158:161], v[58:61]
	v_mfma_f32_16x16x32_bf16 v[54:57], v[82:85], v[146:149], v[54:57]
	v_mfma_f32_16x16x32_bf16 v[50:53], v[82:85], v[154:157], v[50:53]
	v_mfma_f32_16x16x32_bf16 v[46:49], v[186:189], v[150:153], v[46:49]
	v_mfma_f32_16x16x32_bf16 v[42:45], v[186:189], v[158:161], v[42:45]
	v_mfma_f32_16x16x32_bf16 v[38:41], v[190:193], v[146:149], v[38:41]
	v_mfma_f32_16x16x32_bf16 v[34:37], v[190:193], v[154:157], v[34:37]
	v_mfma_f32_16x16x32_bf16 v[210:213], v[86:89], v[150:153], v[54:57]
	v_mfma_f32_16x16x32_bf16 v[214:217], v[86:89], v[158:161], v[50:53]
	v_mfma_f32_16x16x32_bf16 v[146:149], v[194:197], v[150:153], v[38:41]
	v_mfma_f32_16x16x32_bf16 v[150:153], v[194:197], v[158:161], v[34:37]
	s_setprio 0
	s_setprio 1
	v_mfma_f32_16x16x32_bf16 v[30:33], v[66:69], v[98:101], v[30:33]
	v_mfma_f32_16x16x32_bf16 v[26:29], v[66:69], v[114:117], v[26:29]
	v_mfma_f32_16x16x32_bf16 v[14:17], v[182:185], v[98:101], v[14:17]
	v_mfma_f32_16x16x32_bf16 v[10:13], v[182:185], v[114:117], v[10:13]
	v_mfma_f32_16x16x32_bf16 v[30:33], v[70:73], v[102:105], v[30:33]
	v_mfma_f32_16x16x32_bf16 v[26:29], v[70:73], v[118:121], v[26:29]
	v_mfma_f32_16x16x32_bf16 v[22:25], v[82:85], v[98:101], v[22:25]
	v_mfma_f32_16x16x32_bf16 v[18:21], v[82:85], v[114:117], v[18:21]
	v_mfma_f32_16x16x32_bf16 v[14:17], v[186:189], v[102:105], v[14:17]
	v_mfma_f32_16x16x32_bf16 v[10:13], v[186:189], v[118:121], v[10:13]
	v_mfma_f32_16x16x32_bf16 v[6:9], v[190:193], v[98:101], v[6:9]
	v_mfma_f32_16x16x32_bf16 v[2:5], v[190:193], v[114:117], v[2:5]
	v_mfma_f32_16x16x32_bf16 v[154:157], v[86:89], v[102:105], v[22:25]
	v_mfma_f32_16x16x32_bf16 v[158:161], v[86:89], v[118:121], v[18:21]
	v_mfma_f32_16x16x32_bf16 v[182:185], v[194:197], v[102:105], v[6:9]
	v_mfma_f32_16x16x32_bf16 v[186:189], v[194:197], v[118:121], v[2:5]
	s_setprio 0
	s_barrier
	s_nop 1
	ds_read_b128 v[2:5], v140
	ds_read_b128 v[6:9], v140 offset:1024
	ds_read_b128 v[190:193], v140 offset:2048
	ds_read_b128 v[194:197], v140 offset:3072
	ds_read_b128 v[18:21], v138 offset:32768
	ds_read_b128 v[22:25], v138 offset:33792
	ds_read_b128 v[34:37], v137 offset:32768
	ds_read_b128 v[38:41], v137 offset:33792
	ds_read_b128 v[50:53], v136 offset:32768
	ds_read_b128 v[54:57], v136 offset:33792
	ds_read_b128 v[218:221], v135 offset:32768
	ds_read_b128 v[222:225], v135 offset:33792
	s_waitcnt vmcnt(2)
	s_barrier
; #define WAIT_V(n) asm volatile("s_waitcnt vmcnt(" #n ")" ::: "memory")
; #define WAIT_L(n) asm volatile("s_waitcnt lgkmcnt(" #n ")" ::: "memory")
; #define BAR __builtin_amdgcn_s_barrier()
; #define LDA(dst, b, h) for (int m = 0; m < 4; ++m) for (int k = 0; k < 2; ++k) \
;     dst[m][k] = *reinterpret_cast<const bf16x8*>((char*)SA(b, h) + lds_byte(wr * 64 + m * 16 + fr, k * 32 + fq * 8))
; #define LDB(dst, b, h) for (int n = 0; n < 2; ++n) for (int k = 0; k < 2; ++k) \
;     dst[n][k] = *reinterpret_cast<const bf16x8*>((char*)SB(b, h) + lds_byte(wc * 32 + n * 16 + fr, k * 32 + fq * 8))
; #define MMA(ai, bj, At_, Bt_) do { __builtin_amdgcn_s_setprio(1); \
;     for (int m = 0; m < 4; ++m) for (int n = 0; n < 2; ++n) for (int k = 0; k < 2; ++k) \
;       acc[ai][bj][m][n] = __builtin_amdgcn_mfma_f32_16x16x32_bf16(At_[m][k], Bt_[n][k], acc[ai][bj][m][n], 0, 0, 0); \
;     __builtin_amdgcn_s_setprio(0); } while (0)
; template <int K, int LD = K>
; __device__ __forceinline__ void gemm_main(const GAS bf16* A, const GAS bf16* Bt, int brow, int bcol, f32x4 (&acc)[2][2][4][2]) {
;     ...
;   { LDB(B0, 1, 0); LDA(At, 1, 0); WAIT_V(2); BAR; WAIT_L(0); MMA(0, 0, At, B0); BAR;
;     LDB(B1, 1, 1); WAIT_V(0); BAR; WAIT_L(0); MMA(0, 1, At, B1); BAR;
;     LDA(At, 1, 1); BAR; WAIT_L(0); MMA(1, 0, At, B0); MMA(1, 1, At, B1); BAR; }
;   if (wr == 0) BAR;
	s_waitcnt lgkmcnt(0)
	s_setprio 1
	s_waitcnt lgkmcnt(0)
	v_mfma_f32_16x16x32_bf16 v[66:69], v[18:21], v[2:5], v[126:129]
	v_mfma_f32_16x16x32_bf16 v[118:121], v[22:25], v[6:9], v[66:69]
	v_mfma_f32_16x16x32_bf16 v[66:69], v[18:21], v[190:193], v[122:125]
	v_mfma_f32_16x16x32_bf16 v[114:117], v[22:25], v[194:197], v[66:69]
	v_mfma_f32_16x16x32_bf16 v[66:69], v[34:37], v[2:5], v[142:145]
	v_mfma_f32_16x16x32_bf16 v[102:105], v[38:41], v[6:9], v[66:69]
	v_mfma_f32_16x16x32_bf16 v[66:69], v[34:37], v[190:193], v[198:201]
	v_mfma_f32_16x16x32_bf16 v[98:101], v[38:41], v[194:197], v[66:69]
	v_mfma_f32_16x16x32_bf16 v[66:69], v[50:53], v[2:5], v[110:113]
	v_mfma_f32_16x16x32_bf16 v[86:89], v[54:57], v[6:9], v[66:69]
	v_mfma_f32_16x16x32_bf16 v[66:69], v[50:53], v[190:193], v[106:109]
	v_mfma_f32_16x16x32_bf16 v[82:85], v[54:57], v[194:197], v[66:69]
	v_mfma_f32_16x16x32_bf16 v[66:69], v[218:221], v[2:5], v[202:205]
	v_mfma_f32_16x16x32_bf16 v[70:73], v[222:225], v[6:9], v[66:69]
	v_mfma_f32_16x16x32_bf16 v[66:69], v[218:221], v[190:193], v[206:209]
	v_mfma_f32_16x16x32_bf16 v[66:69], v[222:225], v[194:197], v[66:69]
	s_setprio 0
	s_barrier
	ds_read_b128 v[140:143], v139
	ds_read_b128 v[198:201], v139 offset:1024
	ds_read_b128 v[202:205], v139 offset:2048
	ds_read_b128 v[206:209], v139 offset:3072
	s_waitcnt vmcnt(0)
	s_barrier
	s_waitcnt lgkmcnt(0)
	s_setprio 1
	s_waitcnt lgkmcnt(0)
	v_mfma_f32_16x16x32_bf16 v[94:97], v[18:21], v[140:143], v[94:97]
	v_mfma_f32_16x16x32_bf16 v[18:21], v[18:21], v[202:205], v[90:93]
	v_mfma_f32_16x16x32_bf16 v[122:125], v[22:25], v[206:209], v[18:21]
	v_mfma_f32_16x16x32_bf16 v[18:21], v[34:37], v[140:143], v[162:165]
	v_mfma_f32_16x16x32_bf16 v[110:113], v[38:41], v[198:201], v[18:21]
	v_mfma_f32_16x16x32_bf16 v[18:21], v[34:37], v[202:205], v[166:169]
	v_mfma_f32_16x16x32_bf16 v[106:109], v[38:41], v[206:209], v[18:21]
	v_mfma_f32_16x16x32_bf16 v[18:21], v[50:53], v[140:143], v[78:81]
	v_mfma_f32_16x16x32_bf16 v[126:129], v[22:25], v[198:201], v[94:97]
	v_mfma_f32_16x16x32_bf16 v[94:97], v[54:57], v[198:201], v[18:21]
	v_mfma_f32_16x16x32_bf16 v[18:21], v[50:53], v[202:205], v[74:77]
	v_mfma_f32_16x16x32_bf16 v[90:93], v[54:57], v[206:209], v[18:21]
	v_mfma_f32_16x16x32_bf16 v[18:21], v[218:221], v[140:143], v[174:177]
	v_mfma_f32_16x16x32_bf16 v[78:81], v[222:225], v[198:201], v[18:21]
	v_mfma_f32_16x16x32_bf16 v[18:21], v[218:221], v[202:205], v[178:181]
	v_mfma_f32_16x16x32_bf16 v[74:77], v[222:225], v[206:209], v[18:21]
	s_setprio 0
	s_barrier
	ds_read_b128 v[162:165], v138 offset:49152
	ds_read_b128 v[166:169], v138 offset:50176
	ds_read_b128 v[174:177], v137 offset:49152
	ds_read_b128 v[178:181], v137 offset:50176
	ds_read_b128 v[218:221], v136 offset:49152
	ds_read_b128 v[136:139], v136 offset:50176
	ds_read_b128 v[222:225], v135 offset:49152
	ds_read_b128 v[226:229], v135 offset:50176
	s_barrier
	s_waitcnt lgkmcnt(0)
	s_setprio 1
	s_waitcnt lgkmcnt(0)
	v_mfma_f32_16x16x32_bf16 v[18:21], v[162:165], v[2:5], v[62:65]
	v_mfma_f32_16x16x32_bf16 v[54:57], v[166:169], v[6:9], v[18:21]
	v_mfma_f32_16x16x32_bf16 v[18:21], v[162:165], v[190:193], v[58:61]
	v_mfma_f32_16x16x32_bf16 v[50:53], v[166:169], v[194:197], v[18:21]
	v_mfma_f32_16x16x32_bf16 v[18:21], v[174:177], v[2:5], v[210:213]
	v_mfma_f32_16x16x32_bf16 v[38:41], v[178:181], v[6:9], v[18:21]
	v_mfma_f32_16x16x32_bf16 v[18:21], v[174:177], v[190:193], v[214:217]
	v_mfma_f32_16x16x32_bf16 v[34:37], v[178:181], v[194:197], v[18:21]
	v_mfma_f32_16x16x32_bf16 v[18:21], v[218:221], v[2:5], v[46:49]
	v_mfma_f32_16x16x32_bf16 v[2:5], v[222:225], v[2:5], v[146:149]
	v_mfma_f32_16x16x32_bf16 v[22:25], v[136:139], v[6:9], v[18:21]
	v_mfma_f32_16x16x32_bf16 v[18:21], v[218:221], v[190:193], v[42:45]
	v_mfma_f32_16x16x32_bf16 v[6:9], v[226:229], v[6:9], v[2:5]
	v_mfma_f32_16x16x32_bf16 v[2:5], v[222:225], v[190:193], v[150:153]
	v_mfma_f32_16x16x32_bf16 v[18:21], v[136:139], v[194:197], v[18:21]
	v_mfma_f32_16x16x32_bf16 v[2:5], v[226:229], v[194:197], v[2:5]
	s_setprio 0
	s_setprio 1
	v_mfma_f32_16x16x32_bf16 v[26:29], v[162:165], v[202:205], v[26:29]
	v_mfma_f32_16x16x32_bf16 v[58:61], v[166:169], v[206:209], v[26:29]
	v_mfma_f32_16x16x32_bf16 v[26:29], v[174:177], v[140:143], v[154:157]
	v_mfma_f32_16x16x32_bf16 v[46:49], v[178:181], v[198:201], v[26:29]
	v_mfma_f32_16x16x32_bf16 v[26:29], v[174:177], v[202:205], v[158:161]
	v_mfma_f32_16x16x32_bf16 v[10:13], v[218:221], v[202:205], v[10:13]
	v_mfma_f32_16x16x32_bf16 v[30:33], v[162:165], v[140:143], v[30:33]
	v_mfma_f32_16x16x32_bf16 v[42:45], v[178:181], v[206:209], v[26:29]
	v_mfma_f32_16x16x32_bf16 v[14:17], v[218:221], v[140:143], v[14:17]
	v_mfma_f32_16x16x32_bf16 v[26:29], v[136:139], v[206:209], v[10:13]
	v_mfma_f32_16x16x32_bf16 v[10:13], v[222:225], v[140:143], v[182:185]
	v_mfma_f32_16x16x32_bf16 v[62:65], v[166:169], v[198:201], v[30:33]
	v_mfma_f32_16x16x32_bf16 v[30:33], v[136:139], v[198:201], v[14:17]
	v_mfma_f32_16x16x32_bf16 v[14:17], v[226:229], v[198:201], v[10:13]
	v_mfma_f32_16x16x32_bf16 v[10:13], v[222:225], v[202:205], v[186:189]
	v_mfma_f32_16x16x32_bf16 v[10:13], v[226:229], v[206:209], v[10:13]
	s_setprio 0
	v_cmp_gt_u32_e32 vcc, s34, v134
	s_barrier
	s_and_saveexec_b64 s[10:11], vcc
	s_cbranch_execz .LBB0_770
	s_barrier

; #define STAGE(P, GP, ktrel) do { const GAS char* _g = (GP) + (ktrel) * (BK * 2); \
;     __builtin_amdgcn_global_load_lds((const GAS unsigned*)(_g + so0), (unsigned*)((char*)(P) + tid_ * 16), 16, 0, 0); \
;     __builtin_amdgcn_global_load_lds((const GAS unsigned*)(_g + so1), (unsigned*)((char*)(P) + tid_ * 16 + 8192), 16, 0, 0); } while (0)
; #define WAIT_L(n) asm volatile("s_waitcnt lgkmcnt(" #n ")" ::: "memory")
; #define BAR __builtin_amdgcn_s_barrier()
; #define SCHED __builtin_amdgcn_sched_barrier(0)
; #define LDA(dst, b, h) for (int m = 0; m < 4; ++m) for (int k = 0; k < 2; ++k) \
;     dst[m][k] = *reinterpret_cast<const bf16x8*>((char*)SA(b, h) + lds_byte(wr * 64 + m * 16 + fr, k * 32 + fq * 8))
; #define LDB(dst, b, h) for (int n = 0; n < 2; ++n) for (int k = 0; k < 2; ++k) \
;     dst[n][k] = *reinterpret_cast<const bf16x8*>((char*)SB(b, h) + lds_byte(wc * 32 + n * 16 + fr, k * 32 + fq * 8))
; #define MMA(ai, bj, At_, Bt_) do { __builtin_amdgcn_s_setprio(1); \
;     for (int m = 0; m < 4; ++m) for (int n = 0; n < 2; ++n) for (int k = 0; k < 2; ++k) \
;       acc[ai][bj][m][n] = __builtin_amdgcn_mfma_f32_16x16x32_bf16(At_[m][k], Bt_[n][k], acc[ai][bj][m][n], 0, 0, 0); \
;     __builtin_amdgcn_s_setprio(0); } while (0)
; template <int K, int LD = K>
; __device__ __forceinline__ void gemm_main(const GAS bf16* A, const GAS bf16* Bt, int brow, int bcol, f32x4 (&acc)[2][2][4][2]) {
;     ...
;     LDB(B0, 0, 0); SCHED; LDA(At, 0, 0); STAGE(SA(1, 1), pA1, 1);
;     WAIT_L(8); BAR; WAIT_L(0); MMA(0, 0, At, B0); BAR; SCHED;
;     LDB(B1, 0, 1); STAGE(SB(0, 0), pB0, 2);
;     BAR; WAIT_L(0); MMA(0, 1, At, B1); BAR;
;     LDA(At, 0, 1); STAGE(SA(0, 0), pA0, 2);
;     BAR; WAIT_L(0); MMA(1, 0, At, B0); BAR; SCHED;
.LBB0_884:
	ds_read_b128 v[160:163], v145
	ds_read_b128 v[164:167], v145 offset:1024
	ds_read_b128 v[174:177], v145 offset:2048
	ds_read_b128 v[178:181], v145 offset:3072
	v_lshl_add_u64 v[168:169], s[12:13], 0, v[130:131]
	v_readfirstlane_b32 s22, v144
	v_lshl_add_u64 v[214:215], v[168:169], 0, s[6:7]
	s_mov_b32 m0, s22
	v_lshl_add_u64 v[230:231], s[12:13], 0, v[132:133]
	v_readfirstlane_b32 s22, v143
	ds_read_b128 v[182:185], v139
	ds_read_b128 v[186:189], v139 offset:1024
	ds_read_b128 v[190:193], v138
	ds_read_b128 v[194:197], v138 offset:1024
	ds_read_b128 v[198:201], v137
	ds_read_b128 v[202:205], v137 offset:1024
	ds_read_b128 v[206:209], v136
	ds_read_b128 v[210:213], v136 offset:1024
	global_load_lds_dwordx4 v[214:215], off
	v_lshl_add_u64 v[214:215], v[230:231], 0, s[6:7]
	s_mov_b32 m0, s22
	s_nop 0
	global_load_lds_dwordx4 v[214:215], off
	s_waitcnt lgkmcnt(8)
	s_waitcnt vmcnt(10)
	s_barrier
	s_waitcnt lgkmcnt(0)
	s_setprio 1
	s_waitcnt lgkmcnt(0)
	v_mfma_f32_16x16x32_bf16 v[126:129], v[182:185], v[160:163], v[126:129]
	v_mfma_f32_16x16x32_bf16 v[122:125], v[182:185], v[174:177], v[122:125]
	v_mfma_f32_16x16x32_bf16 v[118:121], v[190:193], v[160:163], v[118:121]
	v_mfma_f32_16x16x32_bf16 v[114:117], v[190:193], v[174:177], v[114:117]
	v_mfma_f32_16x16x32_bf16 v[110:113], v[198:201], v[160:163], v[110:113]
	v_mfma_f32_16x16x32_bf16 v[106:109], v[198:201], v[174:177], v[106:109]
	v_mfma_f32_16x16x32_bf16 v[102:105], v[206:209], v[160:163], v[102:105]
	v_mfma_f32_16x16x32_bf16 v[98:101], v[206:209], v[174:177], v[98:101]
	v_mfma_f32_16x16x32_bf16 v[126:129], v[186:189], v[164:167], v[126:129]
	v_mfma_f32_16x16x32_bf16 v[122:125], v[186:189], v[178:181], v[122:125]
	v_mfma_f32_16x16x32_bf16 v[118:121], v[194:197], v[164:167], v[118:121]
	v_mfma_f32_16x16x32_bf16 v[114:117], v[194:197], v[178:181], v[114:117]
	v_mfma_f32_16x16x32_bf16 v[110:113], v[202:205], v[164:167], v[110:113]
	v_mfma_f32_16x16x32_bf16 v[106:109], v[202:205], v[178:181], v[106:109]
	v_mfma_f32_16x16x32_bf16 v[102:105], v[210:213], v[164:167], v[102:105]
	v_mfma_f32_16x16x32_bf16 v[98:101], v[210:213], v[178:181], v[98:101]
	s_setprio 0
	s_barrier
	v_lshl_add_u64 v[232:233], s[20:21], 0, v[130:131]
	v_readfirstlane_b32 s22, v152
	v_lshl_add_u64 v[234:235], v[232:233], 0, s[8:9]
	s_mov_b32 m0, s22
	ds_read_b128 v[214:217], v142
	ds_read_b128 v[218:221], v142 offset:1024
	ds_read_b128 v[222:225], v142 offset:2048
	ds_read_b128 v[226:229], v142 offset:3072
	global_load_lds_dwordx4 v[234:235], off
	v_lshl_add_u64 v[234:235], s[20:21], 0, v[132:133]
	v_readfirstlane_b32 s22, v153
	v_lshl_add_u64 v[236:237], v[234:235], 0, s[8:9]
	s_mov_b32 m0, s22
	s_add_u32 s20, s20, 0x100
	global_load_lds_dwordx4 v[236:237], off
	s_waitcnt vmcnt(10)
	s_barrier
	s_waitcnt lgkmcnt(0)
	s_addc_u32 s21, s21, 0
	s_setprio 1
	s_waitcnt lgkmcnt(0)
	v_mfma_f32_16x16x32_bf16 v[94:97], v[182:185], v[214:217], v[94:97]
	v_mfma_f32_16x16x32_bf16 v[90:93], v[182:185], v[222:225], v[90:93]
	v_mfma_f32_16x16x32_bf16 v[86:89], v[190:193], v[214:217], v[86:89]
	v_mfma_f32_16x16x32_bf16 v[82:85], v[190:193], v[222:225], v[82:85]
	v_mfma_f32_16x16x32_bf16 v[78:81], v[198:201], v[214:217], v[78:81]
	v_mfma_f32_16x16x32_bf16 v[74:77], v[198:201], v[222:225], v[74:77]
	v_mfma_f32_16x16x32_bf16 v[70:73], v[206:209], v[214:217], v[70:73]
	v_mfma_f32_16x16x32_bf16 v[66:69], v[206:209], v[222:225], v[66:69]
	v_mfma_f32_16x16x32_bf16 v[94:97], v[186:189], v[218:221], v[94:97]
	v_mfma_f32_16x16x32_bf16 v[90:93], v[186:189], v[226:229], v[90:93]
	v_mfma_f32_16x16x32_bf16 v[86:89], v[194:197], v[218:221], v[86:89]
	v_mfma_f32_16x16x32_bf16 v[82:85], v[194:197], v[226:229], v[82:85]
	v_mfma_f32_16x16x32_bf16 v[78:81], v[202:205], v[218:221], v[78:81]
	v_mfma_f32_16x16x32_bf16 v[74:77], v[202:205], v[226:229], v[74:77]
	v_mfma_f32_16x16x32_bf16 v[70:73], v[210:213], v[218:221], v[70:73]
	v_mfma_f32_16x16x32_bf16 v[66:69], v[210:213], v[226:229], v[66:69]
	s_setprio 0
	v_lshl_add_u64 v[236:237], s[18:19], 0, v[130:131]
	v_readfirstlane_b32 s22, v146
	v_lshl_add_u64 v[238:239], v[236:237], 0, s[8:9]
	s_mov_b32 m0, s22
	s_barrier
	ds_read_b128 v[182:185], v139 offset:16384
	ds_read_b128 v[186:189], v139 offset:17408
	ds_read_b128 v[190:193], v138 offset:16384
	ds_read_b128 v[194:197], v138 offset:17408
	ds_read_b128 v[198:201], v137 offset:16384
	ds_read_b128 v[202:205], v137 offset:17408
	ds_read_b128 v[206:209], v136 offset:16384
	ds_read_b128 v[210:213], v136 offset:17408
	global_load_lds_dwordx4 v[238:239], off
	v_lshl_add_u64 v[238:239], s[18:19], 0, v[132:133]
	v_readfirstlane_b32 s22, v147
	v_lshl_add_u64 v[240:241], v[238:239], 0, s[8:9]
	s_mov_b32 m0, s22
	s_add_u32 s18, s18, 0x100
	global_load_lds_dwordx4 v[240:241], off
	s_barrier
	s_waitcnt lgkmcnt(0)
	s_addc_u32 s19, s19, 0
	s_setprio 1
	s_waitcnt lgkmcnt(0)
	v_mfma_f32_16x16x32_bf16 v[62:65], v[182:185], v[160:163], v[62:65]
	v_mfma_f32_16x16x32_bf16 v[58:61], v[182:185], v[174:177], v[58:61]
	v_mfma_f32_16x16x32_bf16 v[54:57], v[190:193], v[160:163], v[54:57]
	v_mfma_f32_16x16x32_bf16 v[50:53], v[190:193], v[174:177], v[50:53]
	v_mfma_f32_16x16x32_bf16 v[46:49], v[198:201], v[160:163], v[46:49]
	v_mfma_f32_16x16x32_bf16 v[42:45], v[198:201], v[174:177], v[42:45]
	v_mfma_f32_16x16x32_bf16 v[38:41], v[206:209], v[160:163], v[38:41]
	v_mfma_f32_16x16x32_bf16 v[34:37], v[206:209], v[174:177], v[34:37]
	v_mfma_f32_16x16x32_bf16 v[62:65], v[186:189], v[164:167], v[62:65]
	v_mfma_f32_16x16x32_bf16 v[58:61], v[186:189], v[178:181], v[58:61]
	v_mfma_f32_16x16x32_bf16 v[54:57], v[194:197], v[164:167], v[54:57]
	v_mfma_f32_16x16x32_bf16 v[50:53], v[194:197], v[178:181], v[50:53]
	v_mfma_f32_16x16x32_bf16 v[46:49], v[202:205], v[164:167], v[46:49]
	v_mfma_f32_16x16x32_bf16 v[42:45], v[202:205], v[178:181], v[42:45]
	v_mfma_f32_16x16x32_bf16 v[38:41], v[210:213], v[164:167], v[38:41]
	v_mfma_f32_16x16x32_bf16 v[34:37], v[210:213], v[178:181], v[34:37]
	s_setprio 0
	s_barrier
; #define STAGE(P, GP, ktrel) do { const GAS char* _g = (GP) + (ktrel) * (BK * 2); \
;     __builtin_amdgcn_global_load_lds((const GAS unsigned*)(_g + so0), (unsigned*)((char*)(P) + tid_ * 16), 16, 0, 0); \
;     __builtin_amdgcn_global_load_lds((const GAS unsigned*)(_g + so1), (unsigned*)((char*)(P) + tid_ * 16 + 8192), 16, 0, 0); } while (0)
; #define WAIT_V(n) asm volatile("s_waitcnt vmcnt(" #n ")" ::: "memory")
; #define WAIT_L(n) asm volatile("s_waitcnt lgkmcnt(" #n ")" ::: "memory")
; #define BAR __builtin_amdgcn_s_barrier()
; #define SCHED __builtin_amdgcn_sched_barrier(0)
; #define LDA(dst, b, h) for (int m = 0; m < 4; ++m) for (int k = 0; k < 2; ++k) \
;     dst[m][k] = *reinterpret_cast<const bf16x8*>((char*)SA(b, h) + lds_byte(wr * 64 + m * 16 + fr, k * 32 + fq * 8))
; #define LDB(dst, b, h) for (int n = 0; n < 2; ++n) for (int k = 0; k < 2; ++k) \
;     dst[n][k] = *reinterpret_cast<const bf16x8*>((char*)SB(b, h) + lds_byte(wc * 32 + n * 16 + fr, k * 32 + fq * 8))
; #define MMA(ai, bj, At_, Bt_) do { __builtin_amdgcn_s_setprio(1); \
;     for (int m = 0; m < 4; ++m) for (int n = 0; n < 2; ++n) for (int k = 0; k < 2; ++k) \
;       acc[ai][bj][m][n] = __builtin_amdgcn_mfma_f32_16x16x32_bf16(At_[m][k], Bt_[n][k], acc[ai][bj][m][n], 0, 0, 0); \
;     __builtin_amdgcn_s_setprio(0); } while (0)
; template <int K, int LD = K>
; __device__ __forceinline__ void gemm_main(const GAS bf16* A, const GAS bf16* Bt, int brow, int bcol, f32x4 (&acc)[2][2][4][2]) {
;     ...
;     STAGE(SB(0, 1), pB1, 2);
;     WAIT_V(6); BAR; MMA(1, 1, At, B1); BAR;
;     LDB(B0, 1, 0); SCHED; LDA(At, 1, 0); STAGE(SA(0, 1), pA1, 2);
;     WAIT_L(8); BAR; WAIT_L(0); MMA(0, 0, At, B0); BAR; SCHED;
;     LDB(B1, 1, 1); STAGE(SB(1, 0), pB0, 3);
;     BAR; WAIT_L(0); MMA(0, 1, At, B1); BAR;
	v_lshl_add_u64 v[240:241], s[16:17], 0, v[130:131]
	v_readfirstlane_b32 s22, v154
	v_lshl_add_u64 v[160:161], v[240:241], 0, s[8:9]
	s_mov_b32 m0, s22
	v_lshl_add_u64 v[242:243], s[16:17], 0, v[132:133]
	v_readfirstlane_b32 s22, v155
	global_load_lds_dwordx4 v[160:161], off
	v_lshl_add_u64 v[160:161], v[242:243], 0, s[8:9]
	s_mov_b32 m0, s22
	s_add_u32 s16, s16, 0x100
	global_load_lds_dwordx4 v[160:161], off
	s_waitcnt vmcnt(10)
	s_addc_u32 s17, s17, 0
	s_barrier
	s_setprio 1
	v_mfma_f32_16x16x32_bf16 v[30:33], v[182:185], v[214:217], v[30:33]
	v_mfma_f32_16x16x32_bf16 v[26:29], v[182:185], v[222:225], v[26:29]
	v_mfma_f32_16x16x32_bf16 v[22:25], v[190:193], v[214:217], v[22:25]
	v_mfma_f32_16x16x32_bf16 v[18:21], v[190:193], v[222:225], v[18:21]
	v_mfma_f32_16x16x32_bf16 v[14:17], v[198:201], v[214:217], v[14:17]
	v_mfma_f32_16x16x32_bf16 v[10:13], v[198:201], v[222:225], v[10:13]
	v_mfma_f32_16x16x32_bf16 v[6:9], v[206:209], v[214:217], v[6:9]
	v_mfma_f32_16x16x32_bf16 v[2:5], v[206:209], v[222:225], v[2:5]
	v_mfma_f32_16x16x32_bf16 v[30:33], v[186:189], v[218:221], v[30:33]
	v_mfma_f32_16x16x32_bf16 v[26:29], v[186:189], v[226:229], v[26:29]
	v_mfma_f32_16x16x32_bf16 v[22:25], v[194:197], v[218:221], v[22:25]
	v_mfma_f32_16x16x32_bf16 v[18:21], v[194:197], v[226:229], v[18:21]
	v_mfma_f32_16x16x32_bf16 v[14:17], v[202:205], v[218:221], v[14:17]
	v_mfma_f32_16x16x32_bf16 v[10:13], v[202:205], v[226:229], v[10:13]
	v_mfma_f32_16x16x32_bf16 v[6:9], v[210:213], v[218:221], v[6:9]
	v_mfma_f32_16x16x32_bf16 v[2:5], v[210:213], v[226:229], v[2:5]
	s_setprio 0
	s_barrier
	ds_read_b128 v[160:163], v141
	ds_read_b128 v[164:167], v141 offset:1024
	ds_read_b128 v[174:177], v141 offset:2048
	ds_read_b128 v[178:181], v141 offset:3072
	v_readfirstlane_b32 s22, v148
	v_lshl_add_u64 v[168:169], v[168:169], 0, s[8:9]
	s_mov_b32 m0, s22
	v_readfirstlane_b32 s22, v149
	ds_read_b128 v[182:185], v139 offset:32768
	ds_read_b128 v[186:189], v139 offset:33792
	ds_read_b128 v[190:193], v138 offset:32768
	ds_read_b128 v[194:197], v138 offset:33792
	ds_read_b128 v[198:201], v137 offset:32768
	ds_read_b128 v[202:205], v137 offset:33792
	ds_read_b128 v[206:209], v136 offset:32768
	ds_read_b128 v[210:213], v136 offset:33792
	global_load_lds_dwordx4 v[168:169], off
	v_lshl_add_u64 v[168:169], v[230:231], 0, s[8:9]
	s_mov_b32 m0, s22
	s_add_u32 s12, s12, 0x100
	global_load_lds_dwordx4 v[168:169], off
	s_waitcnt lgkmcnt(8)
	s_waitcnt vmcnt(10)
	s_barrier
	s_waitcnt lgkmcnt(0)
	s_addc_u32 s13, s13, 0
	s_setprio 1
	s_waitcnt lgkmcnt(0)
	v_mfma_f32_16x16x32_bf16 v[126:129], v[182:185], v[160:163], v[126:129]
	v_mfma_f32_16x16x32_bf16 v[122:125], v[182:185], v[174:177], v[122:125]
	v_mfma_f32_16x16x32_bf16 v[118:121], v[190:193], v[160:163], v[118:121]
	v_mfma_f32_16x16x32_bf16 v[114:117], v[190:193], v[174:177], v[114:117]
	v_mfma_f32_16x16x32_bf16 v[110:113], v[198:201], v[160:163], v[110:113]
	v_mfma_f32_16x16x32_bf16 v[106:109], v[198:201], v[174:177], v[106:109]
	v_mfma_f32_16x16x32_bf16 v[102:105], v[206:209], v[160:163], v[102:105]
	v_mfma_f32_16x16x32_bf16 v[98:101], v[206:209], v[174:177], v[98:101]
	v_mfma_f32_16x16x32_bf16 v[126:129], v[186:189], v[164:167], v[126:129]
	v_mfma_f32_16x16x32_bf16 v[122:125], v[186:189], v[178:181], v[122:125]
	v_mfma_f32_16x16x32_bf16 v[118:121], v[194:197], v[164:167], v[118:121]
	v_mfma_f32_16x16x32_bf16 v[114:117], v[194:197], v[178:181], v[114:117]
	v_mfma_f32_16x16x32_bf16 v[110:113], v[202:205], v[164:167], v[110:113]
	v_mfma_f32_16x16x32_bf16 v[106:109], v[202:205], v[178:181], v[106:109]
	v_mfma_f32_16x16x32_bf16 v[102:105], v[210:213], v[164:167], v[102:105]
	v_mfma_f32_16x16x32_bf16 v[98:101], v[210:213], v[178:181], v[98:101]
	s_setprio 0
	s_barrier
	v_readfirstlane_b32 s22, v156
	v_lshl_add_u64 v[168:169], v[232:233], 0, s[10:11]
	s_mov_b32 m0, s22
	v_readfirstlane_b32 s22, v157
	ds_read_b128 v[214:217], v140
	ds_read_b128 v[218:221], v140 offset:1024
	ds_read_b128 v[222:225], v140 offset:2048
	ds_read_b128 v[226:229], v140 offset:3072
	global_load_lds_dwordx4 v[168:169], off
	v_lshl_add_u64 v[168:169], v[234:235], 0, s[10:11]
	s_mov_b32 m0, s22
	s_nop 0
	global_load_lds_dwordx4 v[168:169], off
	s_waitcnt vmcnt(10)
	s_barrier
	s_waitcnt lgkmcnt(0)
	s_setprio 1
	s_waitcnt lgkmcnt(0)
	v_mfma_f32_16x16x32_bf16 v[94:97], v[182:185], v[214:217], v[94:97]
	v_mfma_f32_16x16x32_bf16 v[90:93], v[182:185], v[222:225], v[90:93]
	v_mfma_f32_16x16x32_bf16 v[86:89], v[190:193], v[214:217], v[86:89]
	v_mfma_f32_16x16x32_bf16 v[82:85], v[190:193], v[222:225], v[82:85]
	v_mfma_f32_16x16x32_bf16 v[78:81], v[198:201], v[214:217], v[78:81]
	v_mfma_f32_16x16x32_bf16 v[74:77], v[198:201], v[222:225], v[74:77]
	v_mfma_f32_16x16x32_bf16 v[70:73], v[206:209], v[214:217], v[70:73]
	v_mfma_f32_16x16x32_bf16 v[66:69], v[206:209], v[222:225], v[66:69]
	v_mfma_f32_16x16x32_bf16 v[94:97], v[186:189], v[218:221], v[94:97]
	v_mfma_f32_16x16x32_bf16 v[90:93], v[186:189], v[226:229], v[90:93]
	v_mfma_f32_16x16x32_bf16 v[86:89], v[194:197], v[218:221], v[86:89]
	v_mfma_f32_16x16x32_bf16 v[82:85], v[194:197], v[226:229], v[82:85]
	v_mfma_f32_16x16x32_bf16 v[78:81], v[202:205], v[218:221], v[78:81]
	v_mfma_f32_16x16x32_bf16 v[74:77], v[202:205], v[226:229], v[74:77]
	v_mfma_f32_16x16x32_bf16 v[70:73], v[210:213], v[218:221], v[70:73]
	v_mfma_f32_16x16x32_bf16 v[66:69], v[210:213], v[226:229], v[66:69]
	s_setprio 0
	v_readfirstlane_b32 s22, v150
	v_lshl_add_u64 v[168:169], v[236:237], 0, s[10:11]
	s_mov_b32 m0, s22
	v_readfirstlane_b32 s22, v151
	s_barrier
; #define STAGE(P, GP, ktrel) do { const GAS char* _g = (GP) + (ktrel) * (BK * 2); \
;     __builtin_amdgcn_global_load_lds((const GAS unsigned*)(_g + so0), (unsigned*)((char*)(P) + tid_ * 16), 16, 0, 0); \
;     __builtin_amdgcn_global_load_lds((const GAS unsigned*)(_g + so1), (unsigned*)((char*)(P) + tid_ * 16 + 8192), 16, 0, 0); } while (0)
; #define WAIT_V(n) asm volatile("s_waitcnt vmcnt(" #n ")" ::: "memory")
; #define WAIT_L(n) asm volatile("s_waitcnt lgkmcnt(" #n ")" ::: "memory")
; #define BAR __builtin_amdgcn_s_barrier()
; #define SCHED __builtin_amdgcn_sched_barrier(0)
; #define LDA(dst, b, h) for (int m = 0; m < 4; ++m) for (int k = 0; k < 2; ++k) \
;     dst[m][k] = *reinterpret_cast<const bf16x8*>((char*)SA(b, h) + lds_byte(wr * 64 + m * 16 + fr, k * 32 + fq * 8))
; #define LDB(dst, b, h) for (int n = 0; n < 2; ++n) for (int k = 0; k < 2; ++k) \
;     dst[n][k] = *reinterpret_cast<const bf16x8*>((char*)SB(b, h) + lds_byte(wc * 32 + n * 16 + fr, k * 32 + fq * 8))
; #define MMA(ai, bj, At_, Bt_) do { __builtin_amdgcn_s_setprio(1); \
;     for (int m = 0; m < 4; ++m) for (int n = 0; n < 2; ++n) for (int k = 0; k < 2; ++k) \
;       acc[ai][bj][m][n] = __builtin_amdgcn_mfma_f32_16x16x32_bf16(At_[m][k], Bt_[n][k], acc[ai][bj][m][n], 0, 0, 0); \
;     __builtin_amdgcn_s_setprio(0); } while (0)
; template <int K, int LD = K>
; __device__ __forceinline__ void gemm_main(const GAS bf16* A, const GAS bf16* Bt, int brow, int bcol, f32x4 (&acc)[2][2][4][2]) {
;     ...
;     LDA(At, 1, 1); STAGE(SA(1, 0), pA0, 3);
;     BAR; WAIT_L(0); MMA(1, 0, At, B0); BAR; SCHED;
;     STAGE(SB(1, 1), pB1, 3);
;     WAIT_V(6); BAR; MMA(1, 1, At, B1); BAR;
;     pA0 += 4 * BK; pA1 += 4 * BK; pB0 += 4 * BK; pB1 += 4 * BK;
;     asm volatile("" : "+s"(pA0), "+s"(pA1), "+s"(pB0), "+s"(pB1));
;   }
;   { LDB(B0, 0, 0); LDA(At, 0, 0); STAGE(SA(1, 1), pA1, 1);
;     BAR; WAIT_L(0); MMA(0, 0, At, B0); BAR;
;     LDB(B1, 0, 1); BAR; WAIT_L(0); MMA(0, 1, At, B1); BAR;
	ds_read_b128 v[182:185], v139 offset:49152
	ds_read_b128 v[186:189], v139 offset:50176
	ds_read_b128 v[190:193], v138 offset:49152
	ds_read_b128 v[194:197], v138 offset:50176
	ds_read_b128 v[198:201], v137 offset:49152
	ds_read_b128 v[202:205], v137 offset:50176
	ds_read_b128 v[206:209], v136 offset:49152
	ds_read_b128 v[210:213], v136 offset:50176
	global_load_lds_dwordx4 v[168:169], off
	v_lshl_add_u64 v[168:169], v[238:239], 0, s[10:11]
	s_mov_b32 m0, s22
	s_nop 0
	global_load_lds_dwordx4 v[168:169], off
	s_barrier
	s_waitcnt lgkmcnt(0)
	s_setprio 1
	s_waitcnt lgkmcnt(0)
	v_mfma_f32_16x16x32_bf16 v[62:65], v[182:185], v[160:163], v[62:65]
	v_mfma_f32_16x16x32_bf16 v[58:61], v[182:185], v[174:177], v[58:61]
	v_mfma_f32_16x16x32_bf16 v[54:57], v[190:193], v[160:163], v[54:57]
	v_mfma_f32_16x16x32_bf16 v[50:53], v[190:193], v[174:177], v[50:53]
	v_mfma_f32_16x16x32_bf16 v[46:49], v[198:201], v[160:163], v[46:49]
	v_mfma_f32_16x16x32_bf16 v[42:45], v[198:201], v[174:177], v[42:45]
	v_mfma_f32_16x16x32_bf16 v[38:41], v[206:209], v[160:163], v[38:41]
	v_mfma_f32_16x16x32_bf16 v[34:37], v[206:209], v[174:177], v[34:37]
	v_mfma_f32_16x16x32_bf16 v[62:65], v[186:189], v[164:167], v[62:65]
	v_mfma_f32_16x16x32_bf16 v[58:61], v[186:189], v[178:181], v[58:61]
	v_mfma_f32_16x16x32_bf16 v[54:57], v[194:197], v[164:167], v[54:57]
	v_mfma_f32_16x16x32_bf16 v[50:53], v[194:197], v[178:181], v[50:53]
	v_mfma_f32_16x16x32_bf16 v[46:49], v[202:205], v[164:167], v[46:49]
	v_mfma_f32_16x16x32_bf16 v[42:45], v[202:205], v[178:181], v[42:45]
	v_mfma_f32_16x16x32_bf16 v[38:41], v[210:213], v[164:167], v[38:41]
	v_mfma_f32_16x16x32_bf16 v[34:37], v[210:213], v[178:181], v[34:37]
	s_setprio 0
	s_barrier
	v_readfirstlane_b32 s22, v158
	v_lshl_add_u64 v[160:161], v[240:241], 0, s[10:11]
	s_mov_b32 m0, s22
	v_readfirstlane_b32 s22, v159
	global_load_lds_dwordx4 v[160:161], off
	v_lshl_add_u64 v[160:161], v[242:243], 0, s[10:11]
	s_mov_b32 m0, s22
	s_nop 0
	global_load_lds_dwordx4 v[160:161], off
	s_waitcnt vmcnt(10)
	s_barrier
	s_setprio 1
	v_mfma_f32_16x16x32_bf16 v[30:33], v[182:185], v[214:217], v[30:33]
	v_mfma_f32_16x16x32_bf16 v[26:29], v[182:185], v[222:225], v[26:29]
	v_mfma_f32_16x16x32_bf16 v[22:25], v[190:193], v[214:217], v[22:25]
	v_mfma_f32_16x16x32_bf16 v[18:21], v[190:193], v[222:225], v[18:21]
	v_mfma_f32_16x16x32_bf16 v[14:17], v[198:201], v[214:217], v[14:17]
	v_mfma_f32_16x16x32_bf16 v[10:13], v[198:201], v[222:225], v[10:13]
	v_mfma_f32_16x16x32_bf16 v[6:9], v[206:209], v[214:217], v[6:9]
	v_mfma_f32_16x16x32_bf16 v[2:5], v[206:209], v[222:225], v[2:5]
	v_mfma_f32_16x16x32_bf16 v[30:33], v[186:189], v[218:221], v[30:33]
	v_mfma_f32_16x16x32_bf16 v[26:29], v[186:189], v[226:229], v[26:29]
	v_mfma_f32_16x16x32_bf16 v[22:25], v[194:197], v[218:221], v[22:25]
	v_mfma_f32_16x16x32_bf16 v[18:21], v[194:197], v[226:229], v[18:21]
	v_mfma_f32_16x16x32_bf16 v[14:17], v[202:205], v[218:221], v[14:17]
	v_mfma_f32_16x16x32_bf16 v[10:13], v[202:205], v[226:229], v[10:13]
	v_mfma_f32_16x16x32_bf16 v[6:9], v[210:213], v[218:221], v[6:9]
	v_mfma_f32_16x16x32_bf16 v[2:5], v[210:213], v[226:229], v[2:5]
	s_setprio 0
	s_add_i32 s15, s15, 2
	s_cmp_lt_u32 s15, 12
	s_barrier
	s_cbranch_scc1 .LBB0_884
	v_lshl_add_u64 v[198:199], s[12:13], 0, v[130:131]
	v_readfirstlane_b32 s15, v144
	v_lshl_add_u64 v[198:199], v[198:199], 0, s[6:7]
	s_mov_b32 m0, s15
	v_lshl_add_u64 v[132:133], s[12:13], 0, v[132:133]
	v_readfirstlane_b32 s12, v143
	ds_read_b128 v[146:149], v145
	ds_read_b128 v[150:153], v145 offset:1024
	ds_read_b128 v[154:157], v145 offset:2048
	ds_read_b128 v[158:161], v145 offset:3072
	ds_read_b128 v[162:165], v139
	ds_read_b128 v[166:169], v139 offset:1024
	ds_read_b128 v[174:177], v138
	ds_read_b128 v[178:181], v138 offset:1024
	ds_read_b128 v[182:185], v137
	ds_read_b128 v[186:189], v137 offset:1024
	ds_read_b128 v[190:193], v136
	ds_read_b128 v[194:197], v136 offset:1024
	global_load_lds_dwordx4 v[198:199], off
	v_lshl_add_u64 v[132:133], v[132:133], 0, s[6:7]
	s_mov_b32 m0, s12
	s_nop 0
	global_load_lds_dwordx4 v[132:133], off
	s_waitcnt vmcnt(10)
	s_barrier
	s_waitcnt lgkmcnt(0)
	s_setprio 1
	s_waitcnt lgkmcnt(0)
	v_mfma_f32_16x16x32_bf16 v[126:129], v[162:165], v[146:149], v[126:129]
	v_mfma_f32_16x16x32_bf16 v[122:125], v[162:165], v[154:157], v[122:125]
	v_mfma_f32_16x16x32_bf16 v[110:113], v[182:185], v[146:149], v[110:113]
	v_mfma_f32_16x16x32_bf16 v[106:109], v[182:185], v[154:157], v[106:109]
	v_mfma_f32_16x16x32_bf16 v[126:129], v[166:169], v[150:153], v[126:129]
	v_mfma_f32_16x16x32_bf16 v[122:125], v[166:169], v[158:161], v[122:125]
	v_mfma_f32_16x16x32_bf16 v[118:121], v[174:177], v[146:149], v[118:121]
	v_mfma_f32_16x16x32_bf16 v[114:117], v[174:177], v[154:157], v[114:117]
	v_mfma_f32_16x16x32_bf16 v[110:113], v[186:189], v[150:153], v[110:113]
	v_mfma_f32_16x16x32_bf16 v[106:109], v[186:189], v[158:161], v[106:109]
	v_mfma_f32_16x16x32_bf16 v[102:105], v[190:193], v[146:149], v[102:105]
	v_mfma_f32_16x16x32_bf16 v[98:101], v[190:193], v[154:157], v[98:101]
	v_mfma_f32_16x16x32_bf16 v[198:201], v[178:181], v[150:153], v[118:121]
	v_mfma_f32_16x16x32_bf16 v[202:205], v[178:181], v[158:161], v[114:117]
	v_mfma_f32_16x16x32_bf16 v[206:209], v[194:197], v[150:153], v[102:105]
	v_mfma_f32_16x16x32_bf16 v[210:213], v[194:197], v[158:161], v[98:101]
	s_setprio 0
	s_barrier
	s_nop 1
	ds_read_b128 v[98:101], v142
	ds_read_b128 v[102:105], v142 offset:1024
	ds_read_b128 v[114:117], v142 offset:2048
	ds_read_b128 v[118:121], v142 offset:3072
	s_waitcnt vmcnt(8)
	s_barrier
; #define WAIT_V(n) asm volatile("s_waitcnt vmcnt(" #n ")" ::: "memory")
; #define WAIT_L(n) asm volatile("s_waitcnt lgkmcnt(" #n ")" ::: "memory")
; #define BAR __builtin_amdgcn_s_barrier()
; #define LDA(dst, b, h) for (int m = 0; m < 4; ++m) for (int k = 0; k < 2; ++k) \
;     dst[m][k] = *reinterpret_cast<const bf16x8*>((char*)SA(b, h) + lds_byte(wr * 64 + m * 16 + fr, k * 32 + fq * 8))
; #define LDB(dst, b, h) for (int n = 0; n < 2; ++n) for (int k = 0; k < 2; ++k) \
;     dst[n][k] = *reinterpret_cast<const bf16x8*>((char*)SB(b, h) + lds_byte(wc * 32 + n * 16 + fr, k * 32 + fq * 8))
; #define MMA(ai, bj, At_, Bt_) do { __builtin_amdgcn_s_setprio(1); \
;     for (int m = 0; m < 4; ++m) for (int n = 0; n < 2; ++n) for (int k = 0; k < 2; ++k) \
;       acc[ai][bj][m][n] = __builtin_amdgcn_mfma_f32_16x16x32_bf16(At_[m][k], Bt_[n][k], acc[ai][bj][m][n], 0, 0, 0); \
;     __builtin_amdgcn_s_setprio(0); } while (0)
; template <int K, int LD = K>
; __device__ __forceinline__ void gemm_main(const GAS bf16* A, const GAS bf16* Bt, int brow, int bcol, f32x4 (&acc)[2][2][4][2]) {
;     ...
;     LDB(B1, 0, 1); BAR; WAIT_L(0); MMA(0, 1, At, B1); BAR;
;     LDA(At, 0, 1); WAIT_V(4); BAR; WAIT_L(0); MMA(1, 0, At, B0); MMA(1, 1, At, B1); BAR; }
;   { LDB(B0, 1, 0); LDA(At, 1, 0); WAIT_V(2); BAR; WAIT_L(0); MMA(0, 0, At, B0); BAR;
	s_waitcnt lgkmcnt(0)
	s_setprio 1
	s_waitcnt lgkmcnt(0)
	v_mfma_f32_16x16x32_bf16 v[94:97], v[162:165], v[98:101], v[94:97]
	v_mfma_f32_16x16x32_bf16 v[90:93], v[162:165], v[114:117], v[90:93]
	v_mfma_f32_16x16x32_bf16 v[78:81], v[182:185], v[98:101], v[78:81]
	v_mfma_f32_16x16x32_bf16 v[74:77], v[182:185], v[114:117], v[74:77]
	v_mfma_f32_16x16x32_bf16 v[94:97], v[166:169], v[102:105], v[94:97]
	v_mfma_f32_16x16x32_bf16 v[90:93], v[166:169], v[118:121], v[90:93]
	v_mfma_f32_16x16x32_bf16 v[86:89], v[174:177], v[98:101], v[86:89]
	v_mfma_f32_16x16x32_bf16 v[82:85], v[174:177], v[114:117], v[82:85]
	v_mfma_f32_16x16x32_bf16 v[78:81], v[186:189], v[102:105], v[78:81]
	v_mfma_f32_16x16x32_bf16 v[74:77], v[186:189], v[118:121], v[74:77]
	v_mfma_f32_16x16x32_bf16 v[70:73], v[190:193], v[98:101], v[70:73]
	v_mfma_f32_16x16x32_bf16 v[66:69], v[190:193], v[114:117], v[66:69]
	v_mfma_f32_16x16x32_bf16 v[142:145], v[178:181], v[102:105], v[86:89]
	v_mfma_f32_16x16x32_bf16 v[162:165], v[178:181], v[118:121], v[82:85]
	v_mfma_f32_16x16x32_bf16 v[166:169], v[194:197], v[102:105], v[70:73]
	v_mfma_f32_16x16x32_bf16 v[174:177], v[194:197], v[118:121], v[66:69]
	s_setprio 0
	s_barrier
	s_nop 1
	ds_read_b128 v[66:69], v139 offset:16384
	ds_read_b128 v[70:73], v139 offset:17408
	ds_read_b128 v[82:85], v138 offset:16384
	ds_read_b128 v[86:89], v138 offset:17408
	ds_read_b128 v[178:181], v137 offset:16384
	ds_read_b128 v[182:185], v137 offset:17408
	ds_read_b128 v[186:189], v136 offset:16384
	ds_read_b128 v[190:193], v136 offset:17408
	s_waitcnt vmcnt(4)
	s_barrier
	s_waitcnt lgkmcnt(0)
	s_setprio 1
	s_waitcnt lgkmcnt(0)
	v_mfma_f32_16x16x32_bf16 v[62:65], v[66:69], v[146:149], v[62:65]
	v_mfma_f32_16x16x32_bf16 v[58:61], v[66:69], v[154:157], v[58:61]
	v_mfma_f32_16x16x32_bf16 v[46:49], v[178:181], v[146:149], v[46:49]
	v_mfma_f32_16x16x32_bf16 v[38:41], v[186:189], v[146:149], v[38:41]
	v_mfma_f32_16x16x32_bf16 v[62:65], v[70:73], v[150:153], v[62:65]
	v_mfma_f32_16x16x32_bf16 v[58:61], v[70:73], v[158:161], v[58:61]
	v_mfma_f32_16x16x32_bf16 v[54:57], v[82:85], v[146:149], v[54:57]
	v_mfma_f32_16x16x32_bf16 v[50:53], v[82:85], v[154:157], v[50:53]
	v_mfma_f32_16x16x32_bf16 v[46:49], v[182:185], v[150:153], v[46:49]
	v_mfma_f32_16x16x32_bf16 v[42:45], v[178:181], v[154:157], v[42:45]
	v_mfma_f32_16x16x32_bf16 v[38:41], v[190:193], v[150:153], v[38:41]
	v_mfma_f32_16x16x32_bf16 v[34:37], v[186:189], v[154:157], v[34:37]
	v_mfma_f32_16x16x32_bf16 v[194:197], v[86:89], v[150:153], v[54:57]
	v_mfma_f32_16x16x32_bf16 v[214:217], v[86:89], v[158:161], v[50:53]
	v_mfma_f32_16x16x32_bf16 v[218:221], v[182:185], v[158:161], v[42:45]
	v_mfma_f32_16x16x32_bf16 v[146:149], v[190:193], v[158:161], v[34:37]
	s_setprio 0
	s_setprio 1
	v_mfma_f32_16x16x32_bf16 v[30:33], v[66:69], v[98:101], v[30:33]
	v_mfma_f32_16x16x32_bf16 v[26:29], v[66:69], v[114:117], v[26:29]
	v_mfma_f32_16x16x32_bf16 v[14:17], v[178:181], v[98:101], v[14:17]
	v_mfma_f32_16x16x32_bf16 v[6:9], v[186:189], v[98:101], v[6:9]
	v_mfma_f32_16x16x32_bf16 v[30:33], v[70:73], v[102:105], v[30:33]
	v_mfma_f32_16x16x32_bf16 v[26:29], v[70:73], v[118:121], v[26:29]
	v_mfma_f32_16x16x32_bf16 v[22:25], v[82:85], v[98:101], v[22:25]
	v_mfma_f32_16x16x32_bf16 v[18:21], v[82:85], v[114:117], v[18:21]
	v_mfma_f32_16x16x32_bf16 v[14:17], v[182:185], v[102:105], v[14:17]
	v_mfma_f32_16x16x32_bf16 v[10:13], v[178:181], v[114:117], v[10:13]
	v_mfma_f32_16x16x32_bf16 v[6:9], v[190:193], v[102:105], v[6:9]
	v_mfma_f32_16x16x32_bf16 v[2:5], v[186:189], v[114:117], v[2:5]
	v_mfma_f32_16x16x32_bf16 v[150:153], v[86:89], v[102:105], v[22:25]
	v_mfma_f32_16x16x32_bf16 v[154:157], v[86:89], v[118:121], v[18:21]
	v_mfma_f32_16x16x32_bf16 v[158:161], v[182:185], v[118:121], v[10:13]
	v_mfma_f32_16x16x32_bf16 v[178:181], v[190:193], v[118:121], v[2:5]
	s_setprio 0
	s_barrier
	s_nop 1
	ds_read_b128 v[2:5], v141
	ds_read_b128 v[10:13], v141 offset:1024
	ds_read_b128 v[182:185], v141 offset:2048
	ds_read_b128 v[186:189], v141 offset:3072
	ds_read_b128 v[18:21], v139 offset:32768
	ds_read_b128 v[22:25], v139 offset:33792
	ds_read_b128 v[34:37], v138 offset:32768
	ds_read_b128 v[42:45], v138 offset:33792
	ds_read_b128 v[50:53], v137 offset:32768
	ds_read_b128 v[54:57], v137 offset:33792
	ds_read_b128 v[190:193], v136 offset:32768
	ds_read_b128 v[222:225], v136 offset:33792
	s_waitcnt vmcnt(2)
	s_barrier
; #define WAIT_V(n) asm volatile("s_waitcnt vmcnt(" #n ")" ::: "memory")
; #define WAIT_L(n) asm volatile("s_waitcnt lgkmcnt(" #n ")" ::: "memory")
; #define BAR __builtin_amdgcn_s_barrier()
; #define LDA(dst, b, h) for (int m = 0; m < 4; ++m) for (int k = 0; k < 2; ++k) \
;     dst[m][k] = *reinterpret_cast<const bf16x8*>((char*)SA(b, h) + lds_byte(wr * 64 + m * 16 + fr, k * 32 + fq * 8))
; #define LDB(dst, b, h) for (int n = 0; n < 2; ++n) for (int k = 0; k < 2; ++k) \
;     dst[n][k] = *reinterpret_cast<const bf16x8*>((char*)SB(b, h) + lds_byte(wc * 32 + n * 16 + fr, k * 32 + fq * 8))
; #define MMA(ai, bj, At_, Bt_) do { __builtin_amdgcn_s_setprio(1); \
;     for (int m = 0; m < 4; ++m) for (int n = 0; n < 2; ++n) for (int k = 0; k < 2; ++k) \
;       acc[ai][bj][m][n] = __builtin_amdgcn_mfma_f32_16x16x32_bf16(At_[m][k], Bt_[n][k], acc[ai][bj][m][n], 0, 0, 0); \
;     __builtin_amdgcn_s_setprio(0); } while (0)
; template <int K, int LD = K>
; __device__ __forceinline__ void gemm_main(const GAS bf16* A, const GAS bf16* Bt, int brow, int bcol, f32x4 (&acc)[2][2][4][2]) {
;     ...
;   { LDB(B0, 1, 0); LDA(At, 1, 0); WAIT_V(2); BAR; WAIT_L(0); MMA(0, 0, At, B0); BAR;
;     LDB(B1, 1, 1); WAIT_V(0); BAR; WAIT_L(0); MMA(0, 1, At, B1); BAR;
;     LDA(At, 1, 1); BAR; WAIT_L(0); MMA(1, 0, At, B0); MMA(1, 1, At, B1); BAR; }
;   if (wr == 0) BAR;
	s_waitcnt lgkmcnt(0)
	s_setprio 1
	s_waitcnt lgkmcnt(0)
	v_mfma_f32_16x16x32_bf16 v[66:69], v[18:21], v[2:5], v[126:129]
	v_mfma_f32_16x16x32_bf16 v[118:121], v[22:25], v[10:13], v[66:69]
	v_mfma_f32_16x16x32_bf16 v[66:69], v[18:21], v[182:185], v[122:125]
	v_mfma_f32_16x16x32_bf16 v[114:117], v[22:25], v[186:189], v[66:69]
	v_mfma_f32_16x16x32_bf16 v[66:69], v[34:37], v[2:5], v[198:201]
	v_mfma_f32_16x16x32_bf16 v[102:105], v[42:45], v[10:13], v[66:69]
	v_mfma_f32_16x16x32_bf16 v[66:69], v[34:37], v[182:185], v[202:205]
	v_mfma_f32_16x16x32_bf16 v[98:101], v[42:45], v[186:189], v[66:69]
	v_mfma_f32_16x16x32_bf16 v[66:69], v[50:53], v[2:5], v[110:113]
	v_mfma_f32_16x16x32_bf16 v[86:89], v[54:57], v[10:13], v[66:69]
	v_mfma_f32_16x16x32_bf16 v[66:69], v[50:53], v[182:185], v[106:109]
	v_mfma_f32_16x16x32_bf16 v[82:85], v[54:57], v[186:189], v[66:69]
	v_mfma_f32_16x16x32_bf16 v[66:69], v[190:193], v[2:5], v[206:209]
	v_mfma_f32_16x16x32_bf16 v[70:73], v[222:225], v[10:13], v[66:69]
	v_mfma_f32_16x16x32_bf16 v[66:69], v[190:193], v[182:185], v[210:213]
	v_mfma_f32_16x16x32_bf16 v[66:69], v[222:225], v[186:189], v[66:69]
	s_setprio 0
	s_barrier
	ds_read_b128 v[198:201], v140
	ds_read_b128 v[202:205], v140 offset:1024
	ds_read_b128 v[206:209], v140 offset:2048
	ds_read_b128 v[210:213], v140 offset:3072
	s_waitcnt vmcnt(0)
	s_barrier
	s_waitcnt lgkmcnt(0)
	s_setprio 1
	s_waitcnt lgkmcnt(0)
	v_mfma_f32_16x16x32_bf16 v[94:97], v[18:21], v[198:201], v[94:97]
	v_mfma_f32_16x16x32_bf16 v[18:21], v[18:21], v[206:209], v[90:93]
	v_mfma_f32_16x16x32_bf16 v[122:125], v[22:25], v[210:213], v[18:21]
	v_mfma_f32_16x16x32_bf16 v[18:21], v[34:37], v[198:201], v[142:145]
	v_mfma_f32_16x16x32_bf16 v[110:113], v[42:45], v[202:205], v[18:21]
	v_mfma_f32_16x16x32_bf16 v[18:21], v[34:37], v[206:209], v[162:165]
	v_mfma_f32_16x16x32_bf16 v[106:109], v[42:45], v[210:213], v[18:21]
	v_mfma_f32_16x16x32_bf16 v[18:21], v[50:53], v[198:201], v[78:81]
	v_mfma_f32_16x16x32_bf16 v[126:129], v[22:25], v[202:205], v[94:97]
	v_mfma_f32_16x16x32_bf16 v[94:97], v[54:57], v[202:205], v[18:21]
	v_mfma_f32_16x16x32_bf16 v[18:21], v[50:53], v[206:209], v[74:77]
	v_mfma_f32_16x16x32_bf16 v[90:93], v[54:57], v[210:213], v[18:21]
	v_mfma_f32_16x16x32_bf16 v[18:21], v[190:193], v[198:201], v[166:169]
	v_mfma_f32_16x16x32_bf16 v[78:81], v[222:225], v[202:205], v[18:21]
	v_mfma_f32_16x16x32_bf16 v[18:21], v[190:193], v[206:209], v[174:177]
	v_mfma_f32_16x16x32_bf16 v[74:77], v[222:225], v[210:213], v[18:21]
	s_setprio 0
	s_barrier
	ds_read_b128 v[140:143], v139 offset:49152
	ds_read_b128 v[162:165], v139 offset:50176
	ds_read_b128 v[166:169], v138 offset:49152
	ds_read_b128 v[174:177], v138 offset:50176
	ds_read_b128 v[190:193], v137 offset:49152
	ds_read_b128 v[222:225], v137 offset:50176
	ds_read_b128 v[226:229], v136 offset:49152
	ds_read_b128 v[136:139], v136 offset:50176
	s_barrier
	s_waitcnt lgkmcnt(0)
	s_setprio 1
	s_waitcnt lgkmcnt(0)
	v_mfma_f32_16x16x32_bf16 v[18:21], v[140:143], v[2:5], v[62:65]
	v_mfma_f32_16x16x32_bf16 v[54:57], v[162:165], v[10:13], v[18:21]
	v_mfma_f32_16x16x32_bf16 v[18:21], v[140:143], v[182:185], v[58:61]
	v_mfma_f32_16x16x32_bf16 v[50:53], v[162:165], v[186:189], v[18:21]
	v_mfma_f32_16x16x32_bf16 v[18:21], v[166:169], v[2:5], v[194:197]
	v_mfma_f32_16x16x32_bf16 v[42:45], v[174:177], v[10:13], v[18:21]
	v_mfma_f32_16x16x32_bf16 v[18:21], v[166:169], v[182:185], v[214:217]
	v_mfma_f32_16x16x32_bf16 v[34:37], v[174:177], v[186:189], v[18:21]
	v_mfma_f32_16x16x32_bf16 v[18:21], v[190:193], v[2:5], v[46:49]
	v_mfma_f32_16x16x32_bf16 v[2:5], v[226:229], v[2:5], v[38:41]
	v_mfma_f32_16x16x32_bf16 v[22:25], v[222:225], v[10:13], v[18:21]
	v_mfma_f32_16x16x32_bf16 v[18:21], v[190:193], v[182:185], v[218:221]
	v_mfma_f32_16x16x32_bf16 v[10:13], v[136:139], v[10:13], v[2:5]
	v_mfma_f32_16x16x32_bf16 v[2:5], v[226:229], v[182:185], v[146:149]
	v_mfma_f32_16x16x32_bf16 v[18:21], v[222:225], v[186:189], v[18:21]
	v_mfma_f32_16x16x32_bf16 v[2:5], v[136:139], v[186:189], v[2:5]
	s_setprio 0
	s_setprio 1
	v_mfma_f32_16x16x32_bf16 v[26:29], v[140:143], v[206:209], v[26:29]
	v_mfma_f32_16x16x32_bf16 v[30:33], v[140:143], v[198:201], v[30:33]
	v_mfma_f32_16x16x32_bf16 v[58:61], v[162:165], v[210:213], v[26:29]
	v_mfma_f32_16x16x32_bf16 v[26:29], v[166:169], v[198:201], v[150:153]
	v_mfma_f32_16x16x32_bf16 v[14:17], v[190:193], v[198:201], v[14:17]
	v_mfma_f32_16x16x32_bf16 v[62:65], v[162:165], v[202:205], v[30:33]
	v_mfma_f32_16x16x32_bf16 v[46:49], v[174:177], v[202:205], v[26:29]
	v_mfma_f32_16x16x32_bf16 v[26:29], v[166:169], v[206:209], v[154:157]
	v_mfma_f32_16x16x32_bf16 v[30:33], v[222:225], v[202:205], v[14:17]
	v_mfma_f32_16x16x32_bf16 v[14:17], v[190:193], v[206:209], v[158:161]
	v_mfma_f32_16x16x32_bf16 v[6:9], v[226:229], v[198:201], v[6:9]
	v_mfma_f32_16x16x32_bf16 v[38:41], v[174:177], v[210:213], v[26:29]
	v_mfma_f32_16x16x32_bf16 v[26:29], v[222:225], v[210:213], v[14:17]
	v_mfma_f32_16x16x32_bf16 v[14:17], v[136:139], v[202:205], v[6:9]
	v_mfma_f32_16x16x32_bf16 v[6:9], v[226:229], v[206:209], v[178:181]
	v_mfma_f32_16x16x32_bf16 v[6:9], v[136:139], v[210:213], v[6:9]
	s_setprio 0
	v_cmp_gt_u32_e32 vcc, s34, v135
	s_barrier
	s_and_saveexec_b64 s[12:13], vcc
	s_cbranch_execz .LBB0_887
	s_barrier

; #define STAGE(P, GP, ktrel) do { const GAS char* _g = (GP) + (ktrel) * (BK * 2); \
;     __builtin_amdgcn_global_load_lds((const GAS unsigned*)(_g + so0), (unsigned*)((char*)(P) + tid_ * 16), 16, 0, 0); \
;     __builtin_amdgcn_global_load_lds((const GAS unsigned*)(_g + so1), (unsigned*)((char*)(P) + tid_ * 16 + 8192), 16, 0, 0); } while (0)
; #define WAIT_V(n) asm volatile("s_waitcnt vmcnt(" #n ")" ::: "memory")
; #define WAIT_L(n) asm volatile("s_waitcnt lgkmcnt(" #n ")" ::: "memory")
; #define BAR __builtin_amdgcn_s_barrier()
; #define SCHED __builtin_amdgcn_sched_barrier(0)
; #define LDA(dst, b, h) for (int m = 0; m < 4; ++m) for (int k = 0; k < 2; ++k) \
;     dst[m][k] = *reinterpret_cast<const bf16x8*>((char*)SA(b, h) + lds_byte(wr * 64 + m * 16 + fr, k * 32 + fq * 8))
; #define LDB(dst, b, h) for (int n = 0; n < 2; ++n) for (int k = 0; k < 2; ++k) \
;     dst[n][k] = *reinterpret_cast<const bf16x8*>((char*)SB(b, h) + lds_byte(wc * 32 + n * 16 + fr, k * 32 + fq * 8))
; #define MMA(ai, bj, At_, Bt_) do { __builtin_amdgcn_s_setprio(1); \
;     for (int m = 0; m < 4; ++m) for (int n = 0; n < 2; ++n) for (int k = 0; k < 2; ++k) \
;       acc[ai][bj][m][n] = __builtin_amdgcn_mfma_f32_16x16x32_bf16(At_[m][k], Bt_[n][k], acc[ai][bj][m][n], 0, 0, 0); \
;     __builtin_amdgcn_s_setprio(0); } while (0)
; template <int K, int LD = K>
; __device__ __forceinline__ void gemm_main(const GAS bf16* A, const GAS bf16* Bt, int brow, int bcol, f32x4 (&acc)[2][2][4][2]) {
;     ...
;   for (int t = 0; t < nt - 2; t += 2) {
;     LDB(B0, 0, 0); SCHED; LDA(At, 0, 0); STAGE(SA(1, 1), pA1, 1);
;     WAIT_L(8); BAR; WAIT_L(0); MMA(0, 0, At, B0); BAR; SCHED;
;     LDB(B1, 0, 1); STAGE(SB(0, 0), pB0, 2);
;     BAR; WAIT_L(0); MMA(0, 1, At, B1); BAR;
;     LDA(At, 0, 1); STAGE(SA(0, 0), pA0, 2);
;     BAR; WAIT_L(0); MMA(1, 0, At, B0); BAR; SCHED;
;     STAGE(SB(0, 1), pB1, 2);
;     WAIT_V(6); BAR; MMA(1, 1, At, B1); BAR;
;     LDB(B0, 1, 0); SCHED; LDA(At, 1, 0); STAGE(SA(0, 1), pA1, 2);
;     WAIT_L(8); BAR; WAIT_L(0); MMA(0, 0, At, B0); BAR; SCHED;
;     LDB(B1, 1, 1); STAGE(SB(1, 0), pB0, 3);
;     BAR; WAIT_L(0); MMA(0, 1, At, B1); BAR;
.LBB0_1105:
	ds_read_b128 v[160:163], v144
	ds_read_b128 v[164:167], v144 offset:1024
	ds_read_b128 v[174:177], v144 offset:2048
	ds_read_b128 v[178:181], v144 offset:3072
	v_lshl_add_u64 v[168:169], s[12:13], 0, v[130:131]
	v_readfirstlane_b32 s23, v143
	v_lshl_add_u64 v[214:215], v[168:169], 0, s[6:7]
	s_mov_b32 m0, s23
	v_lshl_add_u64 v[230:231], s[12:13], 0, v[132:133]
	v_readfirstlane_b32 s23, v142
	ds_read_b128 v[182:185], v138
	ds_read_b128 v[186:189], v138 offset:1024
	ds_read_b128 v[190:193], v137
	ds_read_b128 v[194:197], v137 offset:1024
	ds_read_b128 v[198:201], v136
	ds_read_b128 v[202:205], v136 offset:1024
	ds_read_b128 v[206:209], v135
	ds_read_b128 v[210:213], v135 offset:1024
	global_load_lds_dwordx4 v[214:215], off
	v_lshl_add_u64 v[214:215], v[230:231], 0, s[6:7]
	s_mov_b32 m0, s23
	s_nop 0
	global_load_lds_dwordx4 v[214:215], off
	s_waitcnt lgkmcnt(8)
	s_waitcnt vmcnt(10)
	s_barrier
	s_waitcnt lgkmcnt(0)
	s_setprio 1
	s_waitcnt lgkmcnt(0)
	v_mfma_f32_16x16x32_bf16 v[126:129], v[182:185], v[160:163], v[126:129]
	v_mfma_f32_16x16x32_bf16 v[122:125], v[182:185], v[174:177], v[122:125]
	v_mfma_f32_16x16x32_bf16 v[118:121], v[190:193], v[160:163], v[118:121]
	v_mfma_f32_16x16x32_bf16 v[114:117], v[190:193], v[174:177], v[114:117]
	v_mfma_f32_16x16x32_bf16 v[110:113], v[198:201], v[160:163], v[110:113]
	v_mfma_f32_16x16x32_bf16 v[106:109], v[198:201], v[174:177], v[106:109]
	v_mfma_f32_16x16x32_bf16 v[102:105], v[206:209], v[160:163], v[102:105]
	v_mfma_f32_16x16x32_bf16 v[98:101], v[206:209], v[174:177], v[98:101]
	v_mfma_f32_16x16x32_bf16 v[126:129], v[186:189], v[164:167], v[126:129]
	v_mfma_f32_16x16x32_bf16 v[122:125], v[186:189], v[178:181], v[122:125]
	v_mfma_f32_16x16x32_bf16 v[118:121], v[194:197], v[164:167], v[118:121]
	v_mfma_f32_16x16x32_bf16 v[114:117], v[194:197], v[178:181], v[114:117]
	v_mfma_f32_16x16x32_bf16 v[110:113], v[202:205], v[164:167], v[110:113]
	v_mfma_f32_16x16x32_bf16 v[106:109], v[202:205], v[178:181], v[106:109]
	v_mfma_f32_16x16x32_bf16 v[102:105], v[210:213], v[164:167], v[102:105]
	v_mfma_f32_16x16x32_bf16 v[98:101], v[210:213], v[178:181], v[98:101]
	s_setprio 0
	s_barrier
	v_lshl_add_u64 v[232:233], s[20:21], 0, v[130:131]
	v_readfirstlane_b32 s23, v151
	v_lshl_add_u64 v[234:235], v[232:233], 0, s[8:9]
	s_mov_b32 m0, s23
	ds_read_b128 v[214:217], v141
	ds_read_b128 v[218:221], v141 offset:1024
	ds_read_b128 v[222:225], v141 offset:2048
	ds_read_b128 v[226:229], v141 offset:3072
	global_load_lds_dwordx4 v[234:235], off
	v_lshl_add_u64 v[234:235], s[20:21], 0, v[132:133]
	v_readfirstlane_b32 s23, v152
	v_lshl_add_u64 v[236:237], v[234:235], 0, s[8:9]
	s_mov_b32 m0, s23
	s_add_u32 s20, s20, 0x100
	global_load_lds_dwordx4 v[236:237], off
	s_waitcnt vmcnt(10)
	s_barrier
	s_waitcnt lgkmcnt(0)
	s_addc_u32 s21, s21, 0
	s_setprio 1
	s_waitcnt lgkmcnt(0)
	v_mfma_f32_16x16x32_bf16 v[94:97], v[182:185], v[214:217], v[94:97]
	v_mfma_f32_16x16x32_bf16 v[90:93], v[182:185], v[222:225], v[90:93]
	v_mfma_f32_16x16x32_bf16 v[86:89], v[190:193], v[214:217], v[86:89]
	v_mfma_f32_16x16x32_bf16 v[82:85], v[190:193], v[222:225], v[82:85]
	v_mfma_f32_16x16x32_bf16 v[78:81], v[198:201], v[214:217], v[78:81]
	v_mfma_f32_16x16x32_bf16 v[74:77], v[198:201], v[222:225], v[74:77]
	v_mfma_f32_16x16x32_bf16 v[70:73], v[206:209], v[214:217], v[70:73]
	v_mfma_f32_16x16x32_bf16 v[66:69], v[206:209], v[222:225], v[66:69]
	v_mfma_f32_16x16x32_bf16 v[94:97], v[186:189], v[218:221], v[94:97]
	v_mfma_f32_16x16x32_bf16 v[90:93], v[186:189], v[226:229], v[90:93]
	v_mfma_f32_16x16x32_bf16 v[86:89], v[194:197], v[218:221], v[86:89]
	v_mfma_f32_16x16x32_bf16 v[82:85], v[194:197], v[226:229], v[82:85]
	v_mfma_f32_16x16x32_bf16 v[78:81], v[202:205], v[218:221], v[78:81]
	v_mfma_f32_16x16x32_bf16 v[74:77], v[202:205], v[226:229], v[74:77]
	v_mfma_f32_16x16x32_bf16 v[70:73], v[210:213], v[218:221], v[70:73]
	v_mfma_f32_16x16x32_bf16 v[66:69], v[210:213], v[226:229], v[66:69]
	s_setprio 0
	v_lshl_add_u64 v[236:237], s[18:19], 0, v[130:131]
	v_readfirstlane_b32 s23, v145
	v_lshl_add_u64 v[238:239], v[236:237], 0, s[8:9]
	s_mov_b32 m0, s23
	s_barrier
	ds_read_b128 v[182:185], v138 offset:16384
	ds_read_b128 v[186:189], v138 offset:17408
	ds_read_b128 v[190:193], v137 offset:16384
	ds_read_b128 v[194:197], v137 offset:17408
	ds_read_b128 v[198:201], v136 offset:16384
	ds_read_b128 v[202:205], v136 offset:17408
	ds_read_b128 v[206:209], v135 offset:16384
	ds_read_b128 v[210:213], v135 offset:17408
	global_load_lds_dwordx4 v[238:239], off
	v_lshl_add_u64 v[238:239], s[18:19], 0, v[132:133]
	v_readfirstlane_b32 s23, v146
	v_lshl_add_u64 v[240:241], v[238:239], 0, s[8:9]
	s_mov_b32 m0, s23
	s_add_u32 s18, s18, 0x100
	global_load_lds_dwordx4 v[240:241], off
	s_barrier
	s_waitcnt lgkmcnt(0)
	s_addc_u32 s19, s19, 0
	s_setprio 1
	s_waitcnt lgkmcnt(0)
	v_mfma_f32_16x16x32_bf16 v[62:65], v[182:185], v[160:163], v[62:65]
	v_mfma_f32_16x16x32_bf16 v[58:61], v[182:185], v[174:177], v[58:61]
	v_mfma_f32_16x16x32_bf16 v[54:57], v[190:193], v[160:163], v[54:57]
	v_mfma_f32_16x16x32_bf16 v[50:53], v[190:193], v[174:177], v[50:53]
	v_mfma_f32_16x16x32_bf16 v[46:49], v[198:201], v[160:163], v[46:49]
	v_mfma_f32_16x16x32_bf16 v[42:45], v[198:201], v[174:177], v[42:45]
	v_mfma_f32_16x16x32_bf16 v[38:41], v[206:209], v[160:163], v[38:41]
	v_mfma_f32_16x16x32_bf16 v[34:37], v[206:209], v[174:177], v[34:37]
	v_mfma_f32_16x16x32_bf16 v[62:65], v[186:189], v[164:167], v[62:65]
	v_mfma_f32_16x16x32_bf16 v[58:61], v[186:189], v[178:181], v[58:61]
	v_mfma_f32_16x16x32_bf16 v[54:57], v[194:197], v[164:167], v[54:57]
	v_mfma_f32_16x16x32_bf16 v[50:53], v[194:197], v[178:181], v[50:53]
	v_mfma_f32_16x16x32_bf16 v[46:49], v[202:205], v[164:167], v[46:49]
	v_mfma_f32_16x16x32_bf16 v[42:45], v[202:205], v[178:181], v[42:45]
	v_mfma_f32_16x16x32_bf16 v[38:41], v[210:213], v[164:167], v[38:41]
	v_mfma_f32_16x16x32_bf16 v[34:37], v[210:213], v[178:181], v[34:37]
	s_setprio 0
	s_barrier
; #define STAGE(P, GP, ktrel) do { const GAS char* _g = (GP) + (ktrel) * (BK * 2); \
;     __builtin_amdgcn_global_load_lds((const GAS unsigned*)(_g + so0), (unsigned*)((char*)(P) + tid_ * 16), 16, 0, 0); \
;     __builtin_amdgcn_global_load_lds((const GAS unsigned*)(_g + so1), (unsigned*)((char*)(P) + tid_ * 16 + 8192), 16, 0, 0); } while (0)
; #define WAIT_V(n) asm volatile("s_waitcnt vmcnt(" #n ")" ::: "memory")
; #define WAIT_L(n) asm volatile("s_waitcnt lgkmcnt(" #n ")" ::: "memory")
; #define BAR __builtin_amdgcn_s_barrier()
; #define SCHED __builtin_amdgcn_sched_barrier(0)
; #define LDA(dst, b, h) for (int m = 0; m < 4; ++m) for (int k = 0; k < 2; ++k) \
;     dst[m][k] = *reinterpret_cast<const bf16x8*>((char*)SA(b, h) + lds_byte(wr * 64 + m * 16 + fr, k * 32 + fq * 8))
; #define LDB(dst, b, h) for (int n = 0; n < 2; ++n) for (int k = 0; k < 2; ++k) \
;     dst[n][k] = *reinterpret_cast<const bf16x8*>((char*)SB(b, h) + lds_byte(wc * 32 + n * 16 + fr, k * 32 + fq * 8))
; #define MMA(ai, bj, At_, Bt_) do { __builtin_amdgcn_s_setprio(1); \
;     for (int m = 0; m < 4; ++m) for (int n = 0; n < 2; ++n) for (int k = 0; k < 2; ++k) \
;       acc[ai][bj][m][n] = __builtin_amdgcn_mfma_f32_16x16x32_bf16(At_[m][k], Bt_[n][k], acc[ai][bj][m][n], 0, 0, 0); \
;     __builtin_amdgcn_s_setprio(0); } while (0)
; template <int K, int LD = K>
; __device__ __forceinline__ void gemm_main(const GAS bf16* A, const GAS bf16* Bt, int brow, int bcol, f32x4 (&acc)[2][2][4][2]) {
;     ...
;     STAGE(SB(0, 1), pB1, 2);
;     WAIT_V(6); BAR; MMA(1, 1, At, B1); BAR;
;     LDB(B0, 1, 0); SCHED; LDA(At, 1, 0); STAGE(SA(0, 1), pA1, 2);
;     WAIT_L(8); BAR; WAIT_L(0); MMA(0, 0, At, B0); BAR; SCHED;
;     LDB(B1, 1, 1); STAGE(SB(1, 0), pB0, 3);
;     BAR; WAIT_L(0); MMA(0, 1, At, B1); BAR;
;     LDA(At, 1, 1); STAGE(SA(1, 0), pA0, 3);
;     BAR; WAIT_L(0); MMA(1, 0, At, B0); BAR; SCHED;
;     STAGE(SB(1, 1), pB1, 3);
;     WAIT_V(6); BAR; MMA(1, 1, At, B1); BAR;
	v_lshl_add_u64 v[240:241], s[16:17], 0, v[130:131]
	v_readfirstlane_b32 s23, v153
	v_lshl_add_u64 v[160:161], v[240:241], 0, s[8:9]
	s_mov_b32 m0, s23
	v_lshl_add_u64 v[242:243], s[16:17], 0, v[132:133]
	v_readfirstlane_b32 s23, v154
	global_load_lds_dwordx4 v[160:161], off
	v_lshl_add_u64 v[160:161], v[242:243], 0, s[8:9]
	s_mov_b32 m0, s23
	s_add_u32 s16, s16, 0x100
	global_load_lds_dwordx4 v[160:161], off
	s_waitcnt vmcnt(10)
	s_addc_u32 s17, s17, 0
	s_barrier
	s_setprio 1
	v_mfma_f32_16x16x32_bf16 v[30:33], v[182:185], v[214:217], v[30:33]
	v_mfma_f32_16x16x32_bf16 v[26:29], v[182:185], v[222:225], v[26:29]
	v_mfma_f32_16x16x32_bf16 v[22:25], v[190:193], v[214:217], v[22:25]
	v_mfma_f32_16x16x32_bf16 v[18:21], v[190:193], v[222:225], v[18:21]
	v_mfma_f32_16x16x32_bf16 v[14:17], v[198:201], v[214:217], v[14:17]
	v_mfma_f32_16x16x32_bf16 v[10:13], v[198:201], v[222:225], v[10:13]
	v_mfma_f32_16x16x32_bf16 v[6:9], v[206:209], v[214:217], v[6:9]
	v_mfma_f32_16x16x32_bf16 v[2:5], v[206:209], v[222:225], v[2:5]
	v_mfma_f32_16x16x32_bf16 v[30:33], v[186:189], v[218:221], v[30:33]
	v_mfma_f32_16x16x32_bf16 v[26:29], v[186:189], v[226:229], v[26:29]
	v_mfma_f32_16x16x32_bf16 v[22:25], v[194:197], v[218:221], v[22:25]
	v_mfma_f32_16x16x32_bf16 v[18:21], v[194:197], v[226:229], v[18:21]
	v_mfma_f32_16x16x32_bf16 v[14:17], v[202:205], v[218:221], v[14:17]
	v_mfma_f32_16x16x32_bf16 v[10:13], v[202:205], v[226:229], v[10:13]
	v_mfma_f32_16x16x32_bf16 v[6:9], v[210:213], v[218:221], v[6:9]
	v_mfma_f32_16x16x32_bf16 v[2:5], v[210:213], v[226:229], v[2:5]
	s_setprio 0
	s_barrier
	ds_read_b128 v[160:163], v140
	ds_read_b128 v[164:167], v140 offset:1024
	ds_read_b128 v[174:177], v140 offset:2048
	ds_read_b128 v[178:181], v140 offset:3072
	v_readfirstlane_b32 s23, v147
	v_lshl_add_u64 v[168:169], v[168:169], 0, s[8:9]
	s_mov_b32 m0, s23
	v_readfirstlane_b32 s23, v148
	ds_read_b128 v[182:185], v138 offset:32768
	ds_read_b128 v[186:189], v138 offset:33792
	ds_read_b128 v[190:193], v137 offset:32768
	ds_read_b128 v[194:197], v137 offset:33792
	ds_read_b128 v[198:201], v136 offset:32768
	ds_read_b128 v[202:205], v136 offset:33792
	ds_read_b128 v[206:209], v135 offset:32768
	ds_read_b128 v[210:213], v135 offset:33792
	global_load_lds_dwordx4 v[168:169], off
	v_lshl_add_u64 v[168:169], v[230:231], 0, s[8:9]
	s_mov_b32 m0, s23
	s_add_u32 s12, s12, 0x100
	global_load_lds_dwordx4 v[168:169], off
	s_waitcnt lgkmcnt(8)
	s_waitcnt vmcnt(10)
	s_barrier
	s_waitcnt lgkmcnt(0)
	s_addc_u32 s13, s13, 0
	s_setprio 1
	s_waitcnt lgkmcnt(0)
	v_mfma_f32_16x16x32_bf16 v[126:129], v[182:185], v[160:163], v[126:129]
	v_mfma_f32_16x16x32_bf16 v[122:125], v[182:185], v[174:177], v[122:125]
	v_mfma_f32_16x16x32_bf16 v[118:121], v[190:193], v[160:163], v[118:121]
	v_mfma_f32_16x16x32_bf16 v[114:117], v[190:193], v[174:177], v[114:117]
	v_mfma_f32_16x16x32_bf16 v[110:113], v[198:201], v[160:163], v[110:113]
	v_mfma_f32_16x16x32_bf16 v[106:109], v[198:201], v[174:177], v[106:109]
	v_mfma_f32_16x16x32_bf16 v[102:105], v[206:209], v[160:163], v[102:105]
	v_mfma_f32_16x16x32_bf16 v[98:101], v[206:209], v[174:177], v[98:101]
	v_mfma_f32_16x16x32_bf16 v[126:129], v[186:189], v[164:167], v[126:129]
	v_mfma_f32_16x16x32_bf16 v[122:125], v[186:189], v[178:181], v[122:125]
	v_mfma_f32_16x16x32_bf16 v[118:121], v[194:197], v[164:167], v[118:121]
	v_mfma_f32_16x16x32_bf16 v[114:117], v[194:197], v[178:181], v[114:117]
	v_mfma_f32_16x16x32_bf16 v[110:113], v[202:205], v[164:167], v[110:113]
	v_mfma_f32_16x16x32_bf16 v[106:109], v[202:205], v[178:181], v[106:109]
	v_mfma_f32_16x16x32_bf16 v[102:105], v[210:213], v[164:167], v[102:105]
	v_mfma_f32_16x16x32_bf16 v[98:101], v[210:213], v[178:181], v[98:101]
	s_setprio 0
	s_barrier
	v_readfirstlane_b32 s23, v155
	v_lshl_add_u64 v[168:169], v[232:233], 0, s[10:11]
	s_mov_b32 m0, s23
	v_readfirstlane_b32 s23, v156
	ds_read_b128 v[214:217], v139
	ds_read_b128 v[218:221], v139 offset:1024
	ds_read_b128 v[222:225], v139 offset:2048
	ds_read_b128 v[226:229], v139 offset:3072
	global_load_lds_dwordx4 v[168:169], off
	v_lshl_add_u64 v[168:169], v[234:235], 0, s[10:11]
	s_mov_b32 m0, s23
	s_nop 0
	global_load_lds_dwordx4 v[168:169], off
	s_waitcnt vmcnt(10)
	s_barrier
	s_waitcnt lgkmcnt(0)
	s_setprio 1
	s_waitcnt lgkmcnt(0)
	v_mfma_f32_16x16x32_bf16 v[94:97], v[182:185], v[214:217], v[94:97]
	v_mfma_f32_16x16x32_bf16 v[90:93], v[182:185], v[222:225], v[90:93]
	v_mfma_f32_16x16x32_bf16 v[86:89], v[190:193], v[214:217], v[86:89]
	v_mfma_f32_16x16x32_bf16 v[82:85], v[190:193], v[222:225], v[82:85]
	v_mfma_f32_16x16x32_bf16 v[78:81], v[198:201], v[214:217], v[78:81]
	v_mfma_f32_16x16x32_bf16 v[74:77], v[198:201], v[222:225], v[74:77]
	v_mfma_f32_16x16x32_bf16 v[70:73], v[206:209], v[214:217], v[70:73]
	v_mfma_f32_16x16x32_bf16 v[66:69], v[206:209], v[222:225], v[66:69]
	v_mfma_f32_16x16x32_bf16 v[94:97], v[186:189], v[218:221], v[94:97]
	v_mfma_f32_16x16x32_bf16 v[90:93], v[186:189], v[226:229], v[90:93]
	v_mfma_f32_16x16x32_bf16 v[86:89], v[194:197], v[218:221], v[86:89]
	v_mfma_f32_16x16x32_bf16 v[82:85], v[194:197], v[226:229], v[82:85]
	v_mfma_f32_16x16x32_bf16 v[78:81], v[202:205], v[218:221], v[78:81]
	v_mfma_f32_16x16x32_bf16 v[74:77], v[202:205], v[226:229], v[74:77]
	v_mfma_f32_16x16x32_bf16 v[70:73], v[210:213], v[218:221], v[70:73]
	v_mfma_f32_16x16x32_bf16 v[66:69], v[210:213], v[226:229], v[66:69]
	s_setprio 0
	v_readfirstlane_b32 s23, v149
	v_lshl_add_u64 v[168:169], v[236:237], 0, s[10:11]
	s_mov_b32 m0, s23
	v_readfirstlane_b32 s23, v150
	s_barrier
; #define STAGE(P, GP, ktrel) do { const GAS char* _g = (GP) + (ktrel) * (BK * 2); \
;     __builtin_amdgcn_global_load_lds((const GAS unsigned*)(_g + so0), (unsigned*)((char*)(P) + tid_ * 16), 16, 0, 0); \
;     __builtin_amdgcn_global_load_lds((const GAS unsigned*)(_g + so1), (unsigned*)((char*)(P) + tid_ * 16 + 8192), 16, 0, 0); } while (0)
; #define WAIT_V(n) asm volatile("s_waitcnt vmcnt(" #n ")" ::: "memory")
; #define WAIT_L(n) asm volatile("s_waitcnt lgkmcnt(" #n ")" ::: "memory")
; #define BAR __builtin_amdgcn_s_barrier()
; #define SCHED __builtin_amdgcn_sched_barrier(0)
; #define LDA(dst, b, h) for (int m = 0; m < 4; ++m) for (int k = 0; k < 2; ++k) \
;     dst[m][k] = *reinterpret_cast<const bf16x8*>((char*)SA(b, h) + lds_byte(wr * 64 + m * 16 + fr, k * 32 + fq * 8))
; #define LDB(dst, b, h) for (int n = 0; n < 2; ++n) for (int k = 0; k < 2; ++k) \
;     dst[n][k] = *reinterpret_cast<const bf16x8*>((char*)SB(b, h) + lds_byte(wc * 32 + n * 16 + fr, k * 32 + fq * 8))
; #define MMA(ai, bj, At_, Bt_) do { __builtin_amdgcn_s_setprio(1); \
;     for (int m = 0; m < 4; ++m) for (int n = 0; n < 2; ++n) for (int k = 0; k < 2; ++k) \
;       acc[ai][bj][m][n] = __builtin_amdgcn_mfma_f32_16x16x32_bf16(At_[m][k], Bt_[n][k], acc[ai][bj][m][n], 0, 0, 0); \
;     __builtin_amdgcn_s_setprio(0); } while (0)
; template <int K, int LD = K>
; __device__ __forceinline__ void gemm_main(const GAS bf16* A, const GAS bf16* Bt, int brow, int bcol, f32x4 (&acc)[2][2][4][2]) {
;     ...
;     LDA(At, 1, 1); STAGE(SA(1, 0), pA0, 3);
;     BAR; WAIT_L(0); MMA(1, 0, At, B0); BAR; SCHED;
;     STAGE(SB(1, 1), pB1, 3);
;     WAIT_V(6); BAR; MMA(1, 1, At, B1); BAR;
;     pA0 += 4 * BK; pA1 += 4 * BK; pB0 += 4 * BK; pB1 += 4 * BK;
;     asm volatile("" : "+s"(pA0), "+s"(pA1), "+s"(pB0), "+s"(pB1));
;   }
;   { LDB(B0, 0, 0); LDA(At, 0, 0); STAGE(SA(1, 1), pA1, 1);
;     BAR; WAIT_L(0); MMA(0, 0, At, B0); BAR;
;     LDB(B1, 0, 1); BAR; WAIT_L(0); MMA(0, 1, At, B1); BAR;
;     LDA(At, 0, 1); WAIT_V(4); BAR; WAIT_L(0); MMA(1, 0, At, B0); MMA(1, 1, At, B1); BAR; }
	ds_read_b128 v[182:185], v138 offset:49152
	ds_read_b128 v[186:189], v138 offset:50176
	ds_read_b128 v[190:193], v137 offset:49152
	ds_read_b128 v[194:197], v137 offset:50176
	ds_read_b128 v[198:201], v136 offset:49152
	ds_read_b128 v[202:205], v136 offset:50176
	ds_read_b128 v[206:209], v135 offset:49152
	ds_read_b128 v[210:213], v135 offset:50176
	global_load_lds_dwordx4 v[168:169], off
	v_lshl_add_u64 v[168:169], v[238:239], 0, s[10:11]
	s_mov_b32 m0, s23
	s_nop 0
	global_load_lds_dwordx4 v[168:169], off
	s_barrier
	s_waitcnt lgkmcnt(0)
	s_setprio 1
	s_waitcnt lgkmcnt(0)
	v_mfma_f32_16x16x32_bf16 v[62:65], v[182:185], v[160:163], v[62:65]
	v_mfma_f32_16x16x32_bf16 v[58:61], v[182:185], v[174:177], v[58:61]
	v_mfma_f32_16x16x32_bf16 v[54:57], v[190:193], v[160:163], v[54:57]
	v_mfma_f32_16x16x32_bf16 v[50:53], v[190:193], v[174:177], v[50:53]
	v_mfma_f32_16x16x32_bf16 v[46:49], v[198:201], v[160:163], v[46:49]
	v_mfma_f32_16x16x32_bf16 v[42:45], v[198:201], v[174:177], v[42:45]
	v_mfma_f32_16x16x32_bf16 v[38:41], v[206:209], v[160:163], v[38:41]
	v_mfma_f32_16x16x32_bf16 v[34:37], v[206:209], v[174:177], v[34:37]
	v_mfma_f32_16x16x32_bf16 v[62:65], v[186:189], v[164:167], v[62:65]
	v_mfma_f32_16x16x32_bf16 v[58:61], v[186:189], v[178:181], v[58:61]
	v_mfma_f32_16x16x32_bf16 v[54:57], v[194:197], v[164:167], v[54:57]
	v_mfma_f32_16x16x32_bf16 v[50:53], v[194:197], v[178:181], v[50:53]
	v_mfma_f32_16x16x32_bf16 v[46:49], v[202:205], v[164:167], v[46:49]
	v_mfma_f32_16x16x32_bf16 v[42:45], v[202:205], v[178:181], v[42:45]
	v_mfma_f32_16x16x32_bf16 v[38:41], v[210:213], v[164:167], v[38:41]
	v_mfma_f32_16x16x32_bf16 v[34:37], v[210:213], v[178:181], v[34:37]
	s_setprio 0
	s_barrier
	v_readfirstlane_b32 s23, v157
	v_lshl_add_u64 v[160:161], v[240:241], 0, s[10:11]
	s_mov_b32 m0, s23
	v_readfirstlane_b32 s23, v158
	global_load_lds_dwordx4 v[160:161], off
	v_lshl_add_u64 v[160:161], v[242:243], 0, s[10:11]
	s_mov_b32 m0, s23
	s_nop 0
	global_load_lds_dwordx4 v[160:161], off
	s_waitcnt vmcnt(10)
	s_barrier
	s_setprio 1
	v_mfma_f32_16x16x32_bf16 v[30:33], v[182:185], v[214:217], v[30:33]
	v_mfma_f32_16x16x32_bf16 v[26:29], v[182:185], v[222:225], v[26:29]
	v_mfma_f32_16x16x32_bf16 v[22:25], v[190:193], v[214:217], v[22:25]
	v_mfma_f32_16x16x32_bf16 v[18:21], v[190:193], v[222:225], v[18:21]
	v_mfma_f32_16x16x32_bf16 v[14:17], v[198:201], v[214:217], v[14:17]
	v_mfma_f32_16x16x32_bf16 v[10:13], v[198:201], v[222:225], v[10:13]
	v_mfma_f32_16x16x32_bf16 v[6:9], v[206:209], v[214:217], v[6:9]
	v_mfma_f32_16x16x32_bf16 v[2:5], v[206:209], v[222:225], v[2:5]
	v_mfma_f32_16x16x32_bf16 v[30:33], v[186:189], v[218:221], v[30:33]
	v_mfma_f32_16x16x32_bf16 v[26:29], v[186:189], v[226:229], v[26:29]
	v_mfma_f32_16x16x32_bf16 v[22:25], v[194:197], v[218:221], v[22:25]
	v_mfma_f32_16x16x32_bf16 v[18:21], v[194:197], v[226:229], v[18:21]
	v_mfma_f32_16x16x32_bf16 v[14:17], v[202:205], v[218:221], v[14:17]
	v_mfma_f32_16x16x32_bf16 v[10:13], v[202:205], v[226:229], v[10:13]
	v_mfma_f32_16x16x32_bf16 v[6:9], v[210:213], v[218:221], v[6:9]
	v_mfma_f32_16x16x32_bf16 v[2:5], v[210:213], v[226:229], v[2:5]
	s_setprio 0
	s_add_i32 s22, s22, 2
	s_cmp_lt_u32 s22, 40
	s_barrier
	s_cbranch_scc1 .LBB0_1105
	ds_read_b128 v[146:149], v144
	ds_read_b128 v[150:153], v144 offset:1024
	ds_read_b128 v[154:157], v144 offset:2048
	ds_read_b128 v[158:161], v144 offset:3072
	ds_read_b128 v[162:165], v138
	ds_read_b128 v[166:169], v138 offset:1024
	ds_read_b128 v[174:177], v137
	ds_read_b128 v[178:181], v137 offset:1024
	ds_read_b128 v[182:185], v136
	ds_read_b128 v[186:189], v136 offset:1024
	ds_read_b128 v[190:193], v135
	ds_read_b128 v[194:197], v135 offset:1024
	v_lshl_add_u64 v[144:145], s[12:13], 0, v[130:131]
	v_readfirstlane_b32 s16, v143
	v_lshl_add_u64 v[144:145], v[144:145], 0, s[6:7]
	s_mov_b32 m0, s16
	v_lshl_add_u64 v[132:133], s[12:13], 0, v[132:133]
	v_readfirstlane_b32 s12, v142
	global_load_lds_dwordx4 v[144:145], off
	v_lshl_add_u64 v[132:133], v[132:133], 0, s[6:7]
	s_mov_b32 m0, s12
	s_nop 0
	global_load_lds_dwordx4 v[132:133], off
	s_waitcnt vmcnt(10)
	s_barrier
	s_waitcnt lgkmcnt(0)
	s_setprio 1
	s_waitcnt lgkmcnt(0)
	v_mfma_f32_16x16x32_bf16 v[126:129], v[162:165], v[146:149], v[126:129]
	v_mfma_f32_16x16x32_bf16 v[122:125], v[162:165], v[154:157], v[122:125]
	v_mfma_f32_16x16x32_bf16 v[110:113], v[182:185], v[146:149], v[110:113]
	v_mfma_f32_16x16x32_bf16 v[106:109], v[182:185], v[154:157], v[106:109]
	v_mfma_f32_16x16x32_bf16 v[126:129], v[166:169], v[150:153], v[126:129]
	v_mfma_f32_16x16x32_bf16 v[122:125], v[166:169], v[158:161], v[122:125]
	v_mfma_f32_16x16x32_bf16 v[118:121], v[174:177], v[146:149], v[118:121]
	v_mfma_f32_16x16x32_bf16 v[114:117], v[174:177], v[154:157], v[114:117]
	v_mfma_f32_16x16x32_bf16 v[110:113], v[186:189], v[150:153], v[110:113]
	v_mfma_f32_16x16x32_bf16 v[106:109], v[186:189], v[158:161], v[106:109]
	v_mfma_f32_16x16x32_bf16 v[102:105], v[190:193], v[146:149], v[102:105]
	v_mfma_f32_16x16x32_bf16 v[98:101], v[190:193], v[154:157], v[98:101]
	v_mfma_f32_16x16x32_bf16 v[142:145], v[178:181], v[150:153], v[118:121]
	v_mfma_f32_16x16x32_bf16 v[198:201], v[178:181], v[158:161], v[114:117]
	v_mfma_f32_16x16x32_bf16 v[202:205], v[194:197], v[150:153], v[102:105]
	v_mfma_f32_16x16x32_bf16 v[206:209], v[194:197], v[158:161], v[98:101]
	s_setprio 0
	s_barrier
	s_nop 1
	ds_read_b128 v[98:101], v141
	ds_read_b128 v[102:105], v141 offset:1024
	ds_read_b128 v[114:117], v141 offset:2048
	ds_read_b128 v[118:121], v141 offset:3072
	s_waitcnt vmcnt(8)
	s_barrier
; #define WAIT_V(n) asm volatile("s_waitcnt vmcnt(" #n ")" ::: "memory")
; #define WAIT_L(n) asm volatile("s_waitcnt lgkmcnt(" #n ")" ::: "memory")
; #define BAR __builtin_amdgcn_s_barrier()
; #define LDA(dst, b, h) for (int m = 0; m < 4; ++m) for (int k = 0; k < 2; ++k) \
;     dst[m][k] = *reinterpret_cast<const bf16x8*>((char*)SA(b, h) + lds_byte(wr * 64 + m * 16 + fr, k * 32 + fq * 8))
; #define LDB(dst, b, h) for (int n = 0; n < 2; ++n) for (int k = 0; k < 2; ++k) \
;     dst[n][k] = *reinterpret_cast<const bf16x8*>((char*)SB(b, h) + lds_byte(wc * 32 + n * 16 + fr, k * 32 + fq * 8))
; #define MMA(ai, bj, At_, Bt_) do { __builtin_amdgcn_s_setprio(1); \
;     for (int m = 0; m < 4; ++m) for (int n = 0; n < 2; ++n) for (int k = 0; k < 2; ++k) \
;       acc[ai][bj][m][n] = __builtin_amdgcn_mfma_f32_16x16x32_bf16(At_[m][k], Bt_[n][k], acc[ai][bj][m][n], 0, 0, 0); \
;     __builtin_amdgcn_s_setprio(0); } while (0)
; template <int K, int LD = K>
; __device__ __forceinline__ void gemm_main(const GAS bf16* A, const GAS bf16* Bt, int brow, int bcol, f32x4 (&acc)[2][2][4][2]) {
;     ...
;     LDB(B1, 0, 1); BAR; WAIT_L(0); MMA(0, 1, At, B1); BAR;
;     LDA(At, 0, 1); WAIT_V(4); BAR; WAIT_L(0); MMA(1, 0, At, B0); MMA(1, 1, At, B1); BAR; }
;   { LDB(B0, 1, 0); LDA(At, 1, 0); WAIT_V(2); BAR; WAIT_L(0); MMA(0, 0, At, B0); BAR;
;     LDB(B1, 1, 1); WAIT_V(0); BAR; WAIT_L(0); MMA(0, 1, At, B1); BAR;
	s_waitcnt lgkmcnt(0)
	s_setprio 1
	s_waitcnt lgkmcnt(0)
	v_mfma_f32_16x16x32_bf16 v[94:97], v[162:165], v[98:101], v[94:97]
	v_mfma_f32_16x16x32_bf16 v[90:93], v[162:165], v[114:117], v[90:93]
	v_mfma_f32_16x16x32_bf16 v[78:81], v[182:185], v[98:101], v[78:81]
	v_mfma_f32_16x16x32_bf16 v[74:77], v[182:185], v[114:117], v[74:77]
	v_mfma_f32_16x16x32_bf16 v[94:97], v[166:169], v[102:105], v[94:97]
	v_mfma_f32_16x16x32_bf16 v[90:93], v[166:169], v[118:121], v[90:93]
	v_mfma_f32_16x16x32_bf16 v[86:89], v[174:177], v[98:101], v[86:89]
	v_mfma_f32_16x16x32_bf16 v[82:85], v[174:177], v[114:117], v[82:85]
	v_mfma_f32_16x16x32_bf16 v[78:81], v[186:189], v[102:105], v[78:81]
	v_mfma_f32_16x16x32_bf16 v[74:77], v[186:189], v[118:121], v[74:77]
	v_mfma_f32_16x16x32_bf16 v[70:73], v[190:193], v[98:101], v[70:73]
	v_mfma_f32_16x16x32_bf16 v[66:69], v[190:193], v[114:117], v[66:69]
	v_mfma_f32_16x16x32_bf16 v[162:165], v[178:181], v[102:105], v[86:89]
	v_mfma_f32_16x16x32_bf16 v[166:169], v[178:181], v[118:121], v[82:85]
	v_mfma_f32_16x16x32_bf16 v[174:177], v[194:197], v[102:105], v[70:73]
	v_mfma_f32_16x16x32_bf16 v[178:181], v[194:197], v[118:121], v[66:69]
	s_setprio 0
	s_barrier
	s_nop 1
	ds_read_b128 v[66:69], v138 offset:16384
	ds_read_b128 v[70:73], v138 offset:17408
	ds_read_b128 v[82:85], v137 offset:16384
	ds_read_b128 v[86:89], v137 offset:17408
	ds_read_b128 v[182:185], v136 offset:16384
	ds_read_b128 v[186:189], v136 offset:17408
	ds_read_b128 v[190:193], v135 offset:16384
	ds_read_b128 v[194:197], v135 offset:17408
	s_waitcnt vmcnt(4)
	s_barrier
	s_waitcnt lgkmcnt(0)
	s_setprio 1
	s_waitcnt lgkmcnt(0)
	v_mfma_f32_16x16x32_bf16 v[62:65], v[66:69], v[146:149], v[62:65]
	v_mfma_f32_16x16x32_bf16 v[58:61], v[66:69], v[154:157], v[58:61]
	v_mfma_f32_16x16x32_bf16 v[46:49], v[182:185], v[146:149], v[46:49]
	v_mfma_f32_16x16x32_bf16 v[42:45], v[182:185], v[154:157], v[42:45]
	v_mfma_f32_16x16x32_bf16 v[62:65], v[70:73], v[150:153], v[62:65]
	v_mfma_f32_16x16x32_bf16 v[58:61], v[70:73], v[158:161], v[58:61]
	v_mfma_f32_16x16x32_bf16 v[54:57], v[82:85], v[146:149], v[54:57]
	v_mfma_f32_16x16x32_bf16 v[50:53], v[82:85], v[154:157], v[50:53]
	v_mfma_f32_16x16x32_bf16 v[46:49], v[186:189], v[150:153], v[46:49]
	v_mfma_f32_16x16x32_bf16 v[42:45], v[186:189], v[158:161], v[42:45]
	v_mfma_f32_16x16x32_bf16 v[38:41], v[190:193], v[146:149], v[38:41]
	v_mfma_f32_16x16x32_bf16 v[34:37], v[190:193], v[154:157], v[34:37]
	v_mfma_f32_16x16x32_bf16 v[210:213], v[86:89], v[150:153], v[54:57]
	v_mfma_f32_16x16x32_bf16 v[214:217], v[86:89], v[158:161], v[50:53]
	v_mfma_f32_16x16x32_bf16 v[146:149], v[194:197], v[150:153], v[38:41]
	v_mfma_f32_16x16x32_bf16 v[150:153], v[194:197], v[158:161], v[34:37]
	s_setprio 0
	s_setprio 1
	v_mfma_f32_16x16x32_bf16 v[30:33], v[66:69], v[98:101], v[30:33]
	v_mfma_f32_16x16x32_bf16 v[26:29], v[66:69], v[114:117], v[26:29]
	v_mfma_f32_16x16x32_bf16 v[14:17], v[182:185], v[98:101], v[14:17]
	v_mfma_f32_16x16x32_bf16 v[10:13], v[182:185], v[114:117], v[10:13]
	v_mfma_f32_16x16x32_bf16 v[30:33], v[70:73], v[102:105], v[30:33]
	v_mfma_f32_16x16x32_bf16 v[26:29], v[70:73], v[118:121], v[26:29]
	v_mfma_f32_16x16x32_bf16 v[22:25], v[82:85], v[98:101], v[22:25]
	v_mfma_f32_16x16x32_bf16 v[18:21], v[82:85], v[114:117], v[18:21]
	v_mfma_f32_16x16x32_bf16 v[14:17], v[186:189], v[102:105], v[14:17]
	v_mfma_f32_16x16x32_bf16 v[10:13], v[186:189], v[118:121], v[10:13]
	v_mfma_f32_16x16x32_bf16 v[6:9], v[190:193], v[98:101], v[6:9]
	v_mfma_f32_16x16x32_bf16 v[2:5], v[190:193], v[114:117], v[2:5]
	v_mfma_f32_16x16x32_bf16 v[154:157], v[86:89], v[102:105], v[22:25]
	v_mfma_f32_16x16x32_bf16 v[158:161], v[86:89], v[118:121], v[18:21]
	v_mfma_f32_16x16x32_bf16 v[182:185], v[194:197], v[102:105], v[6:9]
	v_mfma_f32_16x16x32_bf16 v[186:189], v[194:197], v[118:121], v[2:5]
	s_setprio 0
	s_barrier
	s_nop 1
	ds_read_b128 v[2:5], v140
	ds_read_b128 v[6:9], v140 offset:1024
	ds_read_b128 v[190:193], v140 offset:2048
	ds_read_b128 v[194:197], v140 offset:3072
	ds_read_b128 v[18:21], v138 offset:32768
	ds_read_b128 v[22:25], v138 offset:33792
	ds_read_b128 v[34:37], v137 offset:32768
	ds_read_b128 v[38:41], v137 offset:33792
	ds_read_b128 v[50:53], v136 offset:32768
	ds_read_b128 v[54:57], v136 offset:33792
	ds_read_b128 v[218:221], v135 offset:32768
	ds_read_b128 v[222:225], v135 offset:33792
	s_waitcnt vmcnt(2)
	s_barrier
; #define WAIT_V(n) asm volatile("s_waitcnt vmcnt(" #n ")" ::: "memory")
; #define WAIT_L(n) asm volatile("s_waitcnt lgkmcnt(" #n ")" ::: "memory")
; #define BAR __builtin_amdgcn_s_barrier()
; #define LDA(dst, b, h) for (int m = 0; m < 4; ++m) for (int k = 0; k < 2; ++k) \
;     dst[m][k] = *reinterpret_cast<const bf16x8*>((char*)SA(b, h) + lds_byte(wr * 64 + m * 16 + fr, k * 32 + fq * 8))
; #define LDB(dst, b, h) for (int n = 0; n < 2; ++n) for (int k = 0; k < 2; ++k) \
;     dst[n][k] = *reinterpret_cast<const bf16x8*>((char*)SB(b, h) + lds_byte(wc * 32 + n * 16 + fr, k * 32 + fq * 8))
; #define MMA(ai, bj, At_, Bt_) do { __builtin_amdgcn_s_setprio(1); \
;     for (int m = 0; m < 4; ++m) for (int n = 0; n < 2; ++n) for (int k = 0; k < 2; ++k) \
;       acc[ai][bj][m][n] = __builtin_amdgcn_mfma_f32_16x16x32_bf16(At_[m][k], Bt_[n][k], acc[ai][bj][m][n], 0, 0, 0); \
;     __builtin_amdgcn_s_setprio(0); } while (0)
; template <int K, int LD = K>
; __device__ __forceinline__ void gemm_main(const GAS bf16* A, const GAS bf16* Bt, int brow, int bcol, f32x4 (&acc)[2][2][4][2]) {
;     ...
;   { LDB(B0, 1, 0); LDA(At, 1, 0); WAIT_V(2); BAR; WAIT_L(0); MMA(0, 0, At, B0); BAR;
;     LDB(B1, 1, 1); WAIT_V(0); BAR; WAIT_L(0); MMA(0, 1, At, B1); BAR;
;     LDA(At, 1, 1); BAR; WAIT_L(0); MMA(1, 0, At, B0); MMA(1, 1, At, B1); BAR; }
;   if (wr == 0) BAR;
	s_waitcnt lgkmcnt(0)
	s_setprio 1
	s_waitcnt lgkmcnt(0)
	v_mfma_f32_16x16x32_bf16 v[66:69], v[18:21], v[2:5], v[126:129]
	v_mfma_f32_16x16x32_bf16 v[118:121], v[22:25], v[6:9], v[66:69]
	v_mfma_f32_16x16x32_bf16 v[66:69], v[18:21], v[190:193], v[122:125]
	v_mfma_f32_16x16x32_bf16 v[114:117], v[22:25], v[194:197], v[66:69]
	v_mfma_f32_16x16x32_bf16 v[66:69], v[34:37], v[2:5], v[142:145]
	v_mfma_f32_16x16x32_bf16 v[102:105], v[38:41], v[6:9], v[66:69]
	v_mfma_f32_16x16x32_bf16 v[66:69], v[34:37], v[190:193], v[198:201]
	v_mfma_f32_16x16x32_bf16 v[98:101], v[38:41], v[194:197], v[66:69]
	v_mfma_f32_16x16x32_bf16 v[66:69], v[50:53], v[2:5], v[110:113]
	v_mfma_f32_16x16x32_bf16 v[86:89], v[54:57], v[6:9], v[66:69]
	v_mfma_f32_16x16x32_bf16 v[66:69], v[50:53], v[190:193], v[106:109]
	v_mfma_f32_16x16x32_bf16 v[82:85], v[54:57], v[194:197], v[66:69]
	v_mfma_f32_16x16x32_bf16 v[66:69], v[218:221], v[2:5], v[202:205]
	v_mfma_f32_16x16x32_bf16 v[70:73], v[222:225], v[6:9], v[66:69]
	v_mfma_f32_16x16x32_bf16 v[66:69], v[218:221], v[190:193], v[206:209]
	v_mfma_f32_16x16x32_bf16 v[66:69], v[222:225], v[194:197], v[66:69]
	s_setprio 0
	s_barrier
	ds_read_b128 v[140:143], v139
	ds_read_b128 v[198:201], v139 offset:1024
	ds_read_b128 v[202:205], v139 offset:2048
	ds_read_b128 v[206:209], v139 offset:3072
	s_waitcnt vmcnt(0)
	s_barrier
	s_waitcnt lgkmcnt(0)
	s_setprio 1
	s_waitcnt lgkmcnt(0)
	v_mfma_f32_16x16x32_bf16 v[94:97], v[18:21], v[140:143], v[94:97]
	v_mfma_f32_16x16x32_bf16 v[18:21], v[18:21], v[202:205], v[90:93]
	v_mfma_f32_16x16x32_bf16 v[122:125], v[22:25], v[206:209], v[18:21]
	v_mfma_f32_16x16x32_bf16 v[18:21], v[34:37], v[140:143], v[162:165]
	v_mfma_f32_16x16x32_bf16 v[110:113], v[38:41], v[198:201], v[18:21]
	v_mfma_f32_16x16x32_bf16 v[18:21], v[34:37], v[202:205], v[166:169]
	v_mfma_f32_16x16x32_bf16 v[106:109], v[38:41], v[206:209], v[18:21]
	v_mfma_f32_16x16x32_bf16 v[18:21], v[50:53], v[140:143], v[78:81]
	v_mfma_f32_16x16x32_bf16 v[126:129], v[22:25], v[198:201], v[94:97]
	v_mfma_f32_16x16x32_bf16 v[94:97], v[54:57], v[198:201], v[18:21]
	v_mfma_f32_16x16x32_bf16 v[18:21], v[50:53], v[202:205], v[74:77]
	v_mfma_f32_16x16x32_bf16 v[90:93], v[54:57], v[206:209], v[18:21]
	v_mfma_f32_16x16x32_bf16 v[18:21], v[218:221], v[140:143], v[174:177]
	v_mfma_f32_16x16x32_bf16 v[78:81], v[222:225], v[198:201], v[18:21]
	v_mfma_f32_16x16x32_bf16 v[18:21], v[218:221], v[202:205], v[178:181]
	v_mfma_f32_16x16x32_bf16 v[74:77], v[222:225], v[206:209], v[18:21]
	s_setprio 0
	s_barrier
	ds_read_b128 v[162:165], v138 offset:49152
	ds_read_b128 v[166:169], v138 offset:50176
	ds_read_b128 v[174:177], v137 offset:49152
	ds_read_b128 v[178:181], v137 offset:50176
	ds_read_b128 v[218:221], v136 offset:49152
	ds_read_b128 v[136:139], v136 offset:50176
	ds_read_b128 v[222:225], v135 offset:49152
	ds_read_b128 v[226:229], v135 offset:50176
	s_barrier
	s_waitcnt lgkmcnt(0)
	s_setprio 1
	s_waitcnt lgkmcnt(0)
	v_mfma_f32_16x16x32_bf16 v[18:21], v[162:165], v[2:5], v[62:65]
	v_mfma_f32_16x16x32_bf16 v[54:57], v[166:169], v[6:9], v[18:21]
	v_mfma_f32_16x16x32_bf16 v[18:21], v[162:165], v[190:193], v[58:61]
	v_mfma_f32_16x16x32_bf16 v[50:53], v[166:169], v[194:197], v[18:21]
	v_mfma_f32_16x16x32_bf16 v[18:21], v[174:177], v[2:5], v[210:213]
	v_mfma_f32_16x16x32_bf16 v[38:41], v[178:181], v[6:9], v[18:21]
	v_mfma_f32_16x16x32_bf16 v[18:21], v[174:177], v[190:193], v[214:217]
	v_mfma_f32_16x16x32_bf16 v[34:37], v[178:181], v[194:197], v[18:21]
	v_mfma_f32_16x16x32_bf16 v[18:21], v[218:221], v[2:5], v[46:49]
	v_mfma_f32_16x16x32_bf16 v[2:5], v[222:225], v[2:5], v[146:149]
	v_mfma_f32_16x16x32_bf16 v[22:25], v[136:139], v[6:9], v[18:21]
	v_mfma_f32_16x16x32_bf16 v[18:21], v[218:221], v[190:193], v[42:45]
	v_mfma_f32_16x16x32_bf16 v[6:9], v[226:229], v[6:9], v[2:5]
	v_mfma_f32_16x16x32_bf16 v[2:5], v[222:225], v[190:193], v[150:153]
	v_mfma_f32_16x16x32_bf16 v[18:21], v[136:139], v[194:197], v[18:21]
	v_mfma_f32_16x16x32_bf16 v[2:5], v[226:229], v[194:197], v[2:5]
	s_setprio 0
	s_setprio 1
	v_mfma_f32_16x16x32_bf16 v[26:29], v[162:165], v[202:205], v[26:29]
	v_mfma_f32_16x16x32_bf16 v[58:61], v[166:169], v[206:209], v[26:29]
	v_mfma_f32_16x16x32_bf16 v[26:29], v[174:177], v[140:143], v[154:157]
	v_mfma_f32_16x16x32_bf16 v[46:49], v[178:181], v[198:201], v[26:29]
	v_mfma_f32_16x16x32_bf16 v[26:29], v[174:177], v[202:205], v[158:161]
	v_mfma_f32_16x16x32_bf16 v[10:13], v[218:221], v[202:205], v[10:13]
	v_mfma_f32_16x16x32_bf16 v[30:33], v[162:165], v[140:143], v[30:33]
	v_mfma_f32_16x16x32_bf16 v[42:45], v[178:181], v[206:209], v[26:29]
	v_mfma_f32_16x16x32_bf16 v[14:17], v[218:221], v[140:143], v[14:17]
	v_mfma_f32_16x16x32_bf16 v[26:29], v[136:139], v[206:209], v[10:13]
	v_mfma_f32_16x16x32_bf16 v[10:13], v[222:225], v[140:143], v[182:185]
	v_mfma_f32_16x16x32_bf16 v[62:65], v[166:169], v[198:201], v[30:33]
	v_mfma_f32_16x16x32_bf16 v[30:33], v[136:139], v[198:201], v[14:17]
	v_mfma_f32_16x16x32_bf16 v[14:17], v[226:229], v[198:201], v[10:13]
	v_mfma_f32_16x16x32_bf16 v[10:13], v[222:225], v[202:205], v[186:189]
	v_mfma_f32_16x16x32_bf16 v[10:13], v[226:229], v[206:209], v[10:13]
	s_setprio 0
	v_cmp_gt_u32_e32 vcc, s33, v134
	s_barrier
	s_and_saveexec_b64 s[12:13], vcc
	s_cbranch_execz .LBB0_1108
	s_barrier

; #define STAGE(P, GP, ktrel) do { const GAS char* _g = (GP) + (ktrel) * (BK * 2); \
;     __builtin_amdgcn_global_load_lds((const GAS unsigned*)(_g + so0), (unsigned*)((char*)(P) + tid_ * 16), 16, 0, 0); \
;     __builtin_amdgcn_global_load_lds((const GAS unsigned*)(_g + so1), (unsigned*)((char*)(P) + tid_ * 16 + 8192), 16, 0, 0); } while (0)
; #define WAIT_V(n) asm volatile("s_waitcnt vmcnt(" #n ")" ::: "memory")
; #define WAIT_L(n) asm volatile("s_waitcnt lgkmcnt(" #n ")" ::: "memory")
; #define BAR __builtin_amdgcn_s_barrier()
; #define SCHED __builtin_amdgcn_sched_barrier(0)
; #define LDA(dst, b, h) for (int m = 0; m < 4; ++m) for (int k = 0; k < 2; ++k) \
;     dst[m][k] = *reinterpret_cast<const bf16x8*>((char*)SA(b, h) + lds_byte(wr * 64 + m * 16 + fr, k * 32 + fq * 8))
; #define LDB(dst, b, h) for (int n = 0; n < 2; ++n) for (int k = 0; k < 2; ++k) \
;     dst[n][k] = *reinterpret_cast<const bf16x8*>((char*)SB(b, h) + lds_byte(wc * 32 + n * 16 + fr, k * 32 + fq * 8))
; #define MMA(ai, bj, At_, Bt_) do { __builtin_amdgcn_s_setprio(1); \
;     for (int m = 0; m < 4; ++m) for (int n = 0; n < 2; ++n) for (int k = 0; k < 2; ++k) \
;       acc[ai][bj][m][n] = __builtin_amdgcn_mfma_f32_16x16x32_bf16(At_[m][k], Bt_[n][k], acc[ai][bj][m][n], 0, 0, 0); \
;     __builtin_amdgcn_s_setprio(0); } while (0)
; template <int K, int LD = K>
; __device__ __forceinline__ void gemm_main(const GAS bf16* A, const GAS bf16* Bt, int brow, int bcol, f32x4 (&acc)[2][2][4][2]) {
;     ...
;   for (int t = 0; t < nt - 2; t += 2) {
;     LDB(B0, 0, 0); SCHED; LDA(At, 0, 0); STAGE(SA(1, 1), pA1, 1);
;     WAIT_L(8); BAR; WAIT_L(0); MMA(0, 0, At, B0); BAR; SCHED;
;     LDB(B1, 0, 1); STAGE(SB(0, 0), pB0, 2);
;     BAR; WAIT_L(0); MMA(0, 1, At, B1); BAR;
;     LDA(At, 0, 1); STAGE(SA(0, 0), pA0, 2);
;     BAR; WAIT_L(0); MMA(1, 0, At, B0); BAR; SCHED;
;     STAGE(SB(0, 1), pB1, 2);
;     WAIT_V(6); BAR; MMA(1, 1, At, B1); BAR;
;     LDB(B0, 1, 0); SCHED; LDA(At, 1, 0); STAGE(SA(0, 1), pA1, 2);
;     WAIT_L(8); BAR; WAIT_L(0); MMA(0, 0, At, B0); BAR; SCHED;
;     LDB(B1, 1, 1); STAGE(SB(1, 0), pB0, 3);
;     BAR; WAIT_L(0); MMA(0, 1, At, B1); BAR;
.LBB0_1226:
	ds_read_b128 v[146:149], v143
	ds_read_b128 v[150:153], v143 offset:1024
	ds_read_b128 v[156:159], v143 offset:2048
	ds_read_b128 v[160:163], v143 offset:3072
	v_add_u32_e32 v155, 0x100, v141
	v_add_u32_e32 v144, 0xc000, v155
	v_lshl_add_u64 v[168:169], s[18:19], 0, v[138:139]
	v_readfirstlane_b32 s30, v144
	v_add_u32_e32 v145, 0xe000, v155
	v_lshl_add_u64 v[202:203], v[168:169], 0, s[8:9]
	s_mov_b32 m0, s30
	v_lshl_add_u64 v[218:219], s[18:19], 0, v[130:131]
	v_readfirstlane_b32 s30, v145
	ds_read_b128 v[164:167], v136
	ds_read_b128 v[174:177], v136 offset:1024
	ds_read_b128 v[178:181], v135
	ds_read_b128 v[182:185], v135 offset:1024
	ds_read_b128 v[186:189], v134
	ds_read_b128 v[190:193], v134 offset:1024
	ds_read_b128 v[194:197], v133
	ds_read_b128 v[198:201], v133 offset:1024
	global_load_lds_dwordx4 v[202:203], off
	v_lshl_add_u64 v[202:203], v[218:219], 0, s[8:9]
	s_mov_b32 m0, s30
	s_nop 0
	global_load_lds_dwordx4 v[202:203], off
	s_waitcnt lgkmcnt(8)
	s_waitcnt vmcnt(10)
	s_barrier
	s_waitcnt lgkmcnt(0)
	s_setprio 1
	s_waitcnt lgkmcnt(0)
	v_mfma_f32_16x16x32_bf16 v[126:129], v[164:167], v[146:149], v[126:129]
	v_mfma_f32_16x16x32_bf16 v[122:125], v[164:167], v[156:159], v[122:125]
	v_mfma_f32_16x16x32_bf16 v[118:121], v[178:181], v[146:149], v[118:121]
	v_mfma_f32_16x16x32_bf16 v[114:117], v[178:181], v[156:159], v[114:117]
	v_mfma_f32_16x16x32_bf16 v[110:113], v[186:189], v[146:149], v[110:113]
	v_mfma_f32_16x16x32_bf16 v[106:109], v[186:189], v[156:159], v[106:109]
	v_mfma_f32_16x16x32_bf16 v[102:105], v[194:197], v[146:149], v[102:105]
	v_mfma_f32_16x16x32_bf16 v[98:101], v[194:197], v[156:159], v[98:101]
	v_mfma_f32_16x16x32_bf16 v[126:129], v[174:177], v[150:153], v[126:129]
	v_mfma_f32_16x16x32_bf16 v[122:125], v[174:177], v[160:163], v[122:125]
	v_mfma_f32_16x16x32_bf16 v[118:121], v[182:185], v[150:153], v[118:121]
	v_mfma_f32_16x16x32_bf16 v[114:117], v[182:185], v[160:163], v[114:117]
	v_mfma_f32_16x16x32_bf16 v[110:113], v[190:193], v[150:153], v[110:113]
	v_mfma_f32_16x16x32_bf16 v[106:109], v[190:193], v[160:163], v[106:109]
	v_mfma_f32_16x16x32_bf16 v[102:105], v[198:201], v[150:153], v[102:105]
	v_mfma_f32_16x16x32_bf16 v[98:101], v[198:201], v[160:163], v[98:101]
	s_setprio 0
	s_barrier
	v_add_u32_e32 v226, s38, v141
	v_lshl_add_u64 v[220:221], s[28:29], 0, v[138:139]
	v_readfirstlane_b32 s30, v226
	v_lshl_add_u64 v[222:223], v[220:221], 0, s[14:15]
	s_mov_b32 m0, s30
	v_add_u32_e32 v226, 0x2000, v226
	ds_read_b128 v[202:205], v142
	ds_read_b128 v[206:209], v142 offset:1024
	ds_read_b128 v[210:213], v142 offset:2048
	ds_read_b128 v[214:217], v142 offset:3072
	global_load_lds_dwordx4 v[222:223], off
	v_lshl_add_u64 v[222:223], s[28:29], 0, v[130:131]
	v_readfirstlane_b32 s30, v226
	v_lshl_add_u64 v[224:225], v[222:223], 0, s[14:15]
	s_mov_b32 m0, s30
	s_add_u32 s28, s28, 0x100
	global_load_lds_dwordx4 v[224:225], off
	s_waitcnt vmcnt(10)
	s_barrier
	s_waitcnt lgkmcnt(0)
	s_addc_u32 s29, s29, 0
	s_setprio 1
	s_waitcnt lgkmcnt(0)
	v_mfma_f32_16x16x32_bf16 v[94:97], v[164:167], v[202:205], v[94:97]
	v_mfma_f32_16x16x32_bf16 v[90:93], v[164:167], v[210:213], v[90:93]
	v_mfma_f32_16x16x32_bf16 v[86:89], v[178:181], v[202:205], v[86:89]
	v_mfma_f32_16x16x32_bf16 v[82:85], v[178:181], v[210:213], v[82:85]
	v_mfma_f32_16x16x32_bf16 v[78:81], v[186:189], v[202:205], v[78:81]
	v_mfma_f32_16x16x32_bf16 v[74:77], v[186:189], v[210:213], v[74:77]
	v_mfma_f32_16x16x32_bf16 v[70:73], v[194:197], v[202:205], v[70:73]
	v_mfma_f32_16x16x32_bf16 v[66:69], v[194:197], v[210:213], v[66:69]
	v_mfma_f32_16x16x32_bf16 v[94:97], v[174:177], v[206:209], v[94:97]
	v_mfma_f32_16x16x32_bf16 v[90:93], v[174:177], v[214:217], v[90:93]
	v_mfma_f32_16x16x32_bf16 v[86:89], v[182:185], v[206:209], v[86:89]
	v_mfma_f32_16x16x32_bf16 v[82:85], v[182:185], v[214:217], v[82:85]
	v_mfma_f32_16x16x32_bf16 v[78:81], v[190:193], v[206:209], v[78:81]
	v_mfma_f32_16x16x32_bf16 v[74:77], v[190:193], v[214:217], v[74:77]
	v_mfma_f32_16x16x32_bf16 v[70:73], v[198:201], v[206:209], v[70:73]
	v_mfma_f32_16x16x32_bf16 v[66:69], v[198:201], v[214:217], v[66:69]
	s_setprio 0
	v_lshl_add_u64 v[224:225], s[26:27], 0, v[138:139]
	v_readfirstlane_b32 s30, v155
	v_lshl_add_u64 v[226:227], v[224:225], 0, s[14:15]
	s_mov_b32 m0, s30
	v_add_u32_e32 v230, 0x2000, v155
	s_barrier
	ds_read_b128 v[164:167], v136 offset:16384
	ds_read_b128 v[174:177], v136 offset:17408
	ds_read_b128 v[178:181], v135 offset:16384
	ds_read_b128 v[182:185], v135 offset:17408
	ds_read_b128 v[186:189], v134 offset:16384
	ds_read_b128 v[190:193], v134 offset:17408
	ds_read_b128 v[194:197], v133 offset:16384
	ds_read_b128 v[198:201], v133 offset:17408
	global_load_lds_dwordx4 v[226:227], off
	v_lshl_add_u64 v[226:227], s[26:27], 0, v[130:131]
	v_readfirstlane_b32 s30, v230
	v_lshl_add_u64 v[228:229], v[226:227], 0, s[14:15]
	s_mov_b32 m0, s30
	s_add_u32 s26, s26, 0x100
	global_load_lds_dwordx4 v[228:229], off
	s_barrier
	s_waitcnt lgkmcnt(0)
	s_addc_u32 s27, s27, 0
	s_setprio 1
	s_waitcnt lgkmcnt(0)
	v_mfma_f32_16x16x32_bf16 v[62:65], v[164:167], v[146:149], v[62:65]
	v_mfma_f32_16x16x32_bf16 v[58:61], v[164:167], v[156:159], v[58:61]
	v_mfma_f32_16x16x32_bf16 v[54:57], v[178:181], v[146:149], v[54:57]
	v_mfma_f32_16x16x32_bf16 v[50:53], v[178:181], v[156:159], v[50:53]
	v_mfma_f32_16x16x32_bf16 v[46:49], v[186:189], v[146:149], v[46:49]
	v_mfma_f32_16x16x32_bf16 v[42:45], v[186:189], v[156:159], v[42:45]
	v_mfma_f32_16x16x32_bf16 v[38:41], v[194:197], v[146:149], v[38:41]
	v_mfma_f32_16x16x32_bf16 v[34:37], v[194:197], v[156:159], v[34:37]
	v_mfma_f32_16x16x32_bf16 v[62:65], v[174:177], v[150:153], v[62:65]
	v_mfma_f32_16x16x32_bf16 v[58:61], v[174:177], v[160:163], v[58:61]
	v_mfma_f32_16x16x32_bf16 v[54:57], v[182:185], v[150:153], v[54:57]
	v_mfma_f32_16x16x32_bf16 v[50:53], v[182:185], v[160:163], v[50:53]
	v_mfma_f32_16x16x32_bf16 v[46:49], v[190:193], v[150:153], v[46:49]
	v_mfma_f32_16x16x32_bf16 v[42:45], v[190:193], v[160:163], v[42:45]
	v_mfma_f32_16x16x32_bf16 v[38:41], v[198:201], v[150:153], v[38:41]
	v_mfma_f32_16x16x32_bf16 v[34:37], v[198:201], v[160:163], v[34:37]
	s_setprio 0
	s_barrier
; #define STAGE(P, GP, ktrel) do { const GAS char* _g = (GP) + (ktrel) * (BK * 2); \
;     __builtin_amdgcn_global_load_lds((const GAS unsigned*)(_g + so0), (unsigned*)((char*)(P) + tid_ * 16), 16, 0, 0); \
;     __builtin_amdgcn_global_load_lds((const GAS unsigned*)(_g + so1), (unsigned*)((char*)(P) + tid_ * 16 + 8192), 16, 0, 0); } while (0)
; #define WAIT_V(n) asm volatile("s_waitcnt vmcnt(" #n ")" ::: "memory")
; #define WAIT_L(n) asm volatile("s_waitcnt lgkmcnt(" #n ")" ::: "memory")
; #define BAR __builtin_amdgcn_s_barrier()
; #define SCHED __builtin_amdgcn_sched_barrier(0)
; #define LDA(dst, b, h) for (int m = 0; m < 4; ++m) for (int k = 0; k < 2; ++k) \
;     dst[m][k] = *reinterpret_cast<const bf16x8*>((char*)SA(b, h) + lds_byte(wr * 64 + m * 16 + fr, k * 32 + fq * 8))
; #define LDB(dst, b, h) for (int n = 0; n < 2; ++n) for (int k = 0; k < 2; ++k) \
;     dst[n][k] = *reinterpret_cast<const bf16x8*>((char*)SB(b, h) + lds_byte(wc * 32 + n * 16 + fr, k * 32 + fq * 8))
; #define MMA(ai, bj, At_, Bt_) do { __builtin_amdgcn_s_setprio(1); \
;     for (int m = 0; m < 4; ++m) for (int n = 0; n < 2; ++n) for (int k = 0; k < 2; ++k) \
;       acc[ai][bj][m][n] = __builtin_amdgcn_mfma_f32_16x16x32_bf16(At_[m][k], Bt_[n][k], acc[ai][bj][m][n], 0, 0, 0); \
;     __builtin_amdgcn_s_setprio(0); } while (0)
; template <int K, int LD = K>
; __device__ __forceinline__ void gemm_main(const GAS bf16* A, const GAS bf16* Bt, int brow, int bcol, f32x4 (&acc)[2][2][4][2]) {
;     ...
;     STAGE(SB(0, 1), pB1, 2);
;     WAIT_V(6); BAR; MMA(1, 1, At, B1); BAR;
;     LDB(B0, 1, 0); SCHED; LDA(At, 1, 0); STAGE(SA(0, 1), pA1, 2);
;     WAIT_L(8); BAR; WAIT_L(0); MMA(0, 0, At, B0); BAR; SCHED;
;     LDB(B1, 1, 1); STAGE(SB(1, 0), pB0, 3);
;     BAR; WAIT_L(0); MMA(0, 1, At, B1); BAR;
;     LDA(At, 1, 1); STAGE(SA(1, 0), pA0, 3);
;     BAR; WAIT_L(0); MMA(1, 0, At, B0); BAR; SCHED;
;     STAGE(SB(1, 1), pB1, 3);
;     WAIT_V(6); BAR; MMA(1, 1, At, B1); BAR;
	v_add_u32_e32 v148, s39, v141
	v_lshl_add_u64 v[228:229], s[24:25], 0, v[138:139]
	v_readfirstlane_b32 s30, v148
	v_add_u32_e32 v148, 0x2000, v148
	v_lshl_add_u64 v[146:147], v[228:229], 0, s[14:15]
	s_mov_b32 m0, s30
	v_lshl_add_u64 v[230:231], s[24:25], 0, v[130:131]
	v_readfirstlane_b32 s30, v148
	global_load_lds_dwordx4 v[146:147], off
	v_lshl_add_u64 v[146:147], v[230:231], 0, s[14:15]
	s_mov_b32 m0, s30
	s_add_u32 s24, s24, 0x100
	global_load_lds_dwordx4 v[146:147], off
	s_waitcnt vmcnt(10)
	s_addc_u32 s25, s25, 0
	s_barrier
	s_setprio 1
	v_mfma_f32_16x16x32_bf16 v[30:33], v[164:167], v[202:205], v[30:33]
	v_mfma_f32_16x16x32_bf16 v[26:29], v[164:167], v[210:213], v[26:29]
	v_mfma_f32_16x16x32_bf16 v[22:25], v[178:181], v[202:205], v[22:25]
	v_mfma_f32_16x16x32_bf16 v[18:21], v[178:181], v[210:213], v[18:21]
	v_mfma_f32_16x16x32_bf16 v[14:17], v[186:189], v[202:205], v[14:17]
	v_mfma_f32_16x16x32_bf16 v[10:13], v[186:189], v[210:213], v[10:13]
	v_mfma_f32_16x16x32_bf16 v[6:9], v[194:197], v[202:205], v[6:9]
	v_mfma_f32_16x16x32_bf16 v[2:5], v[194:197], v[210:213], v[2:5]
	v_mfma_f32_16x16x32_bf16 v[30:33], v[174:177], v[206:209], v[30:33]
	v_mfma_f32_16x16x32_bf16 v[26:29], v[174:177], v[214:217], v[26:29]
	v_mfma_f32_16x16x32_bf16 v[22:25], v[182:185], v[206:209], v[22:25]
	v_mfma_f32_16x16x32_bf16 v[18:21], v[182:185], v[214:217], v[18:21]
	v_mfma_f32_16x16x32_bf16 v[14:17], v[190:193], v[206:209], v[14:17]
	v_mfma_f32_16x16x32_bf16 v[10:13], v[190:193], v[214:217], v[10:13]
	v_mfma_f32_16x16x32_bf16 v[6:9], v[198:201], v[206:209], v[6:9]
	v_mfma_f32_16x16x32_bf16 v[2:5], v[198:201], v[214:217], v[2:5]
	s_setprio 0
	s_barrier
	ds_read_b128 v[146:149], v140
	ds_read_b128 v[150:153], v140 offset:1024
	ds_read_b128 v[156:159], v140 offset:2048
	ds_read_b128 v[160:163], v140 offset:3072
	v_add_u32_e32 v202, 0x4000, v155
	v_lshl_add_u64 v[168:169], v[168:169], 0, s[14:15]
	v_readfirstlane_b32 s30, v202
	v_add_u32_e32 v202, 0x6000, v155
	s_mov_b32 m0, s30
	v_readfirstlane_b32 s30, v202
	ds_read_b128 v[164:167], v136 offset:32768
	ds_read_b128 v[174:177], v136 offset:33792
	ds_read_b128 v[178:181], v135 offset:32768
	ds_read_b128 v[182:185], v135 offset:33792
	ds_read_b128 v[186:189], v134 offset:32768
	ds_read_b128 v[190:193], v134 offset:33792
	ds_read_b128 v[194:197], v133 offset:32768
	ds_read_b128 v[198:201], v133 offset:33792
	global_load_lds_dwordx4 v[168:169], off
	v_lshl_add_u64 v[168:169], v[218:219], 0, s[14:15]
	s_mov_b32 m0, s30
	s_add_u32 s18, s18, 0x100
	global_load_lds_dwordx4 v[168:169], off
	s_waitcnt lgkmcnt(8)
	s_waitcnt vmcnt(10)
	s_barrier
	s_waitcnt lgkmcnt(0)
	s_addc_u32 s19, s19, 0
	s_setprio 1
	s_waitcnt lgkmcnt(0)
	v_mfma_f32_16x16x32_bf16 v[126:129], v[164:167], v[146:149], v[126:129]
	v_mfma_f32_16x16x32_bf16 v[122:125], v[164:167], v[156:159], v[122:125]
	v_mfma_f32_16x16x32_bf16 v[118:121], v[178:181], v[146:149], v[118:121]
	v_mfma_f32_16x16x32_bf16 v[114:117], v[178:181], v[156:159], v[114:117]
	v_mfma_f32_16x16x32_bf16 v[110:113], v[186:189], v[146:149], v[110:113]
	v_mfma_f32_16x16x32_bf16 v[106:109], v[186:189], v[156:159], v[106:109]
	v_mfma_f32_16x16x32_bf16 v[102:105], v[194:197], v[146:149], v[102:105]
	v_mfma_f32_16x16x32_bf16 v[98:101], v[194:197], v[156:159], v[98:101]
	v_mfma_f32_16x16x32_bf16 v[126:129], v[174:177], v[150:153], v[126:129]
	v_mfma_f32_16x16x32_bf16 v[122:125], v[174:177], v[160:163], v[122:125]
	v_mfma_f32_16x16x32_bf16 v[118:121], v[182:185], v[150:153], v[118:121]
	v_mfma_f32_16x16x32_bf16 v[114:117], v[182:185], v[160:163], v[114:117]
	v_mfma_f32_16x16x32_bf16 v[110:113], v[190:193], v[150:153], v[110:113]
	v_mfma_f32_16x16x32_bf16 v[106:109], v[190:193], v[160:163], v[106:109]
	v_mfma_f32_16x16x32_bf16 v[102:105], v[198:201], v[150:153], v[102:105]
	v_mfma_f32_16x16x32_bf16 v[98:101], v[198:201], v[160:163], v[98:101]
	s_setprio 0
	s_barrier
	v_add_u32_e32 v218, s40, v141
	v_lshl_add_u64 v[168:169], v[220:221], 0, s[16:17]
	v_readfirstlane_b32 s30, v218
	v_add_u32_e32 v218, 0x2000, v218
	s_mov_b32 m0, s30
	v_readfirstlane_b32 s30, v218
	ds_read_b128 v[202:205], v137
	ds_read_b128 v[206:209], v137 offset:1024
	ds_read_b128 v[210:213], v137 offset:2048
	ds_read_b128 v[214:217], v137 offset:3072
	global_load_lds_dwordx4 v[168:169], off
	v_lshl_add_u64 v[168:169], v[222:223], 0, s[16:17]
	s_mov_b32 m0, s30
	s_nop 0
	global_load_lds_dwordx4 v[168:169], off
	s_waitcnt vmcnt(10)
	s_barrier
	s_waitcnt lgkmcnt(0)
	s_setprio 1
	s_waitcnt lgkmcnt(0)
	v_mfma_f32_16x16x32_bf16 v[94:97], v[164:167], v[202:205], v[94:97]
	v_mfma_f32_16x16x32_bf16 v[90:93], v[164:167], v[210:213], v[90:93]
	v_mfma_f32_16x16x32_bf16 v[86:89], v[178:181], v[202:205], v[86:89]
	v_mfma_f32_16x16x32_bf16 v[82:85], v[178:181], v[210:213], v[82:85]
	v_mfma_f32_16x16x32_bf16 v[78:81], v[186:189], v[202:205], v[78:81]
	v_mfma_f32_16x16x32_bf16 v[74:77], v[186:189], v[210:213], v[74:77]
	v_mfma_f32_16x16x32_bf16 v[70:73], v[194:197], v[202:205], v[70:73]
	v_mfma_f32_16x16x32_bf16 v[66:69], v[194:197], v[210:213], v[66:69]
	v_mfma_f32_16x16x32_bf16 v[94:97], v[174:177], v[206:209], v[94:97]
	v_mfma_f32_16x16x32_bf16 v[90:93], v[174:177], v[214:217], v[90:93]
	v_mfma_f32_16x16x32_bf16 v[86:89], v[182:185], v[206:209], v[86:89]
	v_mfma_f32_16x16x32_bf16 v[82:85], v[182:185], v[214:217], v[82:85]
	v_mfma_f32_16x16x32_bf16 v[78:81], v[190:193], v[206:209], v[78:81]
	v_mfma_f32_16x16x32_bf16 v[74:77], v[190:193], v[214:217], v[74:77]
	v_mfma_f32_16x16x32_bf16 v[70:73], v[198:201], v[206:209], v[70:73]
	v_mfma_f32_16x16x32_bf16 v[66:69], v[198:201], v[214:217], v[66:69]
	s_setprio 0
	v_add_u32_e32 v218, 0x8000, v155
	v_add_u32_e32 v155, 0xa000, v155
	v_readfirstlane_b32 s30, v218
	v_lshl_add_u64 v[168:169], v[224:225], 0, s[16:17]
	s_mov_b32 m0, s30
	v_readfirstlane_b32 s30, v155
	s_barrier
; #define STAGE(P, GP, ktrel) do { const GAS char* _g = (GP) + (ktrel) * (BK * 2); \
;     __builtin_amdgcn_global_load_lds((const GAS unsigned*)(_g + so0), (unsigned*)((char*)(P) + tid_ * 16), 16, 0, 0); \
;     __builtin_amdgcn_global_load_lds((const GAS unsigned*)(_g + so1), (unsigned*)((char*)(P) + tid_ * 16 + 8192), 16, 0, 0); } while (0)
; #define WAIT_V(n) asm volatile("s_waitcnt vmcnt(" #n ")" ::: "memory")
; #define WAIT_L(n) asm volatile("s_waitcnt lgkmcnt(" #n ")" ::: "memory")
; #define BAR __builtin_amdgcn_s_barrier()
; #define SCHED __builtin_amdgcn_sched_barrier(0)
; #define LDA(dst, b, h) for (int m = 0; m < 4; ++m) for (int k = 0; k < 2; ++k) \
;     dst[m][k] = *reinterpret_cast<const bf16x8*>((char*)SA(b, h) + lds_byte(wr * 64 + m * 16 + fr, k * 32 + fq * 8))
; #define LDB(dst, b, h) for (int n = 0; n < 2; ++n) for (int k = 0; k < 2; ++k) \
;     dst[n][k] = *reinterpret_cast<const bf16x8*>((char*)SB(b, h) + lds_byte(wc * 32 + n * 16 + fr, k * 32 + fq * 8))
; #define MMA(ai, bj, At_, Bt_) do { __builtin_amdgcn_s_setprio(1); \
;     for (int m = 0; m < 4; ++m) for (int n = 0; n < 2; ++n) for (int k = 0; k < 2; ++k) \
;       acc[ai][bj][m][n] = __builtin_amdgcn_mfma_f32_16x16x32_bf16(At_[m][k], Bt_[n][k], acc[ai][bj][m][n], 0, 0, 0); \
;     __builtin_amdgcn_s_setprio(0); } while (0)
; template <int K, int LD = K>
; __device__ __forceinline__ void gemm_main(const GAS bf16* A, const GAS bf16* Bt, int brow, int bcol, f32x4 (&acc)[2][2][4][2]) {
;     ...
;     LDA(At, 1, 1); STAGE(SA(1, 0), pA0, 3);
;     BAR; WAIT_L(0); MMA(1, 0, At, B0); BAR; SCHED;
;     STAGE(SB(1, 1), pB1, 3);
;     WAIT_V(6); BAR; MMA(1, 1, At, B1); BAR;
;     pA0 += 4 * BK; pA1 += 4 * BK; pB0 += 4 * BK; pB1 += 4 * BK;
;     asm volatile("" : "+s"(pA0), "+s"(pA1), "+s"(pB0), "+s"(pB1));
;   }
;   { LDB(B0, 0, 0); LDA(At, 0, 0); STAGE(SA(1, 1), pA1, 1);
;     BAR; WAIT_L(0); MMA(0, 0, At, B0); BAR;
;     LDB(B1, 0, 1); BAR; WAIT_L(0); MMA(0, 1, At, B1); BAR;
;     LDA(At, 0, 1); WAIT_V(4); BAR; WAIT_L(0); MMA(1, 0, At, B0); MMA(1, 1, At, B1); BAR; }
	ds_read_b128 v[164:167], v136 offset:49152
	ds_read_b128 v[174:177], v136 offset:50176
	ds_read_b128 v[178:181], v135 offset:49152
	ds_read_b128 v[182:185], v135 offset:50176
	ds_read_b128 v[186:189], v134 offset:49152
	ds_read_b128 v[190:193], v134 offset:50176
	ds_read_b128 v[194:197], v133 offset:49152
	ds_read_b128 v[198:201], v133 offset:50176
	global_load_lds_dwordx4 v[168:169], off
	v_lshl_add_u64 v[168:169], v[226:227], 0, s[16:17]
	s_mov_b32 m0, s30
	s_nop 0
	global_load_lds_dwordx4 v[168:169], off
	s_barrier
	s_waitcnt lgkmcnt(0)
	s_setprio 1
	s_waitcnt lgkmcnt(0)
	v_mfma_f32_16x16x32_bf16 v[62:65], v[164:167], v[146:149], v[62:65]
	v_mfma_f32_16x16x32_bf16 v[58:61], v[164:167], v[156:159], v[58:61]
	v_mfma_f32_16x16x32_bf16 v[54:57], v[178:181], v[146:149], v[54:57]
	v_mfma_f32_16x16x32_bf16 v[50:53], v[178:181], v[156:159], v[50:53]
	v_mfma_f32_16x16x32_bf16 v[46:49], v[186:189], v[146:149], v[46:49]
	v_mfma_f32_16x16x32_bf16 v[42:45], v[186:189], v[156:159], v[42:45]
	v_mfma_f32_16x16x32_bf16 v[38:41], v[194:197], v[146:149], v[38:41]
	v_mfma_f32_16x16x32_bf16 v[34:37], v[194:197], v[156:159], v[34:37]
	v_mfma_f32_16x16x32_bf16 v[62:65], v[174:177], v[150:153], v[62:65]
	v_mfma_f32_16x16x32_bf16 v[58:61], v[174:177], v[160:163], v[58:61]
	v_mfma_f32_16x16x32_bf16 v[54:57], v[182:185], v[150:153], v[54:57]
	v_mfma_f32_16x16x32_bf16 v[50:53], v[182:185], v[160:163], v[50:53]
	v_mfma_f32_16x16x32_bf16 v[46:49], v[190:193], v[150:153], v[46:49]
	v_mfma_f32_16x16x32_bf16 v[42:45], v[190:193], v[160:163], v[42:45]
	v_mfma_f32_16x16x32_bf16 v[38:41], v[198:201], v[150:153], v[38:41]
	v_mfma_f32_16x16x32_bf16 v[34:37], v[198:201], v[160:163], v[34:37]
	s_setprio 0
	s_barrier
	v_add_u32_e32 v148, s41, v141
	v_lshl_add_u64 v[146:147], v[228:229], 0, s[16:17]
	v_readfirstlane_b32 s30, v148
	v_add_u32_e32 v148, 0x2000, v148
	s_mov_b32 m0, s30
	v_readfirstlane_b32 s30, v148
	global_load_lds_dwordx4 v[146:147], off
	v_lshl_add_u64 v[146:147], v[230:231], 0, s[16:17]
	s_mov_b32 m0, s30
	s_nop 0
	global_load_lds_dwordx4 v[146:147], off
	s_waitcnt vmcnt(10)
	s_barrier
	s_setprio 1
	v_mfma_f32_16x16x32_bf16 v[30:33], v[164:167], v[202:205], v[30:33]
	v_mfma_f32_16x16x32_bf16 v[26:29], v[164:167], v[210:213], v[26:29]
	v_mfma_f32_16x16x32_bf16 v[22:25], v[178:181], v[202:205], v[22:25]
	v_mfma_f32_16x16x32_bf16 v[18:21], v[178:181], v[210:213], v[18:21]
	v_mfma_f32_16x16x32_bf16 v[14:17], v[186:189], v[202:205], v[14:17]
	v_mfma_f32_16x16x32_bf16 v[10:13], v[186:189], v[210:213], v[10:13]
	v_mfma_f32_16x16x32_bf16 v[6:9], v[194:197], v[202:205], v[6:9]
	v_mfma_f32_16x16x32_bf16 v[2:5], v[194:197], v[210:213], v[2:5]
	v_mfma_f32_16x16x32_bf16 v[30:33], v[174:177], v[206:209], v[30:33]
	v_mfma_f32_16x16x32_bf16 v[26:29], v[174:177], v[214:217], v[26:29]
	v_mfma_f32_16x16x32_bf16 v[22:25], v[182:185], v[206:209], v[22:25]
	v_mfma_f32_16x16x32_bf16 v[18:21], v[182:185], v[214:217], v[18:21]
	v_mfma_f32_16x16x32_bf16 v[14:17], v[190:193], v[206:209], v[14:17]
	v_mfma_f32_16x16x32_bf16 v[10:13], v[190:193], v[214:217], v[10:13]
	v_mfma_f32_16x16x32_bf16 v[6:9], v[198:201], v[206:209], v[6:9]
	v_mfma_f32_16x16x32_bf16 v[2:5], v[198:201], v[214:217], v[2:5]
	s_setprio 0
	s_add_i32 s21, s21, 2
	s_cmp_lt_u32 s21, 12
	s_barrier
	s_cbranch_scc1 .LBB0_1226
	v_lshl_add_u64 v[168:169], s[18:19], 0, v[138:139]
	v_readfirstlane_b32 s21, v144
	v_lshl_add_u64 v[168:169], v[168:169], 0, s[8:9]
	s_mov_b32 m0, s21
	v_lshl_add_u64 v[130:131], s[18:19], 0, v[130:131]
	v_readfirstlane_b32 s18, v145
	ds_read_b128 v[146:149], v143
	ds_read_b128 v[150:153], v143 offset:1024
	ds_read_b128 v[156:159], v143 offset:2048
	ds_read_b128 v[160:163], v143 offset:3072
	ds_read_b128 v[164:167], v136
	ds_read_b128 v[174:177], v136 offset:1024
	ds_read_b128 v[178:181], v135
	ds_read_b128 v[182:185], v135 offset:1024
	ds_read_b128 v[186:189], v134
	ds_read_b128 v[190:193], v134 offset:1024
	ds_read_b128 v[194:197], v133
	ds_read_b128 v[198:201], v133 offset:1024
	global_load_lds_dwordx4 v[168:169], off
	v_lshl_add_u64 v[130:131], v[130:131], 0, s[8:9]
	s_mov_b32 m0, s18
	s_nop 0
	global_load_lds_dwordx4 v[130:131], off
	s_waitcnt vmcnt(10)
	s_barrier
	s_waitcnt lgkmcnt(0)
	s_setprio 1
	s_waitcnt lgkmcnt(0)
	v_mfma_f32_16x16x32_bf16 v[126:129], v[164:167], v[146:149], v[126:129]
	v_mfma_f32_16x16x32_bf16 v[122:125], v[164:167], v[156:159], v[122:125]
	v_mfma_f32_16x16x32_bf16 v[110:113], v[186:189], v[146:149], v[110:113]
	v_mfma_f32_16x16x32_bf16 v[106:109], v[186:189], v[156:159], v[106:109]
	v_mfma_f32_16x16x32_bf16 v[126:129], v[174:177], v[150:153], v[126:129]
	v_mfma_f32_16x16x32_bf16 v[122:125], v[174:177], v[160:163], v[122:125]
	v_mfma_f32_16x16x32_bf16 v[118:121], v[178:181], v[146:149], v[118:121]
	v_mfma_f32_16x16x32_bf16 v[114:117], v[178:181], v[156:159], v[114:117]
	v_mfma_f32_16x16x32_bf16 v[110:113], v[190:193], v[150:153], v[110:113]
	v_mfma_f32_16x16x32_bf16 v[106:109], v[190:193], v[160:163], v[106:109]
	v_mfma_f32_16x16x32_bf16 v[102:105], v[194:197], v[146:149], v[102:105]
	v_mfma_f32_16x16x32_bf16 v[98:101], v[194:197], v[156:159], v[98:101]
	v_mfma_f32_16x16x32_bf16 v[202:205], v[182:185], v[150:153], v[118:121]
	v_mfma_f32_16x16x32_bf16 v[206:209], v[182:185], v[160:163], v[114:117]
	v_mfma_f32_16x16x32_bf16 v[210:213], v[198:201], v[150:153], v[102:105]
	v_mfma_f32_16x16x32_bf16 v[214:217], v[198:201], v[160:163], v[98:101]
	s_setprio 0
	s_barrier
	s_nop 1
	ds_read_b128 v[98:101], v142
	ds_read_b128 v[102:105], v142 offset:1024
	ds_read_b128 v[114:117], v142 offset:2048
	ds_read_b128 v[118:121], v142 offset:3072
	s_waitcnt vmcnt(8)
	s_barrier
; #define WAIT_V(n) asm volatile("s_waitcnt vmcnt(" #n ")" ::: "memory")
; #define WAIT_L(n) asm volatile("s_waitcnt lgkmcnt(" #n ")" ::: "memory")
; #define BAR __builtin_amdgcn_s_barrier()
; #define LDA(dst, b, h) for (int m = 0; m < 4; ++m) for (int k = 0; k < 2; ++k) \
;     dst[m][k] = *reinterpret_cast<const bf16x8*>((char*)SA(b, h) + lds_byte(wr * 64 + m * 16 + fr, k * 32 + fq * 8))
; #define LDB(dst, b, h) for (int n = 0; n < 2; ++n) for (int k = 0; k < 2; ++k) \
;     dst[n][k] = *reinterpret_cast<const bf16x8*>((char*)SB(b, h) + lds_byte(wc * 32 + n * 16 + fr, k * 32 + fq * 8))
; #define MMA(ai, bj, At_, Bt_) do { __builtin_amdgcn_s_setprio(1); \
;     for (int m = 0; m < 4; ++m) for (int n = 0; n < 2; ++n) for (int k = 0; k < 2; ++k) \
;       acc[ai][bj][m][n] = __builtin_amdgcn_mfma_f32_16x16x32_bf16(At_[m][k], Bt_[n][k], acc[ai][bj][m][n], 0, 0, 0); \
;     __builtin_amdgcn_s_setprio(0); } while (0)
; template <int K, int LD = K>
; __device__ __forceinline__ void gemm_main(const GAS bf16* A, const GAS bf16* Bt, int brow, int bcol, f32x4 (&acc)[2][2][4][2]) {
;     ...
;     LDB(B1, 0, 1); BAR; WAIT_L(0); MMA(0, 1, At, B1); BAR;
;     LDA(At, 0, 1); WAIT_V(4); BAR; WAIT_L(0); MMA(1, 0, At, B0); MMA(1, 1, At, B1); BAR; }
;   { LDB(B0, 1, 0); LDA(At, 1, 0); WAIT_V(2); BAR; WAIT_L(0); MMA(0, 0, At, B0); BAR;
;     LDB(B1, 1, 1); WAIT_V(0); BAR; WAIT_L(0); MMA(0, 1, At, B1); BAR;
	s_waitcnt lgkmcnt(0)
	s_setprio 1
	s_waitcnt lgkmcnt(0)
	v_mfma_f32_16x16x32_bf16 v[94:97], v[164:167], v[98:101], v[94:97]
	v_mfma_f32_16x16x32_bf16 v[90:93], v[164:167], v[114:117], v[90:93]
	v_mfma_f32_16x16x32_bf16 v[78:81], v[186:189], v[98:101], v[78:81]
	v_mfma_f32_16x16x32_bf16 v[74:77], v[186:189], v[114:117], v[74:77]
	v_mfma_f32_16x16x32_bf16 v[94:97], v[174:177], v[102:105], v[94:97]
	v_mfma_f32_16x16x32_bf16 v[90:93], v[174:177], v[118:121], v[90:93]
	v_mfma_f32_16x16x32_bf16 v[86:89], v[178:181], v[98:101], v[86:89]
	v_mfma_f32_16x16x32_bf16 v[82:85], v[178:181], v[114:117], v[82:85]
	v_mfma_f32_16x16x32_bf16 v[78:81], v[190:193], v[102:105], v[78:81]
	v_mfma_f32_16x16x32_bf16 v[74:77], v[190:193], v[118:121], v[74:77]
	v_mfma_f32_16x16x32_bf16 v[70:73], v[194:197], v[98:101], v[70:73]
	v_mfma_f32_16x16x32_bf16 v[66:69], v[194:197], v[114:117], v[66:69]
	v_mfma_f32_16x16x32_bf16 v[142:145], v[182:185], v[102:105], v[86:89]
	v_mfma_f32_16x16x32_bf16 v[164:167], v[182:185], v[118:121], v[82:85]
	v_mfma_f32_16x16x32_bf16 v[174:177], v[198:201], v[102:105], v[70:73]
	v_mfma_f32_16x16x32_bf16 v[178:181], v[198:201], v[118:121], v[66:69]
	s_setprio 0
	s_barrier
	s_nop 1
	ds_read_b128 v[66:69], v136 offset:16384
	ds_read_b128 v[70:73], v136 offset:17408
	ds_read_b128 v[82:85], v135 offset:16384
	ds_read_b128 v[86:89], v135 offset:17408
	ds_read_b128 v[182:185], v134 offset:16384
	ds_read_b128 v[186:189], v134 offset:17408
	ds_read_b128 v[190:193], v133 offset:16384
	ds_read_b128 v[194:197], v133 offset:17408
	s_waitcnt vmcnt(4)
	s_barrier
	s_waitcnt lgkmcnt(0)
	s_setprio 1
	s_waitcnt lgkmcnt(0)
	v_mfma_f32_16x16x32_bf16 v[62:65], v[66:69], v[146:149], v[62:65]
	v_mfma_f32_16x16x32_bf16 v[58:61], v[66:69], v[156:159], v[58:61]
	v_mfma_f32_16x16x32_bf16 v[46:49], v[182:185], v[146:149], v[46:49]
	v_mfma_f32_16x16x32_bf16 v[42:45], v[182:185], v[156:159], v[42:45]
	v_mfma_f32_16x16x32_bf16 v[62:65], v[70:73], v[150:153], v[62:65]
	v_mfma_f32_16x16x32_bf16 v[58:61], v[70:73], v[160:163], v[58:61]
	v_mfma_f32_16x16x32_bf16 v[54:57], v[82:85], v[146:149], v[54:57]
	v_mfma_f32_16x16x32_bf16 v[50:53], v[82:85], v[156:159], v[50:53]
	v_mfma_f32_16x16x32_bf16 v[46:49], v[186:189], v[150:153], v[46:49]
	v_mfma_f32_16x16x32_bf16 v[42:45], v[186:189], v[160:163], v[42:45]
	v_mfma_f32_16x16x32_bf16 v[38:41], v[190:193], v[146:149], v[38:41]
	v_mfma_f32_16x16x32_bf16 v[34:37], v[190:193], v[156:159], v[34:37]
	v_mfma_f32_16x16x32_bf16 v[198:201], v[86:89], v[150:153], v[54:57]
	v_mfma_f32_16x16x32_bf16 v[218:221], v[86:89], v[160:163], v[50:53]
	v_mfma_f32_16x16x32_bf16 v[146:149], v[194:197], v[150:153], v[38:41]
	v_mfma_f32_16x16x32_bf16 v[150:153], v[194:197], v[160:163], v[34:37]
	s_setprio 0
	s_setprio 1
	v_mfma_f32_16x16x32_bf16 v[30:33], v[66:69], v[98:101], v[30:33]
	v_mfma_f32_16x16x32_bf16 v[26:29], v[66:69], v[114:117], v[26:29]
	v_mfma_f32_16x16x32_bf16 v[10:13], v[182:185], v[114:117], v[10:13]
	v_mfma_f32_16x16x32_bf16 v[2:5], v[190:193], v[114:117], v[2:5]
	v_mfma_f32_16x16x32_bf16 v[30:33], v[70:73], v[102:105], v[30:33]
	v_mfma_f32_16x16x32_bf16 v[26:29], v[70:73], v[118:121], v[26:29]
	v_mfma_f32_16x16x32_bf16 v[22:25], v[82:85], v[98:101], v[22:25]
	v_mfma_f32_16x16x32_bf16 v[18:21], v[82:85], v[114:117], v[18:21]
	v_mfma_f32_16x16x32_bf16 v[14:17], v[182:185], v[98:101], v[14:17]
	v_mfma_f32_16x16x32_bf16 v[10:13], v[186:189], v[118:121], v[10:13]
	v_mfma_f32_16x16x32_bf16 v[6:9], v[190:193], v[98:101], v[6:9]
	v_mfma_f32_16x16x32_bf16 v[2:5], v[194:197], v[118:121], v[2:5]
	v_mfma_f32_16x16x32_bf16 v[156:159], v[86:89], v[102:105], v[22:25]
	v_mfma_f32_16x16x32_bf16 v[160:163], v[86:89], v[118:121], v[18:21]
	v_mfma_f32_16x16x32_bf16 v[222:225], v[186:189], v[102:105], v[14:17]
	v_mfma_f32_16x16x32_bf16 v[182:185], v[194:197], v[102:105], v[6:9]
	s_setprio 0
	s_barrier
	s_nop 0
	ds_read_b128 v[6:9], v140
	ds_read_b128 v[14:17], v140 offset:1024
	ds_read_b128 v[186:189], v140 offset:2048
	ds_read_b128 v[190:193], v140 offset:3072
	ds_read_b128 v[18:21], v136 offset:32768
	ds_read_b128 v[22:25], v136 offset:33792
	ds_read_b128 v[34:37], v135 offset:32768
	ds_read_b128 v[38:41], v135 offset:33792
	ds_read_b128 v[50:53], v134 offset:32768
	ds_read_b128 v[54:57], v134 offset:33792
	ds_read_b128 v[194:197], v133 offset:32768
	ds_read_b128 v[226:229], v133 offset:33792
	s_waitcnt vmcnt(2)
	s_barrier
; #define WAIT_V(n) asm volatile("s_waitcnt vmcnt(" #n ")" ::: "memory")
; #define WAIT_L(n) asm volatile("s_waitcnt lgkmcnt(" #n ")" ::: "memory")
; #define BAR __builtin_amdgcn_s_barrier()
; #define LDA(dst, b, h) for (int m = 0; m < 4; ++m) for (int k = 0; k < 2; ++k) \
;     dst[m][k] = *reinterpret_cast<const bf16x8*>((char*)SA(b, h) + lds_byte(wr * 64 + m * 16 + fr, k * 32 + fq * 8))
; #define LDB(dst, b, h) for (int n = 0; n < 2; ++n) for (int k = 0; k < 2; ++k) \
;     dst[n][k] = *reinterpret_cast<const bf16x8*>((char*)SB(b, h) + lds_byte(wc * 32 + n * 16 + fr, k * 32 + fq * 8))
; #define MMA(ai, bj, At_, Bt_) do { __builtin_amdgcn_s_setprio(1); \
;     for (int m = 0; m < 4; ++m) for (int n = 0; n < 2; ++n) for (int k = 0; k < 2; ++k) \
;       acc[ai][bj][m][n] = __builtin_amdgcn_mfma_f32_16x16x32_bf16(At_[m][k], Bt_[n][k], acc[ai][bj][m][n], 0, 0, 0); \
;     __builtin_amdgcn_s_setprio(0); } while (0)
; template <int K, int LD = K>
; __device__ __forceinline__ void gemm_main(const GAS bf16* A, const GAS bf16* Bt, int brow, int bcol, f32x4 (&acc)[2][2][4][2]) {
;     ...
;   { LDB(B0, 1, 0); LDA(At, 1, 0); WAIT_V(2); BAR; WAIT_L(0); MMA(0, 0, At, B0); BAR;
;     LDB(B1, 1, 1); WAIT_V(0); BAR; WAIT_L(0); MMA(0, 1, At, B1); BAR;
;     LDA(At, 1, 1); BAR; WAIT_L(0); MMA(1, 0, At, B0); MMA(1, 1, At, B1); BAR; }
;   if (wr == 0) BAR;
	s_waitcnt lgkmcnt(0)
	s_setprio 1
	s_waitcnt lgkmcnt(0)
	v_mfma_f32_16x16x32_bf16 v[66:69], v[18:21], v[6:9], v[126:129]
	v_mfma_f32_16x16x32_bf16 v[118:121], v[22:25], v[14:17], v[66:69]
	v_mfma_f32_16x16x32_bf16 v[66:69], v[18:21], v[186:189], v[122:125]
	v_mfma_f32_16x16x32_bf16 v[114:117], v[22:25], v[190:193], v[66:69]
	v_mfma_f32_16x16x32_bf16 v[66:69], v[34:37], v[6:9], v[202:205]
	v_mfma_f32_16x16x32_bf16 v[102:105], v[38:41], v[14:17], v[66:69]
	v_mfma_f32_16x16x32_bf16 v[66:69], v[34:37], v[186:189], v[206:209]
	v_mfma_f32_16x16x32_bf16 v[98:101], v[38:41], v[190:193], v[66:69]
	v_mfma_f32_16x16x32_bf16 v[66:69], v[50:53], v[6:9], v[110:113]
	v_mfma_f32_16x16x32_bf16 v[86:89], v[54:57], v[14:17], v[66:69]
	v_mfma_f32_16x16x32_bf16 v[66:69], v[50:53], v[186:189], v[106:109]
	v_mfma_f32_16x16x32_bf16 v[82:85], v[54:57], v[190:193], v[66:69]
	v_mfma_f32_16x16x32_bf16 v[66:69], v[194:197], v[6:9], v[210:213]
	v_mfma_f32_16x16x32_bf16 v[70:73], v[226:229], v[14:17], v[66:69]
	v_mfma_f32_16x16x32_bf16 v[66:69], v[194:197], v[186:189], v[214:217]
	v_mfma_f32_16x16x32_bf16 v[66:69], v[226:229], v[190:193], v[66:69]
	s_setprio 0
	s_barrier
	ds_read_b128 v[202:205], v137
	ds_read_b128 v[206:209], v137 offset:1024
	ds_read_b128 v[210:213], v137 offset:2048
	ds_read_b128 v[214:217], v137 offset:3072
	s_waitcnt vmcnt(0)
	s_barrier
	s_waitcnt lgkmcnt(0)
	s_setprio 1
	s_waitcnt lgkmcnt(0)
	v_mfma_f32_16x16x32_bf16 v[94:97], v[18:21], v[202:205], v[94:97]
	v_mfma_f32_16x16x32_bf16 v[18:21], v[18:21], v[210:213], v[90:93]
	v_mfma_f32_16x16x32_bf16 v[122:125], v[22:25], v[214:217], v[18:21]
	v_mfma_f32_16x16x32_bf16 v[18:21], v[34:37], v[202:205], v[142:145]
	v_mfma_f32_16x16x32_bf16 v[110:113], v[38:41], v[206:209], v[18:21]
	v_mfma_f32_16x16x32_bf16 v[18:21], v[34:37], v[210:213], v[164:167]
	v_mfma_f32_16x16x32_bf16 v[106:109], v[38:41], v[214:217], v[18:21]
	v_mfma_f32_16x16x32_bf16 v[18:21], v[50:53], v[202:205], v[78:81]
	v_mfma_f32_16x16x32_bf16 v[126:129], v[22:25], v[206:209], v[94:97]
	v_mfma_f32_16x16x32_bf16 v[94:97], v[54:57], v[206:209], v[18:21]
	v_mfma_f32_16x16x32_bf16 v[18:21], v[50:53], v[210:213], v[74:77]
	v_mfma_f32_16x16x32_bf16 v[90:93], v[54:57], v[214:217], v[18:21]
	v_mfma_f32_16x16x32_bf16 v[18:21], v[194:197], v[202:205], v[174:177]
	v_mfma_f32_16x16x32_bf16 v[78:81], v[226:229], v[206:209], v[18:21]
	v_mfma_f32_16x16x32_bf16 v[18:21], v[194:197], v[210:213], v[178:181]
	v_mfma_f32_16x16x32_bf16 v[74:77], v[226:229], v[214:217], v[18:21]
	s_setprio 0
	s_barrier
	ds_read_b128 v[140:143], v136 offset:49152
	ds_read_b128 v[164:167], v136 offset:50176
	ds_read_b128 v[174:177], v135 offset:49152
	ds_read_b128 v[178:181], v135 offset:50176
	ds_read_b128 v[194:197], v134 offset:49152
	ds_read_b128 v[134:137], v134 offset:50176
	ds_read_b128 v[226:229], v133 offset:49152
	ds_read_b128 v[230:233], v133 offset:50176
	s_barrier
	s_waitcnt lgkmcnt(0)
	s_setprio 1
	s_waitcnt lgkmcnt(0)
	v_mfma_f32_16x16x32_bf16 v[18:21], v[140:143], v[6:9], v[62:65]
	v_mfma_f32_16x16x32_bf16 v[54:57], v[164:167], v[14:17], v[18:21]
	v_mfma_f32_16x16x32_bf16 v[18:21], v[140:143], v[186:189], v[58:61]
	v_mfma_f32_16x16x32_bf16 v[50:53], v[164:167], v[190:193], v[18:21]
	v_mfma_f32_16x16x32_bf16 v[18:21], v[174:177], v[6:9], v[198:201]
	v_mfma_f32_16x16x32_bf16 v[38:41], v[178:181], v[14:17], v[18:21]
	v_mfma_f32_16x16x32_bf16 v[18:21], v[174:177], v[186:189], v[218:221]
	v_mfma_f32_16x16x32_bf16 v[34:37], v[178:181], v[190:193], v[18:21]
	v_mfma_f32_16x16x32_bf16 v[18:21], v[194:197], v[6:9], v[46:49]
	v_mfma_f32_16x16x32_bf16 v[6:9], v[226:229], v[6:9], v[146:149]
	v_mfma_f32_16x16x32_bf16 v[22:25], v[134:137], v[14:17], v[18:21]
	v_mfma_f32_16x16x32_bf16 v[18:21], v[194:197], v[186:189], v[42:45]
	v_mfma_f32_16x16x32_bf16 v[14:17], v[230:233], v[14:17], v[6:9]
	v_mfma_f32_16x16x32_bf16 v[6:9], v[226:229], v[186:189], v[150:153]
	v_mfma_f32_16x16x32_bf16 v[18:21], v[134:137], v[190:193], v[18:21]
	v_mfma_f32_16x16x32_bf16 v[6:9], v[230:233], v[190:193], v[6:9]
	s_setprio 0
	s_setprio 1
	v_mfma_f32_16x16x32_bf16 v[26:29], v[140:143], v[210:213], v[26:29]
	v_mfma_f32_16x16x32_bf16 v[58:61], v[164:167], v[214:217], v[26:29]
	v_mfma_f32_16x16x32_bf16 v[26:29], v[174:177], v[202:205], v[156:159]
	v_mfma_f32_16x16x32_bf16 v[46:49], v[178:181], v[206:209], v[26:29]
	v_mfma_f32_16x16x32_bf16 v[26:29], v[174:177], v[210:213], v[160:163]
	v_mfma_f32_16x16x32_bf16 v[30:33], v[140:143], v[202:205], v[30:33]
	v_mfma_f32_16x16x32_bf16 v[42:45], v[178:181], v[214:217], v[26:29]
	v_mfma_f32_16x16x32_bf16 v[26:29], v[194:197], v[202:205], v[222:225]
	v_mfma_f32_16x16x32_bf16 v[10:13], v[194:197], v[210:213], v[10:13]
	v_mfma_f32_16x16x32_bf16 v[62:65], v[164:167], v[206:209], v[30:33]
	v_mfma_f32_16x16x32_bf16 v[30:33], v[134:137], v[206:209], v[26:29]
	v_mfma_f32_16x16x32_bf16 v[26:29], v[134:137], v[214:217], v[10:13]
	v_mfma_f32_16x16x32_bf16 v[10:13], v[226:229], v[202:205], v[182:185]
	v_mfma_f32_16x16x32_bf16 v[2:5], v[226:229], v[210:213], v[2:5]
	v_mfma_f32_16x16x32_bf16 v[10:13], v[230:233], v[206:209], v[10:13]
	v_mfma_f32_16x16x32_bf16 v[2:5], v[230:233], v[214:217], v[2:5]
	s_setprio 0
	v_cmp_gt_u32_e32 vcc, s42, v132
	s_barrier
	s_and_saveexec_b64 s[18:19], vcc
	s_cbranch_execz .LBB0_1229
	s_barrier
